# v28 = v27 + small-GEMM blocks of prep items and conv tiles: weight-fragment loads renamed into a free register ring, hoisted, counted vmcnt waits
# baseline (speedup 1.0000x reference)
.LBB0_386:
	v_ashrrev_i32_e32 v73, 31, v72
	v_bfe_u32 v2, v7, 16, 1
	v_add3_u32 v4, v7, v2, s58
	v_lshlrev_b64 v[2:3], 6, v[72:73]
	v_lshl_add_u64 v[0:1], v[0:1], 0, v[2:3]
	global_store_short_d16_hi v[0:1], v4, off
	v_mov_b32_e32 v1, v65
	s_waitcnt lgkmcnt(0)
	s_barrier
	v_lshlrev_b32_e32 v0, 1, v79
	v_mbcnt_lo_u32_b32 v1, -1, v1
	v_mbcnt_hi_u32_b32 v2, -1, v1
	v_and_b32_e32 v20, 31, v2
	s_movk_i32 s0, 0xff80
	v_and_or_b32 v0, v0, s0, v20
	v_ashrrev_i32_e32 v1, 31, v0
	v_ashrrev_i32_e32 v2, 2, v2
	v_lshlrev_b64 v[0:1], 8, v[0:1]
	v_and_b32_e32 v16, -8, v2
	v_lshl_add_u64 v[0:1], s[8:9], 0, v[0:1]
	v_ashrrev_i32_e32 v17, 31, v16
	v_lshl_add_u64 v[18:19], v[16:17], 1, v[0:1]
	s_mov_b32 s0, 0x1710000
	v_add_co_u32_e32 v0, vcc, s0, v18
	s_mov_b32 s0, 0x1712000
	s_nop 0
	v_addc_co_u32_e32 v1, vcc, 0, v19, vcc
	v_add_co_u32_e32 v76, vcc, s0, v18
	s_mov_b32 s0, 0x1714000
	s_nop 0
	v_addc_co_u32_e32 v77, vcc, 0, v19, vcc
	v_add_co_u32_e32 v74, vcc, s0, v18
	s_mov_b32 s0, 0x1716000
	s_nop 0
	v_addc_co_u32_e32 v75, vcc, 0, v19, vcc
	v_add_co_u32_e32 v118, vcc, s0, v18
	global_load_dwordx4 v[0:3], v[0:1], off
	s_nop 0
	v_addc_co_u32_e32 v119, vcc, 0, v19, vcc
	global_load_dwordx4 v[4:7], v[76:77], off
	global_load_dwordx4 v[98:101], v[76:77], off offset:32
	global_load_dwordx4 v[8:11], v[74:75], off
	global_load_dwordx4 v[12:15], v[118:119], off
	v_lshlrev_b32_e32 v16, 1, v16
	s_mov_b64 s[0:1], 0x1710000
	v_mad_u32_u24 v64, v20, s56, v16
	ds_read_b128 v[86:89], v64
	ds_read_b128 v[94:97], v64 offset:32
	v_lshl_add_u64 v[120:121], v[18:19], 0, s[0:1]
	global_load_dwordx4 v[90:93], v[120:121], off offset:32
	global_load_dwordx4 v[102:105], v[74:75], off offset:32
	global_load_dwordx4 v[106:109], v[76:77], off offset:96
	global_load_dwordx4 v[110:113], v[118:119], off offset:32
	global_load_dwordx4 v[114:117], v[74:75], off offset:96
	s_waitcnt vmcnt(0) lgkmcnt(0)
	global_load_dwordx4 v[208:211], v[120:121], off offset:64
	global_load_dwordx4 v[212:215], v[76:77], off offset:64
	global_load_dwordx4 v[216:219], v[74:75], off offset:64
	global_load_dwordx4 v[220:223], v[118:119], off offset:64
	global_load_dwordx4 v[224:227], v[120:121], off offset:96
	global_load_dwordx4 v[228:231], v[118:119], off offset:96
	global_load_dwordx4 v[232:235], v[120:121], off offset:128
	global_load_dwordx4 v[236:239], v[76:77], off offset:128
	global_load_dwordx4 v[240:243], v[74:75], off offset:128
	global_load_dwordx4 v[244:247], v[118:119], off offset:128
	global_load_dwordx4 v[248:251], v[120:121], off offset:160
	v_mfma_f32_32x32x16_bf16 v[48:63], v[86:89], v[0:3], 0
	v_mfma_f32_32x32x16_bf16 v[32:47], v[86:89], v[4:7], 0
	v_mfma_f32_32x32x16_bf16 v[16:31], v[86:89], v[8:11], 0
	v_mfma_f32_32x32x16_bf16 v[0:15], v[86:89], v[12:15], 0
	v_mfma_f32_32x32x16_bf16 v[48:63], v[94:97], v[90:93], v[48:63]
	v_mfma_f32_32x32x16_bf16 v[32:47], v[94:97], v[98:101], v[32:47]
	v_mfma_f32_32x32x16_bf16 v[16:31], v[94:97], v[102:105], v[16:31]
	v_mfma_f32_32x32x16_bf16 v[0:15], v[94:97], v[110:113], v[0:15]
	ds_read_b128 v[94:97], v64 offset:64
	ds_read_b128 v[110:113], v64 offset:96
	s_waitcnt lgkmcnt(0)
	s_waitcnt vmcnt(10)
	v_mfma_f32_32x32x16_bf16 v[48:63], v[94:97], v[208:211], v[48:63]
	global_load_dwordx4 v[208:211], v[76:77], off offset:160
	s_waitcnt vmcnt(10)
	v_mfma_f32_32x32x16_bf16 v[32:47], v[94:97], v[212:215], v[32:47]
	global_load_dwordx4 v[212:215], v[74:75], off offset:160
	s_waitcnt vmcnt(10)
	v_mfma_f32_32x32x16_bf16 v[16:31], v[94:97], v[216:219], v[16:31]
	global_load_dwordx4 v[216:219], v[118:119], off offset:160
	s_waitcnt vmcnt(10)
	v_mfma_f32_32x32x16_bf16 v[0:15], v[94:97], v[220:223], v[0:15]
	global_load_dwordx4 v[220:223], v[120:121], off offset:192
	v_mfma_f32_32x32x16_bf16 v[32:47], v[110:113], v[106:109], v[32:47]
	s_waitcnt lgkmcnt(0)
	s_waitcnt vmcnt(10)
	v_mfma_f32_32x32x16_bf16 v[48:63], v[110:113], v[224:227], v[48:63]
	global_load_dwordx4 v[224:227], v[76:77], off offset:192
	v_mfma_f32_32x32x16_bf16 v[16:31], v[110:113], v[114:117], v[16:31]
	s_waitcnt lgkmcnt(0)
	s_waitcnt vmcnt(10)
	v_mfma_f32_32x32x16_bf16 v[0:15], v[110:113], v[228:231], v[0:15]
	global_load_dwordx4 v[228:231], v[74:75], off offset:192
	ds_read_b128 v[102:105], v64 offset:128
	ds_read_b128 v[110:113], v64 offset:160
	s_waitcnt lgkmcnt(0)
	s_waitcnt vmcnt(10)
	v_mfma_f32_32x32x16_bf16 v[48:63], v[102:105], v[232:235], v[48:63]
	global_load_dwordx4 v[232:235], v[118:119], off offset:192
	s_waitcnt vmcnt(10)
	v_mfma_f32_32x32x16_bf16 v[32:47], v[102:105], v[236:239], v[32:47]
	global_load_dwordx4 v[236:239], v[120:121], off offset:224
	s_waitcnt vmcnt(10)
	v_mfma_f32_32x32x16_bf16 v[16:31], v[102:105], v[240:243], v[16:31]
	global_load_dwordx4 v[240:243], v[76:77], off offset:224
	s_waitcnt vmcnt(10)
	v_mfma_f32_32x32x16_bf16 v[0:15], v[102:105], v[244:247], v[0:15]
	global_load_dwordx4 v[244:247], v[118:119], off offset:224
	s_waitcnt vmcnt(10)
	v_mfma_f32_32x32x16_bf16 v[48:63], v[110:113], v[248:251], v[48:63]
	global_load_dwordx4 v[248:251], v[74:75], off offset:224
	ds_read_b128 v[106:109], v64 offset:192
	s_waitcnt lgkmcnt(0)
	s_waitcnt vmcnt(10)
	v_mfma_f32_32x32x16_bf16 v[32:47], v[110:113], v[208:211], v[32:47]
	s_waitcnt vmcnt(9)
	v_mfma_f32_32x32x16_bf16 v[16:31], v[110:113], v[212:215], v[16:31]
	s_waitcnt vmcnt(8)
	v_mfma_f32_32x32x16_bf16 v[0:15], v[110:113], v[216:219], v[0:15]
	ds_read_b128 v[110:113], v64 offset:224
	s_waitcnt vmcnt(7)
	v_mfma_f32_32x32x16_bf16 v[48:63], v[106:109], v[220:223], v[48:63]
	s_waitcnt vmcnt(6)
	v_mfma_f32_32x32x16_bf16 v[32:47], v[106:109], v[224:227], v[32:47]
	s_waitcnt lgkmcnt(0)
	s_waitcnt vmcnt(5)
	v_mfma_f32_32x32x16_bf16 v[16:31], v[106:109], v[228:231], v[16:31]
	s_nop 0
	s_waitcnt vmcnt(4)
	v_mfma_f32_32x32x16_bf16 v[0:15], v[106:109], v[232:235], v[0:15]
	s_waitcnt vmcnt(3)
	v_mfma_f32_32x32x16_bf16 v[48:63], v[110:113], v[236:239], v[48:63]
	s_waitcnt vmcnt(2)
	v_mfma_f32_32x32x16_bf16 v[32:47], v[110:113], v[240:243], v[32:47]
	s_waitcnt lgkmcnt(0)
	s_waitcnt vmcnt(0)
	v_mfma_f32_32x32x16_bf16 v[16:31], v[110:113], v[248:251], v[16:31]
	v_mfma_f32_32x32x16_bf16 v[0:15], v[110:113], v[244:247], v[0:15]
	v_lshrrev_b32_e32 v74, 3, v79
	v_and_b32_e32 v74, 4, v74
	s_nop 5
	v_bfe_u32 v76, v48, 16, 1
	v_and_b32_e32 v64, 0xffffffc0, v79
	v_add3_u32 v48, v48, v76, s58
	v_mul_u32_u24_e32 v76, 0x108, v74
	v_or_b32_e32 v75, v64, v80
	v_lshlrev_b32_e32 v76, 1, v76
	v_lshl_add_u32 v75, v75, 1, v76
	ds_write_b16_d16_hi v75, v48 offset:16896
	v_bfe_u32 v48, v49, 16, 1
	v_add3_u32 v48, v49, v48, s58
	ds_write_b16_d16_hi v75, v48 offset:17424
	v_bfe_u32 v48, v50, 16, 1
	v_add3_u32 v48, v50, v48, s58
	ds_write_b16_d16_hi v75, v48 offset:17952
	v_bfe_u32 v48, v51, 16, 1
	v_add3_u32 v48, v51, v48, s58
	ds_write_b16_d16_hi v75, v48 offset:18480
	v_bfe_u32 v48, v52, 16, 1
	v_add3_u32 v48, v52, v48, s58
	ds_write_b16_d16_hi v75, v48 offset:21120
	v_bfe_u32 v48, v53, 16, 1
	v_add3_u32 v48, v53, v48, s58
	ds_write_b16_d16_hi v75, v48 offset:21648
	v_bfe_u32 v48, v54, 16, 1
	v_add3_u32 v48, v54, v48, s58
	ds_write_b16_d16_hi v75, v48 offset:22176
	v_bfe_u32 v48, v55, 16, 1
	v_add3_u32 v48, v55, v48, s58
	ds_write_b16_d16_hi v75, v48 offset:22704
	v_bfe_u32 v48, v56, 16, 1
	v_add3_u32 v48, v56, v48, s58
	ds_write_b16_d16_hi v75, v48 offset:25344
	v_bfe_u32 v48, v57, 16, 1
	v_add3_u32 v48, v57, v48, s58
	ds_write_b16_d16_hi v75, v48 offset:25872
	v_bfe_u32 v48, v58, 16, 1
	v_add3_u32 v48, v58, v48, s58
	ds_write_b16_d16_hi v75, v48 offset:26400
	v_bfe_u32 v48, v59, 16, 1
	v_add3_u32 v48, v59, v48, s58
	ds_write_b16_d16_hi v75, v48 offset:26928
	v_bfe_u32 v48, v60, 16, 1
	v_add3_u32 v48, v60, v48, s58
	ds_write_b16_d16_hi v75, v48 offset:29568
	v_bfe_u32 v48, v61, 16, 1
	v_add3_u32 v48, v61, v48, s58
	ds_write_b16_d16_hi v75, v48 offset:30096
	v_bfe_u32 v48, v62, 16, 1
	v_add3_u32 v48, v62, v48, s58
	ds_write_b16_d16_hi v75, v48 offset:30624
	v_bfe_u32 v48, v63, 16, 1
	v_add3_u32 v48, v63, v48, s58
	ds_write_b16_d16_hi v75, v48 offset:31152
	v_bfe_u32 v48, v32, 16, 1
	v_add3_u32 v32, v32, v48, s58
	ds_write_b16_d16_hi v75, v32 offset:16960
	v_bfe_u32 v32, v33, 16, 1
	v_add3_u32 v32, v33, v32, s58
	ds_write_b16_d16_hi v75, v32 offset:17488
	v_bfe_u32 v32, v34, 16, 1
	v_add3_u32 v32, v34, v32, s58
	ds_write_b16_d16_hi v75, v32 offset:18016
	v_bfe_u32 v32, v35, 16, 1
	v_add3_u32 v32, v35, v32, s58
	ds_write_b16_d16_hi v75, v32 offset:18544
	v_bfe_u32 v32, v36, 16, 1
	v_add3_u32 v32, v36, v32, s58
	ds_write_b16_d16_hi v75, v32 offset:21184
	v_bfe_u32 v32, v37, 16, 1
	v_add3_u32 v32, v37, v32, s58
	ds_write_b16_d16_hi v75, v32 offset:21712
	v_bfe_u32 v32, v38, 16, 1
	v_add3_u32 v32, v38, v32, s58
	ds_write_b16_d16_hi v75, v32 offset:22240
	v_bfe_u32 v32, v39, 16, 1
	v_add3_u32 v32, v39, v32, s58
	ds_write_b16_d16_hi v75, v32 offset:22768
	v_bfe_u32 v32, v40, 16, 1
	v_add3_u32 v32, v40, v32, s58
	ds_write_b16_d16_hi v75, v32 offset:25408
	v_bfe_u32 v32, v41, 16, 1
	v_add3_u32 v32, v41, v32, s58
	ds_write_b16_d16_hi v75, v32 offset:25936
	v_bfe_u32 v32, v42, 16, 1
	v_add3_u32 v32, v42, v32, s58
	ds_write_b16_d16_hi v75, v32 offset:26464
	v_bfe_u32 v32, v43, 16, 1
	v_add3_u32 v32, v43, v32, s58
	ds_write_b16_d16_hi v75, v32 offset:26992
	v_bfe_u32 v32, v44, 16, 1
	v_add3_u32 v32, v44, v32, s58
	ds_write_b16_d16_hi v75, v32 offset:29632
	v_bfe_u32 v32, v45, 16, 1
	v_add3_u32 v32, v45, v32, s58
	ds_write_b16_d16_hi v75, v32 offset:30160
	v_bfe_u32 v32, v46, 16, 1
	v_add3_u32 v32, v46, v32, s58
	ds_write_b16_d16_hi v75, v32 offset:30688
	v_bfe_u32 v32, v47, 16, 1
	v_add3_u32 v32, v47, v32, s58
	ds_write_b16_d16_hi v75, v32 offset:31216
	v_lshl_add_u32 v32, s13, 8, v64
	s_ashr_i32 s13, s12, 31
	v_bfe_u32 v37, v16, 16, 1
	s_lshl_b64 s[0:1], s[12:13], 1
	v_add3_u32 v16, v16, v37, s58
	v_bfe_u32 v37, v17, 16, 1
	s_add_u32 s0, s8, s0
	v_lshrrev_b32_e32 v16, 16, v16
	v_add3_u32 v17, v17, v37, s58
	s_addc_u32 s1, s9, s1
	v_lshlrev_b32_e32 v64, 1, v74
	v_and_or_b32 v16, v17, s54, v16
	v_bfe_u32 v17, v18, 16, 1
	v_or_b32_e32 v36, v32, v80
	v_lshl_add_u64 v[32:33], s[0:1], 0, v[64:65]
	s_mov_b64 s[0:1], 0x144d7900
	v_add3_u32 v17, v18, v17, s58
	v_bfe_u32 v18, v19, 16, 1
	v_lshl_add_u64 v[32:33], v[32:33], 0, s[0:1]
	v_lshrrev_b32_e32 v17, 16, v17
	v_add3_u32 v18, v19, v18, s58
	v_mad_i64_i32 v[34:35], s[0:1], v36, s61, v[32:33]
	v_and_or_b32 v17, v18, s54, v17
	global_store_dwordx2 v[34:35], v[16:17], off
	v_bfe_u32 v16, v20, 16, 1
	v_add3_u32 v16, v20, v16, s58
	v_bfe_u32 v17, v21, 16, 1
	v_lshrrev_b32_e32 v16, 16, v16
	v_add3_u32 v17, v21, v17, s58
	v_and_or_b32 v16, v17, s54, v16
	v_bfe_u32 v17, v22, 16, 1
	v_add3_u32 v17, v22, v17, s58
	v_bfe_u32 v18, v23, 16, 1
	v_lshrrev_b32_e32 v17, 16, v17
	v_add3_u32 v18, v23, v18, s58
	v_and_or_b32 v17, v18, s54, v17
	global_store_dwordx2 v[34:35], v[16:17], off offset:16
	v_bfe_u32 v16, v24, 16, 1
	v_add3_u32 v16, v24, v16, s58
	v_bfe_u32 v17, v25, 16, 1
	v_lshrrev_b32_e32 v16, 16, v16
	v_add3_u32 v17, v25, v17, s58
	v_and_or_b32 v16, v17, s54, v16
	v_bfe_u32 v17, v26, 16, 1
	v_add3_u32 v17, v26, v17, s58
	v_bfe_u32 v18, v27, 16, 1
	v_lshrrev_b32_e32 v17, 16, v17
	v_add3_u32 v18, v27, v18, s58
	v_and_or_b32 v17, v18, s54, v17
	global_store_dwordx2 v[34:35], v[16:17], off offset:32
	v_bfe_u32 v16, v28, 16, 1
	v_add3_u32 v16, v28, v16, s58
	v_bfe_u32 v17, v29, 16, 1
	v_lshrrev_b32_e32 v16, 16, v16
	v_add3_u32 v17, v29, v17, s58
	v_and_or_b32 v16, v17, s54, v16
	v_bfe_u32 v17, v30, 16, 1
	v_add3_u32 v17, v30, v17, s58
	v_bfe_u32 v18, v31, 16, 1
	v_lshrrev_b32_e32 v17, 16, v17
	v_add3_u32 v18, v31, v18, s58
	v_and_or_b32 v17, v18, s54, v17
	v_bfe_u32 v18, v0, 16, 1
	v_add3_u32 v0, v0, v18, s58
	v_bfe_u32 v18, v1, 16, 1
	v_lshrrev_b32_e32 v0, 16, v0
	v_add3_u32 v1, v1, v18, s58
	v_and_or_b32 v0, v1, s54, v0
	v_bfe_u32 v1, v2, 16, 1
	v_add3_u32 v1, v2, v1, s58
	v_bfe_u32 v2, v3, 16, 1
	global_store_dwordx2 v[34:35], v[16:17], off offset:48
	v_or_b32_e32 v16, 32, v36
	v_lshrrev_b32_e32 v1, 16, v1
	v_add3_u32 v2, v3, v2, s58
	v_mad_i64_i32 v[16:17], s[0:1], v16, s61, v[32:33]
	v_and_or_b32 v1, v2, s54, v1
	global_store_dwordx2 v[16:17], v[0:1], off
	v_bfe_u32 v0, v4, 16, 1
	v_add3_u32 v0, v4, v0, s58
	v_bfe_u32 v1, v5, 16, 1
	v_lshrrev_b32_e32 v0, 16, v0
	v_add3_u32 v1, v5, v1, s58
	v_and_or_b32 v0, v1, s54, v0
	v_bfe_u32 v1, v6, 16, 1
	v_add3_u32 v1, v6, v1, s58
	v_bfe_u32 v2, v7, 16, 1
	v_lshrrev_b32_e32 v1, 16, v1
	v_add3_u32 v2, v7, v2, s58
	v_and_or_b32 v1, v2, s54, v1
	global_store_dwordx2 v[16:17], v[0:1], off offset:16
	v_bfe_u32 v0, v8, 16, 1
	v_add3_u32 v0, v8, v0, s58
	v_bfe_u32 v1, v9, 16, 1
	v_lshrrev_b32_e32 v0, 16, v0
	v_add3_u32 v1, v9, v1, s58
	v_and_or_b32 v0, v1, s54, v0
	v_bfe_u32 v1, v10, 16, 1
	v_add3_u32 v1, v10, v1, s58
	v_bfe_u32 v2, v11, 16, 1
	v_lshrrev_b32_e32 v1, 16, v1
	v_add3_u32 v2, v11, v2, s58
	v_and_or_b32 v1, v2, s54, v1
	global_store_dwordx2 v[16:17], v[0:1], off offset:32
	v_bfe_u32 v0, v12, 16, 1
	v_add3_u32 v0, v12, v0, s58
	v_bfe_u32 v1, v13, 16, 1
	v_lshrrev_b32_e32 v0, 16, v0
	v_add3_u32 v1, v13, v1, s58
	v_and_or_b32 v0, v1, s54, v0
	v_bfe_u32 v1, v14, 16, 1
	v_add3_u32 v1, v14, v1, s58
	v_bfe_u32 v2, v15, 16, 1
	v_lshrrev_b32_e32 v1, 16, v1
	v_add3_u32 v2, v15, v2, s58
	v_and_or_b32 v1, v2, s54, v1
	v_and_b32_e32 v64, 0x1f0, v78
	global_store_dwordx2 v[16:17], v[0:1], off offset:48
	v_mad_u64_u32 v[0:1], s[0:1], v81, s62, v[64:65]
	s_waitcnt lgkmcnt(0)
	s_barrier
	ds_read_b128 v[0:3], v0 offset:16896
	v_lshl_add_u64 v[4:5], s[8:9], 0, v[64:65]
	s_mov_b64 s[0:1], 0x13097900
	v_lshl_add_u64 v[4:5], v[4:5], 0, s[0:1]
	v_lshlrev_b64 v[6:7], 9, v[66:67]
	v_lshl_add_u64 v[6:7], v[4:5], 0, v[6:7]
	s_waitcnt lgkmcnt(0)
	global_store_dwordx4 v[6:7], v[0:3], off
	v_lshlrev_b64 v[6:7], 9, v[68:69]
	v_lshl_add_u64 v[6:7], v[4:5], 0, v[6:7]
	v_mad_u64_u32 v[0:1], s[0:1], v82, s62, v[64:65]
	ds_read_b128 v[0:3], v0 offset:16896
	s_waitcnt lgkmcnt(0)
	global_store_dwordx4 v[6:7], v[0:3], off
	s_nop 1
	v_mad_u64_u32 v[0:1], s[0:1], v83, s62, v[64:65]
	ds_read_b128 v[0:3], v0 offset:16896
	v_lshlrev_b64 v[6:7], 9, v[70:71]
	v_lshl_add_u64 v[6:7], v[4:5], 0, v[6:7]
	s_waitcnt lgkmcnt(0)
	global_store_dwordx4 v[6:7], v[0:3], off
	s_nop 1
	v_mad_u64_u32 v[0:1], s[0:1], v84, s62, v[64:65]
	ds_read_b128 v[0:3], v0 offset:16896
	v_lshlrev_b64 v[6:7], 9, v[72:73]
	v_lshl_add_u64 v[4:5], v[4:5], 0, v[6:7]
	s_mov_b64 s[0:1], 0
	s_waitcnt lgkmcnt(0)
	global_store_dwordx4 v[4:5], v[0:3], off
.LBB0_387:
	s_and_b64 vcc, exec, s[0:1]
	s_cbranch_vccz .LBB0_434
	s_mov_b64 s[0:1], s[30:31]
	v_mov_b32_e32 v0, v65
	s_nop 0
	v_mbcnt_lo_u32_b32 v0, -1, v0
	v_mbcnt_hi_u32_b32 v0, -1, v0
	v_add_u32_e32 v48, s33, v0
	v_mov_b64_e32 v[0:1], s[0:1]
	v_ashrrev_i32_e32 v49, 3, v48
	v_add_u32_e32 v2, s18, v49
	v_mad_i64_i32 v[0:1], s[4:5], v2, s34, v[0:1]
	v_mov_b32_e32 v2, s0
	v_mov_b32_e32 v3, s1
	v_add_co_u32_e32 v2, vcc, s55, v2
	v_lshlrev_b32_e32 v4, 5, v48
	s_nop 0
	v_addc_co_u32_e32 v3, vcc, 0, v3, vcc
	global_load_dwordx2 v[2:3], v[2:3], off offset:488
	v_and_b32_e32 v10, 0xe0, v4
	v_lshlrev_b32_e32 v64, 1, v10
	v_lshl_add_u64 v[0:1], v[0:1], 0, v[64:65]
	s_mov_b64 s[4:5], 0x7157f00
	v_lshl_add_u64 v[8:9], v[0:1], 0, s[4:5]
	s_mov_b32 s4, 0x7157000
	v_add_co_u32_e32 v0, vcc, s4, v0
	global_load_dwordx4 v[4:7], v[8:9], off offset:48
	global_load_dwordx4 v[12:15], v[8:9], off offset:16
	global_load_dwordx4 v[16:19], v[8:9], off offset:32
	v_addc_co_u32_e32 v1, vcc, 0, v1, vcc
	global_load_dwordx4 v[20:23], v[0:1], off offset:3840
	v_mov_b32_e32 v1, v65
	v_lshlrev_b32_e32 v0, 2, v10
	s_waitcnt lgkmcnt(0)
	s_barrier
	s_waitcnt vmcnt(0)
	v_readfirstlane_b32 s5, v3
	v_readfirstlane_b32 s4, v2
	v_and_b32_e32 v3, 0xffff0000, v5
	s_nop 0
	v_lshl_add_u64 v[10:11], s[4:5], 0, v[0:1]
	global_load_dwordx4 v[24:27], v[10:11], off
	global_load_dwordx4 v[28:31], v[10:11], off offset:16
	v_lshlrev_b32_e32 v41, 16, v17
	v_lshlrev_b32_e32 v40, 16, v16
	v_and_b32_e32 v43, 0xffff0000, v17
	v_and_b32_e32 v42, 0xffff0000, v16
	v_and_b32_e32 v17, 0xffff0000, v21
	v_and_b32_e32 v16, 0xffff0000, v20
	v_lshlrev_b32_e32 v37, 16, v15
	v_lshlrev_b32_e32 v36, 16, v14
	v_and_b32_e32 v39, 0xffff0000, v15
	v_and_b32_e32 v38, 0xffff0000, v14
	v_lshlrev_b32_e32 v15, 16, v21
	v_lshlrev_b32_e32 v14, 16, v20
	v_and_b32_e32 v21, 0xffff0000, v23
	v_and_b32_e32 v20, 0xffff0000, v22
	v_pk_mul_f32 v[56:57], v[16:17], v[16:17]
	v_lshlrev_b32_e32 v45, 16, v19
	v_lshlrev_b32_e32 v44, 16, v18
	v_and_b32_e32 v47, 0xffff0000, v19
	v_and_b32_e32 v46, 0xffff0000, v18
	v_lshlrev_b32_e32 v19, 16, v23
	v_lshlrev_b32_e32 v18, 16, v22
	v_pk_mul_f32 v[58:59], v[20:21], v[20:21]
	v_pk_fma_f32 v[56:57], v[14:15], v[14:15], v[56:57]
	v_and_b32_e32 v35, 0xffff0000, v13
	v_and_b32_e32 v34, 0xffff0000, v12
	v_pk_fma_f32 v[58:59], v[18:19], v[18:19], v[58:59]
	v_add_f32_e32 v56, v56, v57
	v_lshlrev_b32_e32 v33, 16, v13
	v_lshlrev_b32_e32 v32, 16, v12
	v_pk_mul_f32 v[22:23], v[34:35], v[34:35]
	v_add_f32_e32 v56, v58, v56
	v_pk_fma_f32 v[22:23], v[32:33], v[32:33], v[22:23]
	v_add_f32_e32 v56, v59, v56
	v_pk_mul_f32 v[50:51], v[38:39], v[38:39]
	v_add_f32_e32 v22, v22, v56
	v_pk_fma_f32 v[50:51], v[36:37], v[36:37], v[50:51]
	v_add_f32_e32 v22, v23, v22
	v_pk_mul_f32 v[52:53], v[42:43], v[42:43]
	v_add_f32_e32 v22, v50, v22
	v_pk_fma_f32 v[52:53], v[40:41], v[40:41], v[52:53]
	v_add_f32_e32 v22, v51, v22
	v_pk_mul_f32 v[54:55], v[46:47], v[46:47]
	v_add_f32_e32 v22, v52, v22
	v_and_b32_e32 v2, 0xffff0000, v4
	v_pk_fma_f32 v[54:55], v[44:45], v[44:45], v[54:55]
	v_add_f32_e32 v22, v53, v22
	v_lshlrev_b32_e32 v1, 16, v5
	v_lshlrev_b32_e32 v0, 16, v4
	v_pk_mul_f32 v[8:9], v[2:3], v[2:3]
	v_add_f32_e32 v22, v54, v22
	v_lshlrev_b32_e32 v5, 16, v7
	v_lshlrev_b32_e32 v4, 16, v6
	v_and_b32_e32 v7, 0xffff0000, v7
	v_and_b32_e32 v6, 0xffff0000, v6
	v_pk_fma_f32 v[8:9], v[0:1], v[0:1], v[8:9]
	v_add_f32_e32 v22, v55, v22
	v_pk_mul_f32 v[12:13], v[6:7], v[6:7]
	v_add_f32_e32 v8, v8, v22
	v_pk_fma_f32 v[12:13], v[4:5], v[4:5], v[12:13]
	v_add_f32_e32 v8, v9, v8
	v_add_f32_e32 v8, v12, v8
	v_add_f32_e32 v8, v13, v8
	v_and_b32_e32 v57, 31, v48
	s_waitcnt vmcnt(0) lgkmcnt(0)
	v_mov_b32_e32 v22, v24
	v_add_f32_dpp v8, v8, v8 quad_perm:[1,0,3,2] row_mask:0xf bank_mask:0xf bound_ctrl:1
	v_mov_b32_e32 v23, v26
	v_mov_b32_e32 v26, v25
	v_add_f32_dpp v8, v8, v8 quad_perm:[2,3,0,1] row_mask:0xf bank_mask:0xf bound_ctrl:1
	v_mov_b32_e32 v24, v28
	v_mov_b32_e32 v25, v30
	v_add_f32_dpp v8, v8, v8 row_half_mirror row_mask:0xf bank_mask:0xf bound_ctrl:1
	v_fmamk_f32 v8, v8, 0x3b800000, v127
	v_mul_f32_e32 v9, 0x4b800000, v8
	v_cmp_gt_f32_e32 vcc, s57, v8
	v_mov_b32_e32 v30, v29
	s_nop 0
	v_cndmask_b32_e32 v8, v8, v9, vcc
	v_rsq_f32_e32 v12, v8
	v_mad_u64_u32 v[8:9], s[4:5], v49, s62, v[64:65]
	s_movk_i32 s4, 0x60
	v_mul_f32_e32 v9, 0x45800000, v12
	v_cndmask_b32_e32 v12, v12, v9, vcc
	v_pk_mul_f32 v[14:15], v[12:13], v[14:15] op_sel_hi:[0,1]
	v_pk_mul_f32 v[16:17], v[12:13], v[16:17] op_sel_hi:[0,1]
	v_pk_mul_f32 v[18:19], v[12:13], v[18:19] op_sel_hi:[0,1]
	v_pk_mul_f32 v[20:21], v[12:13], v[20:21] op_sel_hi:[0,1]
	v_pk_mul_f32 v[14:15], v[22:23], v[14:15]
	v_pk_mul_f32 v[16:17], v[26:27], v[16:17]
	v_pk_mul_f32 v[18:19], v[24:25], v[18:19]
	v_pk_mul_f32 v[20:21], v[30:31], v[20:21]
	v_bfe_u32 v22, v17, 16, 1
	v_bfe_u32 v23, v16, 16, 1
	v_bfe_u32 v24, v14, 16, 1
	v_bfe_u32 v25, v15, 16, 1
	v_bfe_u32 v26, v18, 16, 1
	v_bfe_u32 v27, v19, 16, 1
	v_bfe_u32 v9, v21, 16, 1
	v_bfe_u32 v13, v20, 16, 1
	v_add3_u32 v23, v16, v23, s58
	v_add3_u32 v22, v17, v22, s58
	v_add3_u32 v16, v19, v27, s58
	v_add3_u32 v17, v18, v26, s58
	v_add3_u32 v15, v15, v25, s58
	v_add3_u32 v14, v14, v24, s58
	v_add3_u32 v13, v20, v13, s58
	v_add3_u32 v9, v21, v9, s58
	v_lshrrev_b32_e32 v14, 16, v14
	v_lshrrev_b32_e32 v15, 16, v15
	v_lshrrev_b32_e32 v18, 16, v17
	v_lshrrev_b32_e32 v16, 16, v16
	v_and_or_b32 v17, v9, s54, v16
	v_and_or_b32 v16, v13, s54, v18
	v_and_or_b32 v15, v22, s54, v15
	v_and_or_b32 v14, v23, s54, v14
	ds_write_b128 v8, v[14:17]
	global_load_dwordx4 v[14:17], v[10:11], off offset:32
	global_load_dwordx4 v[18:21], v[10:11], off offset:48
	v_pk_mul_f32 v[22:23], v[12:13], v[32:33] op_sel_hi:[0,1]
	v_pk_mul_f32 v[24:25], v[12:13], v[34:35] op_sel_hi:[0,1]
	v_pk_mul_f32 v[26:27], v[12:13], v[36:37] op_sel_hi:[0,1]
	v_pk_mul_f32 v[28:29], v[12:13], v[38:39] op_sel_hi:[0,1]
	s_mov_b32 s5, 0x16e0000
	s_waitcnt vmcnt(0) lgkmcnt(0)
	v_mov_b32_e32 v30, v14
	v_mov_b32_e32 v31, v16
	v_mov_b32_e32 v16, v15
	v_mov_b32_e32 v14, v18
	v_mov_b32_e32 v15, v20
	v_mov_b32_e32 v20, v19
	v_pk_mul_f32 v[18:19], v[30:31], v[22:23]
	v_pk_mul_f32 v[16:17], v[16:17], v[24:25]
	v_pk_mul_f32 v[14:15], v[14:15], v[26:27]
	v_pk_mul_f32 v[20:21], v[20:21], v[28:29]
	v_bfe_u32 v22, v17, 16, 1
	v_bfe_u32 v23, v16, 16, 1
	v_bfe_u32 v24, v18, 16, 1
	v_bfe_u32 v25, v19, 16, 1
	v_bfe_u32 v26, v14, 16, 1
	v_bfe_u32 v27, v15, 16, 1
	v_bfe_u32 v9, v21, 16, 1
	v_bfe_u32 v13, v20, 16, 1
	v_add3_u32 v23, v16, v23, s58
	v_add3_u32 v22, v17, v22, s58
	v_add3_u32 v15, v15, v27, s58
	v_add3_u32 v14, v14, v26, s58
	v_add3_u32 v16, v19, v25, s58
	v_add3_u32 v17, v18, v24, s58
	v_add3_u32 v13, v20, v13, s58
	v_add3_u32 v9, v21, v9, s58
	v_lshrrev_b32_e32 v18, 16, v17
	v_lshrrev_b32_e32 v19, 16, v16
	v_lshrrev_b32_e32 v14, 16, v14
	v_lshrrev_b32_e32 v15, 16, v15
	v_and_or_b32 v17, v9, s54, v15
	v_and_or_b32 v16, v13, s54, v14
	v_and_or_b32 v15, v22, s54, v19
	v_and_or_b32 v14, v23, s54, v18
	ds_write_b128 v8, v[14:17] offset:16
	global_load_dwordx4 v[14:17], v[10:11], off offset:64
	global_load_dwordx4 v[18:21], v[10:11], off offset:80
	v_pk_mul_f32 v[22:23], v[12:13], v[40:41] op_sel_hi:[0,1]
	v_pk_mul_f32 v[24:25], v[12:13], v[42:43] op_sel_hi:[0,1]
	v_pk_mul_f32 v[26:27], v[12:13], v[44:45] op_sel_hi:[0,1]
	v_pk_mul_f32 v[28:29], v[12:13], v[46:47] op_sel_hi:[0,1]
	s_waitcnt vmcnt(0) lgkmcnt(0)
	v_mov_b32_e32 v30, v14
	v_mov_b32_e32 v31, v16
	v_mov_b32_e32 v16, v15
	v_mov_b32_e32 v14, v18
	v_mov_b32_e32 v15, v20
	v_mov_b32_e32 v20, v19
	v_pk_mul_f32 v[18:19], v[30:31], v[22:23]
	v_pk_mul_f32 v[16:17], v[16:17], v[24:25]
	v_pk_mul_f32 v[14:15], v[26:27], v[14:15]
	v_pk_mul_f32 v[20:21], v[28:29], v[20:21]
	v_bfe_u32 v22, v17, 16, 1
	v_bfe_u32 v23, v16, 16, 1
	v_bfe_u32 v24, v18, 16, 1
	v_bfe_u32 v25, v19, 16, 1
	v_bfe_u32 v26, v14, 16, 1
	v_bfe_u32 v27, v15, 16, 1
	v_bfe_u32 v9, v21, 16, 1
	v_bfe_u32 v13, v20, 16, 1
	v_add3_u32 v23, v16, v23, s58
	v_add3_u32 v22, v17, v22, s58
	v_add3_u32 v15, v15, v27, s58
	v_add3_u32 v14, v14, v26, s58
	v_add3_u32 v16, v19, v25, s58
	v_add3_u32 v17, v18, v24, s58
	v_add3_u32 v13, v20, v13, s58
	v_add3_u32 v9, v21, v9, s58
	v_lshrrev_b32_e32 v18, 16, v17
	v_lshrrev_b32_e32 v19, 16, v16
	v_lshrrev_b32_e32 v14, 16, v14
	v_lshrrev_b32_e32 v15, 16, v15
	v_and_or_b32 v17, v9, s54, v15
	v_and_or_b32 v16, v13, s54, v14
	v_and_or_b32 v15, v22, s54, v19
	v_and_or_b32 v14, v23, s54, v18
	ds_write_b128 v8, v[14:17] offset:32
	global_load_dwordx4 v[14:17], v[10:11], off offset:96
	global_load_dwordx4 v[18:21], v[10:11], off offset:112
	v_ashrrev_i32_e32 v10, 6, v48
	v_mul_lo_u32 v56, v10, s4
	v_pk_mul_f32 v[0:1], v[12:13], v[0:1] op_sel_hi:[0,1]
	v_pk_mul_f32 v[2:3], v[12:13], v[2:3] op_sel_hi:[0,1]
	v_pk_mul_f32 v[4:5], v[12:13], v[4:5] op_sel_hi:[0,1]
	v_pk_mul_f32 v[6:7], v[12:13], v[6:7] op_sel_hi:[0,1]
	v_mov_b32_e32 v9, v65
	s_mov_b32 s4, 0x16e4000
	s_waitcnt vmcnt(0) lgkmcnt(0)
	v_mov_b32_e32 v10, v14
	v_mov_b32_e32 v11, v16
	v_mov_b32_e32 v12, v18
	v_mov_b32_e32 v13, v20
	v_mov_b32_e32 v16, v15
	v_mov_b32_e32 v20, v19
	v_pk_mul_f32 v[0:1], v[0:1], v[10:11]
	v_pk_mul_f32 v[4:5], v[4:5], v[12:13]
	v_pk_mul_f32 v[2:3], v[2:3], v[16:17]
	v_pk_mul_f32 v[6:7], v[6:7], v[20:21]
	v_bfe_u32 v14, v0, 16, 1
	v_bfe_u32 v15, v1, 16, 1
	v_bfe_u32 v16, v4, 16, 1
	v_bfe_u32 v17, v5, 16, 1
	v_bfe_u32 v10, v7, 16, 1
	v_bfe_u32 v11, v6, 16, 1
	v_bfe_u32 v12, v3, 16, 1
	v_bfe_u32 v13, v2, 16, 1
	v_add3_u32 v5, v5, v17, s58
	v_add3_u32 v4, v4, v16, s58
	v_add3_u32 v1, v1, v15, s58
	v_add3_u32 v0, v0, v14, s58
	v_add3_u32 v13, v2, v13, s58
	v_add3_u32 v12, v3, v12, s58
	v_add3_u32 v2, v6, v11, s58
	v_add3_u32 v3, v7, v10, s58
	v_lshrrev_b32_e32 v0, 16, v0
	v_lshrrev_b32_e32 v1, 16, v1
	v_lshrrev_b32_e32 v4, 16, v4
	v_lshrrev_b32_e32 v5, 16, v5
	v_and_or_b32 v3, v3, s54, v5
	v_and_or_b32 v2, v2, s54, v4
	v_and_or_b32 v1, v12, s54, v1
	v_and_or_b32 v0, v13, s54, v0
	ds_write_b128 v8, v[0:3] offset:48
	s_waitcnt lgkmcnt(0)
	s_barrier
	s_nop 0
	v_mbcnt_lo_u32_b32 v0, -1, v9
	v_mbcnt_hi_u32_b32 v0, -1, v0
	v_and_b32_e32 v14, 31, v0
	v_ashrrev_i32_e32 v1, 2, v0
	v_or_b32_e32 v0, v14, v56
	v_and_b32_e32 v12, -8, v1
	v_ashrrev_i32_e32 v1, 31, v0
	v_lshlrev_b64 v[0:1], 9, v[0:1]
	v_ashrrev_i32_e32 v13, 31, v12
	v_lshl_add_u64 v[0:1], s[0:1], 0, v[0:1]
	v_lshl_add_u64 v[16:17], v[12:13], 1, v[0:1]
	v_add_co_u32_e32 v0, vcc, s5, v16
	v_lshlrev_b32_e32 v12, 1, v12
	s_nop 0
	v_addc_co_u32_e32 v1, vcc, 0, v17, vcc
	global_load_dwordx4 v[208:211], v[0:1], off
	v_add_co_u32_e32 v50, vcc, s4, v16
	s_mov_b32 s4, 0x16e8000
	s_nop 0
	v_addc_co_u32_e32 v51, vcc, 0, v17, vcc
	v_add_co_u32_e32 v52, vcc, s4, v16
	s_mov_b64 s[4:5], 0x16e0000
	v_lshl_add_u64 v[54:55], v[16:17], 0, s[4:5]
	global_load_dwordx4 v[212:215], v[54:55], off offset:32
	global_load_dwordx4 v[216:219], v[50:51], off
	v_mad_u32_u24 v49, v14, s62, v12
	ds_read_b128 v[12:15], v49
	ds_read_b128 v[66:69], v49 offset:32
	v_addc_co_u32_e32 v53, vcc, 0, v17, vcc
	global_load_dwordx4 v[220:223], v[52:53], off
	global_load_dwordx4 v[224:227], v[50:51], off offset:32
	global_load_dwordx4 v[228:231], v[52:53], off offset:32
	global_load_dwordx4 v[232:235], v[50:51], off offset:96
	global_load_dwordx4 v[236:239], v[54:55], off offset:64
	global_load_dwordx4 v[240:243], v[50:51], off offset:64
	global_load_dwordx4 v[244:247], v[52:53], off offset:64
	global_load_dwordx4 v[248:251], v[54:55], off offset:96
	s_waitcnt lgkmcnt(0)
	s_waitcnt vmcnt(10)
	v_mfma_f32_32x32x16_bf16 v[32:47], v[12:15], v[208:211], 0
	global_load_dwordx4 v[208:211], v[52:53], off offset:96
	s_and_b32 s4, 0xffff, s26
	s_mul_i32 s4, s4, 0xe38f
	s_lshr_b32 s4, s4, 22
	s_mulk_i32 s4, 0xf700
	s_add_i32 s4, s4, s18
	s_waitcnt vmcnt(10)
	v_mfma_f32_32x32x16_bf16 v[32:47], v[66:69], v[212:215], v[32:47]
	global_load_dwordx4 v[212:215], v[54:55], off offset:128
	s_waitcnt vmcnt(10)
	v_mfma_f32_32x32x16_bf16 v[16:31], v[12:15], v[216:219], 0
	global_load_dwordx4 v[216:219], v[50:51], off offset:128
	s_waitcnt vmcnt(10)
	v_mfma_f32_32x32x16_bf16 v[0:15], v[12:15], v[220:223], 0
	global_load_dwordx4 v[220:223], v[52:53], off offset:128
	s_waitcnt vmcnt(10)
	v_mfma_f32_32x32x16_bf16 v[16:31], v[66:69], v[224:227], v[16:31]
	global_load_dwordx4 v[224:227], v[54:55], off offset:160
	s_waitcnt lgkmcnt(0)
	s_waitcnt vmcnt(10)
	v_mfma_f32_32x32x16_bf16 v[0:15], v[66:69], v[228:231], v[0:15]
	global_load_dwordx4 v[228:231], v[50:51], off offset:160
	ds_read_b128 v[66:69], v49 offset:64
	ds_read_b128 v[74:77], v49 offset:96
	s_waitcnt lgkmcnt(1)
	s_waitcnt vmcnt(8)
	v_mfma_f32_32x32x16_bf16 v[16:31], v[66:69], v[240:243], v[16:31]
	v_mfma_f32_32x32x16_bf16 v[32:47], v[66:69], v[236:239], v[32:47]
	s_waitcnt lgkmcnt(0)
	s_waitcnt vmcnt(6)
	v_mfma_f32_32x32x16_bf16 v[32:47], v[74:77], v[248:251], v[32:47]
	v_mfma_f32_32x32x16_bf16 v[0:15], v[66:69], v[244:247], v[0:15]
	v_mfma_f32_32x32x16_bf16 v[16:31], v[74:77], v[232:235], v[16:31]
	global_load_dwordx4 v[232:235], v[52:53], off offset:160
	global_load_dwordx4 v[236:239], v[54:55], off offset:192
	global_load_dwordx4 v[240:243], v[50:51], off offset:192
	global_load_dwordx4 v[244:247], v[52:53], off offset:192
	global_load_dwordx4 v[248:251], v[54:55], off offset:224
	s_waitcnt lgkmcnt(0)
	s_waitcnt vmcnt(10)
	v_mfma_f32_32x32x16_bf16 v[0:15], v[74:77], v[208:211], v[0:15]
	global_load_dwordx4 v[208:211], v[50:51], off offset:224
	ds_read_b128 v[78:81], v49 offset:128
	ds_read_b128 v[82:85], v49 offset:160
	s_waitcnt lgkmcnt(0)
	s_waitcnt vmcnt(10)
	v_mfma_f32_32x32x16_bf16 v[32:47], v[78:81], v[212:215], v[32:47]
	global_load_dwordx4 v[212:215], v[52:53], off offset:224
	s_waitcnt vmcnt(10)
	v_mfma_f32_32x32x16_bf16 v[16:31], v[78:81], v[216:219], v[16:31]
	global_load_dwordx4 v[216:219], v[54:55], off offset:256
	s_waitcnt vmcnt(10)
	v_mfma_f32_32x32x16_bf16 v[0:15], v[78:81], v[220:223], v[0:15]
	global_load_dwordx4 v[220:223], v[50:51], off offset:256
	ds_read_b128 v[78:81], v49 offset:192
	s_waitcnt vmcnt(10)
	v_mfma_f32_32x32x16_bf16 v[32:47], v[82:85], v[224:227], v[32:47]
	global_load_dwordx4 v[224:227], v[52:53], off offset:256
	s_waitcnt lgkmcnt(0)
	s_waitcnt vmcnt(10)
	v_mfma_f32_32x32x16_bf16 v[16:31], v[82:85], v[228:231], v[16:31]
	global_load_dwordx4 v[228:231], v[54:55], off offset:288
	s_waitcnt vmcnt(10)
	v_mfma_f32_32x32x16_bf16 v[0:15], v[82:85], v[232:235], v[0:15]
	global_load_dwordx4 v[232:235], v[50:51], off offset:288
	ds_read_b128 v[82:85], v49 offset:224
	s_waitcnt vmcnt(10)
	v_mfma_f32_32x32x16_bf16 v[32:47], v[78:81], v[236:239], v[32:47]
	global_load_dwordx4 v[236:239], v[52:53], off offset:288
	s_waitcnt vmcnt(10)
	v_mfma_f32_32x32x16_bf16 v[16:31], v[78:81], v[240:243], v[16:31]
	global_load_dwordx4 v[240:243], v[54:55], off offset:320
	s_waitcnt lgkmcnt(0)
	s_waitcnt vmcnt(10)
	v_mfma_f32_32x32x16_bf16 v[0:15], v[78:81], v[244:247], v[0:15]
	global_load_dwordx4 v[244:247], v[50:51], off offset:320
	s_waitcnt vmcnt(9)
	v_mfma_f32_32x32x16_bf16 v[16:31], v[82:85], v[208:211], v[16:31]
	s_waitcnt vmcnt(8)
	v_mfma_f32_32x32x16_bf16 v[0:15], v[82:85], v[212:215], v[0:15]
	v_mfma_f32_32x32x16_bf16 v[32:47], v[82:85], v[248:251], v[32:47]
	global_load_dwordx4 v[248:251], v[52:53], off offset:320
	global_load_dwordx4 v[208:211], v[54:55], off offset:352
	global_load_dwordx4 v[212:215], v[50:51], off offset:352
	ds_read_b128 v[78:81], v49 offset:256
	ds_read_b128 v[82:85], v49 offset:288
	s_waitcnt lgkmcnt(0)
	s_waitcnt vmcnt(10)
	v_mfma_f32_32x32x16_bf16 v[32:47], v[78:81], v[216:219], v[32:47]
	global_load_dwordx4 v[216:219], v[52:53], off offset:352
	s_waitcnt vmcnt(10)
	v_mfma_f32_32x32x16_bf16 v[16:31], v[78:81], v[220:223], v[16:31]
	global_load_dwordx4 v[220:223], v[54:55], off offset:384
	s_waitcnt vmcnt(10)
	v_mfma_f32_32x32x16_bf16 v[0:15], v[78:81], v[224:227], v[0:15]
	global_load_dwordx4 v[224:227], v[50:51], off offset:384
	ds_read_b128 v[78:81], v49 offset:320
	s_waitcnt vmcnt(10)
	v_mfma_f32_32x32x16_bf16 v[32:47], v[82:85], v[228:231], v[32:47]
	global_load_dwordx4 v[228:231], v[52:53], off offset:384
	s_waitcnt lgkmcnt(0)
	s_waitcnt vmcnt(10)
	v_mfma_f32_32x32x16_bf16 v[16:31], v[82:85], v[232:235], v[16:31]
	global_load_dwordx4 v[232:235], v[54:55], off offset:416
	s_waitcnt vmcnt(10)
	v_mfma_f32_32x32x16_bf16 v[0:15], v[82:85], v[236:239], v[0:15]
	global_load_dwordx4 v[236:239], v[50:51], off offset:416
	ds_read_b128 v[82:85], v49 offset:352
	s_waitcnt vmcnt(10)
	v_mfma_f32_32x32x16_bf16 v[32:47], v[78:81], v[240:243], v[32:47]
	global_load_dwordx4 v[240:243], v[52:53], off offset:416
	s_waitcnt vmcnt(10)
	v_mfma_f32_32x32x16_bf16 v[16:31], v[78:81], v[244:247], v[16:31]
	global_load_dwordx4 v[244:247], v[54:55], off offset:448
	s_waitcnt lgkmcnt(0)
	s_waitcnt vmcnt(10)
	v_mfma_f32_32x32x16_bf16 v[0:15], v[78:81], v[248:251], v[0:15]
	global_load_dwordx4 v[248:251], v[50:51], off offset:448
	s_waitcnt vmcnt(9)
	v_mfma_f32_32x32x16_bf16 v[16:31], v[82:85], v[212:215], v[16:31]
	s_waitcnt vmcnt(8)
	v_mfma_f32_32x32x16_bf16 v[0:15], v[82:85], v[216:219], v[0:15]
	v_mfma_f32_32x32x16_bf16 v[32:47], v[82:85], v[208:211], v[32:47]
	global_load_dwordx4 v[208:211], v[52:53], off offset:448
	global_load_dwordx4 v[212:215], v[54:55], off offset:480
	global_load_dwordx4 v[216:219], v[50:51], off offset:480
	ds_read_b128 v[78:81], v49 offset:384
	ds_read_b128 v[82:85], v49 offset:416
	s_waitcnt lgkmcnt(0)
	s_waitcnt vmcnt(10)
	v_mfma_f32_32x32x16_bf16 v[32:47], v[78:81], v[220:223], v[32:47]
	global_load_dwordx4 v[220:223], v[52:53], off offset:480
	s_waitcnt vmcnt(10)
	v_mfma_f32_32x32x16_bf16 v[16:31], v[78:81], v[224:227], v[16:31]
	s_waitcnt vmcnt(9)
	v_mfma_f32_32x32x16_bf16 v[0:15], v[78:81], v[228:231], v[0:15]
	ds_read_b128 v[78:81], v49 offset:448
	s_waitcnt vmcnt(8)
	v_mfma_f32_32x32x16_bf16 v[32:47], v[82:85], v[232:235], v[32:47]
	s_waitcnt lgkmcnt(0)
	s_waitcnt vmcnt(7)
	v_mfma_f32_32x32x16_bf16 v[16:31], v[82:85], v[236:239], v[16:31]
	s_waitcnt vmcnt(6)
	v_mfma_f32_32x32x16_bf16 v[0:15], v[82:85], v[240:243], v[0:15]
	ds_read_b128 v[82:85], v49 offset:480
	s_waitcnt vmcnt(5)
	v_mfma_f32_32x32x16_bf16 v[32:47], v[78:81], v[244:247], v[32:47]
	s_nop 0
	s_waitcnt vmcnt(4)
	v_mfma_f32_32x32x16_bf16 v[16:31], v[78:81], v[248:251], v[16:31]
	s_waitcnt lgkmcnt(0)
	s_waitcnt vmcnt(3)
	v_mfma_f32_32x32x16_bf16 v[0:15], v[78:81], v[208:211], v[0:15]
	s_waitcnt vmcnt(1)
	v_mfma_f32_32x32x16_bf16 v[16:31], v[82:85], v[216:219], v[16:31]
	s_waitcnt vmcnt(0)
	v_mfma_f32_32x32x16_bf16 v[0:15], v[82:85], v[220:223], v[0:15]
	v_mfma_f32_32x32x16_bf16 v[32:47], v[82:85], v[212:215], v[32:47]
	v_lshrrev_b32_e32 v49, 3, v48
	s_nop 10
	v_mul_f32_e32 v32, 0x3e16c740, v32
	v_and_b32_e32 v49, 4, v49
	v_lshlrev_b32_e32 v50, 1, v56
	v_bfe_u32 v52, v32, 16, 1
	v_lshl_or_b32 v51, v57, 1, v50
	v_add3_u32 v32, v32, v52, s58
	v_mul_u32_u24_e32 v52, 0x188, v49
	v_lshl_add_u32 v51, v52, 1, v51
	ds_write_b16_d16_hi v51, v32 offset:16896
	v_mul_f32_e32 v32, 0x3e16c740, v33
	v_bfe_u32 v33, v32, 16, 1
	v_add3_u32 v32, v32, v33, s58
	ds_write_b16_d16_hi v51, v32 offset:17680
	v_mul_f32_e32 v32, 0x3e16c740, v34
	v_bfe_u32 v33, v32, 16, 1
	v_add3_u32 v32, v32, v33, s58
	ds_write_b16_d16_hi v51, v32 offset:18464
	v_mul_f32_e32 v32, 0x3e16c740, v35
	v_bfe_u32 v33, v32, 16, 1
	v_add3_u32 v32, v32, v33, s58
	ds_write_b16_d16_hi v51, v32 offset:19248
	v_mul_f32_e32 v32, 0x3e16c740, v36
	v_bfe_u32 v33, v32, 16, 1
	v_add3_u32 v32, v32, v33, s58
	ds_write_b16_d16_hi v51, v32 offset:23168
	v_mul_f32_e32 v32, 0x3e16c740, v37
	v_bfe_u32 v33, v32, 16, 1
	v_add3_u32 v32, v32, v33, s58
	ds_write_b16_d16_hi v51, v32 offset:23952
	v_mul_f32_e32 v32, 0x3e16c740, v38
	v_bfe_u32 v33, v32, 16, 1
	v_add3_u32 v32, v32, v33, s58
	ds_write_b16_d16_hi v51, v32 offset:24736
	v_mul_f32_e32 v32, 0x3e16c740, v39
	v_bfe_u32 v33, v32, 16, 1
	v_add3_u32 v32, v32, v33, s58
	ds_write_b16_d16_hi v51, v32 offset:25520
	v_mul_f32_e32 v32, 0x3e16c740, v40
	v_bfe_u32 v33, v32, 16, 1
	v_add3_u32 v32, v32, v33, s58
	ds_write_b16_d16_hi v51, v32 offset:29440
	v_mul_f32_e32 v32, 0x3e16c740, v41
	v_bfe_u32 v33, v32, 16, 1
	v_add3_u32 v32, v32, v33, s58
	ds_write_b16_d16_hi v51, v32 offset:30224
	v_mul_f32_e32 v32, 0x3e16c740, v42
	v_bfe_u32 v33, v32, 16, 1
	v_add3_u32 v32, v32, v33, s58
	ds_write_b16_d16_hi v51, v32 offset:31008
	v_mul_f32_e32 v32, 0x3e16c740, v43
	v_bfe_u32 v33, v32, 16, 1
	v_add3_u32 v32, v32, v33, s58
	ds_write_b16_d16_hi v51, v32 offset:31792
	v_mul_f32_e32 v32, 0x3e16c740, v44
	v_bfe_u32 v33, v32, 16, 1
	v_add3_u32 v32, v32, v33, s58
	ds_write_b16_d16_hi v51, v32 offset:35712
	v_mul_f32_e32 v32, 0x3e16c740, v45
	v_bfe_u32 v33, v32, 16, 1
	v_add3_u32 v32, v32, v33, s58
	ds_write_b16_d16_hi v51, v32 offset:36496
	v_mul_f32_e32 v32, 0x3e16c740, v46
	v_bfe_u32 v33, v32, 16, 1
	v_add3_u32 v32, v32, v33, s58
	ds_write_b16_d16_hi v51, v32 offset:37280
	v_mul_f32_e32 v32, 0x3e16c740, v47
	v_bfe_u32 v33, v32, 16, 1
	v_add3_u32 v32, v32, v33, s58
	v_mul_f32_e32 v16, 0x3e16c740, v16
	ds_write_b16_d16_hi v51, v32 offset:38064
	v_bfe_u32 v32, v16, 16, 1
	v_add3_u32 v16, v16, v32, s58
	ds_write_b16_d16_hi v51, v16 offset:16960
	v_mul_f32_e32 v16, 0x3e16c740, v17
	v_bfe_u32 v17, v16, 16, 1
	v_add3_u32 v16, v16, v17, s58
	ds_write_b16_d16_hi v51, v16 offset:17744
	v_mul_f32_e32 v16, 0x3e16c740, v18
	v_bfe_u32 v17, v16, 16, 1
	v_add3_u32 v16, v16, v17, s58
	ds_write_b16_d16_hi v51, v16 offset:18528
	v_mul_f32_e32 v16, 0x3e16c740, v19
	v_bfe_u32 v17, v16, 16, 1
	v_add3_u32 v16, v16, v17, s58
	ds_write_b16_d16_hi v51, v16 offset:19312
	v_mul_f32_e32 v16, 0x3e16c740, v20
	v_bfe_u32 v17, v16, 16, 1
	v_add3_u32 v16, v16, v17, s58
	ds_write_b16_d16_hi v51, v16 offset:23232
	v_mul_f32_e32 v16, 0x3e16c740, v21
	v_bfe_u32 v17, v16, 16, 1
	v_add3_u32 v16, v16, v17, s58
	ds_write_b16_d16_hi v51, v16 offset:24016
	v_mul_f32_e32 v16, 0x3e16c740, v22
	v_bfe_u32 v17, v16, 16, 1
	v_add3_u32 v16, v16, v17, s58
	ds_write_b16_d16_hi v51, v16 offset:24800
	v_mul_f32_e32 v16, 0x3e16c740, v23
	v_bfe_u32 v17, v16, 16, 1
	v_add3_u32 v16, v16, v17, s58
	ds_write_b16_d16_hi v51, v16 offset:25584
	v_mul_f32_e32 v16, 0x3e16c740, v24
	v_bfe_u32 v17, v16, 16, 1
	v_add3_u32 v16, v16, v17, s58
	ds_write_b16_d16_hi v51, v16 offset:29504
	v_mul_f32_e32 v16, 0x3e16c740, v25
	v_bfe_u32 v17, v16, 16, 1
	v_add3_u32 v16, v16, v17, s58
	ds_write_b16_d16_hi v51, v16 offset:30288
	v_mul_f32_e32 v16, 0x3e16c740, v26
	v_bfe_u32 v17, v16, 16, 1
	v_add3_u32 v16, v16, v17, s58
	ds_write_b16_d16_hi v51, v16 offset:31072
	v_mul_f32_e32 v16, 0x3e16c740, v27
	v_bfe_u32 v17, v16, 16, 1
	v_add3_u32 v16, v16, v17, s58
	ds_write_b16_d16_hi v51, v16 offset:31856
	v_mul_f32_e32 v16, 0x3e16c740, v28
	v_bfe_u32 v17, v16, 16, 1
	v_add3_u32 v16, v16, v17, s58
	ds_write_b16_d16_hi v51, v16 offset:35776
	v_mul_f32_e32 v16, 0x3e16c740, v29
	v_bfe_u32 v17, v16, 16, 1
	v_add3_u32 v16, v16, v17, s58
	ds_write_b16_d16_hi v51, v16 offset:36560
	v_mul_f32_e32 v16, 0x3e16c740, v30
	v_bfe_u32 v17, v16, 16, 1
	v_add3_u32 v16, v16, v17, s58
	ds_write_b16_d16_hi v51, v16 offset:37344
	v_mul_f32_e32 v16, 0x3e16c740, v31
	v_bfe_u32 v17, v16, 16, 1
	v_add3_u32 v16, v16, v17, s58
	ds_write_b16_d16_hi v51, v16 offset:38128
	v_and_b32_e32 v16, 7, v48
	v_cvt_f32_ubyte0_e32 v16, v16
	v_mul_f32_e32 v17, 0xbfd49a78, v16
	v_cmp_gt_f32_e32 vcc, s59, v17
	v_and_b32_e32 v18, 64, v131
	v_add_u32_e32 v18, 64, v18
	v_cndmask_b32_e32 v17, 0, v129, vcc
	v_fmac_f32_e32 v17, 0xbfd49a78, v16
	v_exp_f32_e32 v16, v17
	v_xor_b32_e32 v17, 8, v131
	v_cndmask_b32_e32 v19, 0, v130, vcc
	v_cmp_lt_i32_e32 vcc, v17, v18
	s_cmpk_gt_i32 s4, 0xff
	s_cselect_b64 s[10:11], -1, 0
	v_cndmask_b32_e32 v17, v131, v17, vcc
	v_lshlrev_b32_e32 v17, 2, v17
	ds_bpermute_b32 v18, v17, v0
	s_add_i32 s5, s4, 0xffffff00
	s_ashr_i32 s12, s5, 6
	s_and_b32 s13, s18, 32
	v_ldexp_f32 v16, v16, v19
	v_and_b32_e32 v19, 8, v48
	s_cmpk_lt_i32 s4, 0x100
	v_cmp_gt_u32_e64 s[6:7], 16, v57
	v_cmp_eq_u32_e64 s[4:5], 0, v19
	s_cbranch_scc1 .LBB0_390
	v_or_b32_e32 v19, s13, v49
	v_mov_b32_e32 v20, s12
	v_cndmask_b32_e64 v19, v19, v20, s[6:7]
	v_cvt_f32_i32_e32 v19, v19
	v_mul_f32_e32 v19, v16, v19
	v_mul_f32_e32 v19, 0.15915494, v19
	v_sin_f32_e32 v20, v19
	v_cos_f32_e32 v19, v19
	s_waitcnt lgkmcnt(0)
	v_mul_f32_e32 v18, v20, v18
	v_cndmask_b32_e64 v18, v18, -v18, s[4:5]
	v_fmac_f32_e32 v18, v19, v0
	v_mov_b32_e32 v0, v18

.LBB0_423:
	v_add_u32_e32 v4, s25, v135
	v_mul_hi_i32 v2, v4, s64
	v_lshrrev_b32_e32 v3, 31, v2
	v_ashrrev_i32_e32 v2, 3, v2
	v_add_u32_e32 v5, v2, v3
	v_mad_u64_u32 v[20:21], s[0:1], v5, s66, v[0:1]
	v_add_u32_e32 v6, s18, v5
	v_mov_b64_e32 v[2:3], s[52:53]
	v_add_u32_e32 v8, s27, v5
	v_mad_i64_i32 v[6:7], s[0:1], v6, s34, v[2:3]
	v_ashrrev_i32_e32 v21, 31, v20
	v_mad_u64_u32 v[18:19], s[0:1], v5, s65, v[4:5]
	v_lshl_add_u64 v[6:7], v[20:21], 1, v[6:7]
	v_cmp_lt_i32_e32 vcc, s12, v8
	v_lshl_add_u64 v[14:15], v[6:7], 0, s[22:23]
	v_add_co_u32_e64 v6, s[0:1], s67, v6
	v_cndmask_b32_e64 v11, 0, -1, vcc
	v_cndmask_b32_e32 v10, 0, v132, vcc
	v_cmp_gt_i32_e64 s[6:7], s24, v8
	v_addc_co_u32_e64 v7, s[0:1], 0, v7, s[0:1]
	v_lshl_add_u64 v[10:11], v[14:15], 0, v[10:11]
	global_load_dwordx4 v[6:9], v[6:7], off offset:1792
	v_cndmask_b32_e64 v64, 0, v133, s[6:7]
	global_load_dwordx4 v[10:13], v[10:11], off
	v_lshl_add_u64 v[14:15], v[14:15], 0, v[64:65]
	global_load_dwordx4 v[14:17], v[14:15], off
	v_cmp_gt_i32_e64 s[4:5], 32, v18
	v_cmp_gt_i32_e64 s[0:1], 16, v18
	v_lshl_add_u32 v5, v5, 4, v1
	v_add_u32_e32 v4, 0x100, v4
	s_addk_i32 s25, 0x200
	s_cmpk_eq_i32 s25, 0x600
	s_waitcnt vmcnt(0) lgkmcnt(0)
	v_lshlrev_b32_e32 v31, 16, v7
	v_and_b32_e32 v7, 0xffff0000, v7
	v_lshlrev_b32_e32 v26, 16, v12
	v_and_b32_e32 v27, 0xffff0000, v12
	v_lshlrev_b32_e32 v29, 16, v13
	v_and_b32_e32 v30, 0xffff0000, v13
	v_lshlrev_b64 v[12:13], 2, v[20:21]
	v_and_b32_e32 v19, 0xffff0000, v10
	v_lshlrev_b32_e32 v25, 16, v11
	v_and_b32_e32 v11, 0xffff0000, v11
	v_lshl_add_u64 v[20:21], s[10:11], 0, v[12:13]
	v_lshlrev_b32_e32 v10, 16, v10
	v_lshlrev_b32_e32 v32, 16, v14
	v_lshlrev_b32_e32 v33, 16, v15
	v_and_b32_e32 v36, 0xffff0000, v15
	v_and_b32_e32 v37, 0xffff0000, v14
	v_lshlrev_b32_e32 v38, 16, v16
	v_lshlrev_b32_e32 v39, 16, v17
	v_and_b32_e32 v40, 0xffff0000, v17
	v_and_b32_e32 v41, 0xffff0000, v16
	v_lshl_add_u64 v[22:23], s[8:9], 0, v[12:13]
	v_cndmask_b32_e32 v18, 0, v10, vcc
	v_cndmask_b32_e32 v24, 0, v19, vcc
	v_cndmask_b32_e32 v19, 0, v25, vcc
	v_cndmask_b32_e32 v25, 0, v11, vcc
	global_load_dwordx4 v[10:13], v[20:21], off offset:3072
	global_load_dwordx4 v[14:17], v[22:23], off offset:3072
	v_cndmask_b32_e32 v28, 0, v27, vcc
	v_cndmask_b32_e32 v27, 0, v29, vcc
	v_cndmask_b32_e32 v29, 0, v30, vcc
	v_lshlrev_b32_e32 v30, 16, v6
	v_cndmask_b32_e64 v33, 0, v33, s[6:7]
	v_cndmask_b32_e64 v32, 0, v32, s[6:7]
	v_pk_add_f32 v[18:19], v[18:19], v[30:31] neg_lo:[0,1] neg_hi:[0,1]
	v_and_b32_e32 v6, 0xffff0000, v6
	v_pk_add_f32 v[24:25], v[24:25], v[6:7] neg_lo:[0,1] neg_hi:[0,1]
	v_cndmask_b32_e32 v26, 0, v26, vcc
	s_waitcnt vmcnt(0) lgkmcnt(0)
	v_mov_b32_e32 v34, v10
	v_mov_b32_e32 v35, v12
	v_pk_fma_f32 v[18:19], v[34:35], v[18:19], v[30:31]
	v_pk_add_f32 v[30:31], v[32:33], v[30:31] neg_lo:[0,1] neg_hi:[0,1]
	v_mov_b32_e32 v32, v14
	v_mov_b32_e32 v33, v16
	v_pk_fma_f32 v[18:19], v[30:31], v[32:33], v[18:19]
	v_cndmask_b32_e64 v31, 0, v36, s[6:7]
	v_cndmask_b32_e64 v30, 0, v37, s[6:7]
	v_mov_b32_e32 v12, v11
	v_pk_fma_f32 v[12:13], v[12:13], v[24:25], v[6:7]
	v_pk_add_f32 v[6:7], v[30:31], v[6:7] neg_lo:[0,1] neg_hi:[0,1]
	v_mov_b32_e32 v16, v15
	v_pk_fma_f32 v[6:7], v[6:7], v[16:17], v[12:13]
	v_add_f32_e32 v10, v18, v18
	v_add_f32_e32 v11, v6, v6
	v_cndmask_b32_e64 v11, v11, v6, s[0:1]
	v_mul_f32_e32 v11, 0xbfb8aa3b, v11
	v_exp_f32_e32 v12, v11
	v_add_f32_e32 v11, v19, v19
	v_cndmask_b32_e64 v10, v10, v18, s[0:1]
	v_cndmask_b32_e64 v11, v11, v19, s[0:1]
	v_mul_f32_e32 v10, 0xbfb8aa3b, v10
	v_mul_f32_e32 v11, 0xbfb8aa3b, v11
	v_exp_f32_e32 v10, v10
	v_exp_f32_e32 v11, v11
	s_nop 0
	v_pk_add_f32 v[10:11], v[10:11], 1.0 op_sel_hi:[1,0]
	s_nop 0
	v_div_scale_f32 v13, s[78:79], v11, v11, 1.0
	v_rcp_f32_e32 v14, v13
	s_nop 0
	v_fma_f32 v15, -v13, v14, 1.0
	v_fmac_f32_e32 v14, v15, v14
	v_div_scale_f32 v15, vcc, 1.0, v11, 1.0
	v_mul_f32_e32 v16, v15, v14
	v_fma_f32 v17, -v13, v16, v15
	v_fmac_f32_e32 v16, v17, v14
	v_fma_f32 v13, -v13, v16, v15
	v_div_fmas_f32 v13, v13, v14, v16
	v_div_fixup_f32 v11, v13, v11, 1.0
	v_div_scale_f32 v13, s[78:79], v10, v10, 1.0
	v_rcp_f32_e32 v14, v13
	s_nop 0
	v_fma_f32 v15, -v13, v14, 1.0
	v_fmac_f32_e32 v14, v15, v14
	v_div_scale_f32 v15, vcc, 1.0, v10, 1.0
	v_mul_f32_e32 v16, v15, v14
	v_fma_f32 v17, -v13, v16, v15
	v_fmac_f32_e32 v16, v17, v14
	v_fma_f32 v13, -v13, v16, v15
	v_div_fmas_f32 v13, v13, v14, v16
	v_div_fixup_f32 v10, v13, v10, 1.0
	v_pk_fma_f32 v[14:15], v[10:11], 2.0, -1.0 op_sel_hi:[1,0,0]
	v_and_b32_e32 v17, 0xffff0000, v9
	v_cndmask_b32_e64 v13, v18, v14, s[4:5]
	v_cndmask_b32_e64 v25, v13, v10, s[0:1]
	v_add_f32_e32 v10, v7, v7
	v_cndmask_b32_e64 v10, v10, v7, s[0:1]
	v_mul_f32_e32 v10, 0xbfb8aa3b, v10
	v_exp_f32_e32 v13, v10
	v_cndmask_b32_e64 v14, v19, v15, s[4:5]
	v_cndmask_b32_e64 v24, v14, v11, s[0:1]
	v_cndmask_b32_e64 v19, 0, v39, s[6:7]
	v_pk_add_f32 v[10:11], v[12:13], 1.0 op_sel_hi:[1,0]
	v_cndmask_b32_e64 v18, 0, v38, s[6:7]
	v_div_scale_f32 v12, s[78:79], v11, v11, 1.0
	v_rcp_f32_e32 v13, v12
	s_nop 0
	v_fma_f32 v14, -v12, v13, 1.0
	v_fmac_f32_e32 v13, v14, v13
	v_div_scale_f32 v14, vcc, 1.0, v11, 1.0
	v_mul_f32_e32 v15, v14, v13
	v_fma_f32 v16, -v12, v15, v14
	v_fmac_f32_e32 v15, v16, v13
	v_fma_f32 v12, -v12, v15, v14
	v_div_fmas_f32 v12, v12, v13, v15
	v_div_fixup_f32 v11, v12, v11, 1.0
	v_div_scale_f32 v12, s[78:79], v10, v10, 1.0
	v_rcp_f32_e32 v13, v12
	s_nop 0
	v_fma_f32 v14, -v12, v13, 1.0
	v_fmac_f32_e32 v13, v14, v13
	v_div_scale_f32 v14, vcc, 1.0, v10, 1.0
	v_mul_f32_e32 v15, v14, v13
	v_fma_f32 v16, -v12, v15, v14
	v_fmac_f32_e32 v15, v16, v13
	v_fma_f32 v12, -v12, v15, v14
	v_div_fmas_f32 v12, v12, v13, v15
	v_div_fixup_f32 v10, v12, v10, 1.0
	v_pk_fma_f32 v[12:13], v[10:11], 2.0, -1.0 op_sel_hi:[1,0,0]
	v_lshlrev_b32_e32 v15, 16, v9
	v_cndmask_b32_e64 v7, v7, v13, s[4:5]
	v_cndmask_b32_e64 v6, v6, v12, s[4:5]
	v_cndmask_b32_e64 v30, v6, v10, s[0:1]
	v_cndmask_b32_e64 v31, v7, v11, s[0:1]
	v_lshlrev_b32_e32 v14, 16, v8
	v_and_b32_e32 v16, 0xffff0000, v8
	global_load_dwordx4 v[6:9], v[20:21], off offset:3088
	global_load_dwordx4 v[10:13], v[22:23], off offset:3088
	v_pk_add_f32 v[20:21], v[26:27], v[14:15] neg_lo:[0,1] neg_hi:[0,1]
	s_waitcnt vmcnt(0) lgkmcnt(0)
	v_mov_b32_e32 v22, v6
	v_mov_b32_e32 v23, v8
	v_pk_fma_f32 v[20:21], v[20:21], v[22:23], v[14:15]
	v_pk_add_f32 v[14:15], v[18:19], v[14:15] neg_lo:[0,1] neg_hi:[0,1]
	v_mov_b32_e32 v18, v10
	v_mov_b32_e32 v19, v12
	v_pk_fma_f32 v[14:15], v[14:15], v[18:19], v[20:21]
	v_cndmask_b32_e64 v19, 0, v40, s[6:7]
	v_cndmask_b32_e64 v18, 0, v41, s[6:7]
	v_pk_add_f32 v[20:21], v[28:29], v[16:17] neg_lo:[0,1] neg_hi:[0,1]
	v_mov_b32_e32 v8, v7
	v_pk_fma_f32 v[8:9], v[20:21], v[8:9], v[16:17]
	v_pk_add_f32 v[16:17], v[18:19], v[16:17] neg_lo:[0,1] neg_hi:[0,1]
	v_mov_b32_e32 v12, v11
	v_pk_fma_f32 v[8:9], v[16:17], v[12:13], v[8:9]
	v_add_f32_e32 v6, v14, v14
	v_add_f32_e32 v7, v8, v8
	v_cndmask_b32_e64 v7, v7, v8, s[0:1]
	v_mul_f32_e32 v7, 0xbfb8aa3b, v7
	v_exp_f32_e32 v10, v7
	v_add_f32_e32 v7, v15, v15
	v_cndmask_b32_e64 v6, v6, v14, s[0:1]
	v_cndmask_b32_e64 v7, v7, v15, s[0:1]
	v_mul_f32_e32 v6, 0xbfb8aa3b, v6
	v_mul_f32_e32 v7, 0xbfb8aa3b, v7
	v_exp_f32_e32 v6, v6
	v_exp_f32_e32 v7, v7
	s_nop 0
	v_pk_add_f32 v[6:7], v[6:7], 1.0 op_sel_hi:[1,0]
	s_nop 0
	v_div_scale_f32 v11, s[6:7], v7, v7, 1.0
	v_rcp_f32_e32 v12, v11
	s_nop 0
	v_fma_f32 v13, -v11, v12, 1.0
	v_fmac_f32_e32 v12, v13, v12
	v_div_scale_f32 v13, vcc, 1.0, v7, 1.0
	v_mul_f32_e32 v16, v13, v12
	v_fma_f32 v17, -v11, v16, v13
	v_fmac_f32_e32 v16, v17, v12
	v_fma_f32 v11, -v11, v16, v13
	v_div_fmas_f32 v11, v11, v12, v16
	v_div_fixup_f32 v7, v11, v7, 1.0
	v_div_scale_f32 v11, s[6:7], v6, v6, 1.0
	v_rcp_f32_e32 v12, v11
	s_nop 0
	v_fma_f32 v13, -v11, v12, 1.0
	v_fmac_f32_e32 v12, v13, v12
	v_div_scale_f32 v13, vcc, 1.0, v6, 1.0
	v_mul_f32_e32 v16, v13, v12
	v_fma_f32 v17, -v11, v16, v13
	v_fmac_f32_e32 v16, v17, v12
	v_fma_f32 v11, -v11, v16, v13
	v_div_fmas_f32 v11, v11, v12, v16
	v_div_fixup_f32 v6, v11, v6, 1.0
	v_pk_fma_f32 v[12:13], v[6:7], 2.0, -1.0 op_sel_hi:[1,0,0]
	s_nop 0
	v_cndmask_b32_e64 v11, v14, v12, s[4:5]
	v_cndmask_b32_e64 v12, v15, v13, s[4:5]
	v_cndmask_b32_e64 v13, v11, v6, s[0:1]
	v_add_f32_e32 v6, v9, v9
	v_cndmask_b32_e64 v6, v6, v9, s[0:1]
	v_mul_f32_e32 v6, 0xbfb8aa3b, v6
	v_exp_f32_e32 v11, v6
	v_cndmask_b32_e64 v12, v12, v7, s[0:1]
	v_pk_add_f32 v[6:7], v[10:11], 1.0 op_sel_hi:[1,0]
	s_nop 0
	v_div_scale_f32 v10, s[6:7], v7, v7, 1.0
	v_rcp_f32_e32 v11, v10
	s_nop 0
	v_fma_f32 v14, -v10, v11, 1.0
	v_fmac_f32_e32 v11, v14, v11
	v_div_scale_f32 v14, vcc, 1.0, v7, 1.0
	v_mul_f32_e32 v15, v14, v11
	v_fma_f32 v16, -v10, v15, v14
	v_fmac_f32_e32 v15, v16, v11
	v_fma_f32 v10, -v10, v15, v14
	v_div_fmas_f32 v10, v10, v11, v15
	v_div_fixup_f32 v7, v10, v7, 1.0
	v_div_scale_f32 v10, s[6:7], v6, v6, 1.0
	v_rcp_f32_e32 v11, v10
	s_nop 0
	v_fma_f32 v14, -v10, v11, 1.0
	v_fmac_f32_e32 v11, v14, v11
	v_div_scale_f32 v14, vcc, 1.0, v6, 1.0
	v_mul_f32_e32 v15, v14, v11
	v_fma_f32 v16, -v10, v15, v14
	v_fmac_f32_e32 v15, v16, v11
	v_fma_f32 v10, -v10, v15, v14
	v_div_fmas_f32 v10, v10, v11, v15
	v_div_fixup_f32 v6, v10, v6, 1.0
	v_pk_fma_f32 v[10:11], v[6:7], 2.0, -1.0 op_sel_hi:[1,0,0]
	v_bfe_u32 v14, v13, 16, 1
	v_cndmask_b32_e64 v9, v9, v11, s[4:5]
	v_cndmask_b32_e64 v8, v8, v10, s[4:5]
	v_cndmask_b32_e64 v6, v8, v6, s[0:1]
	v_cndmask_b32_e64 v7, v9, v7, s[0:1]
	v_bfe_u32 v8, v7, 16, 1
	v_bfe_u32 v9, v6, 16, 1
	v_add3_u32 v6, v6, v9, s58
	v_add3_u32 v7, v7, v8, s58
	v_bfe_u32 v8, v25, 16, 1
	v_bfe_u32 v9, v24, 16, 1
	v_bfe_u32 v15, v12, 16, 1
	v_bfe_u32 v10, v31, 16, 1
	v_bfe_u32 v11, v30, 16, 1
	v_add3_u32 v12, v12, v15, s58
	v_add3_u32 v13, v13, v14, s58
	v_add3_u32 v9, v24, v9, s58
	v_add3_u32 v8, v25, v8, s58
	v_add3_u32 v11, v30, v11, s58
	v_add3_u32 v10, v31, v10, s58
	v_lshrrev_b32_e32 v14, 16, v8
	v_lshrrev_b32_e32 v15, 16, v9
	v_lshrrev_b32_e32 v8, 16, v13
	v_lshrrev_b32_e32 v9, 16, v12
	v_and_or_b32 v9, v7, s54, v9
	v_and_or_b32 v8, v6, s54, v8
	v_and_or_b32 v7, v10, s54, v15
	v_and_or_b32 v6, v11, s54, v14
	ds_write_b128 v5, v[6:9]
	v_mul_hi_i32 v5, v4, s64
	v_lshrrev_b32_e32 v6, 31, v5
	v_ashrrev_i32_e32 v5, 3, v5
	v_add_u32_e32 v6, v5, v6
	v_mad_u64_u32 v[4:5], s[0:1], v6, s65, v[4:5]
	v_mul_lo_u32 v5, v6, s66
	s_movk_i32 s0, 0x800
	v_add3_u32 v20, v0, v5, s0
	v_add_u32_e32 v7, s18, v6
	v_mad_i64_i32 v[2:3], s[0:1], v7, s34, v[2:3]
	v_ashrrev_i32_e32 v21, 31, v20
	v_lshl_add_u64 v[2:3], v[20:21], 1, v[2:3]
	v_add_u32_e32 v5, s27, v6
	v_lshl_add_u64 v[16:17], v[2:3], 0, s[22:23]
	v_add_co_u32_e64 v2, s[0:1], s67, v2
	v_cmp_lt_i32_e32 vcc, s12, v5
	s_nop 0
	v_addc_co_u32_e64 v3, s[0:1], 0, v3, s[0:1]
	v_cmp_gt_i32_e64 s[6:7], s24, v5
	global_load_dwordx4 v[8:11], v[2:3], off offset:1792
	v_cndmask_b32_e64 v3, 0, -1, vcc
	v_cndmask_b32_e32 v2, 0, v132, vcc
	v_lshl_add_u64 v[2:3], v[16:17], 0, v[2:3]
	v_cndmask_b32_e64 v64, 0, v133, s[6:7]
	global_load_dwordx4 v[12:15], v[2:3], off
	v_lshl_add_u64 v[2:3], v[16:17], 0, v[64:65]
	global_load_dwordx4 v[16:19], v[2:3], off
	v_lshlrev_b64 v[2:3], 2, v[20:21]
	v_cmp_gt_i32_e64 s[4:5], 32, v4
	v_cmp_gt_i32_e64 s[0:1], 16, v4
	v_lshl_add_u32 v6, v6, 4, v1
	v_add_u32_e32 v1, 0x2000, v1
	v_add_u32_e32 v0, 0x1000, v0
	s_waitcnt vmcnt(0) lgkmcnt(0)
	v_lshlrev_b32_e32 v29, 16, v9
	v_lshlrev_b32_e32 v28, 16, v8
	v_and_b32_e32 v9, 0xffff0000, v9
	v_and_b32_e32 v8, 0xffff0000, v8
	v_and_b32_e32 v5, 0xffff0000, v12
	v_lshlrev_b32_e32 v7, 16, v13
	v_and_b32_e32 v13, 0xffff0000, v13
	v_lshlrev_b32_e32 v24, 16, v14
	v_and_b32_e32 v14, 0xffff0000, v14
	v_lshlrev_b32_e32 v25, 16, v15
	v_and_b32_e32 v15, 0xffff0000, v15
	v_lshlrev_b32_e32 v30, 16, v16
	v_lshlrev_b32_e32 v31, 16, v17
	v_and_b32_e32 v34, 0xffff0000, v17
	v_and_b32_e32 v35, 0xffff0000, v16
	v_lshlrev_b32_e32 v36, 16, v18
	v_lshlrev_b32_e32 v37, 16, v19
	v_and_b32_e32 v38, 0xffff0000, v19
	v_and_b32_e32 v39, 0xffff0000, v18
	v_lshl_add_u64 v[16:17], s[10:11], 0, v[2:3]
	v_lshl_add_u64 v[18:19], s[8:9], 0, v[2:3]
	v_lshlrev_b32_e32 v2, 16, v12
	v_cndmask_b32_e32 v20, 0, v2, vcc
	v_cndmask_b32_e32 v22, 0, v5, vcc
	v_cndmask_b32_e32 v23, 0, v13, vcc
	v_cndmask_b32_e32 v26, 0, v14, vcc
	v_cndmask_b32_e32 v27, 0, v15, vcc
	global_load_dwordx4 v[2:5], v[16:17], off offset:3072
	global_load_dwordx4 v[12:15], v[18:19], off offset:3072
	v_cndmask_b32_e32 v21, 0, v7, vcc
	v_cndmask_b32_e64 v31, 0, v31, s[6:7]
	v_cndmask_b32_e64 v30, 0, v30, s[6:7]
	v_pk_add_f32 v[20:21], v[20:21], v[28:29] neg_lo:[0,1] neg_hi:[0,1]
	v_pk_add_f32 v[22:23], v[22:23], v[8:9] neg_lo:[0,1] neg_hi:[0,1]
	v_cndmask_b32_e32 v24, 0, v24, vcc
	v_cndmask_b32_e32 v25, 0, v25, vcc
	s_waitcnt vmcnt(0) lgkmcnt(0)
	v_mov_b32_e32 v32, v2
	v_mov_b32_e32 v33, v4
	v_pk_fma_f32 v[20:21], v[32:33], v[20:21], v[28:29]
	v_pk_add_f32 v[28:29], v[30:31], v[28:29] neg_lo:[0,1] neg_hi:[0,1]
	v_mov_b32_e32 v30, v12
	v_mov_b32_e32 v31, v14
	v_pk_fma_f32 v[20:21], v[28:29], v[30:31], v[20:21]
	v_cndmask_b32_e64 v29, 0, v34, s[6:7]
	v_cndmask_b32_e64 v28, 0, v35, s[6:7]
	v_mov_b32_e32 v4, v3
	v_pk_fma_f32 v[4:5], v[4:5], v[22:23], v[8:9]
	v_pk_add_f32 v[8:9], v[28:29], v[8:9] neg_lo:[0,1] neg_hi:[0,1]
	v_mov_b32_e32 v14, v13
	v_pk_fma_f32 v[4:5], v[8:9], v[14:15], v[4:5]
	v_add_f32_e32 v2, v20, v20
	v_add_f32_e32 v3, v4, v4
	v_cndmask_b32_e64 v3, v3, v4, s[0:1]
	v_mul_f32_e32 v3, 0xbfb8aa3b, v3
	v_exp_f32_e32 v8, v3
	v_add_f32_e32 v3, v21, v21
	v_cndmask_b32_e64 v2, v2, v20, s[0:1]
	v_cndmask_b32_e64 v3, v3, v21, s[0:1]
	v_mul_f32_e32 v2, 0xbfb8aa3b, v2
	v_mul_f32_e32 v3, 0xbfb8aa3b, v3
	v_exp_f32_e32 v2, v2
	v_exp_f32_e32 v3, v3
	v_and_b32_e32 v15, 0xffff0000, v11
	v_pk_add_f32 v[2:3], v[2:3], 1.0 op_sel_hi:[1,0]
	s_nop 0
	v_div_scale_f32 v7, s[78:79], v3, v3, 1.0
	v_rcp_f32_e32 v9, v7
	s_nop 0
	v_fma_f32 v12, -v7, v9, 1.0
	v_fmac_f32_e32 v9, v12, v9
	v_div_scale_f32 v12, vcc, 1.0, v3, 1.0
	v_mul_f32_e32 v13, v12, v9
	v_fma_f32 v14, -v7, v13, v12
	v_fmac_f32_e32 v13, v14, v9
	v_fma_f32 v7, -v7, v13, v12
	v_div_fmas_f32 v7, v7, v9, v13
	v_div_fixup_f32 v3, v7, v3, 1.0
	v_div_scale_f32 v7, s[78:79], v2, v2, 1.0
	v_rcp_f32_e32 v9, v7
	s_nop 0
	v_fma_f32 v12, -v7, v9, 1.0
	v_fmac_f32_e32 v9, v12, v9
	v_div_scale_f32 v12, vcc, 1.0, v2, 1.0
	v_mul_f32_e32 v13, v12, v9
	v_fma_f32 v14, -v7, v13, v12
	v_fmac_f32_e32 v13, v14, v9
	v_fma_f32 v7, -v7, v13, v12
	v_div_fmas_f32 v7, v7, v9, v13
	v_div_fixup_f32 v2, v7, v2, 1.0
	v_pk_fma_f32 v[12:13], v[2:3], 2.0, -1.0 op_sel_hi:[1,0,0]
	s_nop 0
	v_cndmask_b32_e64 v7, v20, v12, s[4:5]
	v_cndmask_b32_e64 v7, v7, v2, s[0:1]
	v_add_f32_e32 v2, v5, v5
	v_cndmask_b32_e64 v2, v2, v5, s[0:1]
	v_cndmask_b32_e64 v9, v21, v13, s[4:5]
	v_mul_f32_e32 v2, 0xbfb8aa3b, v2
	v_cndmask_b32_e64 v22, v9, v3, s[0:1]
	v_exp_f32_e32 v9, v2
	s_nop 0
	v_pk_add_f32 v[2:3], v[8:9], 1.0 op_sel_hi:[1,0]
	s_nop 0
	v_div_scale_f32 v8, s[78:79], v3, v3, 1.0
	v_rcp_f32_e32 v9, v8
	s_nop 0
	v_fma_f32 v12, -v8, v9, 1.0
	v_fmac_f32_e32 v9, v12, v9
	v_div_scale_f32 v12, vcc, 1.0, v3, 1.0
	v_mul_f32_e32 v13, v12, v9
	v_fma_f32 v14, -v8, v13, v12
	v_fmac_f32_e32 v13, v14, v9
	v_fma_f32 v8, -v8, v13, v12
	v_div_fmas_f32 v8, v8, v9, v13
	v_div_fixup_f32 v3, v8, v3, 1.0
	v_div_scale_f32 v8, s[78:79], v2, v2, 1.0
	v_rcp_f32_e32 v9, v8
	s_nop 0
	v_fma_f32 v12, -v8, v9, 1.0
	v_fmac_f32_e32 v9, v12, v9
	v_div_scale_f32 v12, vcc, 1.0, v2, 1.0
	v_mul_f32_e32 v13, v12, v9
	v_fma_f32 v14, -v8, v13, v12
	v_fmac_f32_e32 v13, v14, v9
	v_fma_f32 v8, -v8, v13, v12
	v_div_fmas_f32 v8, v8, v9, v13
	v_div_fixup_f32 v2, v8, v2, 1.0
	v_pk_fma_f32 v[8:9], v[2:3], 2.0, -1.0 op_sel_hi:[1,0,0]
	v_lshlrev_b32_e32 v13, 16, v11
	v_cndmask_b32_e64 v5, v5, v9, s[4:5]
	v_cndmask_b32_e64 v4, v4, v8, s[4:5]
	v_cndmask_b32_e64 v23, v4, v2, s[0:1]
	v_cndmask_b32_e64 v28, v5, v3, s[0:1]
	v_lshlrev_b32_e32 v12, 16, v10
	v_and_b32_e32 v14, 0xffff0000, v10
	global_load_dwordx4 v[2:5], v[16:17], off offset:3088
	global_load_dwordx4 v[8:11], v[18:19], off offset:3088
	v_cndmask_b32_e64 v17, 0, v37, s[6:7]
	v_cndmask_b32_e64 v16, 0, v36, s[6:7]
	v_pk_add_f32 v[18:19], v[24:25], v[12:13] neg_lo:[0,1] neg_hi:[0,1]
	s_waitcnt vmcnt(0) lgkmcnt(0)
	v_mov_b32_e32 v20, v2
	v_mov_b32_e32 v21, v4
	v_pk_fma_f32 v[18:19], v[18:19], v[20:21], v[12:13]
	v_pk_add_f32 v[12:13], v[16:17], v[12:13] neg_lo:[0,1] neg_hi:[0,1]
	v_mov_b32_e32 v16, v8
	v_mov_b32_e32 v17, v10
	v_pk_fma_f32 v[12:13], v[12:13], v[16:17], v[18:19]
	v_cndmask_b32_e64 v17, 0, v38, s[6:7]
	v_cndmask_b32_e64 v16, 0, v39, s[6:7]
	v_pk_add_f32 v[18:19], v[26:27], v[14:15] neg_lo:[0,1] neg_hi:[0,1]
	v_mov_b32_e32 v4, v3
	v_pk_fma_f32 v[4:5], v[18:19], v[4:5], v[14:15]
	v_pk_add_f32 v[14:15], v[16:17], v[14:15] neg_lo:[0,1] neg_hi:[0,1]
	v_mov_b32_e32 v10, v9
	v_pk_fma_f32 v[4:5], v[14:15], v[10:11], v[4:5]
	v_add_f32_e32 v2, v12, v12
	v_add_f32_e32 v3, v4, v4
	v_cndmask_b32_e64 v3, v3, v4, s[0:1]
	v_mul_f32_e32 v3, 0xbfb8aa3b, v3
	v_exp_f32_e32 v8, v3
	v_add_f32_e32 v3, v13, v13
	v_cndmask_b32_e64 v2, v2, v12, s[0:1]
	v_cndmask_b32_e64 v3, v3, v13, s[0:1]
	v_mul_f32_e32 v2, 0xbfb8aa3b, v2
	v_mul_f32_e32 v3, 0xbfb8aa3b, v3
	v_exp_f32_e32 v2, v2
	v_exp_f32_e32 v3, v3
	s_nop 0
	v_pk_add_f32 v[2:3], v[2:3], 1.0 op_sel_hi:[1,0]
	s_nop 0
	v_div_scale_f32 v9, s[6:7], v3, v3, 1.0
	v_rcp_f32_e32 v10, v9
	s_nop 0
	v_fma_f32 v11, -v9, v10, 1.0
	v_fmac_f32_e32 v10, v11, v10
	v_div_scale_f32 v11, vcc, 1.0, v3, 1.0
	v_mul_f32_e32 v14, v11, v10
	v_fma_f32 v15, -v9, v14, v11
	v_fmac_f32_e32 v14, v15, v10
	v_fma_f32 v9, -v9, v14, v11
	v_div_fmas_f32 v9, v9, v10, v14
	v_div_fixup_f32 v3, v9, v3, 1.0
	v_div_scale_f32 v9, s[6:7], v2, v2, 1.0
	v_rcp_f32_e32 v10, v9
	s_nop 0
	v_fma_f32 v11, -v9, v10, 1.0
	v_fmac_f32_e32 v10, v11, v10
	v_div_scale_f32 v11, vcc, 1.0, v2, 1.0
	v_mul_f32_e32 v14, v11, v10
	v_fma_f32 v15, -v9, v14, v11
	v_fmac_f32_e32 v14, v15, v10
	v_fma_f32 v9, -v9, v14, v11
	v_div_fmas_f32 v9, v9, v10, v14
	v_div_fixup_f32 v2, v9, v2, 1.0
	v_pk_fma_f32 v[10:11], v[2:3], 2.0, -1.0 op_sel_hi:[1,0,0]
	s_nop 0
	v_cndmask_b32_e64 v9, v12, v10, s[4:5]
	v_cndmask_b32_e64 v10, v13, v11, s[4:5]
	v_cndmask_b32_e64 v11, v9, v2, s[0:1]
	v_add_f32_e32 v2, v5, v5
	v_cndmask_b32_e64 v2, v2, v5, s[0:1]
	v_mul_f32_e32 v2, 0xbfb8aa3b, v2
	v_exp_f32_e32 v9, v2
	v_cndmask_b32_e64 v10, v10, v3, s[0:1]
	v_pk_add_f32 v[2:3], v[8:9], 1.0 op_sel_hi:[1,0]
	s_nop 0
	v_div_scale_f32 v8, s[6:7], v3, v3, 1.0
	v_rcp_f32_e32 v9, v8
	s_nop 0
	v_fma_f32 v12, -v8, v9, 1.0
	v_fmac_f32_e32 v9, v12, v9
	v_div_scale_f32 v12, vcc, 1.0, v3, 1.0
	v_mul_f32_e32 v13, v12, v9
	v_fma_f32 v14, -v8, v13, v12
	v_fmac_f32_e32 v13, v14, v9
	v_fma_f32 v8, -v8, v13, v12
	v_div_fmas_f32 v8, v8, v9, v13
	v_div_fixup_f32 v3, v8, v3, 1.0
	v_div_scale_f32 v8, s[6:7], v2, v2, 1.0
	v_rcp_f32_e32 v9, v8
	s_nop 0
	v_fma_f32 v12, -v8, v9, 1.0
	v_fmac_f32_e32 v9, v12, v9
	v_div_scale_f32 v12, vcc, 1.0, v2, 1.0
	v_mul_f32_e32 v13, v12, v9
	v_fma_f32 v14, -v8, v13, v12
	v_fmac_f32_e32 v13, v14, v9
	v_fma_f32 v8, -v8, v13, v12
	v_div_fmas_f32 v8, v8, v9, v13
	v_div_fixup_f32 v2, v8, v2, 1.0
	v_pk_fma_f32 v[8:9], v[2:3], 2.0, -1.0 op_sel_hi:[1,0,0]
	v_bfe_u32 v12, v11, 16, 1
	v_cndmask_b32_e64 v5, v5, v9, s[4:5]
	v_cndmask_b32_e64 v4, v4, v8, s[4:5]
	v_cndmask_b32_e64 v2, v4, v2, s[0:1]
	v_cndmask_b32_e64 v3, v5, v3, s[0:1]
	v_bfe_u32 v4, v3, 16, 1
	v_bfe_u32 v5, v2, 16, 1
	v_add3_u32 v2, v2, v5, s58
	v_add3_u32 v3, v3, v4, s58
	v_bfe_u32 v4, v7, 16, 1
	v_bfe_u32 v5, v22, 16, 1
	v_bfe_u32 v13, v10, 16, 1
	v_bfe_u32 v8, v28, 16, 1
	v_bfe_u32 v9, v23, 16, 1
	v_add3_u32 v10, v10, v13, s58
	v_add3_u32 v11, v11, v12, s58
	v_add3_u32 v5, v22, v5, s58
	v_add3_u32 v4, v7, v4, s58
	v_add3_u32 v9, v23, v9, s58
	v_add3_u32 v8, v28, v8, s58
	v_lshrrev_b32_e32 v7, 16, v4
	v_lshrrev_b32_e32 v12, 16, v5
	v_lshrrev_b32_e32 v4, 16, v11
	v_lshrrev_b32_e32 v5, 16, v10
	v_and_or_b32 v5, v3, s54, v5
	v_and_or_b32 v4, v2, s54, v4
	v_and_or_b32 v3, v8, s54, v12
	v_and_or_b32 v2, v9, s54, v7
	ds_write_b128 v6, v[2:5] offset:4096
	s_cbranch_scc0 .LBB0_423
	v_ashrrev_i32_e32 v137, 3, v135
	v_and_b32_e32 v138, -4, v137
	v_add_u32_e32 v16, s27, v138
	v_add_u32_e32 v0, -1, v16
	v_or_b32_e32 v44, 1, v16
	v_and_b32_e32 v126, 31, v135
	v_max_i32_e32 v0, s12, v0
	v_max_i32_e32 v2, s12, v16
	v_max_i32_e32 v10, s12, v44
	v_lshlrev_b32_e32 v34, 4, v126
	v_mov_b32_e32 v35, v65
	s_mulk_i32 s26, 0x900
	v_min_i32_e32 v0, s24, v0
	v_min_i32_e32 v2, s24, v2
	v_min_i32_e32 v10, s24, v10
	v_lshl_add_u64 v[88:89], s[52:53], 0, v[34:35]
	s_mov_b64 s[0:1], 0x7158100
	v_add_u32_e32 v0, s26, v0
	v_add_u32_e32 v2, s26, v2
	v_add_u32_e32 v10, s26, v10
	v_lshl_add_u64 v[8:9], v[88:89], 0, s[0:1]
	v_mul_hi_i32_i24_e32 v29, 0x1240, v0
	v_mul_i32_i24_e32 v28, 0x1240, v0
	v_mul_hi_i32_i24_e32 v47, 0x1240, v2
	v_mul_i32_i24_e32 v46, 0x1240, v2
	v_mul_hi_i32_i24_e32 v49, 0x1240, v10
	v_mul_i32_i24_e32 v48, 0x1240, v10
	v_lshl_add_u64 v[0:1], v[8:9], 0, v[28:29]
	v_lshl_add_u64 v[4:5], v[8:9], 0, v[46:47]
	v_lshl_add_u64 v[10:11], v[8:9], 0, v[48:49]
	v_or_b32_e32 v45, 2, v16
	global_load_dwordx4 v[0:3], v[0:1], off
	s_nop 0
	global_load_dwordx4 v[4:7], v[4:5], off
	v_or_b32_e32 v66, 3, v16
	global_load_dwordx4 v[36:39], v[10:11], off
	v_max_i32_e32 v10, s12, v45
	v_min_i32_e32 v10, s24, v10
	v_add_u32_e32 v10, s26, v10
	v_mul_hi_i32_i24_e32 v51, 0x1240, v10
	v_mul_i32_i24_e32 v50, 0x1240, v10
	v_lshl_add_u64 v[10:11], v[8:9], 0, v[50:51]
	global_load_dwordx4 v[40:43], v[10:11], off
	v_max_i32_e32 v10, s12, v66
	v_min_i32_e32 v10, s24, v10
	v_add_u32_e32 v10, s26, v10
	v_mul_hi_i32_i24_e32 v53, 0x1240, v10
	v_mul_i32_i24_e32 v52, 0x1240, v10
	v_lshl_add_u64 v[10:11], v[8:9], 0, v[52:53]
	v_add_u32_e32 v67, 4, v16
	global_load_dwordx4 v[56:59], v[10:11], off
	v_max_i32_e32 v10, s12, v67
	v_min_i32_e32 v10, s24, v10
	v_add_u32_e32 v10, s26, v10
	v_mul_hi_i32_i24_e32 v55, 0x1240, v10
	v_mul_i32_i24_e32 v54, 0x1240, v10
	v_lshl_add_u64 v[8:9], v[8:9], 0, v[54:55]
	global_load_dwordx4 v[60:63], v[8:9], off
	v_mov_b32_e32 v8, s52
	v_lshlrev_b32_e32 v64, 5, v126
	v_mov_b32_e32 v9, s53
	v_add_co_u32_e32 v32, vcc, s55, v8
	v_lshl_add_u64 v[24:25], s[10:11], 0, v[64:65]
	s_nop 0
	v_addc_co_u32_e32 v33, vcc, 0, v9, vcc
	global_load_dwordx4 v[8:11], v[24:25], off
	v_lshl_add_u64 v[26:27], s[8:9], 0, v[64:65]
	global_load_dwordx2 v[30:31], v[32:33], off offset:464
	global_load_dwordx4 v[12:15], v[26:27], off
	v_cmp_lt_i32_e32 vcc, s12, v16
	v_cmp_ge_i32_e64 s[0:1], s13, v16
	v_cmp_le_i32_e64 s[4:5], s12, v16
	v_cmp_gt_i32_e64 s[6:7], s13, v16
	global_load_dwordx4 v[16:19], v[24:25], off offset:16
	global_load_dwordx4 v[20:23], v[26:27], off offset:16
	v_cmp_le_i32_e64 s[8:9], s12, v44
	v_cmp_gt_i32_e64 s[10:11], s13, v44
	s_and_b64 vcc, vcc, s[0:1]
	s_and_b64 s[4:5], s[4:5], s[6:7]
	s_and_b64 s[6:7], s[8:9], s[10:11]
	v_cmp_le_i32_e64 s[0:1], s12, v45
	v_cmp_gt_i32_e64 s[8:9], s13, v45
	s_and_b64 s[8:9], s[0:1], s[8:9]
	v_cmp_le_i32_e64 s[0:1], s12, v66
	v_cmp_gt_i32_e64 s[10:11], s13, v66
	s_and_b64 s[10:11], s[0:1], s[10:11]
	v_cmp_le_i32_e64 s[0:1], s12, v67
	v_cmp_gt_i32_e64 s[12:13], s13, v67
	s_and_b64 s[12:13], s[0:1], s[12:13]
	v_add_u32_e32 v90, s18, v138
	v_ashrrev_i32_e32 v91, 31, v90
	v_or_b32_e32 v92, 1, v90
	v_ashrrev_i32_e32 v93, 31, v92
	s_mov_b32 s24, 0
	v_lshlrev_b32_e32 v126, 3, v126
	s_waitcnt vmcnt(0) lgkmcnt(0)
	v_cndmask_b32_e32 v44, 0, v1, vcc
	v_cndmask_b32_e32 v68, 0, v0, vcc
	v_cndmask_b32_e64 v69, 0, v5, s[4:5]
	v_cndmask_b32_e64 v73, 0, v4, s[4:5]
	v_cndmask_b32_e64 v76, 0, v39, s[6:7]
	v_cndmask_b32_e64 v78, 0, v38, s[6:7]
	v_cndmask_b32_e64 v38, 0, v37, s[6:7]
	v_cndmask_b32_e64 v39, 0, v36, s[6:7]
	v_and_b32_e32 v37, 0xffff0000, v44
	v_and_b32_e32 v36, 0xffff0000, v68
	v_cndmask_b32_e32 v70, 0, v3, vcc
	v_cndmask_b32_e32 v71, 0, v2, vcc
	v_cndmask_b32_e64 v72, 0, v7, s[4:5]
	v_cndmask_b32_e64 v74, 0, v6, s[4:5]
	v_lshlrev_b32_e32 v45, 16, v69
	v_lshlrev_b32_e32 v75, 16, v76
	v_and_b32_e32 v77, 0xffff0000, v76
	v_and_b32_e32 v76, 0xffff0000, v78
	v_cndmask_b32_e64 v86, 0, v59, s[10:11]
	v_cndmask_b32_e64 v87, 0, v58, s[10:11]
	v_and_b32_e32 v59, 0xffff0000, v69
	v_and_b32_e32 v58, 0xffff0000, v73
	v_pk_add_f32 v[36:37], v[36:37], v[58:59] neg_lo:[0,1] neg_hi:[0,1]
	v_cndmask_b32_e64 v94, 0, v57, s[10:11]
	v_cndmask_b32_e64 v95, 0, v56, s[10:11]
	v_cndmask_b32_e64 v96, 0, v63, s[12:13]
	v_cndmask_b32_e64 v97, 0, v62, s[12:13]
	v_and_b32_e32 v63, 0xffff0000, v38
	v_and_b32_e32 v62, 0xffff0000, v39
	v_cndmask_b32_e64 v118, 0, v61, s[12:13]
	v_cndmask_b32_e64 v119, 0, v60, s[12:13]
	v_lshlrev_b32_e32 v61, 16, v38
	v_lshlrev_b32_e32 v60, 16, v39
	v_lshl_add_u64 v[56:57], v[88:89], 0, s[36:37]
	v_mov_b32_e32 v67, v10
	v_mov_b32_e32 v10, v9
	v_readfirstlane_b32 s1, v31
	v_readfirstlane_b32 s0, v30
	v_lshlrev_b32_e32 v31, 16, v44
	v_lshlrev_b32_e32 v30, 16, v68
	v_lshlrev_b32_e32 v44, 16, v73
	v_mov_b32_e32 v66, v8
	v_mov_b32_e32 v69, v14
	v_pk_fma_f32 v[8:9], v[10:11], v[36:37], v[58:59]
	v_pk_add_f32 v[36:37], v[62:63], v[58:59] neg_lo:[0,1] neg_hi:[0,1]
	v_mov_b32_e32 v14, v13
	v_pk_add_f32 v[30:31], v[30:31], v[44:45] neg_lo:[0,1] neg_hi:[0,1]
	v_mov_b32_e32 v68, v12
	v_pk_fma_f32 v[36:37], v[14:15], v[36:37], v[8:9]
	v_lshlrev_b32_e32 v9, 16, v70
	v_lshlrev_b32_e32 v8, 16, v71
	v_and_b32_e32 v13, 0xffff0000, v70
	v_and_b32_e32 v12, 0xffff0000, v71
	v_lshlrev_b32_e32 v71, 16, v72
	v_lshlrev_b32_e32 v70, 16, v74
	v_pk_fma_f32 v[30:31], v[66:67], v[30:31], v[44:45]
	v_pk_add_f32 v[38:39], v[60:61], v[44:45] neg_lo:[0,1] neg_hi:[0,1]
	v_and_b32_e32 v73, 0xffff0000, v72
	v_and_b32_e32 v72, 0xffff0000, v74
	v_lshlrev_b32_e32 v74, 16, v78
	v_pk_add_f32 v[8:9], v[8:9], v[70:71] neg_lo:[0,1] neg_hi:[0,1]
	v_mov_b32_e32 v78, v16
	v_mov_b32_e32 v79, v18
	v_pk_fma_f32 v[30:31], v[68:69], v[38:39], v[30:31]
	v_pk_fma_f32 v[8:9], v[78:79], v[8:9], v[70:71]
	v_pk_add_f32 v[38:39], v[74:75], v[70:71] neg_lo:[0,1] neg_hi:[0,1]
	v_mov_b32_e32 v80, v20
	v_mov_b32_e32 v81, v22
	v_pk_fma_f32 v[98:99], v[80:81], v[38:39], v[8:9]
	v_pk_add_f32 v[8:9], v[12:13], v[72:73] neg_lo:[0,1] neg_hi:[0,1]
	v_mov_b32_e32 v18, v17
	v_pk_fma_f32 v[8:9], v[18:19], v[8:9], v[72:73]
	v_pk_add_f32 v[12:13], v[76:77], v[72:73] neg_lo:[0,1] neg_hi:[0,1]
	v_mov_b32_e32 v22, v21
	v_pk_fma_f32 v[100:101], v[22:23], v[12:13], v[8:9]
	v_bfe_u32 v8, v30, 16, 1
	v_bfe_u32 v9, v31, 16, 1
	v_bfe_u32 v12, v98, 16, 1
	v_bfe_u32 v13, v99, 16, 1
	v_add3_u32 v13, v99, v13, s58
	v_add3_u32 v12, v98, v12, s58
	v_add3_u32 v9, v31, v9, s58
	v_add3_u32 v8, v30, v8, s58
	v_lshrrev_b32_e32 v8, 16, v8
	v_lshrrev_b32_e32 v9, 16, v9
	v_lshrrev_b32_e32 v12, 16, v12
	v_lshrrev_b32_e32 v13, 16, v13
	v_lshlrev_b64 v[38:39], 9, v[90:91]
	v_cndmask_b32_e64 v82, 0, v43, s[8:9]
	v_cndmask_b32_e64 v83, 0, v42, s[8:9]
	v_cndmask_b32_e64 v84, 0, v41, s[8:9]
	v_cndmask_b32_e64 v85, 0, v40, s[8:9]
	v_lshl_add_u64 v[0:1], s[0:1], 0, v[64:65]
	v_and_or_b32 v43, v101, s54, v13
	v_and_or_b32 v42, v100, s54, v12
	v_and_or_b32 v41, v37, s54, v9
	v_and_or_b32 v40, v36, s54, v8
	v_lshl_add_u64 v[8:9], v[56:57], 0, v[38:39]
	global_load_dwordx4 v[4:7], v[0:1], off
	s_nop 0
	global_load_dwordx4 v[0:3], v[0:1], off offset:16
	v_pk_add_f32 v[16:17], v[44:45], v[60:61] neg_lo:[0,1] neg_hi:[0,1]
	global_store_dwordx4 v[8:9], v[40:43], off
	v_lshlrev_b32_e32 v9, 16, v84
	v_lshlrev_b32_e32 v8, 16, v85
	v_pk_fma_f32 v[16:17], v[66:67], v[16:17], v[60:61]
	v_pk_add_f32 v[20:21], v[8:9], v[60:61] neg_lo:[0,1] neg_hi:[0,1]
	v_and_b32_e32 v13, 0xffff0000, v84
	v_and_b32_e32 v12, 0xffff0000, v85
	v_pk_fma_f32 v[102:103], v[68:69], v[20:21], v[16:17]
	v_pk_add_f32 v[16:17], v[58:59], v[62:63] neg_lo:[0,1] neg_hi:[0,1]
	v_pk_add_f32 v[20:21], v[12:13], v[62:63] neg_lo:[0,1] neg_hi:[0,1]
	v_pk_fma_f32 v[16:17], v[10:11], v[16:17], v[62:63]
	v_pk_add_f32 v[40:41], v[70:71], v[74:75] neg_lo:[0,1] neg_hi:[0,1]
	v_pk_fma_f32 v[104:105], v[14:15], v[20:21], v[16:17]
	v_lshlrev_b32_e32 v17, 16, v82
	v_lshlrev_b32_e32 v16, 16, v83
	v_pk_fma_f32 v[40:41], v[78:79], v[40:41], v[74:75]
	v_pk_add_f32 v[42:43], v[16:17], v[74:75] neg_lo:[0,1] neg_hi:[0,1]
	v_and_b32_e32 v21, 0xffff0000, v82
	v_and_b32_e32 v20, 0xffff0000, v83
	v_pk_fma_f32 v[106:107], v[80:81], v[42:43], v[40:41]
	v_pk_add_f32 v[40:41], v[72:73], v[76:77] neg_lo:[0,1] neg_hi:[0,1]
	v_pk_add_f32 v[42:43], v[20:21], v[76:77] neg_lo:[0,1] neg_hi:[0,1]
	v_pk_fma_f32 v[40:41], v[18:19], v[40:41], v[76:77]
	v_pk_add_f32 v[60:61], v[60:61], v[8:9] neg_lo:[0,1] neg_hi:[0,1]
	v_pk_fma_f32 v[108:109], v[22:23], v[42:43], v[40:41]
	v_bfe_u32 v40, v102, 16, 1
	v_bfe_u32 v41, v103, 16, 1
	v_bfe_u32 v42, v106, 16, 1
	v_bfe_u32 v43, v107, 16, 1
	v_add3_u32 v43, v107, v43, s58
	v_add3_u32 v42, v106, v42, s58
	v_add3_u32 v41, v103, v41, s58
	v_add3_u32 v40, v102, v40, s58
	v_lshrrev_b32_e32 v40, 16, v40
	v_lshrrev_b32_e32 v41, 16, v41
	v_lshrrev_b32_e32 v42, 16, v42
	v_lshrrev_b32_e32 v43, 16, v43
	v_and_or_b32 v45, v109, s54, v43
	v_and_or_b32 v44, v108, s54, v42
	v_and_or_b32 v43, v105, s54, v41
	v_and_or_b32 v42, v104, s54, v40
	v_lshlrev_b64 v[40:41], 9, v[92:93]
	v_lshl_add_u64 v[58:59], v[56:57], 0, v[40:41]
	global_store_dwordx4 v[58:59], v[42:45], off
	v_pk_fma_f32 v[60:61], v[66:67], v[60:61], v[8:9]
	v_and_b32_e32 v71, 0xffff0000, v94
	v_lshlrev_b32_e32 v45, 16, v94
	v_lshlrev_b32_e32 v44, 16, v95
	v_pk_add_f32 v[42:43], v[44:45], v[8:9] neg_lo:[0,1] neg_hi:[0,1]
	v_and_b32_e32 v70, 0xffff0000, v95
	v_pk_fma_f32 v[110:111], v[68:69], v[42:43], v[60:61]
	v_pk_add_f32 v[42:43], v[62:63], v[12:13] neg_lo:[0,1] neg_hi:[0,1]
	v_pk_add_f32 v[58:59], v[70:71], v[12:13] neg_lo:[0,1] neg_hi:[0,1]
	v_pk_fma_f32 v[42:43], v[10:11], v[42:43], v[12:13]
	v_lshlrev_b32_e32 v63, 16, v86
	v_lshlrev_b32_e32 v62, 16, v87
	v_pk_add_f32 v[60:61], v[74:75], v[16:17] neg_lo:[0,1] neg_hi:[0,1]
	v_pk_fma_f32 v[112:113], v[14:15], v[58:59], v[42:43]
	v_pk_add_f32 v[42:43], v[62:63], v[16:17] neg_lo:[0,1] neg_hi:[0,1]
	v_pk_fma_f32 v[60:61], v[78:79], v[60:61], v[16:17]
	v_and_b32_e32 v73, 0xffff0000, v86
	v_and_b32_e32 v72, 0xffff0000, v87
	v_pk_fma_f32 v[114:115], v[80:81], v[42:43], v[60:61]
	v_pk_add_f32 v[42:43], v[76:77], v[20:21] neg_lo:[0,1] neg_hi:[0,1]
	v_pk_add_f32 v[58:59], v[72:73], v[20:21] neg_lo:[0,1] neg_hi:[0,1]
	v_pk_fma_f32 v[42:43], v[18:19], v[42:43], v[20:21]
	v_or_b32_e32 v94, 2, v90
	v_pk_fma_f32 v[116:117], v[22:23], v[58:59], v[42:43]
	v_bfe_u32 v42, v110, 16, 1
	v_bfe_u32 v43, v111, 16, 1
	v_bfe_u32 v58, v114, 16, 1
	v_bfe_u32 v59, v115, 16, 1
	v_add3_u32 v59, v115, v59, s58
	v_add3_u32 v58, v114, v58, s58
	v_add3_u32 v43, v111, v43, s58
	v_add3_u32 v42, v110, v42, s58
	v_lshrrev_b32_e32 v42, 16, v42
	v_lshrrev_b32_e32 v43, 16, v43
	v_lshrrev_b32_e32 v58, 16, v58
	v_lshrrev_b32_e32 v59, 16, v59
	v_ashrrev_i32_e32 v95, 31, v94
	v_and_or_b32 v61, v117, s54, v59
	v_and_or_b32 v60, v116, s54, v58
	v_and_or_b32 v59, v113, s54, v43
	v_and_or_b32 v58, v112, s54, v42
	v_lshlrev_b64 v[42:43], 9, v[94:95]
	v_lshl_add_u64 v[74:75], v[56:57], 0, v[42:43]
	global_store_dwordx4 v[74:75], v[58:61], off
	v_pk_add_f32 v[8:9], v[8:9], v[44:45] neg_lo:[0,1] neg_hi:[0,1]
	v_pk_add_f32 v[12:13], v[12:13], v[70:71] neg_lo:[0,1] neg_hi:[0,1]
	v_lshlrev_b32_e32 v59, 16, v118
	v_lshlrev_b32_e32 v58, 16, v119
	v_and_b32_e32 v61, 0xffff0000, v118
	v_and_b32_e32 v60, 0xffff0000, v119
	v_pk_add_f32 v[58:59], v[58:59], v[44:45] neg_lo:[0,1] neg_hi:[0,1]
	v_pk_fma_f32 v[8:9], v[66:67], v[8:9], v[44:45]
	v_pk_add_f32 v[60:61], v[60:61], v[70:71] neg_lo:[0,1] neg_hi:[0,1]
	v_pk_fma_f32 v[118:119], v[68:69], v[58:59], v[8:9]
	v_pk_fma_f32 v[8:9], v[10:11], v[12:13], v[70:71]
	v_pk_add_f32 v[12:13], v[16:17], v[62:63] neg_lo:[0,1] neg_hi:[0,1]
	v_pk_fma_f32 v[120:121], v[14:15], v[60:61], v[8:9]
	v_lshlrev_b32_e32 v9, 16, v96
	v_lshlrev_b32_e32 v8, 16, v97
	v_and_b32_e32 v11, 0xffff0000, v96
	v_and_b32_e32 v10, 0xffff0000, v97
	v_pk_add_f32 v[8:9], v[8:9], v[62:63] neg_lo:[0,1] neg_hi:[0,1]
	v_pk_add_f32 v[14:15], v[20:21], v[72:73] neg_lo:[0,1] neg_hi:[0,1]
	v_pk_fma_f32 v[12:13], v[78:79], v[12:13], v[62:63]
	v_pk_add_f32 v[10:11], v[10:11], v[72:73] neg_lo:[0,1] neg_hi:[0,1]
	v_pk_fma_f32 v[122:123], v[80:81], v[8:9], v[12:13]
	v_pk_fma_f32 v[8:9], v[18:19], v[14:15], v[72:73]
	v_or_b32_e32 v96, 3, v90
	v_pk_fma_f32 v[124:125], v[22:23], v[10:11], v[8:9]
	v_bfe_u32 v8, v118, 16, 1
	v_bfe_u32 v9, v119, 16, 1
	v_bfe_u32 v10, v122, 16, 1
	v_bfe_u32 v11, v123, 16, 1
	v_add3_u32 v11, v123, v11, s58
	v_add3_u32 v10, v122, v10, s58
	v_add3_u32 v9, v119, v9, s58
	v_add3_u32 v8, v118, v8, s58
	v_ashrrev_i32_e32 v97, 31, v96
	v_lshrrev_b32_e32 v8, 16, v8
	v_lshrrev_b32_e32 v9, 16, v9
	v_lshrrev_b32_e32 v10, 16, v10
	v_lshrrev_b32_e32 v11, 16, v11
	v_lshlrev_b64 v[44:45], 9, v[96:97]
	v_and_or_b32 v11, v125, s54, v11
	v_and_or_b32 v10, v124, s54, v10
	v_and_or_b32 v9, v121, s54, v9
	v_and_or_b32 v8, v120, s54, v8
	v_lshl_add_u64 v[12:13], v[56:57], 0, v[44:45]
	global_store_dwordx4 v[12:13], v[8:11], off
	s_waitcnt vmcnt(0) lgkmcnt(0)
	v_mul_f32_e32 v159, v98, v0
	v_mul_f32_e32 v160, v100, v1
	v_lshl_add_u64 v[8:9], v[88:89], 0, s[38:39]
	v_lshl_add_u64 v[10:11], v[8:9], 0, v[28:29]
	global_load_dwordx4 v[56:59], v[10:11], off
	v_lshl_add_u64 v[10:11], v[8:9], 0, v[46:47]
	global_load_dwordx4 v[60:63], v[10:11], off
	v_lshl_add_u64 v[10:11], v[8:9], 0, v[48:49]
	global_load_dwordx4 v[66:69], v[10:11], off
	v_lshl_add_u64 v[10:11], v[8:9], 0, v[50:51]
	global_load_dwordx4 v[70:73], v[10:11], off
	v_lshl_add_u64 v[10:11], v[8:9], 0, v[52:53]
	global_load_dwordx4 v[74:77], v[10:11], off
	v_lshl_add_u64 v[8:9], v[8:9], 0, v[54:55]
	global_load_dwordx4 v[78:81], v[8:9], off
	s_nop 0
	global_load_dwordx4 v[8:11], v[24:25], off offset:2048
	global_load_dwordx4 v[12:15], v[26:27], off offset:2048
	global_load_dwordx4 v[16:19], v[24:25], off offset:2064
	global_load_dwordx4 v[20:23], v[26:27], off offset:2064
	v_mul_f32_e32 v161, v99, v2
	v_mul_f32_e32 v162, v101, v3
	v_mul_f32_e32 v163, v4, v102
	v_mul_f32_e32 v168, v5, v104
	v_mul_f32_e32 v169, v103, v6
	v_mul_f32_e32 v170, v105, v7
	v_mul_f32_e32 v171, v106, v0
	v_mul_f32_e32 v175, v114, v0
	v_mul_f32_e32 v187, v122, v0
	v_mul_f32_e32 v172, v108, v1
	v_mul_f32_e32 v176, v116, v1
	v_mul_f32_e32 v177, v115, v2
	v_mul_f32_e32 v188, v124, v1
	v_bitop3_b32 v1, v135, 31, v130 bitop3:0xe0
	v_mul_f32_e32 v173, v107, v2
	v_mul_f32_e32 v174, v109, v3
	v_mul_f32_e32 v110, v4, v110
	v_mul_f32_e32 v112, v5, v112
	v_mul_f32_e32 v111, v6, v111
	v_mul_f32_e32 v113, v113, v7
	v_mul_f32_e32 v178, v117, v3
	v_mul_f32_e32 v179, v4, v118
	v_mul_f32_e32 v184, v5, v120
	v_mul_f32_e32 v185, v6, v119
	v_mul_f32_e32 v186, v7, v121
	v_mul_f32_e32 v189, v123, v2
	v_mul_f32_e32 v190, v125, v3
	s_waitcnt vmcnt(0) lgkmcnt(0)
	v_cndmask_b32_e32 v84, 0, v57, vcc
	v_cndmask_b32_e32 v85, 0, v56, vcc
	v_cndmask_b32_e64 v136, 0, v61, s[4:5]
	v_cndmask_b32_e64 v139, 0, v60, s[4:5]
	v_cndmask_b32_e64 v142, 0, v67, s[6:7]
	v_cndmask_b32_e64 v143, 0, v66, s[6:7]
	v_and_b32_e32 v61, 0xffff0000, v84
	v_and_b32_e32 v60, 0xffff0000, v85
	v_and_b32_e32 v67, 0xffff0000, v136
	v_and_b32_e32 v66, 0xffff0000, v139
	v_cndmask_b32_e32 v82, 0, v59, vcc
	v_cndmask_b32_e32 v83, 0, v58, vcc
	v_cndmask_b32_e64 v86, 0, v63, s[4:5]
	v_cndmask_b32_e64 v87, 0, v62, s[4:5]
	v_cndmask_b32_e64 v144, 0, v73, s[8:9]
	v_cndmask_b32_e64 v146, 0, v71, s[8:9]
	v_cndmask_b32_e64 v147, 0, v70, s[8:9]
	v_lshlrev_b32_e32 v59, 16, v84
	v_lshlrev_b32_e32 v58, 16, v85
	v_lshlrev_b32_e32 v63, 16, v136
	v_lshlrev_b32_e32 v62, 16, v139
	v_and_b32_e32 v71, 0xffff0000, v142
	v_and_b32_e32 v70, 0xffff0000, v143
	v_mov_b32_e32 v73, v10
	v_pk_add_f32 v[60:61], v[60:61], v[66:67] neg_lo:[0,1] neg_hi:[0,1]
	v_mov_b32_e32 v10, v9
	v_cndmask_b32_e64 v140, 0, v69, s[6:7]
	v_cndmask_b32_e64 v141, 0, v68, s[6:7]
	v_cndmask_b32_e64 v145, 0, v72, s[8:9]
	v_cndmask_b32_e64 v148, 0, v77, s[10:11]
	v_lshlrev_b32_e32 v69, 16, v142
	v_lshlrev_b32_e32 v68, 16, v143
	v_pk_add_f32 v[58:59], v[58:59], v[62:63] neg_lo:[0,1] neg_hi:[0,1]
	v_mov_b32_e32 v72, v8
	v_mov_b32_e32 v77, v14
	v_pk_fma_f32 v[8:9], v[10:11], v[60:61], v[66:67]
	v_pk_add_f32 v[60:61], v[70:71], v[66:67] neg_lo:[0,1] neg_hi:[0,1]
	v_mov_b32_e32 v14, v13
	v_cndmask_b32_e64 v149, 0, v76, s[10:11]
	v_cndmask_b32_e64 v150, 0, v75, s[10:11]
	v_cndmask_b32_e64 v151, 0, v74, s[10:11]
	v_cndmask_b32_e64 v154, 0, v79, s[12:13]
	v_cndmask_b32_e64 v155, 0, v78, s[12:13]
	v_pk_fma_f32 v[58:59], v[72:73], v[58:59], v[62:63]
	v_pk_add_f32 v[74:75], v[68:69], v[62:63] neg_lo:[0,1] neg_hi:[0,1]
	v_mov_b32_e32 v76, v12
	v_pk_fma_f32 v[8:9], v[14:15], v[60:61], v[8:9]
	v_and_b32_e32 v61, 0xffff0000, v82
	v_and_b32_e32 v60, 0xffff0000, v83
	v_and_b32_e32 v79, 0xffff0000, v86
	v_and_b32_e32 v78, 0xffff0000, v87
	v_pk_fma_f32 v[58:59], v[76:77], v[74:75], v[58:59]
	v_lshlrev_b32_e32 v13, 16, v82
	v_lshlrev_b32_e32 v12, 16, v83
	v_lshlrev_b32_e32 v75, 16, v86
	v_lshlrev_b32_e32 v74, 16, v87
	v_and_b32_e32 v83, 0xffff0000, v140
	v_and_b32_e32 v82, 0xffff0000, v141
	v_mov_b32_e32 v85, v18
	v_pk_add_f32 v[60:61], v[60:61], v[78:79] neg_lo:[0,1] neg_hi:[0,1]
	v_mov_b32_e32 v18, v17
	v_cndmask_b32_e64 v152, 0, v81, s[12:13]
	v_cndmask_b32_e64 v153, 0, v80, s[12:13]
	v_lshlrev_b32_e32 v81, 16, v140
	v_lshlrev_b32_e32 v80, 16, v141
	v_pk_add_f32 v[12:13], v[12:13], v[74:75] neg_lo:[0,1] neg_hi:[0,1]
	v_mov_b32_e32 v84, v16
	v_mov_b32_e32 v141, v22
	v_pk_fma_f32 v[16:17], v[18:19], v[60:61], v[78:79]
	v_pk_add_f32 v[60:61], v[82:83], v[78:79] neg_lo:[0,1] neg_hi:[0,1]
	v_mov_b32_e32 v22, v21
	v_pk_fma_f32 v[12:13], v[84:85], v[12:13], v[74:75]
	v_pk_add_f32 v[86:87], v[80:81], v[74:75] neg_lo:[0,1] neg_hi:[0,1]
	v_mov_b32_e32 v140, v20
	v_pk_fma_f32 v[16:17], v[22:23], v[60:61], v[16:17]
	v_pk_fma_f32 v[12:13], v[140:141], v[86:87], v[12:13]
	v_bfe_u32 v20, v17, 16, 1
	v_bfe_u32 v21, v16, 16, 1
	v_bfe_u32 v60, v9, 16, 1
	v_bfe_u32 v61, v8, 16, 1
	v_add3_u32 v8, v8, v61, s58
	v_add3_u32 v9, v9, v60, s58
	v_add3_u32 v16, v16, v21, s58
	v_add3_u32 v17, v17, v20, s58
	v_bfe_u32 v20, v58, 16, 1
	v_bfe_u32 v21, v59, 16, 1
	v_bfe_u32 v60, v12, 16, 1
	v_bfe_u32 v61, v13, 16, 1
	v_add3_u32 v13, v13, v61, s58
	v_add3_u32 v12, v12, v60, s58
	v_add3_u32 v21, v59, v21, s58
	v_add3_u32 v20, v58, v20, s58
	v_lshl_add_u64 v[56:57], v[88:89], 0, s[40:41]
	v_lshrrev_b32_e32 v20, 16, v20
	v_lshrrev_b32_e32 v21, 16, v21
	v_lshrrev_b32_e32 v12, 16, v12
	v_lshrrev_b32_e32 v13, 16, v13
	v_and_or_b32 v61, v17, s54, v13
	v_and_or_b32 v60, v16, s54, v12
	v_and_or_b32 v59, v9, s54, v21
	v_and_or_b32 v58, v8, s54, v20
	v_lshl_add_u64 v[8:9], v[56:57], 0, v[38:39]
	global_store_dwordx4 v[8:9], v[58:61], off
	v_lshlrev_b32_e32 v9, 16, v146
	v_lshlrev_b32_e32 v8, 16, v147
	v_pk_add_f32 v[16:17], v[62:63], v[68:69] neg_lo:[0,1] neg_hi:[0,1]
	v_pk_add_f32 v[20:21], v[8:9], v[68:69] neg_lo:[0,1] neg_hi:[0,1]
	v_pk_fma_f32 v[16:17], v[72:73], v[16:17], v[68:69]
	v_and_b32_e32 v13, 0xffff0000, v146
	v_and_b32_e32 v12, 0xffff0000, v147
	v_pk_fma_f32 v[16:17], v[76:77], v[20:21], v[16:17]
	v_pk_add_f32 v[20:21], v[66:67], v[70:71] neg_lo:[0,1] neg_hi:[0,1]
	v_pk_add_f32 v[58:59], v[12:13], v[70:71] neg_lo:[0,1] neg_hi:[0,1]
	v_pk_fma_f32 v[20:21], v[10:11], v[20:21], v[70:71]
	v_lshlrev_b32_e32 v63, 16, v144
	v_pk_fma_f32 v[20:21], v[14:15], v[58:59], v[20:21]
	v_lshlrev_b32_e32 v62, 16, v145
	v_pk_add_f32 v[58:59], v[74:75], v[80:81] neg_lo:[0,1] neg_hi:[0,1]
	v_pk_add_f32 v[60:61], v[62:63], v[80:81] neg_lo:[0,1] neg_hi:[0,1]
	v_pk_fma_f32 v[58:59], v[84:85], v[58:59], v[80:81]
	v_and_b32_e32 v67, 0xffff0000, v144
	v_and_b32_e32 v66, 0xffff0000, v145
	v_pk_fma_f32 v[58:59], v[140:141], v[60:61], v[58:59]
	v_pk_add_f32 v[60:61], v[78:79], v[82:83] neg_lo:[0,1] neg_hi:[0,1]
	v_pk_add_f32 v[74:75], v[66:67], v[82:83] neg_lo:[0,1] neg_hi:[0,1]
	v_pk_fma_f32 v[60:61], v[18:19], v[60:61], v[82:83]
	v_bfe_u32 v78, v21, 16, 1
	v_pk_fma_f32 v[60:61], v[22:23], v[74:75], v[60:61]
	v_bfe_u32 v79, v20, 16, 1
	v_bfe_u32 v74, v61, 16, 1
	v_bfe_u32 v75, v60, 16, 1
	v_add3_u32 v20, v20, v79, s58
	v_add3_u32 v21, v21, v78, s58
	v_add3_u32 v60, v60, v75, s58
	v_add3_u32 v61, v61, v74, s58
	v_bfe_u32 v74, v16, 16, 1
	v_bfe_u32 v75, v17, 16, 1
	v_bfe_u32 v78, v58, 16, 1
	v_bfe_u32 v79, v59, 16, 1
	v_add3_u32 v59, v59, v79, s58
	v_add3_u32 v58, v58, v78, s58
	v_add3_u32 v17, v17, v75, s58
	v_add3_u32 v16, v16, v74, s58
	v_lshrrev_b32_e32 v16, 16, v16
	v_lshrrev_b32_e32 v17, 16, v17
	v_lshrrev_b32_e32 v58, 16, v58
	v_lshrrev_b32_e32 v59, 16, v59
	v_and_or_b32 v61, v61, s54, v59
	v_and_or_b32 v60, v60, s54, v58
	v_and_or_b32 v59, v21, s54, v17
	v_and_or_b32 v58, v20, s54, v16
	v_lshl_add_u64 v[16:17], v[56:57], 0, v[40:41]
	global_store_dwordx4 v[16:17], v[58:61], off
	v_lshlrev_b32_e32 v17, 16, v150
	v_lshlrev_b32_e32 v16, 16, v151
	v_pk_add_f32 v[68:69], v[68:69], v[8:9] neg_lo:[0,1] neg_hi:[0,1]
	v_pk_add_f32 v[58:59], v[16:17], v[8:9] neg_lo:[0,1] neg_hi:[0,1]
	v_pk_fma_f32 v[68:69], v[72:73], v[68:69], v[8:9]
	v_and_b32_e32 v21, 0xffff0000, v150
	v_and_b32_e32 v20, 0xffff0000, v151
	v_pk_fma_f32 v[58:59], v[76:77], v[58:59], v[68:69]
	v_pk_add_f32 v[68:69], v[70:71], v[12:13] neg_lo:[0,1] neg_hi:[0,1]
	v_pk_add_f32 v[60:61], v[20:21], v[12:13] neg_lo:[0,1] neg_hi:[0,1]
	v_pk_fma_f32 v[68:69], v[10:11], v[68:69], v[12:13]
	v_pk_add_f32 v[80:81], v[80:81], v[62:63] neg_lo:[0,1] neg_hi:[0,1]
	v_pk_fma_f32 v[60:61], v[14:15], v[60:61], v[68:69]
	v_lshlrev_b32_e32 v69, 16, v148
	v_lshlrev_b32_e32 v68, 16, v149
	v_pk_add_f32 v[74:75], v[68:69], v[62:63] neg_lo:[0,1] neg_hi:[0,1]
	v_pk_fma_f32 v[80:81], v[84:85], v[80:81], v[62:63]
	v_and_b32_e32 v71, 0xffff0000, v148
	v_and_b32_e32 v70, 0xffff0000, v149
	v_pk_fma_f32 v[74:75], v[140:141], v[74:75], v[80:81]
	v_pk_add_f32 v[80:81], v[82:83], v[66:67] neg_lo:[0,1] neg_hi:[0,1]
	v_pk_add_f32 v[78:79], v[70:71], v[66:67] neg_lo:[0,1] neg_hi:[0,1]
	v_pk_fma_f32 v[80:81], v[18:19], v[80:81], v[66:67]
	v_bfe_u32 v82, v61, 16, 1
	v_pk_fma_f32 v[78:79], v[22:23], v[78:79], v[80:81]
	v_bfe_u32 v83, v60, 16, 1
	v_bfe_u32 v80, v79, 16, 1
	v_bfe_u32 v81, v78, 16, 1
	v_add3_u32 v83, v60, v83, s58
	v_add3_u32 v82, v61, v82, s58
	v_add3_u32 v60, v78, v81, s58
	v_add3_u32 v61, v79, v80, s58
	v_bfe_u32 v78, v58, 16, 1
	v_bfe_u32 v79, v59, 16, 1
	v_bfe_u32 v80, v74, 16, 1
	v_bfe_u32 v81, v75, 16, 1
	v_add3_u32 v75, v75, v81, s58
	v_add3_u32 v74, v74, v80, s58
	v_add3_u32 v59, v59, v79, s58
	v_add3_u32 v58, v58, v78, s58
	v_lshrrev_b32_e32 v58, 16, v58
	v_lshrrev_b32_e32 v59, 16, v59
	v_lshrrev_b32_e32 v74, 16, v74
	v_lshrrev_b32_e32 v75, 16, v75
	v_and_or_b32 v61, v61, s54, v75
	v_and_or_b32 v60, v60, s54, v74
	v_and_or_b32 v59, v82, s54, v59
	v_and_or_b32 v58, v83, s54, v58
	v_lshl_add_u64 v[74:75], v[56:57], 0, v[42:43]
	global_store_dwordx4 v[74:75], v[58:61], off
	v_pk_add_f32 v[8:9], v[8:9], v[16:17] neg_lo:[0,1] neg_hi:[0,1]
	v_pk_add_f32 v[12:13], v[12:13], v[20:21] neg_lo:[0,1] neg_hi:[0,1]
	v_lshlrev_b32_e32 v59, 16, v154
	v_lshlrev_b32_e32 v58, 16, v155
	v_and_b32_e32 v61, 0xffff0000, v154
	v_and_b32_e32 v60, 0xffff0000, v155
	v_pk_add_f32 v[58:59], v[58:59], v[16:17] neg_lo:[0,1] neg_hi:[0,1]
	v_pk_add_f32 v[60:61], v[60:61], v[20:21] neg_lo:[0,1] neg_hi:[0,1]
	v_pk_fma_f32 v[8:9], v[72:73], v[8:9], v[16:17]
	v_pk_fma_f32 v[10:11], v[10:11], v[12:13], v[20:21]
	v_lshlrev_b32_e32 v13, 16, v152
	v_lshlrev_b32_e32 v12, 16, v153
	v_pk_add_f32 v[16:17], v[62:63], v[68:69] neg_lo:[0,1] neg_hi:[0,1]
	v_pk_fma_f32 v[10:11], v[14:15], v[60:61], v[10:11]
	v_and_b32_e32 v15, 0xffff0000, v152
	v_and_b32_e32 v14, 0xffff0000, v153
	v_pk_add_f32 v[12:13], v[12:13], v[68:69] neg_lo:[0,1] neg_hi:[0,1]
	v_pk_add_f32 v[20:21], v[66:67], v[70:71] neg_lo:[0,1] neg_hi:[0,1]
	v_pk_fma_f32 v[16:17], v[84:85], v[16:17], v[68:69]
	v_pk_add_f32 v[14:15], v[14:15], v[70:71] neg_lo:[0,1] neg_hi:[0,1]
	v_pk_fma_f32 v[12:13], v[140:141], v[12:13], v[16:17]
	v_pk_fma_f32 v[16:17], v[18:19], v[20:21], v[70:71]
	v_pk_fma_f32 v[8:9], v[76:77], v[58:59], v[8:9]
	v_pk_fma_f32 v[14:15], v[22:23], v[14:15], v[16:17]
	v_bfe_u32 v18, v11, 16, 1
	v_bfe_u32 v16, v15, 16, 1
	v_bfe_u32 v17, v14, 16, 1
	v_bfe_u32 v19, v10, 16, 1
	v_add3_u32 v19, v10, v19, s58
	v_add3_u32 v18, v11, v18, s58
	v_add3_u32 v10, v14, v17, s58
	v_add3_u32 v11, v15, v16, s58
	v_bfe_u32 v14, v8, 16, 1
	v_bfe_u32 v15, v9, 16, 1
	v_bfe_u32 v16, v12, 16, 1
	v_bfe_u32 v17, v13, 16, 1
	v_add3_u32 v13, v13, v17, s58
	v_add3_u32 v12, v12, v16, s58
	v_add3_u32 v9, v9, v15, s58
	v_add3_u32 v8, v8, v14, s58
	v_lshrrev_b32_e32 v8, 16, v8
	v_lshrrev_b32_e32 v9, 16, v9
	v_lshrrev_b32_e32 v12, 16, v12
	v_lshrrev_b32_e32 v13, 16, v13
	v_and_or_b32 v11, v11, s54, v13
	v_and_or_b32 v10, v10, s54, v12
	v_and_or_b32 v9, v18, s54, v9
	v_and_or_b32 v8, v19, s54, v8
	v_lshl_add_u64 v[12:13], v[56:57], 0, v[44:45]
	global_store_dwordx4 v[12:13], v[8:11], off
	v_lshl_add_u64 v[12:13], v[88:89], 0, s[42:43]
	v_lshl_add_u64 v[14:15], v[12:13], 0, v[46:47]
	v_lshl_add_u64 v[8:9], v[12:13], 0, v[28:29]
	global_load_dwordx4 v[8:11], v[8:9], off
	v_and_b32_e32 v136, 0xffffffc0, v135
	global_load_dwordx4 v[56:59], v[14:15], off
	v_lshl_add_u64 v[14:15], v[12:13], 0, v[48:49]
	global_load_dwordx4 v[46:49], v[14:15], off
	v_lshl_add_u64 v[14:15], v[12:13], 0, v[50:51]
	global_load_dwordx4 v[60:63], v[14:15], off
	v_lshl_add_u64 v[14:15], v[12:13], 0, v[52:53]
	v_lshl_add_u64 v[12:13], v[12:13], 0, v[54:55]
	global_load_dwordx4 v[50:53], v[14:15], off
	global_load_dwordx4 v[66:69], v[12:13], off
	s_nop 0
	global_load_dwordx2 v[12:13], v[32:33], off offset:448
	global_load_dwordx4 v[18:21], v[24:25], off offset:1024
	global_load_dwordx4 v[14:17], v[26:27], off offset:1024
	s_waitcnt vmcnt(0) lgkmcnt(0)
	v_cndmask_b32_e32 v82, 0, v9, vcc
	global_load_dwordx4 v[22:25], v[24:25], off offset:1040
	v_cndmask_b32_e32 v83, 0, v8, vcc
	global_load_dwordx4 v[26:29], v[26:27], off offset:1040
	v_cndmask_b32_e64 v54, 0, v57, s[4:5]
	v_cndmask_b32_e64 v56, 0, v56, s[4:5]
	v_cndmask_b32_e64 v55, 0, v47, s[6:7]
	v_cndmask_b32_e64 v57, 0, v46, s[6:7]
	v_cndmask_b32_e32 v139, 0, v11, vcc
	v_cndmask_b32_e32 v146, 0, v10, vcc
	v_cndmask_b32_e64 v151, 0, v63, s[8:9]
	v_cndmask_b32_e64 v152, 0, v62, s[8:9]
	v_cndmask_b32_e64 v157, 0, v67, s[12:13]
	v_cndmask_b32_e64 v158, 0, v66, s[12:13]
	v_lshlrev_b32_e32 v8, 16, v83
	v_lshlrev_b32_e32 v9, 16, v82
	v_lshlrev_b32_e32 v10, 16, v56
	v_lshlrev_b32_e32 v11, 16, v54
	v_lshlrev_b32_e32 v62, 16, v57
	v_lshlrev_b32_e32 v63, 16, v55
	v_readfirstlane_b32 s1, v13
	v_readfirstlane_b32 s0, v12
	v_and_b32_e32 v67, 0xffff0000, v55
	v_and_b32_e32 v66, 0xffff0000, v57
	v_and_b32_e32 v55, 0xffff0000, v54
	v_and_b32_e32 v54, 0xffff0000, v56
	v_and_b32_e32 v57, 0xffff0000, v82
	v_and_b32_e32 v56, 0xffff0000, v83
	v_cndmask_b32_e64 v147, 0, v59, s[4:5]
	v_cndmask_b32_e64 v148, 0, v58, s[4:5]
	v_cndmask_b32_e64 v58, 0, v61, s[8:9]
	v_cndmask_b32_e64 v59, 0, v60, s[8:9]
	v_lshl_add_u64 v[12:13], s[0:1], 0, v[64:65]
	v_pk_add_f32 v[8:9], v[8:9], v[10:11] neg_lo:[0,1] neg_hi:[0,1]
	v_pk_add_f32 v[56:57], v[56:57], v[54:55] neg_lo:[0,1] neg_hi:[0,1]
	v_mov_b32_e32 v82, v18
	v_mov_b32_e32 v83, v20
	v_mov_b32_e32 v20, v19
	v_cndmask_b32_e64 v155, 0, v69, s[12:13]
	v_cndmask_b32_e64 v156, 0, v68, s[12:13]
	v_lshlrev_b32_e32 v68, 16, v59
	v_lshlrev_b32_e32 v69, 16, v58
	v_and_b32_e32 v77, 0xffff0000, v58
	v_and_b32_e32 v76, 0xffff0000, v59
	v_pk_add_f32 v[58:59], v[10:11], v[62:63] neg_lo:[0,1] neg_hi:[0,1]
	v_pk_fma_f32 v[140:141], v[82:83], v[8:9], v[10:11]
	v_pk_fma_f32 v[18:19], v[20:21], v[56:57], v[54:55]
	v_pk_add_f32 v[56:57], v[62:63], v[10:11] neg_lo:[0,1] neg_hi:[0,1]
	global_load_dwordx4 v[8:11], v[12:13], off
	v_mov_b32_e32 v144, v14
	v_mov_b32_e32 v145, v16
	v_mov_b32_e32 v16, v15
	global_load_dwordx4 v[12:15], v[12:13], off offset:16
	v_cndmask_b32_e64 v60, 0, v51, s[10:11]
	v_cndmask_b32_e64 v61, 0, v50, s[10:11]
	v_pk_add_f32 v[142:143], v[66:67], v[54:55] neg_lo:[0,1] neg_hi:[0,1]
	v_lshlrev_b32_e32 v70, 16, v61
	v_lshlrev_b32_e32 v71, 16, v60
	v_and_b32_e32 v79, 0xffff0000, v60
	v_and_b32_e32 v78, 0xffff0000, v61
	v_pk_add_f32 v[60:61], v[54:55], v[66:67] neg_lo:[0,1] neg_hi:[0,1]
	v_pk_fma_f32 v[54:55], v[144:145], v[56:57], v[140:141]
	v_pk_fma_f32 v[56:57], v[16:17], v[142:143], v[18:19]
	v_pk_fma_f32 v[18:19], v[82:83], v[58:59], v[62:63]
	v_pk_add_f32 v[58:59], v[68:69], v[62:63] neg_lo:[0,1] neg_hi:[0,1]
	v_and_b32_e32 v141, 0xffff0000, v157
	v_pk_fma_f32 v[58:59], v[144:145], v[58:59], v[18:19]
	v_pk_fma_f32 v[18:19], v[20:21], v[60:61], v[66:67]
	v_pk_add_f32 v[60:61], v[76:77], v[66:67] neg_lo:[0,1] neg_hi:[0,1]
	v_and_b32_e32 v140, 0xffff0000, v158
	v_pk_fma_f32 v[60:61], v[16:17], v[60:61], v[18:19]
	v_pk_add_f32 v[18:19], v[62:63], v[68:69] neg_lo:[0,1] neg_hi:[0,1]
	v_pk_add_f32 v[62:63], v[70:71], v[68:69] neg_lo:[0,1] neg_hi:[0,1]
	v_pk_fma_f32 v[18:19], v[82:83], v[18:19], v[68:69]
	v_pk_add_f32 v[68:69], v[68:69], v[70:71] neg_lo:[0,1] neg_hi:[0,1]
	v_pk_fma_f32 v[62:63], v[144:145], v[62:63], v[18:19]
	v_pk_add_f32 v[18:19], v[66:67], v[76:77] neg_lo:[0,1] neg_hi:[0,1]
	v_pk_add_f32 v[66:67], v[78:79], v[76:77] neg_lo:[0,1] neg_hi:[0,1]
	v_pk_fma_f32 v[18:19], v[20:21], v[18:19], v[76:77]
	v_pk_fma_f32 v[68:69], v[82:83], v[68:69], v[70:71]
	v_pk_fma_f32 v[66:67], v[16:17], v[66:67], v[18:19]
	v_lshlrev_b32_e32 v19, 16, v157
	v_lshlrev_b32_e32 v18, 16, v158
	v_pk_add_f32 v[18:19], v[18:19], v[70:71] neg_lo:[0,1] neg_hi:[0,1]
	v_cndmask_b32_e64 v149, 0, v49, s[6:7]
	v_pk_fma_f32 v[68:69], v[144:145], v[18:19], v[68:69]
	v_pk_add_f32 v[18:19], v[76:77], v[78:79] neg_lo:[0,1] neg_hi:[0,1]
	v_cndmask_b32_e64 v150, 0, v48, s[6:7]
	v_lshlrev_b32_e32 v74, 16, v146
	v_lshlrev_b32_e32 v75, 16, v139
	v_lshlrev_b32_e32 v72, 16, v148
	v_lshlrev_b32_e32 v73, 16, v147
	v_pk_fma_f32 v[18:19], v[20:21], v[18:19], v[78:79]
	v_pk_add_f32 v[20:21], v[140:141], v[78:79] neg_lo:[0,1] neg_hi:[0,1]
	v_and_b32_e32 v77, 0xffff0000, v147
	v_and_b32_e32 v76, 0xffff0000, v148
	v_and_b32_e32 v141, 0xffff0000, v139
	v_and_b32_e32 v140, 0xffff0000, v146
	v_lshlrev_b32_e32 v80, 16, v150
	v_lshlrev_b32_e32 v81, 16, v149
	v_pk_fma_f32 v[70:71], v[16:17], v[20:21], v[18:19]
	v_and_b32_e32 v17, 0xffff0000, v149
	v_and_b32_e32 v16, 0xffff0000, v150
	v_pk_add_f32 v[74:75], v[74:75], v[72:73] neg_lo:[0,1] neg_hi:[0,1]
	v_pk_add_f32 v[140:141], v[140:141], v[76:77] neg_lo:[0,1] neg_hi:[0,1]
	s_waitcnt vmcnt(0) lgkmcnt(0)
	v_mov_b32_e32 v142, v22
	v_mov_b32_e32 v143, v24
	v_mov_b32_e32 v24, v23
	v_lshlrev_b32_e32 v86, 16, v152
	v_lshlrev_b32_e32 v87, 16, v151
	v_pk_add_f32 v[78:79], v[72:73], v[80:81] neg_lo:[0,1] neg_hi:[0,1]
	v_pk_add_f32 v[82:83], v[76:77], v[16:17] neg_lo:[0,1] neg_hi:[0,1]
	v_pk_fma_f32 v[74:75], v[142:143], v[74:75], v[72:73]
	v_pk_fma_f32 v[22:23], v[24:25], v[140:141], v[76:77]
	v_pk_add_f32 v[72:73], v[80:81], v[72:73] neg_lo:[0,1] neg_hi:[0,1]
	v_pk_add_f32 v[76:77], v[16:17], v[76:77] neg_lo:[0,1] neg_hi:[0,1]
	v_mov_b32_e32 v140, v26
	v_mov_b32_e32 v141, v28
	v_mov_b32_e32 v28, v27
	v_and_b32_e32 v19, 0xffff0000, v151
	v_and_b32_e32 v18, 0xffff0000, v152
	v_pk_fma_f32 v[72:73], v[140:141], v[72:73], v[74:75]
	v_pk_fma_f32 v[74:75], v[28:29], v[76:77], v[22:23]
	v_pk_fma_f32 v[22:23], v[142:143], v[78:79], v[80:81]
	v_pk_add_f32 v[26:27], v[86:87], v[80:81] neg_lo:[0,1] neg_hi:[0,1]
	v_cndmask_b32_e64 v153, 0, v53, s[10:11]
	v_cndmask_b32_e64 v154, 0, v52, s[10:11]
	v_pk_fma_f32 v[76:77], v[140:141], v[26:27], v[22:23]
	v_pk_fma_f32 v[22:23], v[24:25], v[82:83], v[16:17]
	v_pk_add_f32 v[26:27], v[18:19], v[16:17] neg_lo:[0,1] neg_hi:[0,1]
	v_lshlrev_b32_e32 v84, 16, v154
	v_lshlrev_b32_e32 v85, 16, v153
	v_pk_fma_f32 v[78:79], v[28:29], v[26:27], v[22:23]
	v_pk_add_f32 v[22:23], v[80:81], v[86:87] neg_lo:[0,1] neg_hi:[0,1]
	v_and_b32_e32 v21, 0xffff0000, v153
	v_and_b32_e32 v20, 0xffff0000, v154
	v_pk_fma_f32 v[22:23], v[142:143], v[22:23], v[86:87]
	v_pk_add_f32 v[26:27], v[84:85], v[86:87] neg_lo:[0,1] neg_hi:[0,1]
	v_pk_add_f32 v[16:17], v[16:17], v[18:19] neg_lo:[0,1] neg_hi:[0,1]
	v_pk_fma_f32 v[80:81], v[140:141], v[26:27], v[22:23]
	v_pk_fma_f32 v[16:17], v[24:25], v[16:17], v[18:19]
	v_pk_add_f32 v[22:23], v[20:21], v[18:19] neg_lo:[0,1] neg_hi:[0,1]
	v_and_b32_e32 v27, 0xffff0000, v155
	v_pk_fma_f32 v[82:83], v[28:29], v[22:23], v[16:17]
	v_pk_add_f32 v[16:17], v[86:87], v[84:85] neg_lo:[0,1] neg_hi:[0,1]
	v_lshlrev_b32_e32 v23, 16, v155
	v_pk_fma_f32 v[86:87], v[142:143], v[16:17], v[84:85]
	v_mov_b32_e32 v16, v8
	v_mov_b32_e32 v17, v10
	v_mov_b32_e32 v10, v9
	v_pk_mul_f32 v[142:143], v[16:17], v[54:55]
	v_pk_mul_f32 v[144:145], v[56:57], v[10:11]
	v_mov_b32_e32 v8, v143
	v_mov_b32_e32 v9, v145
	v_pk_mul_f32 v[146:147], v[8:9], v[8:9]
	v_mov_b32_e32 v8, v12
	v_mov_b32_e32 v9, v14
	v_mov_b32_e32 v14, v13
	v_mul_f32_e32 v139, v142, v142
	v_pk_mul_f32 v[148:149], v[72:73], v[8:9]
	v_pk_mul_f32 v[12:13], v[74:75], v[14:15]
	v_fmac_f32_e32 v139, v144, v144
	v_mov_b32_e32 v150, v148
	v_mov_b32_e32 v151, v12
	v_add_f32_e32 v139, v139, v146
	v_pk_mul_f32 v[150:151], v[150:151], v[150:151]
	v_add_f32_e32 v139, v139, v147
	v_mov_b32_e32 v152, v149
	v_mov_b32_e32 v153, v13
	v_add_f32_e32 v139, v139, v150
	v_pk_mul_f32 v[152:153], v[152:153], v[152:153]
	v_add_f32_e32 v139, v139, v151
	v_add_f32_e32 v139, v139, v152
	v_add_f32_e32 v139, v139, v153
	v_lshlrev_b32_e32 v22, 16, v156
	v_pk_add_f32 v[22:23], v[22:23], v[84:85] neg_lo:[0,1] neg_hi:[0,1]
	v_add_f32_dpp v139, v139, v139 quad_perm:[1,0,3,2] row_mask:0xf bank_mask:0xf bound_ctrl:1
	v_pk_fma_f32 v[84:85], v[140:141], v[22:23], v[86:87]
	v_and_b32_e32 v26, 0xffff0000, v156
	v_add_f32_dpp v139, v139, v139 quad_perm:[2,3,0,1] row_mask:0xf bank_mask:0xf bound_ctrl:1
	v_pk_add_f32 v[18:19], v[18:19], v[20:21] neg_lo:[0,1] neg_hi:[0,1]
	v_pk_mul_f32 v[140:141], v[78:79], v[14:15]
	v_add_f32_dpp v139, v139, v139 row_half_mirror row_mask:0xf bank_mask:0xf bound_ctrl:1
	v_mul_f32_e32 v146, 0x4f800000, v139
	v_cmp_gt_f32_e32 vcc, s69, v139
	v_pk_fma_f32 v[18:19], v[24:25], v[18:19], v[20:21]
	v_pk_add_f32 v[20:21], v[26:27], v[20:21] neg_lo:[0,1] neg_hi:[0,1]
	v_cndmask_b32_e32 v139, v139, v146, vcc
	v_sqrt_f32_e32 v146, v139
	v_lshl_add_u64 v[52:53], v[88:89], 0, s[44:45]
	v_lshl_add_u64 v[46:47], v[52:53], 0, v[38:39]
	v_lshl_add_u64 v[48:49], v[52:53], 0, v[40:41]
	v_add_u32_e32 v22, -1, v146
	v_fma_f32 v23, -v22, v146, v139
	v_cmp_ge_f32_e64 s[0:1], 0, v23
	v_add_u32_e32 v23, 1, v146
	v_fma_f32 v86, -v23, v146, v139
	v_cndmask_b32_e64 v22, v146, v22, s[0:1]
	v_cmp_lt_f32_e64 s[0:1], 0, v86
	v_pk_fma_f32 v[86:87], v[28:29], v[20:21], v[18:19]
	v_pk_mul_f32 v[28:29], v[76:77], v[8:9]
	v_cndmask_b32_e64 v22, v22, v23, s[0:1]
	v_mul_f32_e32 v23, 0x37800000, v22
	v_cndmask_b32_e32 v22, v22, v23, vcc
	v_cmp_class_f32_e32 vcc, v139, v128
	v_lshl_add_u64 v[50:51], v[52:53], 0, v[42:43]
	v_lshl_add_u64 v[52:53], v[52:53], 0, v[44:45]
	v_cndmask_b32_e32 v22, v22, v139, vcc
	v_max_f32_e32 v22, 0x2b8cbccc, v22
	v_div_scale_f32 v23, s[0:1], v22, v22, 1.0
	v_rcp_f32_e32 v139, v23
	v_mul_f32_e32 v156, v36, v5
	v_mul_f32_e32 v157, v31, v6
	v_mul_f32_e32 v158, v37, v7
	v_fma_f32 v18, -v23, v139, 1.0
	v_fmac_f32_e32 v139, v18, v139
	v_div_scale_f32 v18, vcc, 1.0, v22, 1.0
	v_mul_f32_e32 v19, v18, v139
	v_fma_f32 v20, -v23, v19, v18
	v_fmac_f32_e32 v19, v20, v139
	v_fma_f32 v18, -v23, v19, v18
	v_div_fmas_f32 v18, v18, v139, v19
	v_div_fixup_f32 v18, v18, v22, 1.0
	v_pk_mul_f32 v[20:21], v[142:143], v[18:19] op_sel_hi:[1,0]
	v_pk_mul_f32 v[22:23], v[148:149], v[18:19] op_sel_hi:[1,0]
	v_bfe_u32 v19, v20, 16, 1
	v_bfe_u32 v24, v21, 16, 1
	v_bfe_u32 v25, v22, 16, 1
	v_bfe_u32 v26, v23, 16, 1
	v_add3_u32 v23, v23, v26, s58
	v_add3_u32 v22, v22, v25, s58
	v_add3_u32 v21, v21, v24, s58
	v_add3_u32 v19, v20, v19, s58
	v_pk_mul_f32 v[24:25], v[58:59], v[16:17]
	v_pk_mul_f32 v[26:27], v[60:61], v[10:11]
	v_lshrrev_b32_e32 v139, 16, v19
	v_lshrrev_b32_e32 v19, 16, v21
	v_mov_b32_e32 v20, v27
	v_mov_b32_e32 v21, v25
	v_mul_f32_e32 v148, v24, v24
	v_pk_mul_f32 v[20:21], v[20:21], v[20:21]
	v_fmac_f32_e32 v148, v26, v26
	v_mov_b32_e32 v142, v140
	v_mov_b32_e32 v143, v28
	v_add_f32_e32 v21, v21, v148
	v_pk_mul_f32 v[142:143], v[142:143], v[142:143]
	v_add_f32_e32 v20, v20, v21
	v_lshrrev_b32_e32 v146, 16, v22
	v_lshrrev_b32_e32 v147, 16, v23
	v_pk_mul_f32 v[22:23], v[144:145], v[18:19] op_sel_hi:[1,0]
	v_mov_b32_e32 v144, v141
	v_mov_b32_e32 v145, v29
	v_add_f32_e32 v20, v143, v20
	v_pk_mul_f32 v[144:145], v[144:145], v[144:145]
	v_add_f32_e32 v20, v142, v20
	v_add_f32_e32 v20, v145, v20
	v_add_f32_e32 v20, v144, v20
	v_pk_mul_f32 v[12:13], v[12:13], v[18:19] op_sel_hi:[1,0]
	v_and_or_b32 v19, v23, s54, v19
	v_add_f32_dpp v20, v20, v20 quad_perm:[1,0,3,2] row_mask:0xf bank_mask:0xf bound_ctrl:1
	v_lshlrev_b64 v[36:37], 11, v[94:95]
	v_lshl_add_u64 v[36:37], s[52:53], 0, v[36:37]
	v_add_f32_dpp v20, v20, v20 quad_perm:[2,3,0,1] row_mask:0xf bank_mask:0xf bound_ctrl:1
	v_lshl_add_u64 v[180:181], v[36:37], 0, v[34:35]
	v_or_b32_e32 v36, 3, v137
	v_add_f32_dpp v20, v20, v20 row_half_mirror row_mask:0xf bank_mask:0xf bound_ctrl:1
	v_mul_f32_e32 v21, 0x4f800000, v20
	v_cmp_gt_f32_e32 vcc, s69, v20
	v_mul_lo_u32 v36, v36, s68
	v_add_u32_e32 v119, v64, v36
	v_cndmask_b32_e32 v142, v20, v21, vcc
	v_sqrt_f32_e32 v143, v142
	v_and_or_b32 v20, v12, s54, v146
	v_and_or_b32 v21, v13, s54, v147
	v_lshlrev_b64 v[36:37], 11, v[96:97]
	v_add_u32_e32 v12, -1, v143
	v_fma_f32 v13, -v12, v143, v142
	v_cmp_ge_f32_e64 s[0:1], 0, v13
	v_add_u32_e32 v13, 1, v143
	v_fma_f32 v18, -v13, v143, v142
	v_cndmask_b32_e64 v12, v143, v12, s[0:1]
	v_cmp_lt_f32_e64 s[0:1], 0, v18
	v_and_or_b32 v18, v22, s54, v139
	global_store_dwordx4 v[46:47], v[18:21], off
	v_cndmask_b32_e64 v12, v12, v13, s[0:1]
	v_mul_f32_e32 v13, 0x37800000, v12
	v_cndmask_b32_e32 v12, v12, v13, vcc
	v_cmp_class_f32_e32 vcc, v142, v128
	v_lshl_add_u64 v[36:37], s[52:53], 0, v[36:37]
	v_lshl_add_u64 v[182:183], v[36:37], 0, v[34:35]
	v_cndmask_b32_e32 v12, v12, v142, vcc
	v_max_f32_e32 v12, 0x2b8cbccc, v12
	v_div_scale_f32 v13, s[0:1], v12, v12, 1.0
	v_rcp_f32_e32 v142, v13
	v_mul_f32_e32 v121, v156, v56
	v_mul_f32_e32 v122, v157, v55
	v_mul_f32_e32 v123, v158, v57
	v_fma_f32 v18, -v13, v142, 1.0
	v_fmac_f32_e32 v142, v18, v142
	v_div_scale_f32 v18, vcc, 1.0, v12, 1.0
	v_mul_f32_e32 v19, v18, v142
	v_fma_f32 v20, -v13, v19, v18
	v_fmac_f32_e32 v19, v20, v142
	v_fma_f32 v13, -v13, v19, v18
	v_div_fmas_f32 v13, v13, v142, v19
	v_div_fixup_f32 v12, v13, v12, 1.0
	v_pk_mul_f32 v[18:19], v[24:25], v[12:13] op_sel_hi:[1,0]
	v_pk_mul_f32 v[20:21], v[28:29], v[12:13] op_sel_hi:[1,0]
	v_bfe_u32 v13, v18, 16, 1
	v_bfe_u32 v22, v19, 16, 1
	v_bfe_u32 v23, v20, 16, 1
	v_bfe_u32 v24, v21, 16, 1
	v_add3_u32 v21, v21, v24, s58
	v_add3_u32 v20, v20, v23, s58
	v_add3_u32 v19, v19, v22, s58
	v_add3_u32 v13, v18, v13, s58
	v_pk_mul_f32 v[22:23], v[16:17], v[62:63]
	v_pk_mul_f32 v[24:25], v[66:67], v[10:11]
	v_lshrrev_b32_e32 v139, 16, v13
	v_lshrrev_b32_e32 v146, 16, v19
	v_lshrrev_b32_e32 v147, 16, v20
	v_lshrrev_b32_e32 v148, 16, v21
	v_pk_mul_f32 v[18:19], v[26:27], v[12:13] op_sel_hi:[1,0]
	v_mov_b32_e32 v20, v25
	v_mov_b32_e32 v21, v23
	v_mul_f32_e32 v13, v22, v22
	v_pk_mul_f32 v[20:21], v[20:21], v[20:21]
	v_pk_mul_f32 v[26:27], v[80:81], v[8:9]
	v_pk_mul_f32 v[28:29], v[82:83], v[14:15]
	v_fmac_f32_e32 v13, v24, v24
	v_mov_b32_e32 v142, v28
	v_mov_b32_e32 v143, v26
	v_add_f32_e32 v13, v21, v13
	v_pk_mul_f32 v[142:143], v[142:143], v[142:143]
	v_add_f32_e32 v13, v20, v13
	v_mov_b32_e32 v144, v29
	v_mov_b32_e32 v145, v27
	v_add_f32_e32 v13, v143, v13
	v_pk_mul_f32 v[144:145], v[144:145], v[144:145]
	v_add_f32_e32 v13, v142, v13
	v_add_f32_e32 v13, v145, v13
	v_add_f32_e32 v13, v144, v13
	v_and_or_b32 v19, v19, s54, v146
	v_and_or_b32 v18, v18, s54, v139
	v_add_f32_dpp v13, v13, v13 quad_perm:[1,0,3,2] row_mask:0xf bank_mask:0xf bound_ctrl:1
	v_pk_mul_f32 v[16:17], v[16:17], v[68:69]
	v_pk_mul_f32 v[14:15], v[86:87], v[14:15]
	v_add_f32_dpp v13, v13, v13 quad_perm:[2,3,0,1] row_mask:0xf bank_mask:0xf bound_ctrl:1
	v_mul_f32_e32 v124, v163, v58
	v_mul_f32_e32 v125, v168, v60
	v_add_f32_dpp v13, v13, v13 row_half_mirror row_mask:0xf bank_mask:0xf bound_ctrl:1
	v_mul_f32_e32 v20, 0x4f800000, v13
	v_cmp_gt_f32_e32 vcc, s69, v13
	v_mul_f32_e32 v137, v169, v59
	v_mul_f32_e32 v156, v176, v82
	v_cndmask_b32_e32 v142, v13, v20, vcc
	v_sqrt_f32_e32 v143, v142
	v_pk_mul_f32 v[12:13], v[140:141], v[12:13] op_sel_hi:[1,0]
	v_mul_f32_e32 v157, v177, v81
	v_and_or_b32 v20, v12, s54, v147
	v_add_u32_e32 v12, -1, v143
	v_and_or_b32 v21, v13, s54, v148
	v_fma_f32 v13, -v12, v143, v142
	v_cmp_ge_f32_e64 s[0:1], 0, v13
	v_add_u32_e32 v13, 1, v143
	v_fma_f32 v140, -v13, v143, v142
	v_cndmask_b32_e64 v12, v143, v12, s[0:1]
	v_cmp_lt_f32_e64 s[0:1], 0, v140
	global_store_dwordx4 v[48:49], v[18:21], off
	v_mul_f32_e32 v158, v178, v83
	v_cndmask_b32_e64 v12, v12, v13, s[0:1]
	v_mul_f32_e32 v13, 0x37800000, v12
	v_cndmask_b32_e32 v12, v12, v13, vcc
	v_cmp_class_f32_e32 vcc, v142, v128
	s_nop 1
	v_cndmask_b32_e32 v12, v12, v142, vcc
	v_max_f32_e32 v12, 0x2b8cbccc, v12
	v_div_scale_f32 v13, s[0:1], v12, v12, 1.0
	v_rcp_f32_e32 v140, v13
	s_nop 0
	v_fma_f32 v18, -v13, v140, 1.0
	v_fmac_f32_e32 v140, v18, v140
	v_div_scale_f32 v18, vcc, 1.0, v12, 1.0
	v_mul_f32_e32 v19, v18, v140
	v_fma_f32 v20, -v13, v19, v18
	v_fmac_f32_e32 v19, v20, v140
	v_fma_f32 v13, -v13, v19, v18
	v_div_fmas_f32 v13, v13, v140, v19
	v_div_fixup_f32 v12, v13, v12, 1.0
	v_pk_mul_f32 v[20:21], v[26:27], v[12:13] op_sel_hi:[1,0]
	v_pk_mul_f32 v[18:19], v[22:23], v[12:13] op_sel_hi:[1,0]
	v_bfe_u32 v23, v20, 16, 1
	v_bfe_u32 v26, v21, 16, 1
	v_add3_u32 v21, v21, v26, s58
	v_add3_u32 v20, v20, v23, s58
	v_lshrrev_b32_e32 v27, 16, v20
	v_lshrrev_b32_e32 v139, 16, v21
	v_pk_mul_f32 v[20:21], v[10:11], v[70:71]
	v_bfe_u32 v22, v19, 16, 1
	v_mov_b32_e32 v10, v21
	v_mov_b32_e32 v11, v17
	v_mul_f32_e32 v140, v16, v16
	v_bfe_u32 v13, v18, 16, 1
	v_add3_u32 v19, v19, v22, s58
	v_pk_mul_f32 v[10:11], v[10:11], v[10:11]
	v_pk_mul_f32 v[22:23], v[84:85], v[8:9]
	v_fmac_f32_e32 v140, v20, v20
	v_add3_u32 v13, v18, v13, s58
	v_mov_b32_e32 v8, v14
	v_mov_b32_e32 v9, v22
	v_add_f32_e32 v11, v11, v140
	v_lshrrev_b32_e32 v13, 16, v13
	v_pk_mul_f32 v[8:9], v[8:9], v[8:9]
	v_add_f32_e32 v10, v10, v11
	v_lshrrev_b32_e32 v26, 16, v19
	v_pk_mul_f32 v[18:19], v[24:25], v[12:13] op_sel_hi:[1,0]
	v_mov_b32_e32 v24, v15
	v_mov_b32_e32 v25, v23
	v_add_f32_e32 v9, v9, v10
	v_pk_mul_f32 v[24:25], v[24:25], v[24:25]
	v_add_f32_e32 v8, v8, v9
	v_add_f32_e32 v8, v25, v8
	v_add_f32_e32 v8, v24, v8
	s_nop 1
	v_add_f32_dpp v8, v8, v8 quad_perm:[1,0,3,2] row_mask:0xf bank_mask:0xf bound_ctrl:1
	s_nop 1
	v_add_f32_dpp v8, v8, v8 quad_perm:[2,3,0,1] row_mask:0xf bank_mask:0xf bound_ctrl:1
	s_nop 1
	v_add_f32_dpp v8, v8, v8 row_half_mirror row_mask:0xf bank_mask:0xf bound_ctrl:1
	v_mul_f32_e32 v9, 0x4f800000, v8
	v_cmp_gt_f32_e32 vcc, s69, v8
	s_nop 1
	v_cndmask_b32_e32 v24, v8, v9, vcc
	v_sqrt_f32_e32 v25, v24
	v_pk_mul_f32 v[8:9], v[28:29], v[12:13] op_sel_hi:[1,0]
	s_nop 0
	v_and_or_b32 v10, v8, s54, v27
	v_add_u32_e32 v8, -1, v25
	v_and_or_b32 v11, v9, s54, v139
	v_fma_f32 v9, -v8, v25, v24
	v_cmp_ge_f32_e64 s[0:1], 0, v9
	v_add_u32_e32 v9, 1, v25
	v_fma_f32 v12, -v9, v25, v24
	v_cndmask_b32_e64 v8, v25, v8, s[0:1]
	v_cmp_lt_f32_e64 s[0:1], 0, v12
	v_mul_f32_e32 v139, v4, v30
	v_mul_f32_e32 v120, v139, v54
	v_cndmask_b32_e64 v8, v8, v9, s[0:1]
	v_mul_f32_e32 v9, 0x37800000, v8
	v_cndmask_b32_e32 v8, v8, v9, vcc
	v_cmp_class_f32_e32 vcc, v24, v128
	v_and_or_b32 v9, v19, s54, v26
	v_mul_f32_e32 v139, v110, v62
	v_cndmask_b32_e32 v8, v8, v24, vcc
	v_max_f32_e32 v12, 0x2b8cbccc, v8
	v_div_scale_f32 v24, s[0:1], v12, v12, 1.0
	v_rcp_f32_e32 v25, v24
	v_and_or_b32 v8, v18, s54, v13
	global_store_dwordx4 v[50:51], v[8:11], off
	s_nop 1
	v_fma_f32 v8, -v24, v25, 1.0
	v_fmac_f32_e32 v25, v8, v25
	v_div_scale_f32 v8, vcc, 1.0, v12, 1.0
	v_mul_f32_e32 v9, v8, v25
	v_fma_f32 v10, -v24, v9, v8
	v_fmac_f32_e32 v9, v10, v25
	v_fma_f32 v8, -v24, v9, v8
	v_div_fmas_f32 v8, v8, v25, v9
	v_div_fixup_f32 v8, v8, v12, 1.0
	v_pk_mul_f32 v[10:11], v[16:17], v[8:9] op_sel_hi:[1,0]
	v_pk_mul_f32 v[12:13], v[22:23], v[8:9] op_sel_hi:[1,0]
	v_bfe_u32 v9, v10, 16, 1
	v_bfe_u32 v16, v11, 16, 1
	v_bfe_u32 v17, v12, 16, 1
	v_bfe_u32 v18, v13, 16, 1
	v_add3_u32 v13, v13, v18, s58
	v_add3_u32 v12, v12, v17, s58
	v_add3_u32 v11, v11, v16, s58
	v_add3_u32 v9, v10, v9, s58
	v_lshrrev_b32_e32 v16, 16, v9
	v_lshrrev_b32_e32 v17, 16, v11
	v_lshrrev_b32_e32 v10, 16, v12
	v_lshrrev_b32_e32 v11, 16, v13
	v_pk_mul_f32 v[12:13], v[20:21], v[8:9] op_sel_hi:[1,0]
	v_pk_mul_f32 v[8:9], v[14:15], v[8:9] op_sel_hi:[1,0]
	v_lshlrev_b64 v[24:25], 11, v[90:91]
	v_and_or_b32 v11, v9, s54, v11
	v_and_or_b32 v10, v8, s54, v10
	v_and_or_b32 v9, v13, s54, v17
	v_and_or_b32 v8, v12, s54, v16
	global_store_dwordx4 v[52:53], v[8:11], off
	s_waitcnt lgkmcnt(0)
	s_barrier
	v_mov_b32_e32 v8, v65
	v_lshl_add_u64 v[24:25], s[52:53], 0, v[24:25]
	v_mbcnt_lo_u32_b32 v8, -1, v8
	v_mbcnt_hi_u32_b32 v10, -1, v8
	v_and_b32_e32 v20, 31, v10
	v_or_b32_e32 v8, v20, v136
	v_ashrrev_i32_e32 v9, 31, v8
	v_ashrrev_i32_e32 v10, 2, v10
	v_lshlrev_b64 v[8:9], 8, v[8:9]
	v_and_b32_e32 v12, -8, v10
	v_lshl_add_u64 v[8:9], s[52:53], 0, v[8:9]
	v_ashrrev_i32_e32 v13, 31, v12
	v_lshl_add_u64 v[14:15], v[12:13], 1, v[8:9]
	v_add_co_u32_e32 v8, vcc, s70, v14
	v_lshl_add_u64 v[166:167], v[14:15], 0, s[46:47]
	s_nop 0
	v_addc_co_u32_e32 v9, vcc, 0, v15, vcc
	v_add_co_u32_e32 v164, vcc, s71, v14
	global_load_dwordx4 v[208:211], v[8:9], off
	s_nop 0
	v_addc_co_u32_e32 v165, vcc, 0, v15, vcc
	global_load_dwordx4 v[212:215], v[164:165], off
	global_load_dwordx4 v[216:219], v[166:167], off offset:32
	global_load_dwordx4 v[220:223], v[164:165], off offset:32
	global_load_dwordx4 v[224:227], v[166:167], off offset:64
	global_load_dwordx4 v[228:231], v[166:167], off offset:96
	global_load_dwordx4 v[232:235], v[164:165], off offset:64
	global_load_dwordx4 v[236:239], v[164:165], off offset:96
	global_load_dwordx4 v[240:243], v[166:167], off offset:128
	global_load_dwordx4 v[244:247], v[164:165], off offset:128
	global_load_dwordx4 v[248:251], v[166:167], off offset:160
	v_lshlrev_b32_e32 v0, 1, v12
	v_mad_u32_u24 v191, v20, s63, v0
	ds_read_b128 v[20:23], v191
	ds_read_b128 v[106:109], v191 offset:32
	v_lshrrev_b32_e32 v0, 3, v135
	v_and_b32_e32 v0, 4, v0
	v_mul_u32_u24_e32 v0, 0x410, v0
	v_lshl_add_u64 v[114:115], v[24:25], 0, v[34:35]
	v_lshlrev_b64 v[24:25], 11, v[92:93]
	v_lshl_add_u32 v192, v1, 2, v0
	v_mul_lo_u32 v0, v138, s68
	v_lshl_add_u64 v[24:25], s[52:53], 0, v[24:25]
	v_add_u32_e32 v118, v64, v0
	s_waitcnt lgkmcnt(0)
	s_waitcnt vmcnt(10)
	v_mfma_f32_32x32x16_bf16 v[0:15], v[20:23], v[208:211], 0
	global_load_dwordx4 v[208:211], v[164:165], off offset:160
	v_lshl_add_u64 v[116:117], v[24:25], 0, v[34:35]
	ds_read_b128 v[34:37], v191 offset:64
	v_mul_f32_e32 v138, v170, v61
	s_waitcnt vmcnt(10)
	v_mfma_f32_32x32x16_bf16 v[16:31], v[20:23], v[212:215], 0
	global_load_dwordx4 v[212:215], v[166:167], off offset:192
	s_waitcnt vmcnt(10)
	v_mfma_f32_32x32x16_bf16 v[0:15], v[106:109], v[216:219], v[0:15]
	global_load_dwordx4 v[216:219], v[164:165], off offset:192
	v_mul_f32_e32 v140, v112, v66
	v_mul_f32_e32 v141, v111, v63
	v_mul_f32_e32 v142, v113, v67
	v_mul_f32_e32 v143, v179, v68
	s_waitcnt vmcnt(10)
	v_mfma_f32_32x32x16_bf16 v[16:31], v[106:109], v[220:223], v[16:31]
	global_load_dwordx4 v[220:223], v[166:167], off offset:224
	ds_read_b128 v[106:109], v191 offset:96
	v_mul_f32_e32 v144, v184, v70
	v_mul_f32_e32 v145, v185, v69
	v_mul_f32_e32 v146, v186, v71
	v_mul_f32_e32 v147, v159, v72
	v_mul_f32_e32 v159, v187, v84
	s_waitcnt lgkmcnt(1)
	s_waitcnt vmcnt(10)
	v_mfma_f32_32x32x16_bf16 v[0:15], v[34:37], v[224:227], v[0:15]
	global_load_dwordx4 v[224:227], v[164:165], off offset:224
	v_mul_f32_e32 v148, v160, v74
	v_mul_f32_e32 v149, v161, v73
	v_mul_f32_e32 v150, v162, v75
	v_mul_f32_e32 v151, v171, v76
	v_mul_f32_e32 v160, v188, v86
	v_mul_f32_e32 v161, v189, v85
	v_mul_f32_e32 v162, v190, v87
	s_waitcnt vmcnt(9)
	v_mfma_f32_32x32x16_bf16 v[16:31], v[34:37], v[232:235], v[16:31]
	v_mul_f32_e32 v152, v172, v78
	v_mul_f32_e32 v153, v173, v77
	v_mul_f32_e32 v154, v174, v79
	v_mul_f32_e32 v155, v175, v80
	s_waitcnt lgkmcnt(0)
	v_mfma_f32_32x32x16_bf16 v[0:15], v[106:109], v[228:231], v[0:15]
	s_waitcnt vmcnt(8)
	v_mfma_f32_32x32x16_bf16 v[16:31], v[106:109], v[236:239], v[16:31]
	ds_read_b128 v[102:105], v191 offset:128
	ds_read_b128 v[110:113], v191 offset:160
	s_waitcnt lgkmcnt(0)
	s_waitcnt vmcnt(7)
	v_mfma_f32_32x32x16_bf16 v[0:15], v[102:105], v[240:243], v[0:15]
	s_waitcnt vmcnt(6)
	v_mfma_f32_32x32x16_bf16 v[16:31], v[102:105], v[244:247], v[16:31]
	s_waitcnt vmcnt(5)
	v_mfma_f32_32x32x16_bf16 v[0:15], v[110:113], v[248:251], v[0:15]
	ds_read_b128 v[106:109], v191 offset:192
	s_waitcnt lgkmcnt(0)
	s_waitcnt vmcnt(4)
	v_mfma_f32_32x32x16_bf16 v[16:31], v[110:113], v[208:211], v[16:31]
	ds_read_b128 v[110:113], v191 offset:224
	s_waitcnt vmcnt(3)
	v_mfma_f32_32x32x16_bf16 v[0:15], v[106:109], v[212:215], v[0:15]
	s_waitcnt vmcnt(2)
	v_mfma_f32_32x32x16_bf16 v[16:31], v[106:109], v[216:219], v[16:31]
	s_waitcnt lgkmcnt(0)
	s_waitcnt vmcnt(1)
	v_mfma_f32_32x32x16_bf16 v[0:15], v[110:113], v[220:223], v[0:15]
	s_waitcnt vmcnt(0)
	v_mfma_f32_32x32x16_bf16 v[16:31], v[110:113], v[224:227], v[16:31]
	v_add_u32_e32 v163, 0x6000, v192
	v_add_u32_e32 v164, 0x6400, v192
	v_add_u32_e32 v165, 0x6800, v192
	v_add_u32_e32 v166, 0x6c00, v192
	v_add_u32_e32 v167, 0x8000, v192
	v_add_u32_e32 v168, 0x8400, v192
	v_add_u32_e32 v169, 0x8800, v192
	v_add_u32_e32 v170, 0x8c00, v192
	v_add_u32_e32 v171, 0xa000, v192
	v_add_u32_e32 v172, 0xa400, v192
	v_add_u32_e32 v173, 0xa800, v192
	v_add_u32_e32 v174, 0xac00, v192
	v_add_u32_e32 v175, 0xc200, v192
	v_add_u32_e32 v176, 0xc600, v192
	v_add_u32_e32 v177, 0xca00, v192
	v_add_u32_e32 v178, 0xce00, v192
	ds_write2_b32 v163, v0, v16 offset0:128 offset1:160
	ds_write2_b32 v164, v1, v17 offset0:132 offset1:164
	ds_write2_b32 v165, v2, v18 offset0:136 offset1:168
	ds_write2_b32 v166, v3, v19 offset0:140 offset1:172
	ds_write2_b32 v167, v4, v20 offset0:160 offset1:192
	ds_write2_b32 v168, v5, v21 offset0:164 offset1:196
	ds_write2_b32 v169, v6, v22 offset0:168 offset1:200
	ds_write2_b32 v170, v7, v23 offset0:172 offset1:204
	ds_write2_b32 v171, v8, v24 offset0:192 offset1:224
	ds_write2_b32 v172, v9, v25 offset0:196 offset1:228
	ds_write2_b32 v173, v10, v26 offset0:200 offset1:232
	ds_write2_b32 v174, v11, v27 offset0:204 offset1:236
	ds_write2_b32 v175, v12, v28 offset0:96 offset1:128
	ds_write2_b32 v176, v13, v29 offset0:100 offset1:132
	ds_write2_b32 v177, v14, v30 offset0:104 offset1:136
	ds_write2_b32 v178, v15, v31 offset0:108 offset1:140
	s_waitcnt lgkmcnt(0)
	s_barrier
	ds_read_b128 v[0:3], v118 offset:25088
	ds_read_b128 v[4:7], v118 offset:25104
	s_add_u32 s77, s52, 0x1b0d7900
	s_addc_u32 s78, s53, 0
	s_add_u32 s79, s52, 0x1d4d7900
	s_waitcnt lgkmcnt(1)
	v_and_b32_sdwa v8, v2, v134 dst_sel:DWORD dst_unused:UNUSED_PAD src0_sel:WORD_1 src1_sel:DWORD
	v_and_b32_sdwa v9, v0, v134 dst_sel:DWORD dst_unused:UNUSED_PAD src0_sel:WORD_1 src1_sel:DWORD
	v_add3_u32 v2, v2, v8, s58
	v_and_b32_sdwa v8, v3, v134 dst_sel:DWORD dst_unused:UNUSED_PAD src0_sel:WORD_1 src1_sel:DWORD
	v_add3_u32 v0, v0, v9, s58
	v_and_b32_sdwa v9, v1, v134 dst_sel:DWORD dst_unused:UNUSED_PAD src0_sel:WORD_1 src1_sel:DWORD
	v_add3_u32 v3, v3, v8, s58
	v_add3_u32 v1, v1, v9, s58
	v_and_b32_e32 v3, 0xffff0000, v3
	v_and_b32_e32 v8, 0xffff0000, v1
	v_or_b32_sdwa v1, v3, v2 dst_sel:DWORD dst_unused:UNUSED_PAD src0_sel:DWORD src1_sel:WORD_1
	s_waitcnt lgkmcnt(0)
	v_and_b32_sdwa v2, v6, v134 dst_sel:DWORD dst_unused:UNUSED_PAD src0_sel:WORD_1 src1_sel:DWORD
	v_and_b32_sdwa v3, v4, v134 dst_sel:DWORD dst_unused:UNUSED_PAD src0_sel:WORD_1 src1_sel:DWORD
	v_add3_u32 v4, v4, v3, s58
	v_add3_u32 v2, v6, v2, s58
	v_and_b32_sdwa v3, v7, v134 dst_sel:DWORD dst_unused:UNUSED_PAD src0_sel:WORD_1 src1_sel:DWORD
	v_and_b32_sdwa v6, v5, v134 dst_sel:DWORD dst_unused:UNUSED_PAD src0_sel:WORD_1 src1_sel:DWORD
	v_add3_u32 v3, v7, v3, s58
	v_add3_u32 v5, v5, v6, s58
	v_and_b32_e32 v3, 0xffff0000, v3
	v_and_b32_e32 v5, 0xffff0000, v5
	v_or_b32_sdwa v3, v3, v2 dst_sel:DWORD dst_unused:UNUSED_PAD src0_sel:DWORD src1_sel:WORD_1
	v_or_b32_sdwa v2, v5, v4 dst_sel:DWORD dst_unused:UNUSED_PAD src0_sel:DWORD src1_sel:WORD_1
	v_add_co_u32_e32 v4, vcc, s72, v114
	v_or_b32_sdwa v0, v8, v0 dst_sel:DWORD dst_unused:UNUSED_PAD src0_sel:DWORD src1_sel:WORD_1
	s_nop 0
	v_addc_co_u32_e32 v5, vcc, 0, v115, vcc
	global_store_dwordx4 v[4:5], v[0:3], off offset:2816
	ds_read_b128 v[0:3], v118 offset:26128
	ds_read_b128 v[4:7], v118 offset:26144
	s_addc_u32 s80, s53, 0
	s_add_u32 s81, s52, 0x1738000
	s_addc_u32 s82, s53, 0
	s_waitcnt lgkmcnt(0)
	v_and_b32_sdwa v8, v2, v134 dst_sel:DWORD dst_unused:UNUSED_PAD src0_sel:WORD_1 src1_sel:DWORD
	v_and_b32_sdwa v9, v0, v134 dst_sel:DWORD dst_unused:UNUSED_PAD src0_sel:WORD_1 src1_sel:DWORD
	v_add3_u32 v2, v2, v8, s58
	v_and_b32_sdwa v8, v3, v134 dst_sel:DWORD dst_unused:UNUSED_PAD src0_sel:WORD_1 src1_sel:DWORD
	v_add3_u32 v0, v0, v9, s58
	v_and_b32_sdwa v9, v1, v134 dst_sel:DWORD dst_unused:UNUSED_PAD src0_sel:WORD_1 src1_sel:DWORD
	v_add3_u32 v3, v3, v8, s58
	v_add3_u32 v1, v1, v9, s58
	v_and_b32_e32 v3, 0xffff0000, v3
	v_and_b32_e32 v8, 0xffff0000, v1
	v_or_b32_sdwa v1, v3, v2 dst_sel:DWORD dst_unused:UNUSED_PAD src0_sel:DWORD src1_sel:WORD_1
	v_and_b32_sdwa v2, v6, v134 dst_sel:DWORD dst_unused:UNUSED_PAD src0_sel:WORD_1 src1_sel:DWORD
	v_and_b32_sdwa v3, v4, v134 dst_sel:DWORD dst_unused:UNUSED_PAD src0_sel:WORD_1 src1_sel:DWORD
	v_add3_u32 v4, v4, v3, s58
	v_add3_u32 v2, v6, v2, s58
	v_and_b32_sdwa v3, v7, v134 dst_sel:DWORD dst_unused:UNUSED_PAD src0_sel:WORD_1 src1_sel:DWORD
	v_and_b32_sdwa v6, v5, v134 dst_sel:DWORD dst_unused:UNUSED_PAD src0_sel:WORD_1 src1_sel:DWORD
	v_add3_u32 v3, v7, v3, s58
	v_add3_u32 v5, v5, v6, s58
	v_and_b32_e32 v3, 0xffff0000, v3
	v_and_b32_e32 v5, 0xffff0000, v5
	v_or_b32_sdwa v3, v3, v2 dst_sel:DWORD dst_unused:UNUSED_PAD src0_sel:DWORD src1_sel:WORD_1
	v_or_b32_sdwa v2, v5, v4 dst_sel:DWORD dst_unused:UNUSED_PAD src0_sel:DWORD src1_sel:WORD_1
	v_add_co_u32_e32 v4, vcc, s72, v116
	v_or_b32_sdwa v0, v8, v0 dst_sel:DWORD dst_unused:UNUSED_PAD src0_sel:DWORD src1_sel:WORD_1
	s_nop 0
	v_addc_co_u32_e32 v5, vcc, 0, v117, vcc
	global_store_dwordx4 v[4:5], v[0:3], off offset:2816
	ds_read_b128 v[0:3], v118 offset:27168
	ds_read_b128 v[4:7], v118 offset:27184
	v_lshl_add_u64 v[88:89], v[88:89], 0, s[48:49]
	s_mov_b64 s[8:9], -1
	s_waitcnt lgkmcnt(0)
	v_and_b32_sdwa v8, v2, v134 dst_sel:DWORD dst_unused:UNUSED_PAD src0_sel:WORD_1 src1_sel:DWORD
	v_and_b32_sdwa v9, v0, v134 dst_sel:DWORD dst_unused:UNUSED_PAD src0_sel:WORD_1 src1_sel:DWORD
	v_add3_u32 v2, v2, v8, s58
	v_and_b32_sdwa v8, v3, v134 dst_sel:DWORD dst_unused:UNUSED_PAD src0_sel:WORD_1 src1_sel:DWORD
	v_add3_u32 v0, v0, v9, s58
	v_and_b32_sdwa v9, v1, v134 dst_sel:DWORD dst_unused:UNUSED_PAD src0_sel:WORD_1 src1_sel:DWORD
	v_add3_u32 v3, v3, v8, s58
	v_add3_u32 v1, v1, v9, s58
	v_and_b32_e32 v3, 0xffff0000, v3
	v_and_b32_e32 v8, 0xffff0000, v1
	v_or_b32_sdwa v1, v3, v2 dst_sel:DWORD dst_unused:UNUSED_PAD src0_sel:DWORD src1_sel:WORD_1
	v_and_b32_sdwa v2, v6, v134 dst_sel:DWORD dst_unused:UNUSED_PAD src0_sel:WORD_1 src1_sel:DWORD
	v_and_b32_sdwa v3, v4, v134 dst_sel:DWORD dst_unused:UNUSED_PAD src0_sel:WORD_1 src1_sel:DWORD
	v_add3_u32 v4, v4, v3, s58
	v_add3_u32 v2, v6, v2, s58
	v_and_b32_sdwa v3, v7, v134 dst_sel:DWORD dst_unused:UNUSED_PAD src0_sel:WORD_1 src1_sel:DWORD
	v_and_b32_sdwa v6, v5, v134 dst_sel:DWORD dst_unused:UNUSED_PAD src0_sel:WORD_1 src1_sel:DWORD
	v_add3_u32 v3, v7, v3, s58
	v_add3_u32 v5, v5, v6, s58
	v_and_b32_e32 v3, 0xffff0000, v3
	v_and_b32_e32 v5, 0xffff0000, v5
	v_or_b32_sdwa v3, v3, v2 dst_sel:DWORD dst_unused:UNUSED_PAD src0_sel:DWORD src1_sel:WORD_1
	v_or_b32_sdwa v2, v5, v4 dst_sel:DWORD dst_unused:UNUSED_PAD src0_sel:DWORD src1_sel:WORD_1
	v_add_co_u32_e32 v4, vcc, s72, v180
	v_or_b32_sdwa v0, v8, v0 dst_sel:DWORD dst_unused:UNUSED_PAD src0_sel:DWORD src1_sel:WORD_1
	s_nop 0
	v_addc_co_u32_e32 v5, vcc, 0, v181, vcc
	global_store_dwordx4 v[4:5], v[0:3], off offset:2816
	ds_read_b128 v[0:3], v119 offset:25088
	ds_read_b128 v[4:7], v119 offset:25104
	s_waitcnt lgkmcnt(0)
	v_and_b32_sdwa v8, v2, v134 dst_sel:DWORD dst_unused:UNUSED_PAD src0_sel:WORD_1 src1_sel:DWORD
	v_and_b32_sdwa v9, v0, v134 dst_sel:DWORD dst_unused:UNUSED_PAD src0_sel:WORD_1 src1_sel:DWORD
	v_add3_u32 v2, v2, v8, s58
	v_and_b32_sdwa v8, v3, v134 dst_sel:DWORD dst_unused:UNUSED_PAD src0_sel:WORD_1 src1_sel:DWORD
	v_add3_u32 v0, v0, v9, s58
	v_and_b32_sdwa v9, v1, v134 dst_sel:DWORD dst_unused:UNUSED_PAD src0_sel:WORD_1 src1_sel:DWORD
	v_add3_u32 v3, v3, v8, s58
	v_add3_u32 v1, v1, v9, s58
	v_and_b32_e32 v3, 0xffff0000, v3
	v_and_b32_e32 v8, 0xffff0000, v1
	v_or_b32_sdwa v1, v3, v2 dst_sel:DWORD dst_unused:UNUSED_PAD src0_sel:DWORD src1_sel:WORD_1
	v_and_b32_sdwa v2, v6, v134 dst_sel:DWORD dst_unused:UNUSED_PAD src0_sel:WORD_1 src1_sel:DWORD
	v_and_b32_sdwa v3, v4, v134 dst_sel:DWORD dst_unused:UNUSED_PAD src0_sel:WORD_1 src1_sel:DWORD
	v_add3_u32 v4, v4, v3, s58
	v_add3_u32 v2, v6, v2, s58
	v_and_b32_sdwa v3, v7, v134 dst_sel:DWORD dst_unused:UNUSED_PAD src0_sel:WORD_1 src1_sel:DWORD
	v_and_b32_sdwa v6, v5, v134 dst_sel:DWORD dst_unused:UNUSED_PAD src0_sel:WORD_1 src1_sel:DWORD
	v_add3_u32 v3, v7, v3, s58
	v_add3_u32 v5, v5, v6, s58
	v_and_b32_e32 v3, 0xffff0000, v3
	v_and_b32_e32 v5, 0xffff0000, v5
	v_or_b32_sdwa v3, v3, v2 dst_sel:DWORD dst_unused:UNUSED_PAD src0_sel:DWORD src1_sel:WORD_1
	v_or_b32_sdwa v2, v5, v4 dst_sel:DWORD dst_unused:UNUSED_PAD src0_sel:DWORD src1_sel:WORD_1
	v_add_co_u32_e32 v4, vcc, s72, v182
	v_or_b32_sdwa v0, v8, v0 dst_sel:DWORD dst_unused:UNUSED_PAD src0_sel:DWORD src1_sel:WORD_1
	s_nop 0
	v_addc_co_u32_e32 v5, vcc, 0, v183, vcc
	global_store_dwordx4 v[4:5], v[0:3], off offset:2816
	s_waitcnt lgkmcnt(0)
	s_barrier
	global_load_dwordx2 v[0:1], v[32:33], off offset:456
	v_and_b32_e32 v8, 7, v135
	v_lshlrev_b64 v[2:3], 8, v[92:93]
	v_lshlrev_b64 v[4:5], 8, v[94:95]
	v_lshlrev_b64 v[6:7], 8, v[96:97]
	v_cmp_eq_u32_e64 s[4:5], 0, v8
	v_or_b32_e32 v2, v2, v126
	v_or_b32_e32 v4, v4, v126
	v_or_b32_e32 v6, v6, v126
	v_lshlrev_b64 v[92:93], 4, v[92:93]
	v_lshlrev_b64 v[94:95], 4, v[94:95]
	v_lshlrev_b64 v[96:97], 4, v[96:97]
	v_lshlrev_b64 v[104:105], 1, v[2:3]
	v_lshlrev_b64 v[106:107], 1, v[4:5]
	v_lshlrev_b64 v[108:109], 1, v[6:7]
	s_waitcnt vmcnt(0) lgkmcnt(0)
	v_readfirstlane_b32 s1, v1
	v_readfirstlane_b32 s0, v0
	s_nop 1
	v_lshl_add_u64 v[0:1], s[0:1], 0, v[64:65]
	global_load_dwordx4 v[30:33], v[0:1], off
	global_load_dwordx4 v[34:37], v[0:1], off offset:16
	s_add_u32 s0, s52, 0x2954198
	s_addc_u32 s1, s53, 0
	s_add_u32 s83, s52, 0x1748000
	v_lshlrev_b64 v[0:1], 8, v[90:91]
	s_addc_u32 s84, s53, 0
	v_bfe_u32 v64, v135, 1, 4
	v_or_b32_e32 v0, v0, v126
	s_add_u32 s6, s52, 0x29541a8
	v_lshl_add_u64 v[8:9], s[52:53], 0, v[64:65]
	v_lshlrev_b64 v[90:91], 4, v[90:91]
	s_addc_u32 s7, s53, 0
	v_lshl_add_u64 v[98:99], v[8:9], 0, s[50:51]
	v_lshlrev_b32_e32 v64, 2, v126
	s_waitcnt vmcnt(0) lgkmcnt(0)
	v_mov_b32_e32 v100, v30
	v_mov_b32_e32 v101, v32
	v_mov_b32_e32 v32, v31
	v_mov_b32_e32 v102, v34
	v_mov_b32_e32 v103, v36
	v_mov_b32_e32 v36, v35
	v_lshlrev_b64 v[34:35], 1, v[0:1]
	s_branch .LBB0_426

.LBB0_426:
	v_mov_b32_e32 v0, v65
	s_mul_i32 s18, s24, 0x9000
	v_mbcnt_lo_u32_b32 v0, -1, v0
	s_lshl_b64 s[26:27], s[18:19], 9
	v_mbcnt_hi_u32_b32 v2, -1, v0
	s_add_u32 s10, s79, s26
	v_and_b32_e32 v6, 31, v2
	s_addc_u32 s11, s80, s27
	s_lshl_b32 s52, s24, 7
	s_lshl_b32 s53, s24, 15
	v_or_b32_e32 v0, v6, v136
	s_add_u32 s12, s81, s53
	v_ashrrev_i32_e32 v1, 31, v0
	v_ashrrev_i32_e32 v2, 2, v2
	s_addc_u32 s13, s82, 0
	v_lshlrev_b64 v[0:1], 7, v[0:1]
	v_and_b32_e32 v4, -8, v2
	v_lshl_add_u64 v[0:1], s[12:13], 0, v[0:1]
	v_ashrrev_i32_e32 v5, 31, v4
	v_lshl_add_u64 v[188:189], v[4:5], 1, v[0:1]
	global_load_dwordx4 v[0:3], v[188:189], off
	global_load_dwordx4 v[110:113], v[188:189], off offset:32
	v_mul_u32_u24_e32 v5, 0x310, v6
	v_lshlrev_b32_e32 v4, 1, v4
	v_add3_u32 v126, s52, v5, v4
	ds_read_b128 v[16:19], v126 offset:256
	ds_read_b128 v[114:117], v126 offset:288
	v_add_co_u32_e32 v190, vcc, s35, v188
	ds_read_b128 v[184:187], v126 offset:320
	s_nop 0
	v_addc_co_u32_e32 v191, vcc, 0, v189, vcc
	global_load_dwordx4 v[20:23], v[190:191], off
	global_load_dwordx4 v[180:183], v[190:191], off offset:32
	s_waitcnt vmcnt(0) lgkmcnt(0)
	global_load_dwordx4 v[208:211], v[188:189], off offset:64
	global_load_dwordx4 v[212:215], v[188:189], off offset:96
	global_load_dwordx4 v[216:219], v[190:191], off offset:64
	global_load_dwordx4 v[220:223], v[190:191], off offset:96
	v_mfma_f32_32x32x16_bf16 v[0:15], v[16:19], v[0:3], 0
	v_mfma_f32_32x32x16_bf16 v[0:15], v[114:117], v[110:113], v[0:15]
	v_mfma_f32_32x32x16_bf16 v[16:31], v[16:19], v[20:23], 0
	s_waitcnt lgkmcnt(0)
	s_waitcnt vmcnt(3)
	v_mfma_f32_32x32x16_bf16 v[0:15], v[184:187], v[208:211], v[0:15]
	v_mfma_f32_32x32x16_bf16 v[16:31], v[114:117], v[180:183], v[16:31]
	s_waitcnt lgkmcnt(0)
	s_waitcnt vmcnt(1)
	v_mfma_f32_32x32x16_bf16 v[16:31], v[184:187], v[216:219], v[16:31]
	ds_read_b128 v[114:117], v126 offset:352
	s_waitcnt lgkmcnt(0)
	v_mfma_f32_32x32x16_bf16 v[0:15], v[114:117], v[212:215], v[0:15]
	s_waitcnt lgkmcnt(0)
	s_waitcnt vmcnt(0)
	v_mfma_f32_32x32x16_bf16 v[16:31], v[114:117], v[220:223], v[16:31]
	s_nop 11
	ds_write2_b32 v163, v0, v16 offset0:128 offset1:160
	ds_write2_b32 v164, v1, v17 offset0:132 offset1:164
	ds_write2_b32 v165, v2, v18 offset0:136 offset1:168
	ds_write2_b32 v166, v3, v19 offset0:140 offset1:172
	ds_write2_b32 v167, v4, v20 offset0:160 offset1:192
	ds_write2_b32 v168, v5, v21 offset0:164 offset1:196
	ds_write2_b32 v169, v6, v22 offset0:168 offset1:200
	ds_write2_b32 v170, v7, v23 offset0:172 offset1:204
	ds_write2_b32 v171, v8, v24 offset0:192 offset1:224
	ds_write2_b32 v172, v9, v25 offset0:196 offset1:228
	ds_write2_b32 v173, v10, v26 offset0:200 offset1:232
	ds_write2_b32 v174, v11, v27 offset0:204 offset1:236
	ds_write2_b32 v175, v12, v28 offset0:96 offset1:128
	ds_write2_b32 v176, v13, v29 offset0:100 offset1:132
	ds_write2_b32 v177, v14, v30 offset0:104 offset1:136
	ds_write2_b32 v178, v15, v31 offset0:108 offset1:140
	v_mov_b64_e32 v[0:1], s[0:1]
	s_waitcnt lgkmcnt(0)
	s_barrier
	global_load_dwordx2 v[0:1], v[0:1], off
	s_add_u32 s12, s77, s26
	s_addc_u32 s13, s78, s27
	s_lshl_b32 s24, s24, 8
	s_mov_b32 s25, s19
	s_lshl_b64 s[24:25], s[24:25], 2
	v_lshl_add_u64 v[16:17], v[88:89], 0, s[26:27]
	s_waitcnt vmcnt(0) lgkmcnt(0)
	v_readfirstlane_b32 s86, v0
	v_readfirstlane_b32 s85, v1
	s_add_u32 s86, s86, s24
	s_addc_u32 s87, s85, s25
	v_lshl_add_u64 v[0:1], s[86:87], 0, v[64:65]
	global_load_dwordx4 v[4:7], v[0:1], off
	s_nop 0
	global_load_dwordx4 v[0:3], v[0:1], off offset:16
	ds_read_b128 v[12:15], v118 offset:25088
	ds_read_b128 v[8:11], v118 offset:25104
	s_waitcnt vmcnt(0) lgkmcnt(0)
	v_add_f32_e32 v12, v4, v12
	v_mul_f32_e32 v12, 0xbfb8aa3b, v12
	v_exp_f32_e32 v12, v12
	v_add_f32_e32 v13, v5, v13
	v_mul_f32_e32 v13, 0xbfb8aa3b, v13
	v_exp_f32_e32 v13, v13
	v_add_f32_e32 v12, 1.0, v12
	v_div_scale_f32 v18, s[26:27], v12, v12, 1.0
	v_rcp_f32_e32 v19, v18
	v_add_f32_e32 v13, 1.0, v13
	v_add_f32_e32 v8, v0, v8
	v_mul_f32_e32 v8, 0xbfb8aa3b, v8
	v_fma_f32 v20, -v18, v19, 1.0
	v_fmac_f32_e32 v19, v20, v19
	v_div_scale_f32 v20, vcc, 1.0, v12, 1.0
	v_mul_f32_e32 v21, v20, v19
	v_fma_f32 v22, -v18, v21, v20
	v_fmac_f32_e32 v21, v22, v19
	v_fma_f32 v18, -v18, v21, v20
	v_div_fmas_f32 v18, v18, v19, v21
	v_div_fixup_f32 v12, v18, v12, 1.0
	v_div_scale_f32 v18, s[26:27], v13, v13, 1.0
	v_rcp_f32_e32 v19, v18
	v_exp_f32_e32 v8, v8
	v_add_f32_e32 v9, v1, v9
	v_mul_f32_e32 v9, 0xbfb8aa3b, v9
	v_fma_f32 v20, -v18, v19, 1.0
	v_fmac_f32_e32 v19, v20, v19
	v_div_scale_f32 v20, vcc, 1.0, v13, 1.0
	v_mul_f32_e32 v21, v20, v19
	v_fma_f32 v22, -v18, v21, v20
	v_fmac_f32_e32 v21, v22, v19
	v_fma_f32 v18, -v18, v21, v20
	v_div_fmas_f32 v18, v18, v19, v21
	v_div_fixup_f32 v13, v18, v13, 1.0
	v_mul_f32_e32 v13, 0xbf1b4598, v13
	v_mul_f32_e32 v13, 0x3fb8aa3b, v13
	v_exp_f32_e32 v18, v13
	v_add_f32_e32 v13, v6, v14
	v_mul_f32_e32 v13, 0xbfb8aa3b, v13
	v_exp_f32_e32 v13, v13
	v_add_f32_e32 v8, 1.0, v8
	v_exp_f32_e32 v9, v9
	v_mul_f32_e32 v12, 0xbf1b4598, v12
	v_add_f32_e32 v13, 1.0, v13
	v_div_scale_f32 v14, s[26:27], v13, v13, 1.0
	v_rcp_f32_e32 v19, v14
	v_add_f32_e32 v9, 1.0, v9
	v_mul_f32_e32 v12, 0x3fb8aa3b, v12
	v_exp_f32_e32 v12, v12
	v_fma_f32 v20, -v14, v19, 1.0
	v_fmac_f32_e32 v19, v20, v19
	v_div_scale_f32 v20, vcc, 1.0, v13, 1.0
	v_mul_f32_e32 v21, v20, v19
	v_fma_f32 v22, -v14, v21, v20
	v_fmac_f32_e32 v21, v22, v19
	v_fma_f32 v14, -v14, v21, v20
	v_div_fmas_f32 v14, v14, v19, v21
	v_div_fixup_f32 v13, v14, v13, 1.0
	v_add_f32_e32 v14, v7, v15
	v_mul_f32_e32 v14, 0xbfb8aa3b, v14
	v_exp_f32_e32 v14, v14
	v_mul_f32_e32 v13, 0xbf1b4598, v13
	v_mul_f32_e32 v13, 0x3fb8aa3b, v13
	v_exp_f32_e32 v13, v13
	v_add_f32_e32 v14, 1.0, v14
	v_div_scale_f32 v15, s[26:27], v14, v14, 1.0
	v_rcp_f32_e32 v19, v15
	v_sub_f32_e32 v18, 1.0, v18
	v_fma_f32 v20, -v15, v19, 1.0
	v_fmac_f32_e32 v19, v20, v19
	v_div_scale_f32 v20, vcc, 1.0, v14, 1.0
	v_mul_f32_e32 v21, v20, v19
	v_fma_f32 v22, -v15, v21, v20
	v_fmac_f32_e32 v21, v22, v19
	v_fma_f32 v15, -v15, v21, v20
	v_div_fmas_f32 v15, v15, v19, v21
	v_div_fixup_f32 v14, v15, v14, 1.0
	v_div_scale_f32 v15, s[26:27], v8, v8, 1.0
	v_rcp_f32_e32 v19, v15
	v_mul_f32_e32 v14, 0xbf1b4598, v14
	v_mul_f32_e32 v14, 0x3fb8aa3b, v14
	v_exp_f32_e32 v14, v14
	v_fma_f32 v20, -v15, v19, 1.0
	v_fmac_f32_e32 v19, v20, v19
	v_div_scale_f32 v20, vcc, 1.0, v8, 1.0
	v_mul_f32_e32 v21, v20, v19
	v_fma_f32 v22, -v15, v21, v20
	v_fmac_f32_e32 v21, v22, v19
	v_fma_f32 v15, -v15, v21, v20
	v_div_fmas_f32 v15, v15, v19, v21
	v_div_fixup_f32 v8, v15, v8, 1.0
	v_div_scale_f32 v15, s[26:27], v9, v9, 1.0
	v_rcp_f32_e32 v19, v15
	v_mul_f32_e32 v8, 0xbf1b4598, v8
	v_mul_f32_e32 v8, 0x3fb8aa3b, v8
	v_exp_f32_e32 v8, v8
	v_fma_f32 v20, -v15, v19, 1.0
	v_fmac_f32_e32 v19, v20, v19
	v_div_scale_f32 v20, vcc, 1.0, v9, 1.0
	v_mul_f32_e32 v21, v20, v19
	v_fma_f32 v22, -v15, v21, v20
	v_fmac_f32_e32 v21, v22, v19
	v_fma_f32 v15, -v15, v21, v20
	v_div_fmas_f32 v15, v15, v19, v21
	v_div_fixup_f32 v9, v15, v9, 1.0
	v_mul_f32_e32 v9, 0xbf1b4598, v9
	v_mul_f32_e32 v9, 0x3fb8aa3b, v9
	v_exp_f32_e32 v15, v9
	v_add_f32_e32 v9, v2, v10
	v_mul_f32_e32 v9, 0xbfb8aa3b, v9
	v_exp_f32_e32 v9, v9
	v_sub_f32_e32 v14, 1.0, v14
	v_add_f32_e32 v9, 1.0, v9
	v_div_scale_f32 v10, s[26:27], v9, v9, 1.0
	v_rcp_f32_e32 v19, v10
	s_nop 0
	v_fma_f32 v20, -v10, v19, 1.0
	v_fmac_f32_e32 v19, v20, v19
	v_div_scale_f32 v20, vcc, 1.0, v9, 1.0
	v_mul_f32_e32 v21, v20, v19
	v_fma_f32 v22, -v10, v21, v20
	v_fmac_f32_e32 v21, v22, v19
	v_fma_f32 v10, -v10, v21, v20
	v_div_fmas_f32 v10, v10, v19, v21
	v_div_fixup_f32 v9, v10, v9, 1.0
	v_add_f32_e32 v10, v3, v11
	v_mul_f32_e32 v10, 0xbfb8aa3b, v10
	v_exp_f32_e32 v10, v10
	v_mul_f32_e32 v9, 0xbf1b4598, v9
	v_mul_f32_e32 v9, 0x3fb8aa3b, v9
	v_exp_f32_e32 v9, v9
	v_add_f32_e32 v10, 1.0, v10
	v_div_scale_f32 v11, s[26:27], v10, v10, 1.0
	v_rcp_f32_e32 v19, v11
	v_pk_add_f32 v[8:9], v[8:9], 1.0 op_sel_hi:[1,0] neg_lo:[1,0] neg_hi:[1,0]
	v_fma_f32 v20, -v11, v19, 1.0
	v_fmac_f32_e32 v19, v20, v19
	v_div_scale_f32 v20, vcc, 1.0, v10, 1.0
	v_mul_f32_e32 v21, v20, v19
	v_fma_f32 v22, -v11, v21, v20
	v_fmac_f32_e32 v21, v22, v19
	v_fma_f32 v11, -v11, v21, v20
	v_div_fmas_f32 v11, v11, v19, v21
	v_div_fixup_f32 v10, v11, v10, 1.0
	v_mul_f32_e32 v10, 0xbf1b4598, v10
	v_mul_f32_e32 v10, 0x3fb8aa3b, v10
	v_exp_f32_e32 v19, v10
	v_pk_add_f32 v[10:11], v[12:13], 1.0 op_sel_hi:[1,0] neg_lo:[1,0] neg_hi:[1,0]
	v_bfe_u32 v20, v8, 16, 1
	v_bfe_u32 v12, v10, 16, 1
	v_bfe_u32 v13, v11, 16, 1
	v_bfe_u32 v21, v9, 16, 1
	v_add3_u32 v9, v9, v21, s58
	v_add3_u32 v8, v8, v20, s58
	v_add3_u32 v11, v11, v13, s58
	v_add3_u32 v10, v10, v12, s58
	v_lshrrev_b32_e32 v12, 16, v10
	v_lshrrev_b32_e32 v13, 16, v11
	v_lshrrev_b32_e32 v8, 16, v8
	v_lshrrev_b32_e32 v9, 16, v9
	v_sub_f32_e32 v10, 1.0, v15
	v_sub_f32_e32 v11, 1.0, v19
	v_and_or_b32 v11, v11, s54, v9
	v_and_or_b32 v10, v10, s54, v8
	v_and_or_b32 v9, v14, s54, v13
	v_and_or_b32 v8, v18, s54, v12
	v_lshl_add_u64 v[12:13], v[16:17], 0, v[38:39]
	global_store_dwordx4 v[12:13], v[8:11], off
	ds_read_b128 v[12:15], v118 offset:26128
	ds_read_b128 v[8:11], v118 offset:26144
	s_waitcnt lgkmcnt(0)
	v_add_f32_e32 v12, v4, v12
	v_mul_f32_e32 v12, 0xbfb8aa3b, v12
	v_exp_f32_e32 v12, v12
	v_add_f32_e32 v13, v5, v13
	v_mul_f32_e32 v13, 0xbfb8aa3b, v13
	v_exp_f32_e32 v13, v13
	v_add_f32_e32 v12, 1.0, v12
	v_div_scale_f32 v18, s[26:27], v12, v12, 1.0
	v_rcp_f32_e32 v19, v18
	v_add_f32_e32 v13, 1.0, v13
	v_add_f32_e32 v8, v0, v8
	v_mul_f32_e32 v8, 0xbfb8aa3b, v8
	v_fma_f32 v20, -v18, v19, 1.0
	v_fmac_f32_e32 v19, v20, v19
	v_div_scale_f32 v20, vcc, 1.0, v12, 1.0
	v_mul_f32_e32 v21, v20, v19
	v_fma_f32 v22, -v18, v21, v20
	v_fmac_f32_e32 v21, v22, v19
	v_fma_f32 v18, -v18, v21, v20
	v_div_fmas_f32 v18, v18, v19, v21
	v_div_fixup_f32 v12, v18, v12, 1.0
	v_div_scale_f32 v18, s[26:27], v13, v13, 1.0
	v_rcp_f32_e32 v19, v18
	v_exp_f32_e32 v8, v8
	v_add_f32_e32 v9, v1, v9
	v_mul_f32_e32 v9, 0xbfb8aa3b, v9
	v_fma_f32 v20, -v18, v19, 1.0
	v_fmac_f32_e32 v19, v20, v19
	v_div_scale_f32 v20, vcc, 1.0, v13, 1.0
	v_mul_f32_e32 v21, v20, v19
	v_fma_f32 v22, -v18, v21, v20
	v_fmac_f32_e32 v21, v22, v19
	v_fma_f32 v18, -v18, v21, v20
	v_div_fmas_f32 v18, v18, v19, v21
	v_div_fixup_f32 v13, v18, v13, 1.0
	v_mul_f32_e32 v13, 0xbf1b4598, v13
	v_mul_f32_e32 v13, 0x3fb8aa3b, v13
	v_exp_f32_e32 v18, v13
	v_add_f32_e32 v13, v6, v14
	v_mul_f32_e32 v13, 0xbfb8aa3b, v13
	v_exp_f32_e32 v13, v13
	v_add_f32_e32 v8, 1.0, v8
	v_exp_f32_e32 v9, v9
	v_mul_f32_e32 v12, 0xbf1b4598, v12
	v_add_f32_e32 v13, 1.0, v13
	v_div_scale_f32 v14, s[26:27], v13, v13, 1.0
	v_rcp_f32_e32 v19, v14
	v_add_f32_e32 v9, 1.0, v9
	v_mul_f32_e32 v12, 0x3fb8aa3b, v12
	v_exp_f32_e32 v12, v12
	v_fma_f32 v20, -v14, v19, 1.0
	v_fmac_f32_e32 v19, v20, v19
	v_div_scale_f32 v20, vcc, 1.0, v13, 1.0
	v_mul_f32_e32 v21, v20, v19
	v_fma_f32 v22, -v14, v21, v20
	v_fmac_f32_e32 v21, v22, v19
	v_fma_f32 v14, -v14, v21, v20
	v_div_fmas_f32 v14, v14, v19, v21
	v_div_fixup_f32 v13, v14, v13, 1.0
	v_add_f32_e32 v14, v7, v15
	v_mul_f32_e32 v14, 0xbfb8aa3b, v14
	v_exp_f32_e32 v14, v14
	v_mul_f32_e32 v13, 0xbf1b4598, v13
	v_mul_f32_e32 v13, 0x3fb8aa3b, v13
	v_exp_f32_e32 v13, v13
	v_add_f32_e32 v14, 1.0, v14
	v_div_scale_f32 v15, s[26:27], v14, v14, 1.0
	v_rcp_f32_e32 v19, v15
	v_sub_f32_e32 v18, 1.0, v18
	v_fma_f32 v20, -v15, v19, 1.0
	v_fmac_f32_e32 v19, v20, v19
	v_div_scale_f32 v20, vcc, 1.0, v14, 1.0
	v_mul_f32_e32 v21, v20, v19
	v_fma_f32 v22, -v15, v21, v20
	v_fmac_f32_e32 v21, v22, v19
	v_fma_f32 v15, -v15, v21, v20
	v_div_fmas_f32 v15, v15, v19, v21
	v_div_fixup_f32 v14, v15, v14, 1.0
	v_div_scale_f32 v15, s[26:27], v8, v8, 1.0
	v_rcp_f32_e32 v19, v15
	v_mul_f32_e32 v14, 0xbf1b4598, v14
	v_mul_f32_e32 v14, 0x3fb8aa3b, v14
	v_exp_f32_e32 v14, v14
	v_fma_f32 v20, -v15, v19, 1.0
	v_fmac_f32_e32 v19, v20, v19
	v_div_scale_f32 v20, vcc, 1.0, v8, 1.0
	v_mul_f32_e32 v21, v20, v19
	v_fma_f32 v22, -v15, v21, v20
	v_fmac_f32_e32 v21, v22, v19
	v_fma_f32 v15, -v15, v21, v20
	v_div_fmas_f32 v15, v15, v19, v21
	v_div_fixup_f32 v8, v15, v8, 1.0
	v_div_scale_f32 v15, s[26:27], v9, v9, 1.0
	v_rcp_f32_e32 v19, v15
	v_mul_f32_e32 v8, 0xbf1b4598, v8
	v_mul_f32_e32 v8, 0x3fb8aa3b, v8
	v_exp_f32_e32 v8, v8
	v_fma_f32 v20, -v15, v19, 1.0
	v_fmac_f32_e32 v19, v20, v19
	v_div_scale_f32 v20, vcc, 1.0, v9, 1.0
	v_mul_f32_e32 v21, v20, v19
	v_fma_f32 v22, -v15, v21, v20
	v_fmac_f32_e32 v21, v22, v19
	v_fma_f32 v15, -v15, v21, v20
	v_div_fmas_f32 v15, v15, v19, v21
	v_div_fixup_f32 v9, v15, v9, 1.0
	v_mul_f32_e32 v9, 0xbf1b4598, v9
	v_mul_f32_e32 v9, 0x3fb8aa3b, v9
	v_exp_f32_e32 v15, v9
	v_add_f32_e32 v9, v2, v10
	v_mul_f32_e32 v9, 0xbfb8aa3b, v9
	v_exp_f32_e32 v9, v9
	v_sub_f32_e32 v14, 1.0, v14
	v_add_f32_e32 v9, 1.0, v9
	v_div_scale_f32 v10, s[26:27], v9, v9, 1.0
	v_rcp_f32_e32 v19, v10
	s_nop 0
	v_fma_f32 v20, -v10, v19, 1.0
	v_fmac_f32_e32 v19, v20, v19
	v_div_scale_f32 v20, vcc, 1.0, v9, 1.0
	v_mul_f32_e32 v21, v20, v19
	v_fma_f32 v22, -v10, v21, v20
	v_fmac_f32_e32 v21, v22, v19
	v_fma_f32 v10, -v10, v21, v20
	v_div_fmas_f32 v10, v10, v19, v21
	v_div_fixup_f32 v9, v10, v9, 1.0
	v_add_f32_e32 v10, v3, v11
	v_mul_f32_e32 v10, 0xbfb8aa3b, v10
	v_exp_f32_e32 v10, v10
	v_mul_f32_e32 v9, 0xbf1b4598, v9
	v_mul_f32_e32 v9, 0x3fb8aa3b, v9
	v_exp_f32_e32 v9, v9
	v_add_f32_e32 v10, 1.0, v10
	v_div_scale_f32 v11, s[26:27], v10, v10, 1.0
	v_rcp_f32_e32 v19, v11
	v_pk_add_f32 v[8:9], v[8:9], 1.0 op_sel_hi:[1,0] neg_lo:[1,0] neg_hi:[1,0]
	v_fma_f32 v20, -v11, v19, 1.0
	v_fmac_f32_e32 v19, v20, v19
	v_div_scale_f32 v20, vcc, 1.0, v10, 1.0
	v_mul_f32_e32 v21, v20, v19
	v_fma_f32 v22, -v11, v21, v20
	v_fmac_f32_e32 v21, v22, v19
	v_fma_f32 v11, -v11, v21, v20
	v_div_fmas_f32 v11, v11, v19, v21
	v_div_fixup_f32 v10, v11, v10, 1.0
	v_mul_f32_e32 v10, 0xbf1b4598, v10
	v_mul_f32_e32 v10, 0x3fb8aa3b, v10
	v_exp_f32_e32 v19, v10
	v_pk_add_f32 v[10:11], v[12:13], 1.0 op_sel_hi:[1,0] neg_lo:[1,0] neg_hi:[1,0]
	v_bfe_u32 v20, v8, 16, 1
	v_bfe_u32 v12, v10, 16, 1
	v_bfe_u32 v13, v11, 16, 1
	v_bfe_u32 v21, v9, 16, 1
	v_add3_u32 v9, v9, v21, s58
	v_add3_u32 v8, v8, v20, s58
	v_add3_u32 v11, v11, v13, s58
	v_add3_u32 v10, v10, v12, s58
	v_lshrrev_b32_e32 v12, 16, v10
	v_lshrrev_b32_e32 v13, 16, v11
	v_lshrrev_b32_e32 v8, 16, v8
	v_lshrrev_b32_e32 v9, 16, v9
	v_sub_f32_e32 v10, 1.0, v15
	v_sub_f32_e32 v11, 1.0, v19
	v_and_or_b32 v11, v11, s54, v9
	v_and_or_b32 v10, v10, s54, v8
	v_and_or_b32 v9, v14, s54, v13
	v_and_or_b32 v8, v18, s54, v12
	v_lshl_add_u64 v[12:13], v[16:17], 0, v[40:41]
	global_store_dwordx4 v[12:13], v[8:11], off
	ds_read_b128 v[12:15], v118 offset:27168
	ds_read_b128 v[8:11], v118 offset:27184
	s_waitcnt lgkmcnt(0)
	v_add_f32_e32 v12, v4, v12
	v_mul_f32_e32 v12, 0xbfb8aa3b, v12
	v_exp_f32_e32 v12, v12
	v_add_f32_e32 v13, v5, v13
	v_mul_f32_e32 v13, 0xbfb8aa3b, v13
	v_exp_f32_e32 v13, v13
	v_add_f32_e32 v12, 1.0, v12
	v_div_scale_f32 v18, s[26:27], v12, v12, 1.0
	v_rcp_f32_e32 v19, v18
	v_add_f32_e32 v13, 1.0, v13
	v_add_f32_e32 v8, v0, v8
	v_mul_f32_e32 v8, 0xbfb8aa3b, v8
	v_fma_f32 v20, -v18, v19, 1.0
	v_fmac_f32_e32 v19, v20, v19
	v_div_scale_f32 v20, vcc, 1.0, v12, 1.0
	v_mul_f32_e32 v21, v20, v19
	v_fma_f32 v22, -v18, v21, v20
	v_fmac_f32_e32 v21, v22, v19
	v_fma_f32 v18, -v18, v21, v20
	v_div_fmas_f32 v18, v18, v19, v21
	v_div_fixup_f32 v12, v18, v12, 1.0
	v_div_scale_f32 v18, s[26:27], v13, v13, 1.0
	v_rcp_f32_e32 v19, v18
	v_exp_f32_e32 v8, v8
	v_add_f32_e32 v9, v1, v9
	v_mul_f32_e32 v9, 0xbfb8aa3b, v9
	v_fma_f32 v20, -v18, v19, 1.0
	v_fmac_f32_e32 v19, v20, v19
	v_div_scale_f32 v20, vcc, 1.0, v13, 1.0
	v_mul_f32_e32 v21, v20, v19
	v_fma_f32 v22, -v18, v21, v20
	v_fmac_f32_e32 v21, v22, v19
	v_fma_f32 v18, -v18, v21, v20
	v_div_fmas_f32 v18, v18, v19, v21
	v_div_fixup_f32 v13, v18, v13, 1.0
	v_mul_f32_e32 v13, 0xbf1b4598, v13
	v_mul_f32_e32 v13, 0x3fb8aa3b, v13
	v_exp_f32_e32 v18, v13
	v_add_f32_e32 v13, v6, v14
	v_mul_f32_e32 v13, 0xbfb8aa3b, v13
	v_exp_f32_e32 v13, v13
	v_add_f32_e32 v8, 1.0, v8
	v_exp_f32_e32 v9, v9
	v_mul_f32_e32 v12, 0xbf1b4598, v12
	v_add_f32_e32 v13, 1.0, v13
	v_div_scale_f32 v14, s[26:27], v13, v13, 1.0
	v_rcp_f32_e32 v19, v14
	v_add_f32_e32 v9, 1.0, v9
	v_mul_f32_e32 v12, 0x3fb8aa3b, v12
	v_exp_f32_e32 v12, v12
	v_fma_f32 v20, -v14, v19, 1.0
	v_fmac_f32_e32 v19, v20, v19
	v_div_scale_f32 v20, vcc, 1.0, v13, 1.0
	v_mul_f32_e32 v21, v20, v19
	v_fma_f32 v22, -v14, v21, v20
	v_fmac_f32_e32 v21, v22, v19
	v_fma_f32 v14, -v14, v21, v20
	v_div_fmas_f32 v14, v14, v19, v21
	v_div_fixup_f32 v13, v14, v13, 1.0
	v_add_f32_e32 v14, v7, v15
	v_mul_f32_e32 v14, 0xbfb8aa3b, v14
	v_exp_f32_e32 v14, v14
	v_mul_f32_e32 v13, 0xbf1b4598, v13
	v_mul_f32_e32 v13, 0x3fb8aa3b, v13
	v_exp_f32_e32 v13, v13
	v_add_f32_e32 v14, 1.0, v14
	v_div_scale_f32 v15, s[26:27], v14, v14, 1.0
	v_rcp_f32_e32 v19, v15
	v_sub_f32_e32 v18, 1.0, v18
	v_fma_f32 v20, -v15, v19, 1.0
	v_fmac_f32_e32 v19, v20, v19
	v_div_scale_f32 v20, vcc, 1.0, v14, 1.0
	v_mul_f32_e32 v21, v20, v19
	v_fma_f32 v22, -v15, v21, v20
	v_fmac_f32_e32 v21, v22, v19
	v_fma_f32 v15, -v15, v21, v20
	v_div_fmas_f32 v15, v15, v19, v21
	v_div_fixup_f32 v14, v15, v14, 1.0
	v_div_scale_f32 v15, s[26:27], v8, v8, 1.0
	v_rcp_f32_e32 v19, v15
	v_mul_f32_e32 v14, 0xbf1b4598, v14
	v_mul_f32_e32 v14, 0x3fb8aa3b, v14
	v_exp_f32_e32 v14, v14
	v_fma_f32 v20, -v15, v19, 1.0
	v_fmac_f32_e32 v19, v20, v19
	v_div_scale_f32 v20, vcc, 1.0, v8, 1.0
	v_mul_f32_e32 v21, v20, v19
	v_fma_f32 v22, -v15, v21, v20
	v_fmac_f32_e32 v21, v22, v19
	v_fma_f32 v15, -v15, v21, v20
	v_div_fmas_f32 v15, v15, v19, v21
	v_div_fixup_f32 v8, v15, v8, 1.0
	v_div_scale_f32 v15, s[26:27], v9, v9, 1.0
	v_rcp_f32_e32 v19, v15
	v_mul_f32_e32 v8, 0xbf1b4598, v8
	v_mul_f32_e32 v8, 0x3fb8aa3b, v8
	v_exp_f32_e32 v8, v8
	v_fma_f32 v20, -v15, v19, 1.0
	v_fmac_f32_e32 v19, v20, v19
	v_div_scale_f32 v20, vcc, 1.0, v9, 1.0
	v_mul_f32_e32 v21, v20, v19
	v_fma_f32 v22, -v15, v21, v20
	v_fmac_f32_e32 v21, v22, v19
	v_fma_f32 v15, -v15, v21, v20
	v_div_fmas_f32 v15, v15, v19, v21
	v_div_fixup_f32 v9, v15, v9, 1.0
	v_mul_f32_e32 v9, 0xbf1b4598, v9
	v_mul_f32_e32 v9, 0x3fb8aa3b, v9
	v_exp_f32_e32 v15, v9
	v_add_f32_e32 v9, v2, v10
	v_mul_f32_e32 v9, 0xbfb8aa3b, v9
	v_exp_f32_e32 v9, v9
	v_sub_f32_e32 v14, 1.0, v14
	v_add_f32_e32 v9, 1.0, v9
	v_div_scale_f32 v10, s[26:27], v9, v9, 1.0
	v_rcp_f32_e32 v19, v10
	s_nop 0
	v_fma_f32 v20, -v10, v19, 1.0
	v_fmac_f32_e32 v19, v20, v19
	v_div_scale_f32 v20, vcc, 1.0, v9, 1.0
	v_mul_f32_e32 v21, v20, v19
	v_fma_f32 v22, -v10, v21, v20
	v_fmac_f32_e32 v21, v22, v19
	v_fma_f32 v10, -v10, v21, v20
	v_div_fmas_f32 v10, v10, v19, v21
	v_div_fixup_f32 v9, v10, v9, 1.0
	v_add_f32_e32 v10, v3, v11
	v_mul_f32_e32 v10, 0xbfb8aa3b, v10
	v_exp_f32_e32 v10, v10
	v_mul_f32_e32 v9, 0xbf1b4598, v9
	v_mul_f32_e32 v9, 0x3fb8aa3b, v9
	v_exp_f32_e32 v9, v9
	v_add_f32_e32 v10, 1.0, v10
	v_div_scale_f32 v11, s[26:27], v10, v10, 1.0
	v_rcp_f32_e32 v19, v11
	v_pk_add_f32 v[8:9], v[8:9], 1.0 op_sel_hi:[1,0] neg_lo:[1,0] neg_hi:[1,0]
	v_fma_f32 v20, -v11, v19, 1.0
	v_fmac_f32_e32 v19, v20, v19
	v_div_scale_f32 v20, vcc, 1.0, v10, 1.0
	v_mul_f32_e32 v21, v20, v19
	v_fma_f32 v22, -v11, v21, v20
	v_fmac_f32_e32 v21, v22, v19
	v_fma_f32 v11, -v11, v21, v20
	v_div_fmas_f32 v11, v11, v19, v21
	v_div_fixup_f32 v10, v11, v10, 1.0
	v_mul_f32_e32 v10, 0xbf1b4598, v10
	v_mul_f32_e32 v10, 0x3fb8aa3b, v10
	v_exp_f32_e32 v19, v10
	v_pk_add_f32 v[10:11], v[12:13], 1.0 op_sel_hi:[1,0] neg_lo:[1,0] neg_hi:[1,0]
	v_bfe_u32 v20, v8, 16, 1
	v_bfe_u32 v12, v10, 16, 1
	v_bfe_u32 v13, v11, 16, 1
	v_bfe_u32 v21, v9, 16, 1
	v_add3_u32 v9, v9, v21, s58
	v_add3_u32 v8, v8, v20, s58
	v_add3_u32 v11, v11, v13, s58
	v_add3_u32 v10, v10, v12, s58
	v_lshrrev_b32_e32 v12, 16, v10
	v_lshrrev_b32_e32 v13, 16, v11
	v_lshrrev_b32_e32 v8, 16, v8
	v_lshrrev_b32_e32 v9, 16, v9
	v_sub_f32_e32 v10, 1.0, v15
	v_sub_f32_e32 v11, 1.0, v19
	v_and_or_b32 v11, v11, s54, v9
	v_and_or_b32 v10, v10, s54, v8
	v_and_or_b32 v9, v14, s54, v13
	v_and_or_b32 v8, v18, s54, v12
	v_lshl_add_u64 v[12:13], v[16:17], 0, v[42:43]
	global_store_dwordx4 v[12:13], v[8:11], off
	ds_read_b128 v[12:15], v119 offset:25088
	ds_read_b128 v[8:11], v119 offset:25104
	s_waitcnt lgkmcnt(0)
	v_add_f32_e32 v4, v4, v12
	v_mul_f32_e32 v4, 0xbfb8aa3b, v4
	v_exp_f32_e32 v4, v4
	v_add_f32_e32 v5, v5, v13
	v_mul_f32_e32 v5, 0xbfb8aa3b, v5
	v_exp_f32_e32 v5, v5
	v_add_f32_e32 v4, 1.0, v4
	v_div_scale_f32 v12, s[26:27], v4, v4, 1.0
	v_rcp_f32_e32 v18, v12
	v_add_f32_e32 v5, 1.0, v5
	v_add_f32_e32 v0, v0, v8
	v_mul_f32_e32 v0, 0xbfb8aa3b, v0
	v_fma_f32 v19, -v12, v18, 1.0
	v_fmac_f32_e32 v18, v19, v18
	v_div_scale_f32 v19, vcc, 1.0, v4, 1.0
	v_mul_f32_e32 v20, v19, v18
	v_fma_f32 v21, -v12, v20, v19
	v_fmac_f32_e32 v20, v21, v18
	v_fma_f32 v12, -v12, v20, v19
	v_div_fmas_f32 v12, v12, v18, v20
	v_div_fixup_f32 v4, v12, v4, 1.0
	v_div_scale_f32 v12, s[26:27], v5, v5, 1.0
	v_rcp_f32_e32 v13, v12
	v_exp_f32_e32 v0, v0
	v_add_f32_e32 v1, v1, v9
	v_mul_f32_e32 v1, 0xbfb8aa3b, v1
	v_fma_f32 v18, -v12, v13, 1.0
	v_fmac_f32_e32 v13, v18, v13
	v_div_scale_f32 v18, vcc, 1.0, v5, 1.0
	v_mul_f32_e32 v19, v18, v13
	v_fma_f32 v20, -v12, v19, v18
	v_fmac_f32_e32 v19, v20, v13
	v_fma_f32 v12, -v12, v19, v18
	v_div_fmas_f32 v12, v12, v13, v19
	v_div_fixup_f32 v5, v12, v5, 1.0
	v_mul_f32_e32 v5, 0xbf1b4598, v5
	v_mul_f32_e32 v5, 0x3fb8aa3b, v5
	v_exp_f32_e32 v12, v5
	v_add_f32_e32 v5, v6, v14
	v_mul_f32_e32 v5, 0xbfb8aa3b, v5
	v_exp_f32_e32 v5, v5
	v_add_f32_e32 v0, 1.0, v0
	v_exp_f32_e32 v1, v1
	v_mul_f32_e32 v4, 0xbf1b4598, v4
	v_add_f32_e32 v5, 1.0, v5
	v_div_scale_f32 v6, s[26:27], v5, v5, 1.0
	v_rcp_f32_e32 v13, v6
	v_add_f32_e32 v1, 1.0, v1
	v_mul_f32_e32 v4, 0x3fb8aa3b, v4
	v_exp_f32_e32 v4, v4
	v_fma_f32 v14, -v6, v13, 1.0
	v_fmac_f32_e32 v13, v14, v13
	v_div_scale_f32 v14, vcc, 1.0, v5, 1.0
	v_mul_f32_e32 v18, v14, v13
	v_fma_f32 v19, -v6, v18, v14
	v_fmac_f32_e32 v18, v19, v13
	v_fma_f32 v6, -v6, v18, v14
	v_div_fmas_f32 v6, v6, v13, v18
	v_div_fixup_f32 v5, v6, v5, 1.0
	v_add_f32_e32 v6, v7, v15
	v_mul_f32_e32 v6, 0xbfb8aa3b, v6
	v_exp_f32_e32 v6, v6
	v_mul_f32_e32 v5, 0xbf1b4598, v5
	v_mul_f32_e32 v5, 0x3fb8aa3b, v5
	v_exp_f32_e32 v5, v5
	v_add_f32_e32 v6, 1.0, v6
	v_div_scale_f32 v7, s[26:27], v6, v6, 1.0
	v_rcp_f32_e32 v13, v7
	s_nop 0
	v_fma_f32 v14, -v7, v13, 1.0
	v_fmac_f32_e32 v13, v14, v13
	v_div_scale_f32 v14, vcc, 1.0, v6, 1.0
	v_mul_f32_e32 v15, v14, v13
	v_fma_f32 v18, -v7, v15, v14
	v_fmac_f32_e32 v15, v18, v13
	v_fma_f32 v7, -v7, v15, v14
	v_div_fmas_f32 v7, v7, v13, v15
	v_div_fixup_f32 v6, v7, v6, 1.0
	v_div_scale_f32 v7, s[26:27], v0, v0, 1.0
	v_rcp_f32_e32 v8, v7
	v_mul_f32_e32 v6, 0xbf1b4598, v6
	v_mul_f32_e32 v6, 0x3fb8aa3b, v6
	v_exp_f32_e32 v6, v6
	v_fma_f32 v13, -v7, v8, 1.0
	v_fmac_f32_e32 v8, v13, v8
	v_div_scale_f32 v13, vcc, 1.0, v0, 1.0
	v_mul_f32_e32 v14, v13, v8
	v_fma_f32 v15, -v7, v14, v13
	v_fmac_f32_e32 v14, v15, v8
	v_fma_f32 v7, -v7, v14, v13
	v_div_fmas_f32 v7, v7, v8, v14
	v_div_fixup_f32 v0, v7, v0, 1.0
	v_div_scale_f32 v7, s[26:27], v1, v1, 1.0
	v_rcp_f32_e32 v8, v7
	v_mul_f32_e32 v0, 0xbf1b4598, v0
	v_mul_f32_e32 v0, 0x3fb8aa3b, v0
	v_exp_f32_e32 v0, v0
	v_fma_f32 v9, -v7, v8, 1.0
	v_fmac_f32_e32 v8, v9, v8
	v_div_scale_f32 v9, vcc, 1.0, v1, 1.0
	v_mul_f32_e32 v13, v9, v8
	v_fma_f32 v14, -v7, v13, v9
	v_fmac_f32_e32 v13, v14, v8
	v_fma_f32 v7, -v7, v13, v9
	v_div_fmas_f32 v7, v7, v8, v13
	v_div_fixup_f32 v1, v7, v1, 1.0
	v_mul_f32_e32 v1, 0xbf1b4598, v1
	v_mul_f32_e32 v1, 0x3fb8aa3b, v1
	v_exp_f32_e32 v7, v1
	v_add_f32_e32 v1, v2, v10
	v_mul_f32_e32 v1, 0xbfb8aa3b, v1
	v_exp_f32_e32 v1, v1
	v_sub_f32_e32 v6, 1.0, v6
	v_add_f32_e32 v1, 1.0, v1
	v_div_scale_f32 v2, s[26:27], v1, v1, 1.0
	v_rcp_f32_e32 v8, v2
	s_nop 0
	v_fma_f32 v9, -v2, v8, 1.0
	v_fmac_f32_e32 v8, v9, v8
	v_div_scale_f32 v9, vcc, 1.0, v1, 1.0
	v_mul_f32_e32 v10, v9, v8
	v_fma_f32 v13, -v2, v10, v9
	v_fmac_f32_e32 v10, v13, v8
	v_fma_f32 v2, -v2, v10, v9
	v_div_fmas_f32 v2, v2, v8, v10
	v_div_fixup_f32 v1, v2, v1, 1.0
	v_add_f32_e32 v2, v3, v11
	v_mul_f32_e32 v2, 0xbfb8aa3b, v2
	v_exp_f32_e32 v2, v2
	v_mul_f32_e32 v1, 0xbf1b4598, v1
	v_mul_f32_e32 v1, 0x3fb8aa3b, v1
	v_exp_f32_e32 v1, v1
	v_add_f32_e32 v2, 1.0, v2
	v_div_scale_f32 v3, s[26:27], v2, v2, 1.0
	v_rcp_f32_e32 v8, v3
	v_pk_add_f32 v[0:1], v[0:1], 1.0 op_sel_hi:[1,0] neg_lo:[1,0] neg_hi:[1,0]
	s_add_u32 s26, s83, s53
	s_addc_u32 s27, s84, 0
	v_fma_f32 v9, -v3, v8, 1.0
	v_fmac_f32_e32 v8, v9, v8
	v_div_scale_f32 v9, vcc, 1.0, v2, 1.0
	v_mul_f32_e32 v10, v9, v8
	v_fma_f32 v11, -v3, v10, v9
	v_fmac_f32_e32 v10, v11, v8
	v_fma_f32 v3, -v3, v10, v9
	v_div_fmas_f32 v3, v3, v8, v10
	v_div_fixup_f32 v2, v3, v2, 1.0
	v_mul_f32_e32 v2, 0xbf1b4598, v2
	v_mul_f32_e32 v2, 0x3fb8aa3b, v2
	v_exp_f32_e32 v8, v2
	v_pk_add_f32 v[2:3], v[4:5], 1.0 op_sel_hi:[1,0] neg_lo:[1,0] neg_hi:[1,0]
	v_bfe_u32 v9, v0, 16, 1
	v_bfe_u32 v4, v2, 16, 1
	v_bfe_u32 v5, v3, 16, 1
	v_bfe_u32 v10, v1, 16, 1
	v_add3_u32 v1, v1, v10, s58
	v_add3_u32 v0, v0, v9, s58
	v_add3_u32 v3, v3, v5, s58
	v_add3_u32 v2, v2, v4, s58
	v_lshrrev_b32_e32 v4, 16, v2
	v_lshrrev_b32_e32 v5, 16, v3
	v_lshrrev_b32_e32 v0, 16, v0
	v_lshrrev_b32_e32 v1, 16, v1
	v_sub_f32_e32 v9, 1.0, v12
	v_sub_f32_e32 v2, 1.0, v7
	v_sub_f32_e32 v3, 1.0, v8
	v_and_or_b32 v3, v3, s54, v1
	v_and_or_b32 v2, v2, s54, v0
	v_and_or_b32 v1, v6, s54, v5
	v_and_or_b32 v0, v9, s54, v4
	v_lshl_add_u64 v[4:5], v[16:17], 0, v[44:45]
	global_store_dwordx4 v[4:5], v[0:3], off
	s_waitcnt lgkmcnt(0)
	s_barrier
	v_mov_b32_e32 v0, v65
	s_nop 0
	v_mbcnt_lo_u32_b32 v0, -1, v0
	v_mbcnt_hi_u32_b32 v2, -1, v0
	v_and_b32_e32 v6, 31, v2
	v_or_b32_e32 v0, v6, v136
	v_ashrrev_i32_e32 v1, 31, v0
	v_ashrrev_i32_e32 v2, 2, v2
	v_lshlrev_b64 v[0:1], 7, v[0:1]
	v_and_b32_e32 v2, -8, v2
	v_lshl_add_u64 v[0:1], s[26:27], 0, v[0:1]
	v_ashrrev_i32_e32 v3, 31, v2
	v_lshl_add_u64 v[4:5], v[2:3], 1, v[0:1]
	v_mul_u32_u24_e32 v0, 0x310, v6
	v_add_co_u32_e32 v6, vcc, s35, v4
	v_lshlrev_b32_e32 v1, 1, v2
	s_nop 0
	v_addc_co_u32_e32 v7, vcc, 0, v5, vcc
	v_add3_u32 v8, s52, v0, v1
	global_load_dwordx4 v[0:3], v[4:5], off
	global_load_dwordx4 v[16:19], v[6:7], off
	ds_read_b128 v[20:23], v8 offset:512
	ds_read_b128 v[110:113], v8 offset:544
	global_load_dwordx4 v[114:117], v[4:5], off offset:32
	global_load_dwordx4 v[180:183], v[6:7], off offset:32
	ds_read_b128 v[184:187], v8 offset:576
	global_load_dwordx4 v[188:191], v[4:5], off offset:64
	global_load_dwordx4 v[192:195], v[6:7], off offset:64
	ds_read_b128 v[196:199], v8 offset:608
	global_load_dwordx4 v[200:203], v[4:5], off offset:96
	global_load_dwordx4 v[204:207], v[6:7], off offset:96
	s_waitcnt vmcnt(0) lgkmcnt(0)
	v_mfma_f32_32x32x16_bf16 v[0:15], v[20:23], v[0:3], 0
	v_mfma_f32_32x32x16_bf16 v[16:31], v[20:23], v[16:19], 0
	v_mfma_f32_32x32x16_bf16 v[0:15], v[110:113], v[114:117], v[0:15]
	v_mfma_f32_32x32x16_bf16 v[16:31], v[110:113], v[180:183], v[16:31]
	v_mfma_f32_32x32x16_bf16 v[0:15], v[184:187], v[188:191], v[0:15]
	v_mfma_f32_32x32x16_bf16 v[16:31], v[184:187], v[192:195], v[16:31]
	v_mfma_f32_32x32x16_bf16 v[0:15], v[196:199], v[200:203], v[0:15]
	v_mfma_f32_32x32x16_bf16 v[16:31], v[196:199], v[204:207], v[16:31]
	s_nop 11
	ds_write2_b32 v163, v0, v16 offset0:128 offset1:160
	ds_write2_b32 v164, v1, v17 offset0:132 offset1:164
	ds_write2_b32 v165, v2, v18 offset0:136 offset1:168
	ds_write2_b32 v166, v3, v19 offset0:140 offset1:172
	ds_write2_b32 v167, v4, v20 offset0:160 offset1:192
	ds_write2_b32 v168, v5, v21 offset0:164 offset1:196
	ds_write2_b32 v169, v6, v22 offset0:168 offset1:200
	ds_write2_b32 v170, v7, v23 offset0:172 offset1:204
	ds_write2_b32 v171, v8, v24 offset0:192 offset1:224
	ds_write2_b32 v172, v9, v25 offset0:196 offset1:228
	ds_write2_b32 v173, v10, v26 offset0:200 offset1:232
	ds_write2_b32 v174, v11, v27 offset0:204 offset1:236
	ds_write2_b32 v175, v12, v28 offset0:96 offset1:128
	ds_write2_b32 v176, v13, v29 offset0:100 offset1:132
	ds_write2_b32 v177, v14, v30 offset0:104 offset1:136
	ds_write2_b32 v178, v15, v31 offset0:108 offset1:140
	v_mov_b64_e32 v[0:1], s[6:7]
	s_waitcnt lgkmcnt(0)
	s_barrier
	global_load_dwordx2 v[0:1], v[0:1], off
	v_lshl_add_u64 v[24:25], s[18:19], 4, v[98:99]
	s_waitcnt vmcnt(0) lgkmcnt(0)
	v_readfirstlane_b32 s27, v0
	v_readfirstlane_b32 s26, v1
	s_add_u32 s24, s27, s24
	s_addc_u32 s25, s26, s25
	v_lshl_add_u64 v[0:1], s[24:25], 0, v[64:65]
	global_load_dwordx4 v[8:11], v[0:1], off
	global_load_dwordx4 v[4:7], v[0:1], off offset:16
	global_load_dwordx4 v[20:23], v[46:47], off
	global_load_dwordx4 v[16:19], v[48:49], off
	global_load_dwordx4 v[12:15], v[50:51], off
	s_nop 0
	global_load_dwordx4 v[0:3], v[52:53], off
	ds_read_b128 v[28:31], v118 offset:25088
	ds_read_b128 v[114:117], v118 offset:25104
	s_waitcnt vmcnt(0) lgkmcnt(0)
	v_add_f32_e32 v27, v9, v29
	v_mul_f32_e32 v27, 0xbfb8aa3b, v27
	v_add_f32_e32 v26, v8, v28
	v_exp_f32_e32 v28, v27
	v_add_f32_e32 v27, v10, v30
	v_add_f32_e32 v30, v4, v114
	v_mul_f32_e32 v30, 0xbfb8aa3b, v30
	v_mul_f32_e32 v26, 0xbfb8aa3b, v26
	v_mul_f32_e32 v27, 0xbfb8aa3b, v27
	v_exp_f32_e32 v112, v30
	v_add_f32_e32 v30, v5, v115
	v_exp_f32_e32 v26, v26
	v_exp_f32_e32 v27, v27
	v_mul_f32_e32 v30, 0xbfb8aa3b, v30
	v_exp_f32_e32 v114, v30
	v_add_f32_e32 v30, v6, v116
	v_mul_f32_e32 v30, 0xbfb8aa3b, v30
	v_exp_f32_e32 v113, v30
	v_add_f32_e32 v30, v7, v117
	v_mul_f32_e32 v30, 0xbfb8aa3b, v30
	v_pk_add_f32 v[26:27], v[26:27], 1.0 op_sel_hi:[1,0]
	v_exp_f32_e32 v115, v30
	v_div_scale_f32 v30, s[24:25], v27, v27, 1.0
	v_add_f32_e32 v29, v11, v31
	v_rcp_f32_e32 v31, v30
	v_mul_f32_e32 v29, 0xbfb8aa3b, v29
	v_exp_f32_e32 v29, v29
	v_pk_add_f32 v[112:113], v[112:113], 1.0 op_sel_hi:[1,0]
	v_fma_f32 v110, -v30, v31, 1.0
	v_fmac_f32_e32 v31, v110, v31
	v_div_scale_f32 v110, vcc, 1.0, v27, 1.0
	v_mul_f32_e32 v111, v110, v31
	v_fma_f32 v116, -v30, v111, v110
	v_fmac_f32_e32 v111, v116, v31
	v_fma_f32 v30, -v30, v111, v110
	v_div_fmas_f32 v30, v30, v31, v111
	v_div_fixup_f32 v27, v30, v27, 1.0
	v_div_scale_f32 v30, s[24:25], v26, v26, 1.0
	v_rcp_f32_e32 v31, v30
	v_pk_add_f32 v[28:29], v[28:29], 1.0 op_sel_hi:[1,0]
	v_pk_add_f32 v[114:115], v[114:115], 1.0 op_sel_hi:[1,0]
	v_fma_f32 v110, -v30, v31, 1.0
	v_fmac_f32_e32 v31, v110, v31
	v_div_scale_f32 v110, vcc, 1.0, v26, 1.0
	v_mul_f32_e32 v111, v110, v31
	v_fma_f32 v116, -v30, v111, v110
	v_fmac_f32_e32 v111, v116, v31
	v_fma_f32 v30, -v30, v111, v110
	v_div_fmas_f32 v30, v30, v31, v111
	v_div_fixup_f32 v26, v30, v26, 1.0
	v_pk_add_f32 v[30:31], v[26:27], -1.0 op_sel_hi:[1,0]
	s_nop 0
	v_pk_fma_f32 v[116:117], v[100:101], v[30:31], 1.0 op_sel_hi:[1,1,0]
	v_div_scale_f32 v30, s[24:25], v29, v29, 1.0
	v_rcp_f32_e32 v31, v30
	v_fma_f32 v126, v120, v116, 0
	v_fma_f32 v110, -v30, v31, 1.0
	v_fmac_f32_e32 v31, v110, v31
	v_div_scale_f32 v110, vcc, 1.0, v29, 1.0
	v_mul_f32_e32 v111, v110, v31
	v_fma_f32 v135, -v30, v111, v110
	v_fmac_f32_e32 v111, v135, v31
	v_fma_f32 v30, -v30, v111, v110
	v_div_fmas_f32 v30, v30, v31, v111
	v_div_fixup_f32 v29, v30, v29, 1.0
	v_div_scale_f32 v30, s[24:25], v28, v28, 1.0
	v_rcp_f32_e32 v31, v30
	s_nop 0
	v_fma_f32 v110, -v30, v31, 1.0
	v_fmac_f32_e32 v31, v110, v31
	v_div_scale_f32 v110, vcc, 1.0, v28, 1.0
	v_mul_f32_e32 v111, v110, v31
	v_fma_f32 v135, -v30, v111, v110
	v_fmac_f32_e32 v111, v135, v31
	v_fma_f32 v30, -v30, v111, v110
	v_div_fmas_f32 v30, v30, v31, v111
	v_div_fixup_f32 v28, v30, v28, 1.0
	v_pk_add_f32 v[30:31], v[28:29], -1.0 op_sel_hi:[1,0]
	v_pk_mul_f32 v[110:111], v[54:55], v[116:117]
	v_pk_fma_f32 v[30:31], v[32:33], v[30:31], 1.0 op_sel_hi:[1,1,0]
	v_div_scale_f32 v116, s[24:25], v113, v113, 1.0
	v_fmac_f32_e32 v126, v121, v30
	v_fmac_f32_e32 v126, v122, v117
	v_rcp_f32_e32 v117, v116
	v_fmac_f32_e32 v126, v123, v31
	v_pk_mul_f32 v[30:31], v[56:57], v[30:31]
	v_fma_f32 v135, -v116, v117, 1.0
	v_fmac_f32_e32 v117, v135, v117
	v_div_scale_f32 v135, vcc, 1.0, v113, 1.0
	v_mul_f32_e32 v179, v135, v117
	v_fma_f32 v180, -v116, v179, v135
	v_fmac_f32_e32 v179, v180, v117
	v_fma_f32 v116, -v116, v179, v135
	v_div_fmas_f32 v116, v116, v117, v179
	v_div_fixup_f32 v113, v116, v113, 1.0
	v_div_scale_f32 v116, s[24:25], v112, v112, 1.0
	v_rcp_f32_e32 v117, v116
	s_nop 0
	v_fma_f32 v135, -v116, v117, 1.0
	v_fmac_f32_e32 v117, v135, v117
	v_div_scale_f32 v135, vcc, 1.0, v112, 1.0
	v_mul_f32_e32 v179, v135, v117
	v_fma_f32 v180, -v116, v179, v135
	v_fmac_f32_e32 v179, v180, v117
	v_fma_f32 v116, -v116, v179, v135
	v_div_scale_f32 v135, s[24:25], v115, v115, 1.0
	v_div_fmas_f32 v116, v116, v117, v179
	v_rcp_f32_e32 v179, v135
	v_div_fixup_f32 v112, v116, v112, 1.0
	v_pk_add_f32 v[116:117], v[112:113], -1.0 op_sel_hi:[1,0]
	v_fma_f32 v180, -v135, v179, 1.0
	v_fmac_f32_e32 v179, v180, v179
	v_div_scale_f32 v180, vcc, 1.0, v115, 1.0
	v_mul_f32_e32 v181, v180, v179
	v_fma_f32 v182, -v135, v181, v180
	v_fmac_f32_e32 v181, v182, v179
	v_fma_f32 v135, -v135, v181, v180
	v_div_fmas_f32 v135, v135, v179, v181
	v_div_fixup_f32 v115, v135, v115, 1.0
	v_div_scale_f32 v135, s[24:25], v114, v114, 1.0
	v_rcp_f32_e32 v179, v135
	v_pk_fma_f32 v[116:117], v[102:103], v[116:117], 1.0 op_sel_hi:[1,1,0]
	v_fma_f32 v180, -v135, v179, 1.0
	v_fmac_f32_e32 v179, v180, v179
	v_div_scale_f32 v180, vcc, 1.0, v114, 1.0
	v_mul_f32_e32 v181, v180, v179
	v_fma_f32 v182, -v135, v181, v180
	v_fmac_f32_e32 v181, v182, v179
	v_fma_f32 v135, -v135, v181, v180
	v_div_fmas_f32 v135, v135, v179, v181
	v_div_fixup_f32 v114, v135, v114, 1.0
	v_pk_add_f32 v[180:181], v[114:115], -1.0 op_sel_hi:[1,0]
	v_fmac_f32_e32 v126, v147, v116
	v_pk_fma_f32 v[180:181], v[36:37], v[180:181], 1.0 op_sel_hi:[1,1,0]
	v_pk_mul_f32 v[182:183], v[72:73], v[116:117]
	v_fmac_f32_e32 v126, v148, v180
	v_fmac_f32_e32 v126, v149, v117
	v_bfe_u32 v116, v110, 16, 1
	v_bfe_u32 v117, v111, 16, 1
	v_bfe_u32 v135, v182, 16, 1
	v_bfe_u32 v179, v183, 16, 1
	v_add3_u32 v179, v183, v179, s58
	v_add3_u32 v135, v182, v135, s58
	v_add3_u32 v111, v111, v117, s58
	v_add3_u32 v110, v110, v116, s58
	v_lshrrev_b32_e32 v116, 16, v110
	v_lshrrev_b32_e32 v117, 16, v111
	v_lshrrev_b32_e32 v135, 16, v135
	v_lshrrev_b32_e32 v179, 16, v179
	v_pk_mul_f32 v[110:111], v[74:75], v[180:181]
	v_fmac_f32_e32 v126, v150, v181
	v_and_or_b32 v183, v111, s54, v179
	v_and_or_b32 v182, v110, s54, v135
	v_and_or_b32 v181, v31, s54, v117
	v_and_or_b32 v180, v30, s54, v116
	v_lshl_add_u64 v[30:31], s[12:13], 0, v[34:35]
	global_store_dwordx4 v[30:31], v[180:183], off
	v_lshlrev_b32_e32 v31, 16, v21
	v_lshlrev_b32_e32 v30, 16, v20
	v_pk_mul_f32 v[26:27], v[26:27], v[30:31]
	v_lshlrev_b32_e32 v31, 16, v23
	v_lshlrev_b32_e32 v30, 16, v22
	v_pk_mul_f32 v[30:31], v[112:113], v[30:31]
	v_bfe_u32 v110, v26, 16, 1
	v_bfe_u32 v111, v27, 16, 1
	v_bfe_u32 v112, v30, 16, 1
	v_bfe_u32 v113, v31, 16, 1
	v_add3_u32 v31, v31, v113, s58
	v_add3_u32 v30, v30, v112, s58
	v_add3_u32 v27, v27, v111, s58
	v_add3_u32 v26, v26, v110, s58
	v_and_b32_e32 v23, 0xffff0000, v23
	v_and_b32_e32 v22, 0xffff0000, v22
	v_and_b32_e32 v21, 0xffff0000, v21
	v_and_b32_e32 v20, 0xffff0000, v20
	v_lshrrev_b32_e32 v26, 16, v26
	v_lshrrev_b32_e32 v27, 16, v27
	v_lshrrev_b32_e32 v30, 16, v30
	v_lshrrev_b32_e32 v31, 16, v31
	v_pk_mul_f32 v[20:21], v[28:29], v[20:21]
	v_pk_mul_f32 v[22:23], v[114:115], v[22:23]
	v_and_or_b32 v21, v21, s54, v27
	v_and_or_b32 v23, v23, s54, v31
	v_and_or_b32 v22, v22, s54, v30
	v_and_or_b32 v20, v20, s54, v26
	v_lshl_add_u64 v[26:27], s[10:11], 0, v[34:35]
	global_store_dwordx4 v[26:27], v[20:23], off
	s_nop 1
	v_add_f32_dpp v20, v126, v126 quad_perm:[1,0,3,2] row_mask:0xf bank_mask:0xf bound_ctrl:1
	s_nop 1
	v_add_f32_dpp v20, v20, v20 quad_perm:[2,3,0,1] row_mask:0xf bank_mask:0xf bound_ctrl:1
	s_nop 1
	v_mov_b32_dpp v21, v20 row_half_mirror row_mask:0xf bank_mask:0xf bound_ctrl:1
	s_and_saveexec_b64 s[24:25], s[4:5]
	s_cbranch_execz .LBB0_428
	v_add_f32_e32 v22, v20, v21
	v_lshl_add_u64 v[20:21], v[24:25], 0, v[90:91]
	global_store_dword v[20:21], v22, off

.LBB0_683:
	v_add_u32_e32 v35, s0, v24
	v_add_u32_e32 v37, s0, v25
	ds_read_b128 v[50:53], v35
	ds_read_b128 v[54:57], v37
	s_addk_i32 s0, 0x200
	s_cmpk_lg_i32 s0, 0x3e00
	s_waitcnt lgkmcnt(1)
	v_lshlrev_b32_e32 v75, 16, v51
	v_lshlrev_b32_e32 v74, 16, v50
	s_waitcnt lgkmcnt(0)
	v_lshlrev_b32_e32 v77, 16, v55
	v_lshlrev_b32_e32 v76, 16, v54
	v_and_b32_e32 v51, 0xffff0000, v51
	v_and_b32_e32 v50, 0xffff0000, v50
	v_and_b32_e32 v55, 0xffff0000, v55
	v_and_b32_e32 v54, 0xffff0000, v54
	v_lshlrev_b32_e32 v79, 16, v53
	v_lshlrev_b32_e32 v78, 16, v52
	v_lshlrev_b32_e32 v81, 16, v57
	v_lshlrev_b32_e32 v80, 16, v56
	v_and_b32_e32 v53, 0xffff0000, v53
	v_and_b32_e32 v52, 0xffff0000, v52
	v_and_b32_e32 v57, 0xffff0000, v57
	v_and_b32_e32 v56, 0xffff0000, v56
	v_pk_fma_f32 v[68:69], v[8:9], v[76:77], v[68:69]
	v_pk_fma_f32 v[64:65], v[12:13], v[54:55], v[64:65]
	v_pk_fma_f32 v[60:61], v[16:17], v[80:81], v[60:61]
	v_pk_fma_f32 v[58:59], v[22:23], v[56:57], v[58:59]
	v_pk_fma_f32 v[72:73], v[0:1], v[76:77], v[72:73]
	v_pk_fma_f32 v[70:71], v[4:5], v[54:55], v[70:71]
	v_pk_fma_f32 v[66:67], v[10:11], v[80:81], v[66:67]
	v_pk_fma_f32 v[62:63], v[18:19], v[56:57], v[62:63]
	v_pk_fma_f32 v[48:49], v[2:3], v[76:77], v[48:49]
	v_pk_fma_f32 v[46:47], v[6:7], v[54:55], v[46:47]
	v_pk_fma_f32 v[44:45], v[14:15], v[80:81], v[44:45]
	v_pk_fma_f32 v[42:43], v[20:21], v[56:57], v[42:43]
	v_pk_fma_f32 v[40:41], v[74:75], v[76:77], v[40:41]
	v_pk_fma_f32 v[30:31], v[50:51], v[54:55], v[30:31]
	v_pk_fma_f32 v[28:29], v[78:79], v[80:81], v[28:29]
	v_pk_fma_f32 v[26:27], v[52:53], v[56:57], v[26:27]
	v_mov_b64_e32 v[22:23], v[18:19]
	v_mov_b64_e32 v[18:19], v[20:21]
	v_mov_b64_e32 v[20:21], v[52:53]
	v_mov_b64_e32 v[16:17], v[10:11]
	v_mov_b64_e32 v[10:11], v[14:15]
	v_mov_b64_e32 v[14:15], v[78:79]
	v_mov_b64_e32 v[12:13], v[4:5]
	v_mov_b64_e32 v[4:5], v[6:7]
	v_mov_b64_e32 v[6:7], v[50:51]
	v_mov_b64_e32 v[8:9], v[0:1]
	v_mov_b64_e32 v[0:1], v[2:3]
	v_mov_b64_e32 v[2:3], v[74:75]
	s_cbranch_scc1 .LBB0_683
	v_mov_b32_e32 v0, s8
	v_add_co_u32_e32 v4, vcc, 0x2954000, v0
	v_mov_b32_e32 v0, s9
	s_nop 0
	v_addc_co_u32_e32 v5, vcc, 0, v0, vcc
	global_load_dwordx4 v[0:3], v[4:5], off offset:344
	s_nop 0
	global_load_dwordx2 v[4:5], v[4:5], off offset:360
	v_lshlrev_b32_e32 v116, 2, v38
	v_mov_b64_e32 v[52:53], s[20:21]
	s_waitcnt vmcnt(0) lgkmcnt(0)
	v_readfirstlane_b32 s1, v1
	v_readfirstlane_b32 s0, v0
	v_readfirstlane_b32 s5, v3
	v_readfirstlane_b32 s4, v2
	v_lshl_add_u64 v[0:1], s[0:1], 0, v[116:117]
	global_load_dwordx4 v[16:19], v[0:1], off
	v_readfirstlane_b32 s7, v5
	v_readfirstlane_b32 s6, v4
	v_lshl_add_u64 v[2:3], s[4:5], 0, v[116:117]
	global_load_dwordx4 v[8:11], v[2:3], off
	v_lshl_add_u64 v[4:5], s[6:7], 0, v[116:117]
	global_load_dwordx4 v[12:15], v[4:5], off
	global_load_dwordx4 v[20:23], v[0:1], off offset:16
	s_nop 0
	global_load_dwordx4 v[0:3], v[2:3], off offset:16
	s_nop 0
	global_load_dwordx4 v[4:7], v[4:5], off offset:16
	v_mad_u64_u32 v[24:25], s[0:1], v33, s64, v[36:37]
	s_waitcnt lgkmcnt(0)
	s_barrier
	s_waitcnt vmcnt(0)
	v_mov_b32_e32 v54, v16
	v_mov_b32_e32 v55, v18
	v_mov_b32_e32 v18, v17
	v_pk_add_f32 v[74:75], v[72:73], v[54:55]
	v_mov_b32_e32 v56, v20
	v_mov_b32_e32 v57, v22
	v_mov_b32_e32 v22, v21
	v_pk_add_f32 v[20:21], v[68:69], v[54:55]
	v_mov_b32_e32 v16, v8
	v_mov_b32_e32 v17, v10
	v_mov_b32_e32 v10, v9
	v_mov_b32_e32 v8, v0
	v_mov_b32_e32 v9, v2
	v_pk_add_f32 v[64:65], v[64:65], v[18:19]
	v_pk_add_f32 v[76:77], v[70:71], v[18:19]
	v_add_f32_e32 v0, 0, v20
	v_add_f32_e32 v2, 0, v74
	v_add_f32_e32 v0, v0, v64
	v_add_f32_e32 v2, v2, v76
	v_add_f32_e32 v0, v0, v21
	v_add_f32_e32 v2, v2, v75
	v_pk_add_f32 v[60:61], v[60:61], v[56:57]
	v_pk_add_f32 v[78:79], v[66:67], v[56:57]
	v_add_f32_e32 v0, v0, v65
	v_add_f32_e32 v2, v2, v77
	v_pk_add_f32 v[58:59], v[58:59], v[22:23]
	v_pk_add_f32 v[80:81], v[62:63], v[22:23]
	v_add_f32_e32 v0, v0, v60
	v_add_f32_e32 v2, v2, v78
	v_add_f32_e32 v0, v0, v58
	v_add_f32_e32 v2, v2, v80
	v_add_f32_e32 v0, v0, v61
	v_add_f32_e32 v2, v2, v79
	v_add_f32_e32 v0, v0, v59
	v_add_f32_e32 v2, v2, v81
	v_mov_b32_e32 v50, v12
	v_add_f32_dpp v0, v0, v0 quad_perm:[1,0,3,2] row_mask:0xf bank_mask:0xf bound_ctrl:1
	v_add_f32_dpp v2, v2, v2 quad_perm:[1,0,3,2] row_mask:0xf bank_mask:0xf bound_ctrl:1
	v_mov_b32_e32 v12, v4
	v_add_f32_dpp v0, v0, v0 quad_perm:[2,3,0,1] row_mask:0xf bank_mask:0xf bound_ctrl:1
	v_add_f32_dpp v2, v2, v2 quad_perm:[2,3,0,1] row_mask:0xf bank_mask:0xf bound_ctrl:1
	v_mov_b32_e32 v51, v14
	v_add_f32_dpp v0, v0, v0 row_half_mirror row_mask:0xf bank_mask:0xf bound_ctrl:1
	v_add_f32_dpp v2, v2, v2 row_half_mirror row_mask:0xf bank_mask:0xf bound_ctrl:1
	v_mul_f32_e32 v0, 0x3c800000, v0
	v_mul_f32_e32 v2, 0x3c800000, v2
	v_pk_add_f32 v[72:73], v[20:21], v[0:1] op_sel_hi:[1,0] neg_lo:[0,1] neg_hi:[0,1]
	v_pk_add_f32 v[70:71], v[64:65], v[0:1] op_sel_hi:[1,0] neg_lo:[0,1] neg_hi:[0,1]
	v_pk_add_f32 v[68:69], v[60:61], v[0:1] op_sel_hi:[1,0] neg_lo:[0,1] neg_hi:[0,1]
	v_pk_add_f32 v[62:63], v[74:75], v[2:3] op_sel_hi:[1,0] neg_lo:[0,1] neg_hi:[0,1]
	v_pk_add_f32 v[60:61], v[76:77], v[2:3] op_sel_hi:[1,0] neg_lo:[0,1] neg_hi:[0,1]
	v_pk_add_f32 v[20:21], v[80:81], v[2:3] op_sel_hi:[1,0] neg_lo:[0,1] neg_hi:[0,1]
	v_mov_b32_e32 v64, v72
	v_mov_b32_e32 v65, v70
	v_mov_b32_e32 v80, v62
	v_mov_b32_e32 v81, v60
	v_mov_b32_e32 v74, v71
	v_mov_b32_e32 v75, v73
	v_mov_b32_e32 v82, v61
	v_mov_b32_e32 v83, v63
	v_pk_mul_f32 v[64:65], v[64:65], v[64:65]
	v_pk_mul_f32 v[80:81], v[80:81], v[80:81]
	v_pk_add_f32 v[66:67], v[58:59], v[0:1] op_sel_hi:[1,0] neg_lo:[0,1] neg_hi:[0,1]
	v_pk_add_f32 v[58:59], v[78:79], v[2:3] op_sel_hi:[1,0] neg_lo:[0,1] neg_hi:[0,1]
	v_pk_mul_f32 v[74:75], v[74:75], v[74:75]
	v_pk_mul_f32 v[82:83], v[82:83], v[82:83]
	v_mov_b32_e32 v88, v80
	v_mov_b32_e32 v89, v64
	v_mov_b32_e32 v64, v81
	v_mov_b32_e32 v76, v66
	v_mov_b32_e32 v77, v68
	v_mov_b32_e32 v84, v20
	v_mov_b32_e32 v85, v58
	v_mov_b32_e32 v80, v83
	v_mov_b32_e32 v81, v75
	v_pk_add_f32 v[64:65], v[88:89], v[64:65]
	v_pk_mul_f32 v[76:77], v[76:77], v[76:77]
	v_pk_mul_f32 v[84:85], v[84:85], v[84:85]
	v_mov_b32_e32 v83, v74
	v_pk_add_f32 v[64:65], v[80:81], v[64:65]
	v_mov_b32_e32 v78, v67
	v_mov_b32_e32 v79, v69
	v_mov_b32_e32 v86, v21
	v_mov_b32_e32 v87, v59
	v_mov_b32_e32 v74, v85
	v_mov_b32_e32 v75, v77
	v_pk_add_f32 v[64:65], v[82:83], v[64:65]
	v_pk_mul_f32 v[78:79], v[78:79], v[78:79]
	v_pk_mul_f32 v[86:87], v[86:87], v[86:87]
	v_mov_b32_e32 v85, v76
	v_pk_add_f32 v[64:65], v[74:75], v[64:65]
	v_mov_b32_e32 v76, v87
	v_mov_b32_e32 v77, v79
	v_pk_add_f32 v[64:65], v[84:85], v[64:65]
	v_mov_b32_e32 v87, v78
	v_pk_add_f32 v[64:65], v[76:77], v[64:65]
	v_mov_b32_e32 v2, v1
	v_pk_add_f32 v[64:65], v[86:87], v[64:65]
	v_mov_b32_e32 v14, v13
	v_mov_b32_e32 v13, v6
	v_mov_b32_dpp v75, v65 quad_perm:[1,0,3,2] row_mask:0xf bank_mask:0xf bound_ctrl:1
	v_mov_b32_dpp v74, v64 quad_perm:[1,0,3,2] row_mask:0xf bank_mask:0xf bound_ctrl:1
	v_pk_add_f32 v[64:65], v[64:65], v[74:75]
	v_mov_b32_e32 v6, v5
	v_pk_add_f32 v[42:43], v[42:43], v[22:23]
	v_mov_b32_dpp v75, v65 quad_perm:[2,3,0,1] row_mask:0xf bank_mask:0xf bound_ctrl:1
	v_mov_b32_dpp v74, v64 quad_perm:[2,3,0,1] row_mask:0xf bank_mask:0xf bound_ctrl:1
	v_pk_add_f32 v[64:65], v[64:65], v[74:75]
	v_pk_add_f32 v[28:29], v[28:29], v[56:57]
	v_pk_add_f32 v[22:23], v[26:27], v[22:23]
	v_mov_b32_dpp v75, v65 row_half_mirror row_mask:0xf bank_mask:0xf bound_ctrl:1
	v_mov_b32_dpp v74, v64 row_half_mirror row_mask:0xf bank_mask:0xf bound_ctrl:1
	v_pk_add_f32 v[64:65], v[64:65], v[74:75]
	s_nop 0
	v_pk_fma_f32 v[64:65], v[64:65], s[18:19], v[52:53] op_sel_hi:[1,0,0]
	s_nop 0
	v_mul_f32_e32 v0, 0x4b800000, v65
	v_cmp_gt_f32_e32 vcc, s65, v65
	s_nop 1
	v_cndmask_b32_e32 v0, v65, v0, vcc
	v_rsq_f32_e32 v0, v0
	s_nop 0
	v_mul_f32_e32 v1, 0x45800000, v0
	v_cndmask_b32_e32 v4, v0, v1, vcc
	v_pk_mul_f32 v[0:1], v[72:73], v[4:5] op_sel_hi:[1,0]
	v_pk_mul_f32 v[70:71], v[70:71], v[4:5] op_sel_hi:[1,0]
	v_pk_fma_f32 v[72:73], v[16:17], v[0:1], v[50:51]
	v_pk_mul_f32 v[68:69], v[68:69], v[4:5] op_sel_hi:[1,0]
	v_mul_f32_e32 v5, 0xbfb8aa3b, v72
	v_mul_f32_e32 v35, 0xbfb8aa3b, v73
	v_pk_fma_f32 v[70:71], v[10:11], v[70:71], v[14:15]
	v_pk_fma_f32 v[0:1], v[8:9], v[68:69], v[12:13]
	v_exp_f32_e32 v68, v5
	v_exp_f32_e32 v69, v35
	v_mul_f32_e32 v25, 0xbfb8aa3b, v70
	v_mul_f32_e32 v37, 0xbfb8aa3b, v71
	v_exp_f32_e32 v74, v25
	v_exp_f32_e32 v75, v37
	v_pk_mul_f32 v[78:79], v[66:67], v[4:5] op_sel_hi:[1,0]
	v_pk_add_f32 v[4:5], v[68:69], 1.0 op_sel_hi:[1,0]
	v_mul_f32_e32 v65, 0xbfb8aa3b, v1
	v_div_scale_f32 v25, s[0:1], v5, v5, 1.0
	v_pk_add_f32 v[68:69], v[74:75], 1.0 op_sel_hi:[1,0]
	v_div_scale_f32 v37, s[0:1], v4, v4, 1.0
	v_rcp_f32_e32 v80, v25
	v_exp_f32_e32 v77, v65
	v_div_scale_f32 v65, s[4:5], v69, v69, 1.0
	v_rcp_f32_e32 v81, v37
	v_div_scale_f32 v75, s[6:7], v68, v68, 1.0
	v_rcp_f32_e32 v82, v65
	v_mul_f32_e32 v39, 0xbfb8aa3b, v0
	v_rcp_f32_e32 v83, v75
	v_exp_f32_e32 v76, v39
	v_fma_f32 v84, -v25, v80, 1.0
	v_div_scale_f32 v35, vcc, 1.0, v5, 1.0
	v_fma_f32 v85, -v37, v81, 1.0
	v_fmac_f32_e32 v80, v84, v80
	v_div_scale_f32 v39, s[0:1], 1.0, v4, 1.0
	v_fma_f32 v86, -v65, v82, 1.0
	v_fmac_f32_e32 v81, v85, v81
	v_mul_f32_e32 v84, v35, v80
	v_div_scale_f32 v74, s[4:5], 1.0, v69, 1.0
	v_fma_f32 v87, -v75, v83, 1.0
	v_fmac_f32_e32 v82, v86, v82
	v_mul_f32_e32 v85, v39, v81
	v_fma_f32 v88, -v25, v84, v35
	v_pk_add_f32 v[66:67], v[76:77], 1.0 op_sel_hi:[1,0]
	v_div_scale_f32 v76, s[6:7], 1.0, v68, 1.0
	v_fmac_f32_e32 v83, v87, v83
	v_mul_f32_e32 v86, v74, v82
	v_fma_f32 v89, -v37, v85, v39
	v_fmac_f32_e32 v84, v88, v80
	v_mul_f32_e32 v87, v76, v83
	v_fma_f32 v90, -v65, v86, v74
	v_fmac_f32_e32 v85, v89, v81
	v_fma_f32 v25, -v25, v84, v35
	v_fma_f32 v91, -v75, v87, v76
	v_fmac_f32_e32 v86, v90, v82
	v_fma_f32 v35, -v37, v85, v39
	v_div_fmas_f32 v25, v25, v80, v84
	s_mov_b64 vcc, s[0:1]
	v_fmac_f32_e32 v87, v91, v83
	v_fma_f32 v37, -v65, v86, v74
	v_div_fixup_f32 v5, v25, v5, 1.0
	v_div_fmas_f32 v25, v35, v81, v85
	s_mov_b64 vcc, s[4:5]
	v_fma_f32 v39, -v75, v87, v76
	v_div_fixup_f32 v4, v25, v4, 1.0
	v_div_fmas_f32 v25, v37, v82, v86
	s_mov_b64 vcc, s[6:7]
	v_div_scale_f32 v77, s[24:25], v67, v67, 1.0
	v_div_fixup_f32 v69, v25, v69, 1.0
	v_div_fmas_f32 v25, v39, v83, v87
	v_div_fixup_f32 v68, v25, v68, 1.0
	v_rcp_f32_e32 v25, v77
	v_pk_mul_f32 v[68:69], v[70:71], v[68:69]
	v_pk_fma_f32 v[70:71], v[2:3], v[78:79], v[6:7]
	v_pk_mul_f32 v[4:5], v[72:73], v[4:5]
	v_mul_f32_e32 v35, 0xbfb8aa3b, v70
	v_exp_f32_e32 v72, v35
	v_fma_f32 v35, -v77, v25, 1.0
	v_fmac_f32_e32 v25, v35, v25
	v_div_scale_f32 v35, vcc, 1.0, v67, 1.0
	v_mul_f32_e32 v37, v35, v25
	v_fma_f32 v39, -v77, v37, v35
	v_fmac_f32_e32 v37, v39, v25
	v_div_scale_f32 v39, s[0:1], v66, v66, 1.0
	v_rcp_f32_e32 v65, v39
	v_fma_f32 v35, -v77, v37, v35
	v_div_fmas_f32 v25, v35, v25, v37
	v_mul_f32_e32 v37, 0xbfb8aa3b, v71
	v_exp_f32_e32 v73, v37
	v_div_fixup_f32 v67, v25, v67, 1.0
	v_fma_f32 v25, -v39, v65, 1.0
	v_fmac_f32_e32 v65, v25, v65
	v_div_scale_f32 v25, vcc, 1.0, v66, 1.0
	v_mul_f32_e32 v35, v25, v65
	v_fma_f32 v37, -v39, v35, v25
	v_pk_add_f32 v[72:73], v[72:73], 1.0 op_sel_hi:[1,0]
	v_fmac_f32_e32 v35, v37, v65
	v_div_scale_f32 v37, s[0:1], v73, v73, 1.0
	v_fma_f32 v25, -v39, v35, v25
	v_rcp_f32_e32 v39, v37
	v_div_fmas_f32 v25, v25, v65, v35
	v_div_fixup_f32 v66, v25, v66, 1.0
	v_pk_mul_f32 v[0:1], v[0:1], v[66:67]
	v_fma_f32 v25, -v37, v39, 1.0
	v_fmac_f32_e32 v39, v25, v39
	v_div_scale_f32 v25, vcc, 1.0, v73, 1.0
	v_mul_f32_e32 v35, v25, v39
	v_fma_f32 v65, -v37, v35, v25
	v_fmac_f32_e32 v35, v65, v39
	v_fma_f32 v25, -v37, v35, v25
	v_div_scale_f32 v37, s[0:1], v72, v72, 1.0
	v_rcp_f32_e32 v65, v37
	v_div_fmas_f32 v25, v25, v39, v35
	v_div_fixup_f32 v67, v25, v73, 1.0
	v_fma_f32 v25, -v37, v65, 1.0
	v_fmac_f32_e32 v65, v25, v65
	v_div_scale_f32 v25, vcc, 1.0, v72, 1.0
	v_mul_f32_e32 v35, v25, v65
	v_fma_f32 v39, -v37, v35, v25
	v_fmac_f32_e32 v35, v39, v65
	v_fma_f32 v25, -v37, v35, v25
	v_div_fmas_f32 v25, v25, v65, v35
	v_div_fixup_f32 v66, v25, v72, 1.0
	v_pk_mul_f32 v[66:67], v[70:71], v[66:67]
	v_bfe_u32 v39, v68, 16, 1
	v_bfe_u32 v35, v66, 16, 1
	v_add3_u32 v35, v66, v35, s59
	v_bfe_u32 v65, v4, 16, 1
	v_bfe_u32 v66, v5, 16, 1
	v_add3_u32 v39, v68, v39, s59
	v_bfe_u32 v68, v1, 16, 1
	v_add3_u32 v5, v5, v66, s59
	v_add3_u32 v4, v4, v65, s59
	v_add3_u32 v1, v1, v68, s59
	v_lshrrev_b32_e32 v68, 16, v4
	v_lshrrev_b32_e32 v4, 16, v5
	v_mul_f32_e32 v5, 0x4b800000, v64
	v_cmp_gt_f32_e32 vcc, s65, v64
	v_bfe_u32 v25, v67, 16, 1
	v_add3_u32 v25, v67, v25, s59
	v_cndmask_b32_e32 v5, v64, v5, vcc
	v_rsq_f32_e32 v5, v5
	v_bfe_u32 v67, v0, 16, 1
	v_add3_u32 v0, v0, v67, s59
	v_bfe_u32 v37, v69, 16, 1
	v_lshrrev_b32_e32 v0, 16, v0
	v_add3_u32 v37, v69, v37, s59
	v_and_or_b32 v66, v35, s63, v0
	v_mul_f32_e32 v0, 0x45800000, v5
	v_lshrrev_b32_e32 v1, 16, v1
	v_and_or_b32 v65, v37, s63, v4
	v_cndmask_b32_e32 v4, v5, v0, vcc
	v_and_or_b32 v67, v25, s63, v1
	v_pk_mul_f32 v[0:1], v[62:63], v[4:5] op_sel_hi:[1,0]
	v_and_or_b32 v64, v39, s63, v68
	v_pk_fma_f32 v[0:1], v[16:17], v[0:1], v[50:51]
	ds_write_b128 v24, v[64:67]
	v_mul_f32_e32 v5, 0xbfb8aa3b, v0
	v_exp_f32_e32 v62, v5
	v_mul_f32_e32 v5, 0xbfb8aa3b, v1
	v_exp_f32_e32 v63, v5
	v_pk_mul_f32 v[60:61], v[60:61], v[4:5] op_sel_hi:[1,0]
	v_pk_add_f32 v[62:63], v[62:63], 1.0 op_sel_hi:[1,0]
	s_nop 0
	v_div_scale_f32 v5, s[0:1], v63, v63, 1.0
	v_rcp_f32_e32 v25, v5
	v_pk_fma_f32 v[60:61], v[10:11], v[60:61], v[14:15]
	s_nop 0
	v_mul_f32_e32 v35, 0xbfb8aa3b, v60
	v_exp_f32_e32 v64, v35
	v_fma_f32 v35, -v5, v25, 1.0
	v_fmac_f32_e32 v25, v35, v25
	v_div_scale_f32 v35, vcc, 1.0, v63, 1.0
	v_mul_f32_e32 v37, v35, v25
	v_fma_f32 v39, -v5, v37, v35
	v_fmac_f32_e32 v37, v39, v25
	v_fma_f32 v5, -v5, v37, v35
	v_div_scale_f32 v35, s[0:1], v62, v62, 1.0
	v_rcp_f32_e32 v39, v35
	v_div_fmas_f32 v5, v5, v25, v37
	v_mul_f32_e32 v37, 0xbfb8aa3b, v61
	v_div_fixup_f32 v63, v5, v63, 1.0
	v_fma_f32 v5, -v35, v39, 1.0
	v_exp_f32_e32 v65, v37
	v_fmac_f32_e32 v39, v5, v39
	v_div_scale_f32 v5, vcc, 1.0, v62, 1.0
	v_mul_f32_e32 v25, v5, v39
	v_fma_f32 v37, -v35, v25, v5
	v_fmac_f32_e32 v25, v37, v39
	v_pk_add_f32 v[64:65], v[64:65], 1.0 op_sel_hi:[1,0]
	v_fma_f32 v5, -v35, v25, v5
	v_div_scale_f32 v35, s[0:1], v65, v65, 1.0
	v_rcp_f32_e32 v37, v35
	v_div_fmas_f32 v5, v5, v39, v25
	v_div_fixup_f32 v62, v5, v62, 1.0
	v_pk_mul_f32 v[0:1], v[0:1], v[62:63]
	v_fma_f32 v5, -v35, v37, 1.0
	v_fmac_f32_e32 v37, v5, v37
	v_div_scale_f32 v5, vcc, 1.0, v65, 1.0
	v_mul_f32_e32 v25, v5, v37
	v_fma_f32 v39, -v35, v25, v5
	v_fmac_f32_e32 v25, v39, v37
	v_fma_f32 v5, -v35, v25, v5
	v_div_scale_f32 v35, s[0:1], v64, v64, 1.0
	v_rcp_f32_e32 v39, v35
	v_div_fmas_f32 v5, v5, v37, v25
	v_div_fixup_f32 v63, v5, v65, 1.0
	v_fma_f32 v5, -v35, v39, 1.0
	v_fmac_f32_e32 v39, v5, v39
	v_div_scale_f32 v5, vcc, 1.0, v64, 1.0
	v_mul_f32_e32 v25, v5, v39
	v_fma_f32 v37, -v35, v25, v5
	v_fmac_f32_e32 v25, v37, v39
	v_fma_f32 v5, -v35, v25, v5
	v_div_fmas_f32 v5, v5, v39, v25
	v_pk_mul_f32 v[58:59], v[58:59], v[4:5] op_sel_hi:[1,0]
	v_div_fixup_f32 v62, v5, v64, 1.0
	v_pk_fma_f32 v[58:59], v[8:9], v[58:59], v[12:13]
	v_pk_mul_f32 v[4:5], v[20:21], v[4:5] op_sel_hi:[1,0]
	v_mul_f32_e32 v25, 0xbfb8aa3b, v58
	v_exp_f32_e32 v66, v25
	v_mul_f32_e32 v25, 0xbfb8aa3b, v59
	v_exp_f32_e32 v67, v25
	v_pk_fma_f32 v[4:5], v[2:3], v[4:5], v[6:7]
	v_pk_mul_f32 v[60:61], v[60:61], v[62:63]
	v_mul_f32_e32 v37, 0xbfb8aa3b, v4
	v_pk_add_f32 v[20:21], v[66:67], 1.0 op_sel_hi:[1,0]
	v_exp_f32_e32 v62, v37
	v_div_scale_f32 v25, s[0:1], v21, v21, 1.0
	v_rcp_f32_e32 v35, v25
	s_nop 0
	v_fma_f32 v37, -v25, v35, 1.0
	v_fmac_f32_e32 v35, v37, v35
	v_div_scale_f32 v37, vcc, 1.0, v21, 1.0
	v_mul_f32_e32 v39, v37, v35
	v_fma_f32 v63, -v25, v39, v37
	v_fmac_f32_e32 v39, v63, v35
	v_fma_f32 v25, -v25, v39, v37
	v_div_scale_f32 v37, s[0:1], v20, v20, 1.0
	v_rcp_f32_e32 v64, v37
	v_div_fmas_f32 v25, v25, v35, v39
	v_mul_f32_e32 v39, 0xbfb8aa3b, v5
	v_div_fixup_f32 v21, v25, v21, 1.0
	v_fma_f32 v25, -v37, v64, 1.0
	v_exp_f32_e32 v63, v39
	v_fmac_f32_e32 v64, v25, v64
	v_div_scale_f32 v25, vcc, 1.0, v20, 1.0
	v_mul_f32_e32 v35, v25, v64
	v_fma_f32 v39, -v37, v35, v25
	v_fmac_f32_e32 v35, v39, v64
	v_pk_add_f32 v[62:63], v[62:63], 1.0 op_sel_hi:[1,0]
	v_fma_f32 v25, -v37, v35, v25
	v_div_scale_f32 v37, s[0:1], v63, v63, 1.0
	v_rcp_f32_e32 v39, v37
	v_div_fmas_f32 v25, v25, v64, v35
	v_div_fixup_f32 v20, v25, v20, 1.0
	v_pk_mul_f32 v[20:21], v[58:59], v[20:21]
	v_fma_f32 v25, -v37, v39, 1.0
	v_fmac_f32_e32 v39, v25, v39
	v_div_scale_f32 v25, vcc, 1.0, v63, 1.0
	v_mul_f32_e32 v35, v25, v39
	v_fma_f32 v58, -v37, v35, v25
	v_fmac_f32_e32 v35, v58, v39
	v_fma_f32 v25, -v37, v35, v25
	v_div_scale_f32 v37, s[0:1], v62, v62, 1.0
	v_rcp_f32_e32 v58, v37
	v_div_fmas_f32 v25, v25, v39, v35
	v_div_fixup_f32 v59, v25, v63, 1.0
	v_fma_f32 v25, -v37, v58, 1.0
	v_fmac_f32_e32 v58, v25, v58
	v_div_scale_f32 v25, vcc, 1.0, v62, 1.0
	v_mul_f32_e32 v35, v25, v58
	v_fma_f32 v39, -v37, v35, v25
	v_fmac_f32_e32 v35, v39, v58
	v_fma_f32 v25, -v37, v35, v25
	v_div_fmas_f32 v25, v25, v58, v35
	v_div_fixup_f32 v58, v25, v62, 1.0
	v_pk_mul_f32 v[4:5], v[4:5], v[58:59]
	v_bfe_u32 v58, v20, 16, 1
	v_bfe_u32 v25, v5, 16, 1
	v_bfe_u32 v35, v4, 16, 1
	v_add3_u32 v35, v4, v35, s59
	v_add3_u32 v25, v5, v25, s59
	v_bfe_u32 v4, v0, 16, 1
	v_bfe_u32 v5, v1, 16, 1
	v_add3_u32 v1, v1, v5, s59
	v_add3_u32 v0, v0, v4, s59
	v_add3_u32 v20, v20, v58, s59
	v_lshrrev_b32_e32 v64, 16, v0
	v_lshrrev_b32_e32 v65, 16, v1
	v_pk_add_f32 v[0:1], v[48:49], v[54:55]
	v_lshrrev_b32_e32 v66, 16, v20
	v_add_f32_e32 v20, 0, v0
	v_pk_add_f32 v[4:5], v[46:47], v[18:19]
	v_bfe_u32 v59, v21, 16, 1
	v_add_f32_e32 v20, v20, v4
	v_add3_u32 v21, v21, v59, s59
	v_add_f32_e32 v20, v20, v1
	v_lshrrev_b32_e32 v67, 16, v21
	v_add_f32_e32 v46, v20, v5
	v_pk_add_f32 v[20:21], v[44:45], v[56:57]
	v_bfe_u32 v37, v61, 16, 1
	v_add_f32_e32 v44, v46, v20
	v_add_f32_e32 v44, v44, v42
	v_add_f32_e32 v44, v44, v21
	v_add_f32_e32 v44, v44, v43
	v_bfe_u32 v39, v60, 16, 1
	v_add3_u32 v39, v60, v39, s59
	v_add_f32_dpp v44, v44, v44 quad_perm:[1,0,3,2] row_mask:0xf bank_mask:0xf bound_ctrl:1
	v_add3_u32 v37, v61, v37, s59
	v_pk_add_f32 v[18:19], v[30:31], v[18:19]
	v_add_f32_dpp v44, v44, v44 quad_perm:[2,3,0,1] row_mask:0xf bank_mask:0xf bound_ctrl:1
	s_nop 1
	v_add_f32_dpp v44, v44, v44 row_half_mirror row_mask:0xf bank_mask:0xf bound_ctrl:1
	v_mul_f32_e32 v46, 0x3c800000, v44
	v_pk_add_f32 v[48:49], v[0:1], v[46:47] op_sel_hi:[1,0] neg_lo:[0,1] neg_hi:[0,1]
	v_pk_add_f32 v[58:59], v[4:5], v[46:47] op_sel_hi:[1,0] neg_lo:[0,1] neg_hi:[0,1]
	v_mov_b32_e32 v5, v49
	v_mov_b32_e32 v4, v59
	v_pk_add_f32 v[44:45], v[20:21], v[46:47] op_sel_hi:[1,0] neg_lo:[0,1] neg_hi:[0,1]
	v_pk_add_f32 v[42:43], v[42:43], v[46:47] op_sel_hi:[1,0] neg_lo:[0,1] neg_hi:[0,1]
	v_pk_mul_f32 v[60:61], v[4:5], v[4:5]
	v_mov_b32_e32 v4, v42
	v_mov_b32_e32 v5, v44
	v_pk_mul_f32 v[46:47], v[4:5], v[4:5]
	v_mov_b32_e32 v4, v43
	v_mov_b32_e32 v5, v45
	v_pk_mul_f32 v[62:63], v[4:5], v[4:5]
	v_pk_add_f32 v[4:5], v[40:41], v[54:55]
	v_mov_b32_e32 v0, v48
	v_add_f32_e32 v20, 0, v4
	v_add_f32_e32 v20, v20, v18
	v_add_f32_e32 v20, v20, v5
	v_add_f32_e32 v20, v20, v19
	v_add_f32_e32 v20, v20, v28
	v_add_f32_e32 v20, v20, v22
	v_add_f32_e32 v20, v20, v29
	v_add_f32_e32 v20, v20, v23
	v_mov_b32_e32 v1, v58
	v_pk_mul_f32 v[0:1], v[0:1], v[0:1]
	v_add_f32_dpp v20, v20, v20 quad_perm:[1,0,3,2] row_mask:0xf bank_mask:0xf bound_ctrl:1
	v_mov_b32_e32 v31, v0
	s_nop 0
	v_add_f32_dpp v20, v20, v20 quad_perm:[2,3,0,1] row_mask:0xf bank_mask:0xf bound_ctrl:1
	s_nop 1
	v_add_f32_dpp v20, v20, v20 row_half_mirror row_mask:0xf bank_mask:0xf bound_ctrl:1
	v_mul_f32_e32 v26, 0x3c800000, v20
	v_pk_add_f32 v[20:21], v[4:5], v[26:27] op_sel_hi:[1,0] neg_lo:[0,1] neg_hi:[0,1]
	v_pk_add_f32 v[18:19], v[18:19], v[26:27] op_sel_hi:[1,0] neg_lo:[0,1] neg_hi:[0,1]
	v_mov_b32_e32 v4, v20
	v_mov_b32_e32 v5, v18
	v_pk_mul_f32 v[4:5], v[4:5], v[4:5]
	s_nop 0
	v_mov_b32_e32 v30, v4
	v_mov_b32_e32 v0, v5
	v_pk_add_f32 v[30:31], v[30:31], v[0:1]
	v_mov_b32_e32 v0, v19
	v_mov_b32_e32 v1, v21
	v_pk_mul_f32 v[40:41], v[0:1], v[0:1]
	v_pk_add_f32 v[4:5], v[28:29], v[26:27] op_sel_hi:[1,0] neg_lo:[0,1] neg_hi:[0,1]
	v_pk_add_f32 v[0:1], v[22:23], v[26:27] op_sel_hi:[1,0] neg_lo:[0,1] neg_hi:[0,1]
	v_mov_b32_e32 v23, v4
	v_mov_b32_e32 v22, v0
	v_mov_b32_e32 v28, v41
	v_mov_b32_e32 v29, v61
	v_pk_mul_f32 v[22:23], v[22:23], v[22:23]
	v_pk_add_f32 v[28:29], v[28:29], v[30:31]
	v_mov_b32_e32 v41, v60
	v_mov_b32_e32 v26, v1
	v_mov_b32_e32 v27, v5
	v_pk_add_f32 v[28:29], v[40:41], v[28:29]
	v_mov_b32_e32 v30, v23
	v_mov_b32_e32 v31, v47
	v_pk_mul_f32 v[26:27], v[26:27], v[26:27]
	v_pk_add_f32 v[28:29], v[30:31], v[28:29]
	v_mov_b32_e32 v23, v46
	v_pk_add_f32 v[22:23], v[22:23], v[28:29]
	v_mov_b32_e32 v28, v27
	v_mov_b32_e32 v29, v63
	v_pk_add_f32 v[22:23], v[28:29], v[22:23]
	v_mov_b32_e32 v27, v62
	v_pk_add_f32 v[22:23], v[26:27], v[22:23]
	v_and_or_b32 v29, v25, s63, v67
	v_and_or_b32 v28, v35, s63, v66
	v_mov_b32_dpp v27, v23 quad_perm:[1,0,3,2] row_mask:0xf bank_mask:0xf bound_ctrl:1
	v_mov_b32_dpp v26, v22 quad_perm:[1,0,3,2] row_mask:0xf bank_mask:0xf bound_ctrl:1
	v_pk_add_f32 v[22:23], v[22:23], v[26:27]
	s_nop 1
	v_mov_b32_dpp v27, v23 quad_perm:[2,3,0,1] row_mask:0xf bank_mask:0xf bound_ctrl:1
	v_mov_b32_dpp v26, v22 quad_perm:[2,3,0,1] row_mask:0xf bank_mask:0xf bound_ctrl:1
	v_pk_add_f32 v[22:23], v[22:23], v[26:27]
	s_nop 1
	v_mov_b32_dpp v27, v23 row_half_mirror row_mask:0xf bank_mask:0xf bound_ctrl:1
	v_mov_b32_dpp v26, v22 row_half_mirror row_mask:0xf bank_mask:0xf bound_ctrl:1
	v_pk_add_f32 v[22:23], v[22:23], v[26:27]
	v_and_or_b32 v27, v37, s63, v65
	v_pk_fma_f32 v[22:23], v[22:23], s[18:19], v[52:53] op_sel_hi:[1,0,0]
	s_nop 0
	v_mul_f32_e32 v26, 0x4b800000, v23
	v_cmp_gt_f32_e32 vcc, s65, v23
	s_nop 1
	v_cndmask_b32_e32 v23, v23, v26, vcc
	v_rsq_f32_e32 v23, v23
	v_and_or_b32 v26, v39, s63, v64
	ds_write_b128 v24, v[26:29] offset:528
	v_mul_f32_e32 v25, 0x45800000, v23
	v_cndmask_b32_e32 v30, v23, v25, vcc
	v_pk_mul_f32 v[40:41], v[48:49], v[30:31] op_sel_hi:[1,0]
	v_pk_mul_f32 v[26:27], v[58:59], v[30:31] op_sel_hi:[1,0]
	v_pk_fma_f32 v[40:41], v[16:17], v[40:41], v[50:51]
	s_nop 0
	v_mul_f32_e32 v23, 0xbfb8aa3b, v40
	v_exp_f32_e32 v46, v23
	v_mul_f32_e32 v23, 0xbfb8aa3b, v41
	v_exp_f32_e32 v47, v23
	s_nop 0
	v_pk_add_f32 v[28:29], v[46:47], 1.0 op_sel_hi:[1,0]
	s_nop 0
	v_div_scale_f32 v23, s[0:1], v29, v29, 1.0
	v_rcp_f32_e32 v25, v23
	v_pk_fma_f32 v[46:47], v[10:11], v[26:27], v[14:15]
	v_fma_f32 v27, -v23, v25, 1.0
	v_fmac_f32_e32 v25, v27, v25
	v_div_scale_f32 v27, vcc, 1.0, v29, 1.0
	v_mul_f32_e32 v31, v27, v25
	v_fma_f32 v35, -v23, v31, v27
	v_fmac_f32_e32 v31, v35, v25
	v_div_scale_f32 v35, s[0:1], v28, v28, 1.0
	v_rcp_f32_e32 v37, v35
	v_mul_f32_e32 v26, 0xbfb8aa3b, v46
	v_fma_f32 v23, -v23, v31, v27
	v_mul_f32_e32 v27, 0xbfb8aa3b, v47
	v_exp_f32_e32 v26, v26
	v_div_fmas_f32 v23, v23, v25, v31
	v_exp_f32_e32 v27, v27
	v_div_fixup_f32 v29, v23, v29, 1.0
	v_fma_f32 v23, -v35, v37, 1.0
	v_fmac_f32_e32 v37, v23, v37
	v_div_scale_f32 v23, vcc, 1.0, v28, 1.0
	v_mul_f32_e32 v25, v23, v37
	v_fma_f32 v31, -v35, v25, v23
	v_pk_add_f32 v[48:49], v[26:27], 1.0 op_sel_hi:[1,0]
	v_fmac_f32_e32 v25, v31, v37
	v_div_scale_f32 v31, s[0:1], v49, v49, 1.0
	v_fma_f32 v23, -v35, v25, v23
	v_rcp_f32_e32 v35, v31
	v_div_fmas_f32 v23, v23, v37, v25
	v_div_fixup_f32 v28, v23, v28, 1.0
	v_pk_mul_f32 v[26:27], v[40:41], v[28:29]
	v_fma_f32 v23, -v31, v35, 1.0
	v_fmac_f32_e32 v35, v23, v35
	v_div_scale_f32 v23, vcc, 1.0, v49, 1.0
	v_mul_f32_e32 v25, v23, v35
	v_fma_f32 v28, -v31, v25, v23
	v_fmac_f32_e32 v25, v28, v35
	v_div_scale_f32 v28, s[0:1], v48, v48, 1.0
	v_fma_f32 v23, -v31, v25, v23
	v_rcp_f32_e32 v31, v28
	v_div_fmas_f32 v23, v23, v35, v25
	v_div_fixup_f32 v29, v23, v49, 1.0
	v_fma_f32 v23, -v28, v31, 1.0
	v_fmac_f32_e32 v31, v23, v31
	v_div_scale_f32 v23, vcc, 1.0, v48, 1.0
	v_mul_f32_e32 v25, v23, v31
	v_fma_f32 v35, -v28, v25, v23
	v_fmac_f32_e32 v25, v35, v31
	v_pk_mul_f32 v[40:41], v[44:45], v[30:31] op_sel_hi:[1,0]
	v_fma_f32 v23, -v28, v25, v23
	v_pk_fma_f32 v[40:41], v[8:9], v[40:41], v[12:13]
	v_div_fmas_f32 v23, v23, v31, v25
	v_mul_f32_e32 v25, 0xbfb8aa3b, v40
	v_exp_f32_e32 v44, v25
	v_mul_f32_e32 v25, 0xbfb8aa3b, v41
	v_exp_f32_e32 v45, v25
	v_pk_mul_f32 v[30:31], v[42:43], v[30:31] op_sel_hi:[1,0]
	v_div_fixup_f32 v28, v23, v48, 1.0
	v_pk_fma_f32 v[30:31], v[2:3], v[30:31], v[6:7]
	v_pk_add_f32 v[42:43], v[44:45], 1.0 op_sel_hi:[1,0]
	v_mul_f32_e32 v35, 0xbfb8aa3b, v30
	v_div_scale_f32 v23, s[0:1], v43, v43, 1.0
	v_rcp_f32_e32 v25, v23
	v_exp_f32_e32 v44, v35
	v_pk_mul_f32 v[28:29], v[46:47], v[28:29]
	v_fma_f32 v35, -v23, v25, 1.0
	v_fmac_f32_e32 v25, v35, v25
	v_div_scale_f32 v35, vcc, 1.0, v43, 1.0
	v_mul_f32_e32 v37, v35, v25
	v_fma_f32 v39, -v23, v37, v35
	v_fmac_f32_e32 v37, v39, v25
	v_fma_f32 v23, -v23, v37, v35
	v_div_scale_f32 v35, s[0:1], v42, v42, 1.0
	v_rcp_f32_e32 v39, v35
	v_div_fmas_f32 v23, v23, v25, v37
	v_mul_f32_e32 v37, 0xbfb8aa3b, v31
	v_div_fixup_f32 v43, v23, v43, 1.0
	v_fma_f32 v23, -v35, v39, 1.0
	v_exp_f32_e32 v45, v37
	v_fmac_f32_e32 v39, v23, v39
	v_div_scale_f32 v23, vcc, 1.0, v42, 1.0
	v_mul_f32_e32 v25, v23, v39
	v_fma_f32 v37, -v35, v25, v23
	v_fmac_f32_e32 v25, v37, v39
	v_pk_add_f32 v[44:45], v[44:45], 1.0 op_sel_hi:[1,0]
	v_fma_f32 v23, -v35, v25, v23
	v_div_scale_f32 v35, s[0:1], v45, v45, 1.0
	v_rcp_f32_e32 v37, v35
	v_div_fmas_f32 v23, v23, v39, v25
	v_div_fixup_f32 v42, v23, v42, 1.0
	v_pk_mul_f32 v[40:41], v[40:41], v[42:43]
	v_fma_f32 v23, -v35, v37, 1.0
	v_fmac_f32_e32 v37, v23, v37
	v_div_scale_f32 v23, vcc, 1.0, v45, 1.0
	v_mul_f32_e32 v25, v23, v37
	v_fma_f32 v39, -v35, v25, v23
	v_fmac_f32_e32 v25, v39, v37
	v_fma_f32 v23, -v35, v25, v23
	v_div_scale_f32 v35, s[0:1], v44, v44, 1.0
	v_rcp_f32_e32 v39, v35
	v_div_fmas_f32 v23, v23, v37, v25
	v_div_fixup_f32 v43, v23, v45, 1.0
	v_fma_f32 v23, -v35, v39, 1.0
	v_fmac_f32_e32 v39, v23, v39
	v_div_scale_f32 v23, vcc, 1.0, v44, 1.0
	v_mul_f32_e32 v25, v23, v39
	v_fma_f32 v37, -v35, v25, v23
	v_fmac_f32_e32 v25, v37, v39
	v_fma_f32 v23, -v35, v25, v23
	v_div_fmas_f32 v23, v23, v39, v25
	v_div_fixup_f32 v42, v23, v44, 1.0
	v_pk_mul_f32 v[30:31], v[30:31], v[42:43]
	v_bfe_u32 v37, v28, 16, 1
	v_bfe_u32 v25, v30, 16, 1
	v_add3_u32 v25, v30, v25, s59
	v_bfe_u32 v30, v40, 16, 1
	v_add3_u32 v37, v28, v37, s59
	v_bfe_u32 v28, v26, 16, 1
	v_add3_u32 v30, v40, v30, s59
	v_add3_u32 v26, v26, v28, s59
	v_lshrrev_b32_e32 v28, 16, v30
	v_mul_f32_e32 v30, 0x4b800000, v22
	v_cmp_gt_f32_e32 vcc, s65, v22
	v_bfe_u32 v23, v31, 16, 1
	v_bfe_u32 v35, v29, 16, 1
	v_cndmask_b32_e32 v22, v22, v30, vcc
	v_rsq_f32_e32 v22, v22
	v_add3_u32 v23, v31, v23, s59
	v_bfe_u32 v31, v41, 16, 1
	v_add3_u32 v35, v29, v35, s59
	v_bfe_u32 v29, v27, 16, 1
	v_add3_u32 v31, v41, v31, s59
	v_add3_u32 v27, v27, v29, s59
	v_lshrrev_b32_e32 v29, 16, v31
	v_and_or_b32 v29, v23, s63, v29
	v_mul_f32_e32 v23, 0x45800000, v22
	v_cndmask_b32_e32 v22, v22, v23, vcc
	v_pk_mul_f32 v[20:21], v[20:21], v[22:23] op_sel_hi:[1,0]
	v_pk_mul_f32 v[18:19], v[18:19], v[22:23] op_sel_hi:[1,0]
	v_pk_fma_f32 v[16:17], v[16:17], v[20:21], v[50:51]
	v_and_or_b32 v28, v25, s63, v28
	v_mul_f32_e32 v20, 0xbfb8aa3b, v16
	v_mul_f32_e32 v21, 0xbfb8aa3b, v17
	v_exp_f32_e32 v20, v20
	v_exp_f32_e32 v21, v21
	v_pk_fma_f32 v[14:15], v[10:11], v[18:19], v[14:15]
	v_lshrrev_b32_e32 v26, 16, v26
	v_lshrrev_b32_e32 v27, 16, v27
	v_pk_add_f32 v[20:21], v[20:21], 1.0 op_sel_hi:[1,0]
	v_and_or_b32 v27, v35, s63, v27
	v_div_scale_f32 v23, s[0:1], v21, v21, 1.0
	v_rcp_f32_e32 v25, v23
	v_and_or_b32 v26, v37, s63, v26
	ds_write_b128 v24, v[26:29] offset:1056
	v_mul_f32_e32 v10, 0xbfb8aa3b, v14
	v_fma_f32 v11, -v23, v25, 1.0
	v_fmac_f32_e32 v25, v11, v25
	v_div_scale_f32 v11, vcc, 1.0, v21, 1.0
	v_mul_f32_e32 v18, v11, v25
	v_fma_f32 v19, -v23, v18, v11
	v_fmac_f32_e32 v18, v19, v25
	v_fma_f32 v11, -v23, v18, v11
	v_div_scale_f32 v23, s[0:1], v20, v20, 1.0
	v_rcp_f32_e32 v28, v23
	v_div_fmas_f32 v11, v11, v25, v18
	v_div_fixup_f32 v19, v11, v21, 1.0
	v_exp_f32_e32 v10, v10
	v_fma_f32 v11, -v23, v28, 1.0
	v_fmac_f32_e32 v28, v11, v28
	v_mul_f32_e32 v11, 0xbfb8aa3b, v15
	v_exp_f32_e32 v11, v11
	v_div_scale_f32 v18, vcc, 1.0, v20, 1.0
	v_mul_f32_e32 v21, v18, v28
	v_fma_f32 v25, -v23, v21, v18
	v_fmac_f32_e32 v21, v25, v28
	v_pk_add_f32 v[26:27], v[10:11], 1.0 op_sel_hi:[1,0]
	v_fma_f32 v18, -v23, v21, v18
	v_div_scale_f32 v23, s[0:1], v27, v27, 1.0
	v_rcp_f32_e32 v25, v23
	v_div_fmas_f32 v10, v18, v28, v21
	v_div_fixup_f32 v18, v10, v20, 1.0
	v_pk_mul_f32 v[10:11], v[16:17], v[18:19]
	v_fma_f32 v16, -v23, v25, 1.0
	v_fmac_f32_e32 v25, v16, v25
	v_div_scale_f32 v16, vcc, 1.0, v27, 1.0
	v_mul_f32_e32 v17, v16, v25
	v_fma_f32 v18, -v23, v17, v16
	v_fmac_f32_e32 v17, v18, v25
	v_div_scale_f32 v18, s[0:1], v26, v26, 1.0
	v_rcp_f32_e32 v19, v18
	v_fma_f32 v16, -v23, v17, v16
	v_div_fmas_f32 v16, v16, v25, v17
	v_div_fixup_f32 v17, v16, v27, 1.0
	v_fma_f32 v16, -v18, v19, 1.0
	v_pk_mul_f32 v[4:5], v[4:5], v[22:23] op_sel_hi:[1,0]
	v_fmac_f32_e32 v19, v16, v19
	v_div_scale_f32 v16, vcc, 1.0, v26, 1.0
	v_pk_fma_f32 v[4:5], v[8:9], v[4:5], v[12:13]
	v_mul_f32_e32 v20, v16, v19
	v_mul_f32_e32 v8, 0xbfb8aa3b, v4
	v_mul_f32_e32 v9, 0xbfb8aa3b, v5
	v_fma_f32 v21, -v18, v20, v16
	v_exp_f32_e32 v8, v8
	v_exp_f32_e32 v9, v9
	v_fmac_f32_e32 v20, v21, v19
	v_fma_f32 v16, -v18, v20, v16
	v_div_fmas_f32 v16, v16, v19, v20
	v_div_fixup_f32 v16, v16, v26, 1.0
	v_pk_add_f32 v[8:9], v[8:9], 1.0 op_sel_hi:[1,0]
	v_pk_mul_f32 v[12:13], v[14:15], v[16:17]
	v_div_scale_f32 v14, s[0:1], v9, v9, 1.0
	v_rcp_f32_e32 v15, v14
	v_pk_mul_f32 v[0:1], v[0:1], v[22:23] op_sel_hi:[1,0]
	s_nop 0
	v_pk_fma_f32 v[0:1], v[2:3], v[0:1], v[6:7]
	v_fma_f32 v3, -v14, v15, 1.0
	v_fmac_f32_e32 v15, v3, v15
	v_div_scale_f32 v3, vcc, 1.0, v9, 1.0
	v_mul_f32_e32 v6, v3, v15
	v_fma_f32 v7, -v14, v6, v3
	v_fmac_f32_e32 v6, v7, v15
	v_fma_f32 v3, -v14, v6, v3
	v_div_scale_f32 v14, s[0:1], v8, v8, 1.0
	v_rcp_f32_e32 v16, v14
	v_div_fmas_f32 v3, v3, v15, v6
	v_div_fixup_f32 v7, v3, v9, 1.0
	v_mul_f32_e32 v2, 0xbfb8aa3b, v0
	v_fma_f32 v3, -v14, v16, 1.0
	v_fmac_f32_e32 v16, v3, v16
	v_mul_f32_e32 v3, 0xbfb8aa3b, v1
	v_exp_f32_e32 v2, v2
	v_exp_f32_e32 v3, v3
	v_div_scale_f32 v6, vcc, 1.0, v8, 1.0
	v_mul_f32_e32 v9, v6, v16
	v_fma_f32 v15, -v14, v9, v6
	v_fmac_f32_e32 v9, v15, v16
	v_pk_add_f32 v[2:3], v[2:3], 1.0 op_sel_hi:[1,0]
	v_fma_f32 v6, -v14, v9, v6
	v_div_scale_f32 v14, s[0:1], v3, v3, 1.0
	v_rcp_f32_e32 v15, v14
	v_div_fmas_f32 v6, v6, v16, v9
	v_div_fixup_f32 v6, v6, v8, 1.0
	v_pk_mul_f32 v[4:5], v[4:5], v[6:7]
	v_fma_f32 v6, -v14, v15, 1.0
	v_fmac_f32_e32 v15, v6, v15
	v_div_scale_f32 v6, vcc, 1.0, v3, 1.0
	v_mul_f32_e32 v7, v6, v15
	v_fma_f32 v8, -v14, v7, v6
	v_fmac_f32_e32 v7, v8, v15
	v_div_scale_f32 v8, s[0:1], v2, v2, 1.0
	v_rcp_f32_e32 v9, v8
	v_fma_f32 v6, -v14, v7, v6
	v_div_fmas_f32 v6, v6, v15, v7
	v_div_fixup_f32 v3, v6, v3, 1.0
	v_fma_f32 v6, -v8, v9, 1.0
	v_fmac_f32_e32 v9, v6, v9
	v_div_scale_f32 v6, vcc, 1.0, v2, 1.0
	v_mul_f32_e32 v7, v6, v9
	v_fma_f32 v14, -v8, v7, v6
	v_fmac_f32_e32 v7, v14, v9
	v_fma_f32 v6, -v8, v7, v6
	v_div_fmas_f32 v6, v6, v9, v7
	v_div_fixup_f32 v2, v6, v2, 1.0
	v_pk_mul_f32 v[0:1], v[0:1], v[2:3]
	v_bfe_u32 v8, v4, 16, 1
	v_bfe_u32 v2, v1, 16, 1
	v_bfe_u32 v3, v0, 16, 1
	v_add3_u32 v0, v0, v3, s59
	v_add3_u32 v1, v1, v2, s59
	v_bfe_u32 v2, v10, 16, 1
	v_bfe_u32 v3, v11, 16, 1
	v_bfe_u32 v9, v5, 16, 1
	v_bfe_u32 v6, v13, 16, 1
	v_bfe_u32 v7, v12, 16, 1
	v_add3_u32 v5, v5, v9, s59
	v_add3_u32 v4, v4, v8, s59
	v_add3_u32 v3, v11, v3, s59
	v_add3_u32 v2, v10, v2, s59
	v_add3_u32 v7, v12, v7, s59
	v_add3_u32 v6, v13, v6, s59
	v_lshrrev_b32_e32 v8, 16, v2
	v_lshrrev_b32_e32 v9, 16, v3
	v_lshrrev_b32_e32 v2, 16, v4
	v_lshrrev_b32_e32 v3, 16, v5
	v_and_or_b32 v3, v1, s63, v3
	v_and_or_b32 v2, v0, s63, v2
	v_and_or_b32 v1, v6, s63, v9
	v_and_or_b32 v0, v7, s63, v8
	ds_write_b128 v24, v[0:3] offset:1584
	v_mov_b32_e32 v0, v117
	s_waitcnt lgkmcnt(0)
	s_barrier
	s_nop 0
	v_mbcnt_lo_u32_b32 v0, -1, v0
	v_mbcnt_hi_u32_b32 v2, -1, v0
	v_and_b32_e32 v12, 31, v2
	v_and_or_b32 v0, v32, s66, v12
	v_ashrrev_i32_e32 v1, 31, v0
	v_ashrrev_i32_e32 v2, 2, v2
	v_lshlrev_b64 v[0:1], 9, v[0:1]
	v_and_b32_e32 v8, -8, v2
	v_lshl_add_u64 v[0:1], s[8:9], 0, v[0:1]
	v_ashrrev_i32_e32 v9, 31, v8
	v_lshl_add_u64 v[10:11], v[8:9], 1, v[0:1]
	v_add_co_u32_e32 v0, vcc, s67, v10
	v_lshl_add_u64 v[62:63], v[10:11], 0, s[22:23]
	s_nop 0
	v_addc_co_u32_e32 v1, vcc, 0, v11, vcc
	global_load_dwordx4 v[198:201], v[0:1], off
	global_load_dwordx4 v[202:205], v[62:63], off offset:32
	v_add_co_u32_e32 v60, vcc, s68, v10
	s_nop 0
	s_nop 0
	v_addc_co_u32_e32 v61, vcc, 0, v11, vcc
	global_load_dwordx4 v[206:209], v[60:61], off
	global_load_dwordx4 v[210:213], v[60:61], off offset:32
	global_load_dwordx4 v[214:217], v[62:63], off offset:64
	global_load_dwordx4 v[218:221], v[60:61], off offset:64
	global_load_dwordx4 v[224:227], v[62:63], off offset:96
	global_load_dwordx4 v[228:231], v[60:61], off offset:96
	global_load_dwordx4 v[232:235], v[62:63], off offset:128
	global_load_dwordx4 v[236:239], v[60:61], off offset:128
	global_load_dwordx4 v[240:243], v[62:63], off offset:160
	global_load_dwordx4 v[248:251], v[60:61], off offset:160
	v_lshlrev_b32_e32 v8, 1, v8
	v_mad_u32_u24 v35, v12, s60, v8
	ds_read_b128 v[8:11], v35
	ds_read_b128 v[44:47], v35 offset:32
	s_waitcnt lgkmcnt(0)
	s_waitcnt vmcnt(11)
	v_mfma_f32_32x32x16_bf16 v[16:31], v[8:11], v[198:201], 0
	global_load_dwordx4 v[198:201], v[62:63], off offset:192
	s_waitcnt vmcnt(11)
	v_mfma_f32_32x32x16_bf16 v[16:31], v[44:47], v[202:205], v[16:31]
	global_load_dwordx4 v[202:205], v[60:61], off offset:192
	s_waitcnt vmcnt(11)
	v_mfma_f32_32x32x16_bf16 v[0:15], v[8:11], v[206:209], 0
	global_load_dwordx4 v[206:209], v[62:63], off offset:224
	s_waitcnt lgkmcnt(0)
	s_waitcnt vmcnt(11)
	v_mfma_f32_32x32x16_bf16 v[0:15], v[44:47], v[210:213], v[0:15]
	global_load_dwordx4 v[210:213], v[60:61], off offset:224
	ds_read_b128 v[44:47], v35 offset:64
	ds_read_b128 v[48:51], v35 offset:96
	s_waitcnt lgkmcnt(1)
	s_waitcnt vmcnt(10)
	v_mfma_f32_32x32x16_bf16 v[0:15], v[44:47], v[218:221], v[0:15]
	v_mfma_f32_32x32x16_bf16 v[16:31], v[44:47], v[214:217], v[16:31]
	global_load_dwordx4 v[214:217], v[62:63], off offset:256
	global_load_dwordx4 v[218:221], v[60:61], off offset:256
	s_waitcnt lgkmcnt(0)
	s_waitcnt vmcnt(11)
	v_mfma_f32_32x32x16_bf16 v[16:31], v[48:51], v[224:227], v[16:31]
	global_load_dwordx4 v[224:227], v[62:63], off offset:288
	s_waitcnt lgkmcnt(0)
	s_waitcnt vmcnt(11)
	v_mfma_f32_32x32x16_bf16 v[0:15], v[48:51], v[228:231], v[0:15]
	global_load_dwordx4 v[228:231], v[60:61], off offset:288
	ds_read_b128 v[48:51], v35 offset:128
	ds_read_b128 v[56:59], v35 offset:160
	s_waitcnt lgkmcnt(0)
	s_waitcnt vmcnt(11)
	v_mfma_f32_32x32x16_bf16 v[16:31], v[48:51], v[232:235], v[16:31]
	global_load_dwordx4 v[232:235], v[62:63], off offset:320
	s_waitcnt vmcnt(11)
	v_mfma_f32_32x32x16_bf16 v[0:15], v[48:51], v[236:239], v[0:15]
	global_load_dwordx4 v[236:239], v[60:61], off offset:320
	s_waitcnt vmcnt(11)
	v_mfma_f32_32x32x16_bf16 v[16:31], v[56:59], v[240:243], v[16:31]
	global_load_dwordx4 v[240:243], v[62:63], off offset:352
	ds_read_b128 v[52:55], v35 offset:192
	s_waitcnt lgkmcnt(0)
	s_waitcnt vmcnt(11)
	v_mfma_f32_32x32x16_bf16 v[0:15], v[56:59], v[248:251], v[0:15]
	global_load_dwordx4 v[248:251], v[60:61], off offset:352
	ds_read_b128 v[56:59], v35 offset:224
	s_waitcnt vmcnt(11)
	v_mfma_f32_32x32x16_bf16 v[16:31], v[52:55], v[198:201], v[16:31]
	global_load_dwordx4 v[198:201], v[62:63], off offset:384
	s_waitcnt vmcnt(11)
	v_mfma_f32_32x32x16_bf16 v[0:15], v[52:55], v[202:205], v[0:15]
	global_load_dwordx4 v[202:205], v[60:61], off offset:384
	s_waitcnt lgkmcnt(0)
	s_waitcnt vmcnt(11)
	v_mfma_f32_32x32x16_bf16 v[16:31], v[56:59], v[206:209], v[16:31]
	global_load_dwordx4 v[206:209], v[62:63], off offset:416
	s_waitcnt vmcnt(11)
	v_mfma_f32_32x32x16_bf16 v[0:15], v[56:59], v[210:213], v[0:15]
	global_load_dwordx4 v[210:213], v[60:61], off offset:416
	ds_read_b128 v[48:51], v35 offset:256
	ds_read_b128 v[56:59], v35 offset:288
	s_waitcnt lgkmcnt(0)
	s_waitcnt vmcnt(11)
	v_mfma_f32_32x32x16_bf16 v[16:31], v[48:51], v[214:217], v[16:31]
	global_load_dwordx4 v[214:217], v[62:63], off offset:448
	s_waitcnt vmcnt(11)
	v_mfma_f32_32x32x16_bf16 v[0:15], v[48:51], v[218:221], v[0:15]
	global_load_dwordx4 v[218:221], v[60:61], off offset:448
	s_waitcnt vmcnt(11)
	v_mfma_f32_32x32x16_bf16 v[16:31], v[56:59], v[224:227], v[16:31]
	global_load_dwordx4 v[224:227], v[62:63], off offset:480
	ds_read_b128 v[52:55], v35 offset:320
	s_waitcnt lgkmcnt(0)
	s_waitcnt vmcnt(11)
	v_mfma_f32_32x32x16_bf16 v[0:15], v[56:59], v[228:231], v[0:15]
	global_load_dwordx4 v[228:231], v[60:61], off offset:480
	ds_read_b128 v[56:59], v35 offset:352
	s_waitcnt vmcnt(11)
	v_mfma_f32_32x32x16_bf16 v[16:31], v[52:55], v[232:235], v[16:31]
	s_waitcnt vmcnt(10)
	v_mfma_f32_32x32x16_bf16 v[0:15], v[52:55], v[236:239], v[0:15]
	s_waitcnt lgkmcnt(0)
	s_waitcnt vmcnt(9)
	v_mfma_f32_32x32x16_bf16 v[16:31], v[56:59], v[240:243], v[16:31]
	s_waitcnt vmcnt(8)
	v_mfma_f32_32x32x16_bf16 v[0:15], v[56:59], v[248:251], v[0:15]
	ds_read_b128 v[48:51], v35 offset:384
	ds_read_b128 v[56:59], v35 offset:416
	s_waitcnt lgkmcnt(0)
	s_waitcnt vmcnt(7)
	v_mfma_f32_32x32x16_bf16 v[16:31], v[48:51], v[198:201], v[16:31]
	s_waitcnt vmcnt(6)
	v_mfma_f32_32x32x16_bf16 v[0:15], v[48:51], v[202:205], v[0:15]
	s_waitcnt vmcnt(5)
	v_mfma_f32_32x32x16_bf16 v[16:31], v[56:59], v[206:209], v[16:31]
	ds_read_b128 v[52:55], v35 offset:448
	s_waitcnt lgkmcnt(0)
	s_waitcnt vmcnt(4)
	v_mfma_f32_32x32x16_bf16 v[0:15], v[56:59], v[210:213], v[0:15]
	ds_read_b128 v[56:59], v35 offset:480
	s_waitcnt vmcnt(3)
	v_mfma_f32_32x32x16_bf16 v[16:31], v[52:55], v[214:217], v[16:31]
	s_waitcnt vmcnt(2)
	v_mfma_f32_32x32x16_bf16 v[0:15], v[52:55], v[218:221], v[0:15]
	s_waitcnt lgkmcnt(0)
	s_waitcnt vmcnt(1)
	v_mfma_f32_32x32x16_bf16 v[16:31], v[56:59], v[224:227], v[16:31]
	s_waitcnt vmcnt(0)
	v_mfma_f32_32x32x16_bf16 v[0:15], v[56:59], v[228:231], v[0:15]
	v_lshrrev_b32_e32 v35, 3, v32
	v_and_b32_e32 v35, 4, v35
	v_mul_u32_u24_e32 v35, 0x108, v35
	v_and_b32_e32 v37, 0x7fffffdf, v32
	s_nop 6
	v_bfe_u32 v39, v16, 16, 1
	v_lshlrev_b32_e32 v35, 1, v35
	v_add3_u32 v16, v16, v39, s59
	v_lshl_add_u32 v35, v37, 1, v35
	ds_write_b16_d16_hi v35, v16 offset:16896
	v_bfe_u32 v16, v17, 16, 1
	v_add3_u32 v16, v17, v16, s59
	ds_write_b16_d16_hi v35, v16 offset:17424
	v_bfe_u32 v16, v18, 16, 1
	v_add3_u32 v16, v18, v16, s59
	ds_write_b16_d16_hi v35, v16 offset:17952
	v_bfe_u32 v16, v19, 16, 1
	v_add3_u32 v16, v19, v16, s59
	ds_write_b16_d16_hi v35, v16 offset:18480
	v_bfe_u32 v16, v20, 16, 1
	v_add3_u32 v16, v20, v16, s59
	ds_write_b16_d16_hi v35, v16 offset:21120
	v_bfe_u32 v16, v21, 16, 1
	v_add3_u32 v16, v21, v16, s59
	ds_write_b16_d16_hi v35, v16 offset:21648
	v_bfe_u32 v16, v22, 16, 1
	v_add3_u32 v16, v22, v16, s59
	ds_write_b16_d16_hi v35, v16 offset:22176
	v_bfe_u32 v16, v23, 16, 1
	v_add3_u32 v16, v23, v16, s59
	ds_write_b16_d16_hi v35, v16 offset:22704
	v_bfe_u32 v16, v24, 16, 1
	v_add3_u32 v16, v24, v16, s59
	ds_write_b16_d16_hi v35, v16 offset:25344
	v_bfe_u32 v16, v25, 16, 1
	v_add3_u32 v16, v25, v16, s59
	ds_write_b16_d16_hi v35, v16 offset:25872
	v_bfe_u32 v16, v26, 16, 1
	v_add3_u32 v16, v26, v16, s59
	ds_write_b16_d16_hi v35, v16 offset:26400
	v_bfe_u32 v16, v27, 16, 1
	v_add3_u32 v16, v27, v16, s59
	ds_write_b16_d16_hi v35, v16 offset:26928
	v_bfe_u32 v16, v28, 16, 1
	v_add3_u32 v16, v28, v16, s59
	ds_write_b16_d16_hi v35, v16 offset:29568
	v_bfe_u32 v16, v29, 16, 1
	v_add3_u32 v16, v29, v16, s59
	ds_write_b16_d16_hi v35, v16 offset:30096
	v_bfe_u32 v16, v30, 16, 1
	v_add3_u32 v16, v30, v16, s59
	ds_write_b16_d16_hi v35, v16 offset:30624
	v_bfe_u32 v16, v31, 16, 1
	v_add3_u32 v16, v31, v16, s59
	ds_write_b16_d16_hi v35, v16 offset:31152
	v_bfe_u32 v16, v0, 16, 1
	v_add3_u32 v0, v0, v16, s59
	ds_write_b16_d16_hi v35, v0 offset:16960
	v_bfe_u32 v0, v1, 16, 1
	v_add3_u32 v0, v1, v0, s59
	ds_write_b16_d16_hi v35, v0 offset:17488
	v_bfe_u32 v0, v2, 16, 1
	v_add3_u32 v0, v2, v0, s59
	ds_write_b16_d16_hi v35, v0 offset:18016
	v_bfe_u32 v0, v3, 16, 1
	v_add3_u32 v0, v3, v0, s59
	ds_write_b16_d16_hi v35, v0 offset:18544
	v_bfe_u32 v0, v4, 16, 1
	v_add3_u32 v0, v4, v0, s59
	ds_write_b16_d16_hi v35, v0 offset:21184
	v_bfe_u32 v0, v5, 16, 1
	v_add3_u32 v0, v5, v0, s59
	ds_write_b16_d16_hi v35, v0 offset:21712
	v_bfe_u32 v0, v6, 16, 1
	v_add3_u32 v0, v6, v0, s59
	ds_write_b16_d16_hi v35, v0 offset:22240
	v_bfe_u32 v0, v7, 16, 1
	v_add3_u32 v0, v7, v0, s59
	ds_write_b16_d16_hi v35, v0 offset:22768
	v_bfe_u32 v0, v8, 16, 1
	v_add3_u32 v0, v8, v0, s59
	ds_write_b16_d16_hi v35, v0 offset:25408
	v_bfe_u32 v0, v9, 16, 1
	v_add3_u32 v0, v9, v0, s59
	ds_write_b16_d16_hi v35, v0 offset:25936
	v_bfe_u32 v0, v10, 16, 1
	v_add3_u32 v0, v10, v0, s59
	ds_write_b16_d16_hi v35, v0 offset:26464
	v_bfe_u32 v0, v11, 16, 1
	v_add3_u32 v0, v11, v0, s59
	ds_write_b16_d16_hi v35, v0 offset:26992
	v_bfe_u32 v0, v12, 16, 1
	v_add3_u32 v0, v12, v0, s59
	ds_write_b16_d16_hi v35, v0 offset:29632
	v_bfe_u32 v0, v13, 16, 1
	v_add3_u32 v0, v13, v0, s59
	ds_write_b16_d16_hi v35, v0 offset:30160
	v_bfe_u32 v0, v14, 16, 1
	v_add3_u32 v0, v14, v0, s59
	ds_write_b16_d16_hi v35, v0 offset:30688
	v_bfe_u32 v0, v15, 16, 1
	v_add3_u32 v0, v15, v0, s59
	v_lshlrev_b32_e32 v116, 1, v38
	ds_write_b16_d16_hi v35, v0 offset:31216
	v_lshl_add_u64 v[0:1], s[8:9], 0, v[116:117]
	v_lshl_add_u64 v[4:5], v[0:1], 0, s[36:37]
	v_mad_u64_u32 v[0:1], s[0:1], v33, s60, v[36:37]
	s_waitcnt lgkmcnt(0)
	s_barrier
	ds_read_b128 v[0:3], v0 offset:16896
	v_add_u32_e32 v6, s53, v33
	v_ashrrev_i32_e32 v7, 31, v6
	v_lshlrev_b64 v[6:7], 11, v[6:7]
	v_lshl_add_u64 v[6:7], v[4:5], 0, v[6:7]
	s_waitcnt lgkmcnt(0)
	global_store_dwordx4 v[6:7], v[0:3], off
	s_nop 1
	v_add_u32_e32 v0, 0x100, v32
	v_ashrrev_i32_e32 v6, 5, v0
	v_mad_u64_u32 v[0:1], s[0:1], v6, s60, v[36:37]
	ds_read_b128 v[0:3], v0 offset:16896
	v_add_u32_e32 v6, s53, v6
	v_ashrrev_i32_e32 v7, 31, v6
	v_lshlrev_b64 v[6:7], 11, v[6:7]
	v_lshl_add_u64 v[6:7], v[4:5], 0, v[6:7]
	s_waitcnt lgkmcnt(0)
	global_store_dwordx4 v[6:7], v[0:3], off
	v_ashrrev_i32_e32 v6, 5, v34
	s_nop 0
	v_mad_u64_u32 v[0:1], s[0:1], v6, s60, v[36:37]
	ds_read_b128 v[0:3], v0 offset:16896
	v_add_u32_e32 v6, s53, v6
	v_ashrrev_i32_e32 v7, 31, v6
	v_lshlrev_b64 v[6:7], 11, v[6:7]
	v_lshl_add_u64 v[6:7], v[4:5], 0, v[6:7]
	s_waitcnt lgkmcnt(0)
	global_store_dwordx4 v[6:7], v[0:3], off
	s_nop 1
	v_add_u32_e32 v0, 0x300, v32
	v_ashrrev_i32_e32 v6, 5, v0
	v_mad_u64_u32 v[0:1], s[0:1], v6, s60, v[36:37]
	ds_read_b128 v[0:3], v0 offset:16896
	v_add_u32_e32 v6, s53, v6
	v_ashrrev_i32_e32 v7, 31, v6
	v_lshlrev_b64 v[6:7], 11, v[6:7]
	v_lshl_add_u64 v[4:5], v[4:5], 0, v[6:7]
	s_waitcnt lgkmcnt(0)
	global_store_dwordx4 v[4:5], v[0:3], off

.LBB0_1369:
	v_ashrrev_i32_e32 v73, 31, v72
	v_bfe_u32 v2, v7, 16, 1
	v_add3_u32 v4, v7, v2, s60
	v_lshlrev_b64 v[2:3], 6, v[72:73]
	v_lshl_add_u64 v[0:1], v[0:1], 0, v[2:3]
	global_store_short_d16_hi v[0:1], v4, off
	v_mov_b32_e32 v1, v65
	s_waitcnt lgkmcnt(0)
	s_barrier
	v_lshlrev_b32_e32 v0, 1, v79
	v_mbcnt_lo_u32_b32 v1, -1, v1
	v_mbcnt_hi_u32_b32 v2, -1, v1
	v_and_b32_e32 v20, 31, v2
	s_movk_i32 s0, 0xff80
	v_and_or_b32 v0, v0, s0, v20
	v_ashrrev_i32_e32 v1, 31, v0
	v_ashrrev_i32_e32 v2, 2, v2
	v_lshlrev_b64 v[0:1], 8, v[0:1]
	v_and_b32_e32 v16, -8, v2
	v_lshl_add_u64 v[0:1], s[8:9], 0, v[0:1]
	v_ashrrev_i32_e32 v17, 31, v16
	v_lshl_add_u64 v[18:19], v[16:17], 1, v[0:1]
	s_mov_b32 s0, 0x1710000
	v_add_co_u32_e32 v0, vcc, s0, v18
	s_mov_b32 s0, 0x1712000
	s_nop 0
	v_addc_co_u32_e32 v1, vcc, 0, v19, vcc
	v_add_co_u32_e32 v76, vcc, s0, v18
	s_mov_b32 s0, 0x1714000
	s_nop 0
	v_addc_co_u32_e32 v77, vcc, 0, v19, vcc
	v_add_co_u32_e32 v74, vcc, s0, v18
	s_mov_b32 s0, 0x1716000
	s_nop 0
	v_addc_co_u32_e32 v75, vcc, 0, v19, vcc
	v_add_co_u32_e32 v118, vcc, s0, v18
	global_load_dwordx4 v[0:3], v[0:1], off
	s_nop 0
	v_addc_co_u32_e32 v119, vcc, 0, v19, vcc
	global_load_dwordx4 v[4:7], v[76:77], off
	global_load_dwordx4 v[98:101], v[76:77], off offset:32
	global_load_dwordx4 v[8:11], v[74:75], off
	global_load_dwordx4 v[12:15], v[118:119], off
	v_lshlrev_b32_e32 v16, 1, v16
	s_mov_b64 s[0:1], 0x1710000
	v_mad_u32_u24 v64, v20, s58, v16
	ds_read_b128 v[86:89], v64
	ds_read_b128 v[94:97], v64 offset:32
	v_lshl_add_u64 v[120:121], v[18:19], 0, s[0:1]
	global_load_dwordx4 v[90:93], v[120:121], off offset:32
	global_load_dwordx4 v[102:105], v[74:75], off offset:32
	global_load_dwordx4 v[106:109], v[76:77], off offset:96
	global_load_dwordx4 v[110:113], v[118:119], off offset:32
	global_load_dwordx4 v[114:117], v[74:75], off offset:96
	s_waitcnt vmcnt(0) lgkmcnt(0)
	global_load_dwordx4 v[208:211], v[120:121], off offset:64
	global_load_dwordx4 v[212:215], v[76:77], off offset:64
	global_load_dwordx4 v[216:219], v[74:75], off offset:64
	global_load_dwordx4 v[220:223], v[118:119], off offset:64
	global_load_dwordx4 v[224:227], v[120:121], off offset:96
	global_load_dwordx4 v[228:231], v[118:119], off offset:96
	global_load_dwordx4 v[232:235], v[120:121], off offset:128
	global_load_dwordx4 v[236:239], v[76:77], off offset:128
	global_load_dwordx4 v[240:243], v[74:75], off offset:128
	global_load_dwordx4 v[244:247], v[118:119], off offset:128
	global_load_dwordx4 v[248:251], v[120:121], off offset:160
	v_mfma_f32_32x32x16_bf16 v[48:63], v[86:89], v[0:3], 0
	v_mfma_f32_32x32x16_bf16 v[32:47], v[86:89], v[4:7], 0
	v_mfma_f32_32x32x16_bf16 v[16:31], v[86:89], v[8:11], 0
	v_mfma_f32_32x32x16_bf16 v[0:15], v[86:89], v[12:15], 0
	v_mfma_f32_32x32x16_bf16 v[48:63], v[94:97], v[90:93], v[48:63]
	v_mfma_f32_32x32x16_bf16 v[32:47], v[94:97], v[98:101], v[32:47]
	v_mfma_f32_32x32x16_bf16 v[16:31], v[94:97], v[102:105], v[16:31]
	v_mfma_f32_32x32x16_bf16 v[0:15], v[94:97], v[110:113], v[0:15]
	ds_read_b128 v[94:97], v64 offset:64
	ds_read_b128 v[110:113], v64 offset:96
	s_waitcnt lgkmcnt(0)
	s_waitcnt vmcnt(10)
	v_mfma_f32_32x32x16_bf16 v[48:63], v[94:97], v[208:211], v[48:63]
	global_load_dwordx4 v[208:211], v[76:77], off offset:160
	s_waitcnt vmcnt(10)
	v_mfma_f32_32x32x16_bf16 v[32:47], v[94:97], v[212:215], v[32:47]
	global_load_dwordx4 v[212:215], v[74:75], off offset:160
	s_waitcnt vmcnt(10)
	v_mfma_f32_32x32x16_bf16 v[16:31], v[94:97], v[216:219], v[16:31]
	global_load_dwordx4 v[216:219], v[118:119], off offset:160
	s_waitcnt vmcnt(10)
	v_mfma_f32_32x32x16_bf16 v[0:15], v[94:97], v[220:223], v[0:15]
	global_load_dwordx4 v[220:223], v[120:121], off offset:192
	v_mfma_f32_32x32x16_bf16 v[32:47], v[110:113], v[106:109], v[32:47]
	s_waitcnt lgkmcnt(0)
	s_waitcnt vmcnt(10)
	v_mfma_f32_32x32x16_bf16 v[48:63], v[110:113], v[224:227], v[48:63]
	global_load_dwordx4 v[224:227], v[76:77], off offset:192
	v_mfma_f32_32x32x16_bf16 v[16:31], v[110:113], v[114:117], v[16:31]
	s_waitcnt lgkmcnt(0)
	s_waitcnt vmcnt(10)
	v_mfma_f32_32x32x16_bf16 v[0:15], v[110:113], v[228:231], v[0:15]
	global_load_dwordx4 v[228:231], v[74:75], off offset:192
	ds_read_b128 v[102:105], v64 offset:128
	ds_read_b128 v[110:113], v64 offset:160
	s_waitcnt lgkmcnt(0)
	s_waitcnt vmcnt(10)
	v_mfma_f32_32x32x16_bf16 v[48:63], v[102:105], v[232:235], v[48:63]
	global_load_dwordx4 v[232:235], v[118:119], off offset:192
	s_waitcnt vmcnt(10)
	v_mfma_f32_32x32x16_bf16 v[32:47], v[102:105], v[236:239], v[32:47]
	global_load_dwordx4 v[236:239], v[120:121], off offset:224
	s_waitcnt vmcnt(10)
	v_mfma_f32_32x32x16_bf16 v[16:31], v[102:105], v[240:243], v[16:31]
	global_load_dwordx4 v[240:243], v[76:77], off offset:224
	s_waitcnt vmcnt(10)
	v_mfma_f32_32x32x16_bf16 v[0:15], v[102:105], v[244:247], v[0:15]
	global_load_dwordx4 v[244:247], v[118:119], off offset:224
	s_waitcnt vmcnt(10)
	v_mfma_f32_32x32x16_bf16 v[48:63], v[110:113], v[248:251], v[48:63]
	global_load_dwordx4 v[248:251], v[74:75], off offset:224
	ds_read_b128 v[106:109], v64 offset:192
	s_waitcnt lgkmcnt(0)
	s_waitcnt vmcnt(10)
	v_mfma_f32_32x32x16_bf16 v[32:47], v[110:113], v[208:211], v[32:47]
	s_waitcnt vmcnt(9)
	v_mfma_f32_32x32x16_bf16 v[16:31], v[110:113], v[212:215], v[16:31]
	s_waitcnt vmcnt(8)
	v_mfma_f32_32x32x16_bf16 v[0:15], v[110:113], v[216:219], v[0:15]
	ds_read_b128 v[110:113], v64 offset:224
	s_waitcnt vmcnt(7)
	v_mfma_f32_32x32x16_bf16 v[48:63], v[106:109], v[220:223], v[48:63]
	s_waitcnt vmcnt(6)
	v_mfma_f32_32x32x16_bf16 v[32:47], v[106:109], v[224:227], v[32:47]
	s_waitcnt lgkmcnt(0)
	s_waitcnt vmcnt(5)
	v_mfma_f32_32x32x16_bf16 v[16:31], v[106:109], v[228:231], v[16:31]
	s_nop 0
	s_waitcnt vmcnt(4)
	v_mfma_f32_32x32x16_bf16 v[0:15], v[106:109], v[232:235], v[0:15]
	s_waitcnt vmcnt(3)
	v_mfma_f32_32x32x16_bf16 v[48:63], v[110:113], v[236:239], v[48:63]
	s_waitcnt vmcnt(2)
	v_mfma_f32_32x32x16_bf16 v[32:47], v[110:113], v[240:243], v[32:47]
	s_waitcnt lgkmcnt(0)
	s_waitcnt vmcnt(0)
	v_mfma_f32_32x32x16_bf16 v[16:31], v[110:113], v[248:251], v[16:31]
	v_mfma_f32_32x32x16_bf16 v[0:15], v[110:113], v[244:247], v[0:15]
	v_lshrrev_b32_e32 v74, 3, v79
	v_and_b32_e32 v74, 4, v74
	s_nop 5
	v_bfe_u32 v76, v48, 16, 1
	v_and_b32_e32 v64, 0xffffffc0, v79
	v_add3_u32 v48, v48, v76, s60
	v_mul_u32_u24_e32 v76, 0x108, v74
	v_or_b32_e32 v75, v64, v80
	v_lshlrev_b32_e32 v76, 1, v76
	v_lshl_add_u32 v75, v75, 1, v76
	ds_write_b16_d16_hi v75, v48 offset:16896
	v_bfe_u32 v48, v49, 16, 1
	v_add3_u32 v48, v49, v48, s60
	ds_write_b16_d16_hi v75, v48 offset:17424
	v_bfe_u32 v48, v50, 16, 1
	v_add3_u32 v48, v50, v48, s60
	ds_write_b16_d16_hi v75, v48 offset:17952
	v_bfe_u32 v48, v51, 16, 1
	v_add3_u32 v48, v51, v48, s60
	ds_write_b16_d16_hi v75, v48 offset:18480
	v_bfe_u32 v48, v52, 16, 1
	v_add3_u32 v48, v52, v48, s60
	ds_write_b16_d16_hi v75, v48 offset:21120
	v_bfe_u32 v48, v53, 16, 1
	v_add3_u32 v48, v53, v48, s60
	ds_write_b16_d16_hi v75, v48 offset:21648
	v_bfe_u32 v48, v54, 16, 1
	v_add3_u32 v48, v54, v48, s60
	ds_write_b16_d16_hi v75, v48 offset:22176
	v_bfe_u32 v48, v55, 16, 1
	v_add3_u32 v48, v55, v48, s60
	ds_write_b16_d16_hi v75, v48 offset:22704
	v_bfe_u32 v48, v56, 16, 1
	v_add3_u32 v48, v56, v48, s60
	ds_write_b16_d16_hi v75, v48 offset:25344
	v_bfe_u32 v48, v57, 16, 1
	v_add3_u32 v48, v57, v48, s60
	ds_write_b16_d16_hi v75, v48 offset:25872
	v_bfe_u32 v48, v58, 16, 1
	v_add3_u32 v48, v58, v48, s60
	ds_write_b16_d16_hi v75, v48 offset:26400
	v_bfe_u32 v48, v59, 16, 1
	v_add3_u32 v48, v59, v48, s60
	ds_write_b16_d16_hi v75, v48 offset:26928
	v_bfe_u32 v48, v60, 16, 1
	v_add3_u32 v48, v60, v48, s60
	ds_write_b16_d16_hi v75, v48 offset:29568
	v_bfe_u32 v48, v61, 16, 1
	v_add3_u32 v48, v61, v48, s60
	ds_write_b16_d16_hi v75, v48 offset:30096
	v_bfe_u32 v48, v62, 16, 1
	v_add3_u32 v48, v62, v48, s60
	ds_write_b16_d16_hi v75, v48 offset:30624
	v_bfe_u32 v48, v63, 16, 1
	v_add3_u32 v48, v63, v48, s60
	ds_write_b16_d16_hi v75, v48 offset:31152
	v_bfe_u32 v48, v32, 16, 1
	v_add3_u32 v32, v32, v48, s60
	ds_write_b16_d16_hi v75, v32 offset:16960
	v_bfe_u32 v32, v33, 16, 1
	v_add3_u32 v32, v33, v32, s60
	ds_write_b16_d16_hi v75, v32 offset:17488
	v_bfe_u32 v32, v34, 16, 1
	v_add3_u32 v32, v34, v32, s60
	ds_write_b16_d16_hi v75, v32 offset:18016
	v_bfe_u32 v32, v35, 16, 1
	v_add3_u32 v32, v35, v32, s60
	ds_write_b16_d16_hi v75, v32 offset:18544
	v_bfe_u32 v32, v36, 16, 1
	v_add3_u32 v32, v36, v32, s60
	ds_write_b16_d16_hi v75, v32 offset:21184
	v_bfe_u32 v32, v37, 16, 1
	v_add3_u32 v32, v37, v32, s60
	ds_write_b16_d16_hi v75, v32 offset:21712
	v_bfe_u32 v32, v38, 16, 1
	v_add3_u32 v32, v38, v32, s60
	ds_write_b16_d16_hi v75, v32 offset:22240
	v_bfe_u32 v32, v39, 16, 1
	v_add3_u32 v32, v39, v32, s60
	ds_write_b16_d16_hi v75, v32 offset:22768
	v_bfe_u32 v32, v40, 16, 1
	v_add3_u32 v32, v40, v32, s60
	ds_write_b16_d16_hi v75, v32 offset:25408
	v_bfe_u32 v32, v41, 16, 1
	v_add3_u32 v32, v41, v32, s60
	ds_write_b16_d16_hi v75, v32 offset:25936
	v_bfe_u32 v32, v42, 16, 1
	v_add3_u32 v32, v42, v32, s60
	ds_write_b16_d16_hi v75, v32 offset:26464
	v_bfe_u32 v32, v43, 16, 1
	v_add3_u32 v32, v43, v32, s60
	ds_write_b16_d16_hi v75, v32 offset:26992
	v_bfe_u32 v32, v44, 16, 1
	v_add3_u32 v32, v44, v32, s60
	ds_write_b16_d16_hi v75, v32 offset:29632
	v_bfe_u32 v32, v45, 16, 1
	v_add3_u32 v32, v45, v32, s60
	ds_write_b16_d16_hi v75, v32 offset:30160
	v_bfe_u32 v32, v46, 16, 1
	v_add3_u32 v32, v46, v32, s60
	ds_write_b16_d16_hi v75, v32 offset:30688
	v_bfe_u32 v32, v47, 16, 1
	v_add3_u32 v32, v47, v32, s60
	ds_write_b16_d16_hi v75, v32 offset:31216
	v_lshl_add_u32 v32, s13, 8, v64
	s_ashr_i32 s13, s12, 31
	v_bfe_u32 v37, v16, 16, 1
	s_lshl_b64 s[0:1], s[12:13], 1
	v_add3_u32 v16, v16, v37, s60
	v_bfe_u32 v37, v17, 16, 1
	s_add_u32 s0, s8, s0
	v_lshrrev_b32_e32 v16, 16, v16
	v_add3_u32 v17, v17, v37, s60
	s_addc_u32 s1, s9, s1
	v_lshlrev_b32_e32 v64, 1, v74
	v_and_or_b32 v16, v17, s56, v16
	v_bfe_u32 v17, v18, 16, 1
	v_or_b32_e32 v36, v32, v80
	v_lshl_add_u64 v[32:33], s[0:1], 0, v[64:65]
	s_mov_b64 s[0:1], 0x144d7900
	v_add3_u32 v17, v18, v17, s60
	v_bfe_u32 v18, v19, 16, 1
	v_lshl_add_u64 v[32:33], v[32:33], 0, s[0:1]
	v_lshrrev_b32_e32 v17, 16, v17
	v_add3_u32 v18, v19, v18, s60
	v_mad_i64_i32 v[34:35], s[0:1], v36, s63, v[32:33]
	v_and_or_b32 v17, v18, s56, v17
	global_store_dwordx2 v[34:35], v[16:17], off
	v_bfe_u32 v16, v20, 16, 1
	v_add3_u32 v16, v20, v16, s60
	v_bfe_u32 v17, v21, 16, 1
	v_lshrrev_b32_e32 v16, 16, v16
	v_add3_u32 v17, v21, v17, s60
	v_and_or_b32 v16, v17, s56, v16
	v_bfe_u32 v17, v22, 16, 1
	v_add3_u32 v17, v22, v17, s60
	v_bfe_u32 v18, v23, 16, 1
	v_lshrrev_b32_e32 v17, 16, v17
	v_add3_u32 v18, v23, v18, s60
	v_and_or_b32 v17, v18, s56, v17
	global_store_dwordx2 v[34:35], v[16:17], off offset:16
	v_bfe_u32 v16, v24, 16, 1
	v_add3_u32 v16, v24, v16, s60
	v_bfe_u32 v17, v25, 16, 1
	v_lshrrev_b32_e32 v16, 16, v16
	v_add3_u32 v17, v25, v17, s60
	v_and_or_b32 v16, v17, s56, v16
	v_bfe_u32 v17, v26, 16, 1
	v_add3_u32 v17, v26, v17, s60
	v_bfe_u32 v18, v27, 16, 1
	v_lshrrev_b32_e32 v17, 16, v17
	v_add3_u32 v18, v27, v18, s60
	v_and_or_b32 v17, v18, s56, v17
	global_store_dwordx2 v[34:35], v[16:17], off offset:32
	v_bfe_u32 v16, v28, 16, 1
	v_add3_u32 v16, v28, v16, s60
	v_bfe_u32 v17, v29, 16, 1
	v_lshrrev_b32_e32 v16, 16, v16
	v_add3_u32 v17, v29, v17, s60
	v_and_or_b32 v16, v17, s56, v16
	v_bfe_u32 v17, v30, 16, 1
	v_add3_u32 v17, v30, v17, s60
	v_bfe_u32 v18, v31, 16, 1
	v_lshrrev_b32_e32 v17, 16, v17
	v_add3_u32 v18, v31, v18, s60
	v_and_or_b32 v17, v18, s56, v17
	v_bfe_u32 v18, v0, 16, 1
	v_add3_u32 v0, v0, v18, s60
	v_bfe_u32 v18, v1, 16, 1
	v_lshrrev_b32_e32 v0, 16, v0
	v_add3_u32 v1, v1, v18, s60
	v_and_or_b32 v0, v1, s56, v0
	v_bfe_u32 v1, v2, 16, 1
	v_add3_u32 v1, v2, v1, s60
	v_bfe_u32 v2, v3, 16, 1
	global_store_dwordx2 v[34:35], v[16:17], off offset:48
	v_or_b32_e32 v16, 32, v36
	v_lshrrev_b32_e32 v1, 16, v1
	v_add3_u32 v2, v3, v2, s60
	v_mad_i64_i32 v[16:17], s[0:1], v16, s63, v[32:33]
	v_and_or_b32 v1, v2, s56, v1
	global_store_dwordx2 v[16:17], v[0:1], off
	v_bfe_u32 v0, v4, 16, 1
	v_add3_u32 v0, v4, v0, s60
	v_bfe_u32 v1, v5, 16, 1
	v_lshrrev_b32_e32 v0, 16, v0
	v_add3_u32 v1, v5, v1, s60
	v_and_or_b32 v0, v1, s56, v0
	v_bfe_u32 v1, v6, 16, 1
	v_add3_u32 v1, v6, v1, s60
	v_bfe_u32 v2, v7, 16, 1
	v_lshrrev_b32_e32 v1, 16, v1
	v_add3_u32 v2, v7, v2, s60
	v_and_or_b32 v1, v2, s56, v1
	global_store_dwordx2 v[16:17], v[0:1], off offset:16
	v_bfe_u32 v0, v8, 16, 1
	v_add3_u32 v0, v8, v0, s60
	v_bfe_u32 v1, v9, 16, 1
	v_lshrrev_b32_e32 v0, 16, v0
	v_add3_u32 v1, v9, v1, s60
	v_and_or_b32 v0, v1, s56, v0
	v_bfe_u32 v1, v10, 16, 1
	v_add3_u32 v1, v10, v1, s60
	v_bfe_u32 v2, v11, 16, 1
	v_lshrrev_b32_e32 v1, 16, v1
	v_add3_u32 v2, v11, v2, s60
	v_and_or_b32 v1, v2, s56, v1
	global_store_dwordx2 v[16:17], v[0:1], off offset:32
	v_bfe_u32 v0, v12, 16, 1
	v_add3_u32 v0, v12, v0, s60
	v_bfe_u32 v1, v13, 16, 1
	v_lshrrev_b32_e32 v0, 16, v0
	v_add3_u32 v1, v13, v1, s60
	v_and_or_b32 v0, v1, s56, v0
	v_bfe_u32 v1, v14, 16, 1
	v_add3_u32 v1, v14, v1, s60
	v_bfe_u32 v2, v15, 16, 1
	v_lshrrev_b32_e32 v1, 16, v1
	v_add3_u32 v2, v15, v2, s60
	v_and_or_b32 v1, v2, s56, v1
	v_and_b32_e32 v64, 0x1f0, v78
	global_store_dwordx2 v[16:17], v[0:1], off offset:48
	v_mad_u64_u32 v[0:1], s[0:1], v81, s64, v[64:65]
	s_waitcnt lgkmcnt(0)
	s_barrier
	ds_read_b128 v[0:3], v0 offset:16896
	v_lshl_add_u64 v[4:5], s[8:9], 0, v[64:65]
	s_mov_b64 s[0:1], 0x13097900
	v_lshl_add_u64 v[4:5], v[4:5], 0, s[0:1]
	v_lshlrev_b64 v[6:7], 9, v[66:67]
	v_lshl_add_u64 v[6:7], v[4:5], 0, v[6:7]
	s_waitcnt lgkmcnt(0)
	global_store_dwordx4 v[6:7], v[0:3], off
	v_lshlrev_b64 v[6:7], 9, v[68:69]
	v_lshl_add_u64 v[6:7], v[4:5], 0, v[6:7]
	v_mad_u64_u32 v[0:1], s[0:1], v82, s64, v[64:65]
	ds_read_b128 v[0:3], v0 offset:16896
	s_mov_b64 s[4:5], 0
	s_waitcnt lgkmcnt(0)
	global_store_dwordx4 v[6:7], v[0:3], off
	s_nop 1
	v_mad_u64_u32 v[0:1], s[0:1], v83, s64, v[64:65]
	ds_read_b128 v[0:3], v0 offset:16896
	v_lshlrev_b64 v[6:7], 9, v[70:71]
	v_lshl_add_u64 v[6:7], v[4:5], 0, v[6:7]
	s_waitcnt lgkmcnt(0)
	global_store_dwordx4 v[6:7], v[0:3], off
	s_nop 1
	v_mad_u64_u32 v[0:1], s[0:1], v84, s64, v[64:65]
	ds_read_b128 v[0:3], v0 offset:16896
	v_lshlrev_b64 v[6:7], 9, v[72:73]
	v_lshl_add_u64 v[4:5], v[4:5], 0, v[6:7]
	s_waitcnt lgkmcnt(0)
	global_store_dwordx4 v[4:5], v[0:3], off
.LBB0_1370:
	s_and_b64 vcc, exec, s[4:5]
	s_cbranch_vccz .LBB0_1417
	s_mov_b64 s[0:1], s[30:31]
	v_mov_b32_e32 v0, v65
	s_nop 0
	v_mbcnt_lo_u32_b32 v0, -1, v0
	v_mbcnt_hi_u32_b32 v0, -1, v0
	v_add_u32_e32 v48, s33, v0
	v_mov_b64_e32 v[0:1], s[0:1]
	v_ashrrev_i32_e32 v49, 3, v48
	v_add_u32_e32 v2, s27, v49
	v_mad_i64_i32 v[0:1], s[4:5], v2, s34, v[0:1]
	v_mov_b32_e32 v2, s0
	v_mov_b32_e32 v3, s1
	v_add_co_u32_e32 v2, vcc, s57, v2
	v_lshlrev_b32_e32 v4, 5, v48
	s_nop 0
	v_addc_co_u32_e32 v3, vcc, 0, v3, vcc
	global_load_dwordx2 v[2:3], v[2:3], off offset:488
	v_and_b32_e32 v10, 0xe0, v4
	v_lshlrev_b32_e32 v64, 1, v10
	v_lshl_add_u64 v[0:1], v[0:1], 0, v[64:65]
	s_mov_b64 s[4:5], 0x7157f00
	v_lshl_add_u64 v[8:9], v[0:1], 0, s[4:5]
	s_mov_b32 s4, 0x7157000
	v_add_co_u32_e32 v0, vcc, s4, v0
	global_load_dwordx4 v[4:7], v[8:9], off offset:48
	global_load_dwordx4 v[12:15], v[8:9], off offset:16
	global_load_dwordx4 v[16:19], v[8:9], off offset:32
	v_addc_co_u32_e32 v1, vcc, 0, v1, vcc
	global_load_dwordx4 v[20:23], v[0:1], off offset:3840
	v_mov_b32_e32 v1, v65
	v_lshlrev_b32_e32 v0, 2, v10
	s_waitcnt lgkmcnt(0)
	s_barrier
	s_waitcnt vmcnt(0)
	v_readfirstlane_b32 s5, v3
	v_readfirstlane_b32 s4, v2
	v_and_b32_e32 v3, 0xffff0000, v5
	s_nop 0
	v_lshl_add_u64 v[10:11], s[4:5], 0, v[0:1]
	global_load_dwordx4 v[24:27], v[10:11], off offset:1024
	global_load_dwordx4 v[28:31], v[10:11], off offset:1040
	v_lshlrev_b32_e32 v41, 16, v17
	v_lshlrev_b32_e32 v40, 16, v16
	v_and_b32_e32 v43, 0xffff0000, v17
	v_and_b32_e32 v42, 0xffff0000, v16
	v_and_b32_e32 v17, 0xffff0000, v21
	v_and_b32_e32 v16, 0xffff0000, v20
	v_lshlrev_b32_e32 v37, 16, v15
	v_lshlrev_b32_e32 v36, 16, v14
	v_and_b32_e32 v39, 0xffff0000, v15
	v_and_b32_e32 v38, 0xffff0000, v14
	v_lshlrev_b32_e32 v15, 16, v21
	v_lshlrev_b32_e32 v14, 16, v20
	v_and_b32_e32 v21, 0xffff0000, v23
	v_and_b32_e32 v20, 0xffff0000, v22
	v_pk_mul_f32 v[56:57], v[16:17], v[16:17]
	v_lshlrev_b32_e32 v45, 16, v19
	v_lshlrev_b32_e32 v44, 16, v18
	v_and_b32_e32 v47, 0xffff0000, v19
	v_and_b32_e32 v46, 0xffff0000, v18
	v_lshlrev_b32_e32 v19, 16, v23
	v_lshlrev_b32_e32 v18, 16, v22
	v_pk_mul_f32 v[58:59], v[20:21], v[20:21]
	v_pk_fma_f32 v[56:57], v[14:15], v[14:15], v[56:57]
	v_and_b32_e32 v35, 0xffff0000, v13
	v_and_b32_e32 v34, 0xffff0000, v12
	v_pk_fma_f32 v[58:59], v[18:19], v[18:19], v[58:59]
	v_add_f32_e32 v56, v56, v57
	v_lshlrev_b32_e32 v33, 16, v13
	v_lshlrev_b32_e32 v32, 16, v12
	v_pk_mul_f32 v[22:23], v[34:35], v[34:35]
	v_add_f32_e32 v56, v58, v56
	v_pk_fma_f32 v[22:23], v[32:33], v[32:33], v[22:23]
	v_add_f32_e32 v56, v59, v56
	v_pk_mul_f32 v[50:51], v[38:39], v[38:39]
	v_add_f32_e32 v22, v22, v56
	v_pk_fma_f32 v[50:51], v[36:37], v[36:37], v[50:51]
	v_add_f32_e32 v22, v23, v22
	v_pk_mul_f32 v[52:53], v[42:43], v[42:43]
	v_add_f32_e32 v22, v50, v22
	v_pk_fma_f32 v[52:53], v[40:41], v[40:41], v[52:53]
	v_add_f32_e32 v22, v51, v22
	v_pk_mul_f32 v[54:55], v[46:47], v[46:47]
	v_add_f32_e32 v22, v52, v22
	v_and_b32_e32 v2, 0xffff0000, v4
	v_pk_fma_f32 v[54:55], v[44:45], v[44:45], v[54:55]
	v_add_f32_e32 v22, v53, v22
	v_lshlrev_b32_e32 v1, 16, v5
	v_lshlrev_b32_e32 v0, 16, v4
	v_pk_mul_f32 v[8:9], v[2:3], v[2:3]
	v_add_f32_e32 v22, v54, v22
	v_lshlrev_b32_e32 v5, 16, v7
	v_lshlrev_b32_e32 v4, 16, v6
	v_and_b32_e32 v7, 0xffff0000, v7
	v_and_b32_e32 v6, 0xffff0000, v6
	v_pk_fma_f32 v[8:9], v[0:1], v[0:1], v[8:9]
	v_add_f32_e32 v22, v55, v22
	v_pk_mul_f32 v[12:13], v[6:7], v[6:7]
	v_add_f32_e32 v8, v8, v22
	v_pk_fma_f32 v[12:13], v[4:5], v[4:5], v[12:13]
	v_add_f32_e32 v8, v9, v8
	v_add_f32_e32 v8, v12, v8
	v_add_f32_e32 v8, v13, v8
	v_and_b32_e32 v57, 31, v48
	s_waitcnt vmcnt(0) lgkmcnt(0)
	v_mov_b32_e32 v22, v24
	v_add_f32_dpp v8, v8, v8 quad_perm:[1,0,3,2] row_mask:0xf bank_mask:0xf bound_ctrl:1
	v_mov_b32_e32 v23, v26
	v_mov_b32_e32 v26, v25
	v_add_f32_dpp v8, v8, v8 quad_perm:[2,3,0,1] row_mask:0xf bank_mask:0xf bound_ctrl:1
	v_mov_b32_e32 v24, v28
	v_mov_b32_e32 v25, v30
	v_add_f32_dpp v8, v8, v8 row_half_mirror row_mask:0xf bank_mask:0xf bound_ctrl:1
	v_fmamk_f32 v8, v8, 0x3b800000, v127
	v_mul_f32_e32 v9, 0x4b800000, v8
	v_cmp_gt_f32_e32 vcc, s59, v8
	v_mov_b32_e32 v30, v29
	s_nop 0
	v_cndmask_b32_e32 v8, v8, v9, vcc
	v_rsq_f32_e32 v12, v8
	v_mad_u64_u32 v[8:9], s[4:5], v49, s64, v[64:65]
	s_movk_i32 s4, 0x60
	v_mul_f32_e32 v9, 0x45800000, v12
	v_cndmask_b32_e32 v12, v12, v9, vcc
	v_pk_mul_f32 v[14:15], v[12:13], v[14:15] op_sel_hi:[0,1]
	v_pk_mul_f32 v[16:17], v[12:13], v[16:17] op_sel_hi:[0,1]
	v_pk_mul_f32 v[18:19], v[12:13], v[18:19] op_sel_hi:[0,1]
	v_pk_mul_f32 v[20:21], v[12:13], v[20:21] op_sel_hi:[0,1]
	v_pk_mul_f32 v[14:15], v[22:23], v[14:15]
	v_pk_mul_f32 v[16:17], v[26:27], v[16:17]
	v_pk_mul_f32 v[18:19], v[24:25], v[18:19]
	v_pk_mul_f32 v[20:21], v[30:31], v[20:21]
	v_bfe_u32 v22, v17, 16, 1
	v_bfe_u32 v23, v16, 16, 1
	v_bfe_u32 v24, v14, 16, 1
	v_bfe_u32 v25, v15, 16, 1
	v_bfe_u32 v26, v18, 16, 1
	v_bfe_u32 v27, v19, 16, 1
	v_bfe_u32 v9, v21, 16, 1
	v_bfe_u32 v13, v20, 16, 1
	v_add3_u32 v23, v16, v23, s60
	v_add3_u32 v22, v17, v22, s60
	v_add3_u32 v16, v19, v27, s60
	v_add3_u32 v17, v18, v26, s60
	v_add3_u32 v15, v15, v25, s60
	v_add3_u32 v14, v14, v24, s60
	v_add3_u32 v13, v20, v13, s60
	v_add3_u32 v9, v21, v9, s60
	v_lshrrev_b32_e32 v14, 16, v14
	v_lshrrev_b32_e32 v15, 16, v15
	v_lshrrev_b32_e32 v18, 16, v17
	v_lshrrev_b32_e32 v16, 16, v16
	v_and_or_b32 v17, v9, s56, v16
	v_and_or_b32 v16, v13, s56, v18
	v_and_or_b32 v15, v22, s56, v15
	v_and_or_b32 v14, v23, s56, v14
	ds_write_b128 v8, v[14:17]
	global_load_dwordx4 v[14:17], v[10:11], off offset:1056
	global_load_dwordx4 v[18:21], v[10:11], off offset:1072
	v_pk_mul_f32 v[22:23], v[12:13], v[32:33] op_sel_hi:[0,1]
	v_pk_mul_f32 v[24:25], v[12:13], v[34:35] op_sel_hi:[0,1]
	v_pk_mul_f32 v[26:27], v[12:13], v[36:37] op_sel_hi:[0,1]
	v_pk_mul_f32 v[28:29], v[12:13], v[38:39] op_sel_hi:[0,1]
	s_mov_b32 s5, 0x16e0000
	s_waitcnt vmcnt(0) lgkmcnt(0)
	v_mov_b32_e32 v30, v14
	v_mov_b32_e32 v31, v16
	v_mov_b32_e32 v16, v15
	v_mov_b32_e32 v14, v18
	v_mov_b32_e32 v15, v20
	v_mov_b32_e32 v20, v19
	v_pk_mul_f32 v[18:19], v[30:31], v[22:23]
	v_pk_mul_f32 v[16:17], v[16:17], v[24:25]
	v_pk_mul_f32 v[14:15], v[14:15], v[26:27]
	v_pk_mul_f32 v[20:21], v[20:21], v[28:29]
	v_bfe_u32 v22, v17, 16, 1
	v_bfe_u32 v23, v16, 16, 1
	v_bfe_u32 v24, v18, 16, 1
	v_bfe_u32 v25, v19, 16, 1
	v_bfe_u32 v26, v14, 16, 1
	v_bfe_u32 v27, v15, 16, 1
	v_bfe_u32 v9, v21, 16, 1
	v_bfe_u32 v13, v20, 16, 1
	v_add3_u32 v23, v16, v23, s60
	v_add3_u32 v22, v17, v22, s60
	v_add3_u32 v15, v15, v27, s60
	v_add3_u32 v14, v14, v26, s60
	v_add3_u32 v16, v19, v25, s60
	v_add3_u32 v17, v18, v24, s60
	v_add3_u32 v13, v20, v13, s60
	v_add3_u32 v9, v21, v9, s60
	v_lshrrev_b32_e32 v18, 16, v17
	v_lshrrev_b32_e32 v19, 16, v16
	v_lshrrev_b32_e32 v14, 16, v14
	v_lshrrev_b32_e32 v15, 16, v15
	v_and_or_b32 v17, v9, s56, v15
	v_and_or_b32 v16, v13, s56, v14
	v_and_or_b32 v15, v22, s56, v19
	v_and_or_b32 v14, v23, s56, v18
	ds_write_b128 v8, v[14:17] offset:16
	global_load_dwordx4 v[14:17], v[10:11], off offset:1088
	global_load_dwordx4 v[18:21], v[10:11], off offset:1104
	v_pk_mul_f32 v[22:23], v[12:13], v[40:41] op_sel_hi:[0,1]
	v_pk_mul_f32 v[24:25], v[12:13], v[42:43] op_sel_hi:[0,1]
	v_pk_mul_f32 v[26:27], v[12:13], v[44:45] op_sel_hi:[0,1]
	v_pk_mul_f32 v[28:29], v[12:13], v[46:47] op_sel_hi:[0,1]
	s_waitcnt vmcnt(0) lgkmcnt(0)
	v_mov_b32_e32 v30, v14
	v_mov_b32_e32 v31, v16
	v_mov_b32_e32 v16, v15
	v_mov_b32_e32 v14, v18
	v_mov_b32_e32 v15, v20
	v_mov_b32_e32 v20, v19
	v_pk_mul_f32 v[18:19], v[30:31], v[22:23]
	v_pk_mul_f32 v[16:17], v[16:17], v[24:25]
	v_pk_mul_f32 v[14:15], v[26:27], v[14:15]
	v_pk_mul_f32 v[20:21], v[28:29], v[20:21]
	v_bfe_u32 v22, v17, 16, 1
	v_bfe_u32 v23, v16, 16, 1
	v_bfe_u32 v24, v18, 16, 1
	v_bfe_u32 v25, v19, 16, 1
	v_bfe_u32 v26, v14, 16, 1
	v_bfe_u32 v27, v15, 16, 1
	v_bfe_u32 v9, v21, 16, 1
	v_bfe_u32 v13, v20, 16, 1
	v_add3_u32 v23, v16, v23, s60
	v_add3_u32 v22, v17, v22, s60
	v_add3_u32 v15, v15, v27, s60
	v_add3_u32 v14, v14, v26, s60
	v_add3_u32 v16, v19, v25, s60
	v_add3_u32 v17, v18, v24, s60
	v_add3_u32 v13, v20, v13, s60
	v_add3_u32 v9, v21, v9, s60
	v_lshrrev_b32_e32 v18, 16, v17
	v_lshrrev_b32_e32 v19, 16, v16
	v_lshrrev_b32_e32 v14, 16, v14
	v_lshrrev_b32_e32 v15, 16, v15
	v_and_or_b32 v17, v9, s56, v15
	v_and_or_b32 v16, v13, s56, v14
	v_and_or_b32 v15, v22, s56, v19
	v_and_or_b32 v14, v23, s56, v18
	ds_write_b128 v8, v[14:17] offset:32
	global_load_dwordx4 v[14:17], v[10:11], off offset:1120
	global_load_dwordx4 v[18:21], v[10:11], off offset:1136
	v_ashrrev_i32_e32 v10, 6, v48
	v_mul_lo_u32 v56, v10, s4
	v_pk_mul_f32 v[0:1], v[12:13], v[0:1] op_sel_hi:[0,1]
	v_pk_mul_f32 v[2:3], v[12:13], v[2:3] op_sel_hi:[0,1]
	v_pk_mul_f32 v[4:5], v[12:13], v[4:5] op_sel_hi:[0,1]
	v_pk_mul_f32 v[6:7], v[12:13], v[6:7] op_sel_hi:[0,1]
	v_mov_b32_e32 v9, v65
	s_mov_b32 s4, 0x16e4000
	s_waitcnt vmcnt(0) lgkmcnt(0)
	v_mov_b32_e32 v10, v14
	v_mov_b32_e32 v11, v16
	v_mov_b32_e32 v12, v18
	v_mov_b32_e32 v13, v20
	v_mov_b32_e32 v16, v15
	v_mov_b32_e32 v20, v19
	v_pk_mul_f32 v[0:1], v[0:1], v[10:11]
	v_pk_mul_f32 v[4:5], v[4:5], v[12:13]
	v_pk_mul_f32 v[2:3], v[2:3], v[16:17]
	v_pk_mul_f32 v[6:7], v[6:7], v[20:21]
	v_bfe_u32 v14, v0, 16, 1
	v_bfe_u32 v15, v1, 16, 1
	v_bfe_u32 v16, v4, 16, 1
	v_bfe_u32 v17, v5, 16, 1
	v_bfe_u32 v10, v7, 16, 1
	v_bfe_u32 v11, v6, 16, 1
	v_bfe_u32 v12, v3, 16, 1
	v_bfe_u32 v13, v2, 16, 1
	v_add3_u32 v5, v5, v17, s60
	v_add3_u32 v4, v4, v16, s60
	v_add3_u32 v1, v1, v15, s60
	v_add3_u32 v0, v0, v14, s60
	v_add3_u32 v13, v2, v13, s60
	v_add3_u32 v12, v3, v12, s60
	v_add3_u32 v2, v6, v11, s60
	v_add3_u32 v3, v7, v10, s60
	v_lshrrev_b32_e32 v0, 16, v0
	v_lshrrev_b32_e32 v1, 16, v1
	v_lshrrev_b32_e32 v4, 16, v4
	v_lshrrev_b32_e32 v5, 16, v5
	v_and_or_b32 v3, v3, s56, v5
	v_and_or_b32 v2, v2, s56, v4
	v_and_or_b32 v1, v12, s56, v1
	v_and_or_b32 v0, v13, s56, v0
	ds_write_b128 v8, v[0:3] offset:48
	s_waitcnt lgkmcnt(0)
	s_barrier
	s_nop 0
	v_mbcnt_lo_u32_b32 v0, -1, v9
	v_mbcnt_hi_u32_b32 v0, -1, v0
	v_and_b32_e32 v14, 31, v0
	v_ashrrev_i32_e32 v1, 2, v0
	v_or_b32_e32 v0, v14, v56
	v_and_b32_e32 v12, -8, v1
	v_ashrrev_i32_e32 v1, 31, v0
	v_lshlrev_b64 v[0:1], 9, v[0:1]
	v_ashrrev_i32_e32 v13, 31, v12
	v_lshl_add_u64 v[0:1], s[0:1], 0, v[0:1]
	v_lshl_add_u64 v[16:17], v[12:13], 1, v[0:1]
	v_add_co_u32_e32 v0, vcc, s5, v16
	v_lshlrev_b32_e32 v12, 1, v12
	s_nop 0
	v_addc_co_u32_e32 v1, vcc, 0, v17, vcc
	global_load_dwordx4 v[208:211], v[0:1], off
	v_add_co_u32_e32 v50, vcc, s4, v16
	s_mov_b32 s4, 0x16e8000
	s_nop 0
	v_addc_co_u32_e32 v51, vcc, 0, v17, vcc
	v_add_co_u32_e32 v52, vcc, s4, v16
	s_mov_b64 s[4:5], 0x16e0000
	v_lshl_add_u64 v[54:55], v[16:17], 0, s[4:5]
	global_load_dwordx4 v[212:215], v[54:55], off offset:32
	global_load_dwordx4 v[216:219], v[50:51], off
	v_mad_u32_u24 v49, v14, s64, v12
	ds_read_b128 v[12:15], v49
	ds_read_b128 v[66:69], v49 offset:32
	v_addc_co_u32_e32 v53, vcc, 0, v17, vcc
	global_load_dwordx4 v[220:223], v[52:53], off
	global_load_dwordx4 v[224:227], v[50:51], off offset:32
	global_load_dwordx4 v[228:231], v[52:53], off offset:32
	global_load_dwordx4 v[232:235], v[50:51], off offset:96
	global_load_dwordx4 v[236:239], v[54:55], off offset:64
	global_load_dwordx4 v[240:243], v[50:51], off offset:64
	global_load_dwordx4 v[244:247], v[52:53], off offset:64
	global_load_dwordx4 v[248:251], v[54:55], off offset:96
	s_waitcnt lgkmcnt(0)
	s_waitcnt vmcnt(10)
	v_mfma_f32_32x32x16_bf16 v[32:47], v[12:15], v[208:211], 0
	global_load_dwordx4 v[208:211], v[52:53], off offset:96
	s_and_b32 s4, 0xffff, s26
	s_mul_i32 s4, s4, 0xe38f
	s_lshr_b32 s4, s4, 22
	s_mulk_i32 s4, 0xf700
	s_add_i32 s4, s4, s27
	s_waitcnt vmcnt(10)
	v_mfma_f32_32x32x16_bf16 v[32:47], v[66:69], v[212:215], v[32:47]
	global_load_dwordx4 v[212:215], v[54:55], off offset:128
	s_waitcnt vmcnt(10)
	v_mfma_f32_32x32x16_bf16 v[16:31], v[12:15], v[216:219], 0
	global_load_dwordx4 v[216:219], v[50:51], off offset:128
	s_waitcnt vmcnt(10)
	v_mfma_f32_32x32x16_bf16 v[0:15], v[12:15], v[220:223], 0
	global_load_dwordx4 v[220:223], v[52:53], off offset:128
	s_waitcnt vmcnt(10)
	v_mfma_f32_32x32x16_bf16 v[16:31], v[66:69], v[224:227], v[16:31]
	global_load_dwordx4 v[224:227], v[54:55], off offset:160
	s_waitcnt lgkmcnt(0)
	s_waitcnt vmcnt(10)
	v_mfma_f32_32x32x16_bf16 v[0:15], v[66:69], v[228:231], v[0:15]
	global_load_dwordx4 v[228:231], v[50:51], off offset:160
	ds_read_b128 v[66:69], v49 offset:64
	ds_read_b128 v[74:77], v49 offset:96
	s_waitcnt lgkmcnt(1)
	s_waitcnt vmcnt(8)
	v_mfma_f32_32x32x16_bf16 v[16:31], v[66:69], v[240:243], v[16:31]
	v_mfma_f32_32x32x16_bf16 v[32:47], v[66:69], v[236:239], v[32:47]
	s_waitcnt lgkmcnt(0)
	s_waitcnt vmcnt(6)
	v_mfma_f32_32x32x16_bf16 v[32:47], v[74:77], v[248:251], v[32:47]
	v_mfma_f32_32x32x16_bf16 v[0:15], v[66:69], v[244:247], v[0:15]
	v_mfma_f32_32x32x16_bf16 v[16:31], v[74:77], v[232:235], v[16:31]
	global_load_dwordx4 v[232:235], v[52:53], off offset:160
	global_load_dwordx4 v[236:239], v[54:55], off offset:192
	global_load_dwordx4 v[240:243], v[50:51], off offset:192
	global_load_dwordx4 v[244:247], v[52:53], off offset:192
	global_load_dwordx4 v[248:251], v[54:55], off offset:224
	s_waitcnt lgkmcnt(0)
	s_waitcnt vmcnt(10)
	v_mfma_f32_32x32x16_bf16 v[0:15], v[74:77], v[208:211], v[0:15]
	global_load_dwordx4 v[208:211], v[50:51], off offset:224
	ds_read_b128 v[78:81], v49 offset:128
	ds_read_b128 v[82:85], v49 offset:160
	s_waitcnt lgkmcnt(0)
	s_waitcnt vmcnt(10)
	v_mfma_f32_32x32x16_bf16 v[32:47], v[78:81], v[212:215], v[32:47]
	global_load_dwordx4 v[212:215], v[52:53], off offset:224
	s_waitcnt vmcnt(10)
	v_mfma_f32_32x32x16_bf16 v[16:31], v[78:81], v[216:219], v[16:31]
	global_load_dwordx4 v[216:219], v[54:55], off offset:256
	s_waitcnt vmcnt(10)
	v_mfma_f32_32x32x16_bf16 v[0:15], v[78:81], v[220:223], v[0:15]
	global_load_dwordx4 v[220:223], v[50:51], off offset:256
	ds_read_b128 v[78:81], v49 offset:192
	s_waitcnt vmcnt(10)
	v_mfma_f32_32x32x16_bf16 v[32:47], v[82:85], v[224:227], v[32:47]
	global_load_dwordx4 v[224:227], v[52:53], off offset:256
	s_waitcnt lgkmcnt(0)
	s_waitcnt vmcnt(10)
	v_mfma_f32_32x32x16_bf16 v[16:31], v[82:85], v[228:231], v[16:31]
	global_load_dwordx4 v[228:231], v[54:55], off offset:288
	s_waitcnt vmcnt(10)
	v_mfma_f32_32x32x16_bf16 v[0:15], v[82:85], v[232:235], v[0:15]
	global_load_dwordx4 v[232:235], v[50:51], off offset:288
	ds_read_b128 v[82:85], v49 offset:224
	s_waitcnt vmcnt(10)
	v_mfma_f32_32x32x16_bf16 v[32:47], v[78:81], v[236:239], v[32:47]
	global_load_dwordx4 v[236:239], v[52:53], off offset:288
	s_waitcnt vmcnt(10)
	v_mfma_f32_32x32x16_bf16 v[16:31], v[78:81], v[240:243], v[16:31]
	global_load_dwordx4 v[240:243], v[54:55], off offset:320
	s_waitcnt lgkmcnt(0)
	s_waitcnt vmcnt(10)
	v_mfma_f32_32x32x16_bf16 v[0:15], v[78:81], v[244:247], v[0:15]
	global_load_dwordx4 v[244:247], v[50:51], off offset:320
	s_waitcnt vmcnt(9)
	v_mfma_f32_32x32x16_bf16 v[16:31], v[82:85], v[208:211], v[16:31]
	s_waitcnt vmcnt(8)
	v_mfma_f32_32x32x16_bf16 v[0:15], v[82:85], v[212:215], v[0:15]
	v_mfma_f32_32x32x16_bf16 v[32:47], v[82:85], v[248:251], v[32:47]
	global_load_dwordx4 v[248:251], v[52:53], off offset:320
	global_load_dwordx4 v[208:211], v[54:55], off offset:352
	global_load_dwordx4 v[212:215], v[50:51], off offset:352
	ds_read_b128 v[78:81], v49 offset:256
	ds_read_b128 v[82:85], v49 offset:288
	s_waitcnt lgkmcnt(0)
	s_waitcnt vmcnt(10)
	v_mfma_f32_32x32x16_bf16 v[32:47], v[78:81], v[216:219], v[32:47]
	global_load_dwordx4 v[216:219], v[52:53], off offset:352
	s_waitcnt vmcnt(10)
	v_mfma_f32_32x32x16_bf16 v[16:31], v[78:81], v[220:223], v[16:31]
	global_load_dwordx4 v[220:223], v[54:55], off offset:384
	s_waitcnt vmcnt(10)
	v_mfma_f32_32x32x16_bf16 v[0:15], v[78:81], v[224:227], v[0:15]
	global_load_dwordx4 v[224:227], v[50:51], off offset:384
	ds_read_b128 v[78:81], v49 offset:320
	s_waitcnt vmcnt(10)
	v_mfma_f32_32x32x16_bf16 v[32:47], v[82:85], v[228:231], v[32:47]
	global_load_dwordx4 v[228:231], v[52:53], off offset:384
	s_waitcnt lgkmcnt(0)
	s_waitcnt vmcnt(10)
	v_mfma_f32_32x32x16_bf16 v[16:31], v[82:85], v[232:235], v[16:31]
	global_load_dwordx4 v[232:235], v[54:55], off offset:416
	s_waitcnt vmcnt(10)
	v_mfma_f32_32x32x16_bf16 v[0:15], v[82:85], v[236:239], v[0:15]
	global_load_dwordx4 v[236:239], v[50:51], off offset:416
	ds_read_b128 v[82:85], v49 offset:352
	s_waitcnt vmcnt(10)
	v_mfma_f32_32x32x16_bf16 v[32:47], v[78:81], v[240:243], v[32:47]
	global_load_dwordx4 v[240:243], v[52:53], off offset:416
	s_waitcnt vmcnt(10)
	v_mfma_f32_32x32x16_bf16 v[16:31], v[78:81], v[244:247], v[16:31]
	global_load_dwordx4 v[244:247], v[54:55], off offset:448
	s_waitcnt lgkmcnt(0)
	s_waitcnt vmcnt(10)
	v_mfma_f32_32x32x16_bf16 v[0:15], v[78:81], v[248:251], v[0:15]
	global_load_dwordx4 v[248:251], v[50:51], off offset:448
	s_waitcnt vmcnt(9)
	v_mfma_f32_32x32x16_bf16 v[16:31], v[82:85], v[212:215], v[16:31]
	s_waitcnt vmcnt(8)
	v_mfma_f32_32x32x16_bf16 v[0:15], v[82:85], v[216:219], v[0:15]
	v_mfma_f32_32x32x16_bf16 v[32:47], v[82:85], v[208:211], v[32:47]
	global_load_dwordx4 v[208:211], v[52:53], off offset:448
	global_load_dwordx4 v[212:215], v[54:55], off offset:480
	global_load_dwordx4 v[216:219], v[50:51], off offset:480
	ds_read_b128 v[78:81], v49 offset:384
	ds_read_b128 v[82:85], v49 offset:416
	s_waitcnt lgkmcnt(0)
	s_waitcnt vmcnt(10)
	v_mfma_f32_32x32x16_bf16 v[32:47], v[78:81], v[220:223], v[32:47]
	global_load_dwordx4 v[220:223], v[52:53], off offset:480
	s_waitcnt vmcnt(10)
	v_mfma_f32_32x32x16_bf16 v[16:31], v[78:81], v[224:227], v[16:31]
	s_waitcnt vmcnt(9)
	v_mfma_f32_32x32x16_bf16 v[0:15], v[78:81], v[228:231], v[0:15]
	ds_read_b128 v[78:81], v49 offset:448
	s_waitcnt vmcnt(8)
	v_mfma_f32_32x32x16_bf16 v[32:47], v[82:85], v[232:235], v[32:47]
	s_waitcnt lgkmcnt(0)
	s_waitcnt vmcnt(7)
	v_mfma_f32_32x32x16_bf16 v[16:31], v[82:85], v[236:239], v[16:31]
	s_waitcnt vmcnt(6)
	v_mfma_f32_32x32x16_bf16 v[0:15], v[82:85], v[240:243], v[0:15]
	ds_read_b128 v[82:85], v49 offset:480
	s_waitcnt vmcnt(5)
	v_mfma_f32_32x32x16_bf16 v[32:47], v[78:81], v[244:247], v[32:47]
	s_nop 0
	s_waitcnt vmcnt(4)
	v_mfma_f32_32x32x16_bf16 v[16:31], v[78:81], v[248:251], v[16:31]
	s_waitcnt lgkmcnt(0)
	s_waitcnt vmcnt(3)
	v_mfma_f32_32x32x16_bf16 v[0:15], v[78:81], v[208:211], v[0:15]
	s_waitcnt vmcnt(1)
	v_mfma_f32_32x32x16_bf16 v[16:31], v[82:85], v[216:219], v[16:31]
	s_waitcnt vmcnt(0)
	v_mfma_f32_32x32x16_bf16 v[0:15], v[82:85], v[220:223], v[0:15]
	v_mfma_f32_32x32x16_bf16 v[32:47], v[82:85], v[212:215], v[32:47]
	v_lshrrev_b32_e32 v49, 3, v48
	s_nop 10
	v_mul_f32_e32 v32, 0x3e16c740, v32
	v_and_b32_e32 v49, 4, v49
	v_lshlrev_b32_e32 v50, 1, v56
	v_bfe_u32 v52, v32, 16, 1
	v_lshl_or_b32 v51, v57, 1, v50
	v_add3_u32 v32, v32, v52, s60
	v_mul_u32_u24_e32 v52, 0x188, v49
	v_lshl_add_u32 v51, v52, 1, v51
	ds_write_b16_d16_hi v51, v32 offset:16896
	v_mul_f32_e32 v32, 0x3e16c740, v33
	v_bfe_u32 v33, v32, 16, 1
	v_add3_u32 v32, v32, v33, s60
	ds_write_b16_d16_hi v51, v32 offset:17680
	v_mul_f32_e32 v32, 0x3e16c740, v34
	v_bfe_u32 v33, v32, 16, 1
	v_add3_u32 v32, v32, v33, s60
	ds_write_b16_d16_hi v51, v32 offset:18464
	v_mul_f32_e32 v32, 0x3e16c740, v35
	v_bfe_u32 v33, v32, 16, 1
	v_add3_u32 v32, v32, v33, s60
	ds_write_b16_d16_hi v51, v32 offset:19248
	v_mul_f32_e32 v32, 0x3e16c740, v36
	v_bfe_u32 v33, v32, 16, 1
	v_add3_u32 v32, v32, v33, s60
	ds_write_b16_d16_hi v51, v32 offset:23168
	v_mul_f32_e32 v32, 0x3e16c740, v37
	v_bfe_u32 v33, v32, 16, 1
	v_add3_u32 v32, v32, v33, s60
	ds_write_b16_d16_hi v51, v32 offset:23952
	v_mul_f32_e32 v32, 0x3e16c740, v38
	v_bfe_u32 v33, v32, 16, 1
	v_add3_u32 v32, v32, v33, s60
	ds_write_b16_d16_hi v51, v32 offset:24736
	v_mul_f32_e32 v32, 0x3e16c740, v39
	v_bfe_u32 v33, v32, 16, 1
	v_add3_u32 v32, v32, v33, s60
	ds_write_b16_d16_hi v51, v32 offset:25520
	v_mul_f32_e32 v32, 0x3e16c740, v40
	v_bfe_u32 v33, v32, 16, 1
	v_add3_u32 v32, v32, v33, s60
	ds_write_b16_d16_hi v51, v32 offset:29440
	v_mul_f32_e32 v32, 0x3e16c740, v41
	v_bfe_u32 v33, v32, 16, 1
	v_add3_u32 v32, v32, v33, s60
	ds_write_b16_d16_hi v51, v32 offset:30224
	v_mul_f32_e32 v32, 0x3e16c740, v42
	v_bfe_u32 v33, v32, 16, 1
	v_add3_u32 v32, v32, v33, s60
	ds_write_b16_d16_hi v51, v32 offset:31008
	v_mul_f32_e32 v32, 0x3e16c740, v43
	v_bfe_u32 v33, v32, 16, 1
	v_add3_u32 v32, v32, v33, s60
	ds_write_b16_d16_hi v51, v32 offset:31792
	v_mul_f32_e32 v32, 0x3e16c740, v44
	v_bfe_u32 v33, v32, 16, 1
	v_add3_u32 v32, v32, v33, s60
	ds_write_b16_d16_hi v51, v32 offset:35712
	v_mul_f32_e32 v32, 0x3e16c740, v45
	v_bfe_u32 v33, v32, 16, 1
	v_add3_u32 v32, v32, v33, s60
	ds_write_b16_d16_hi v51, v32 offset:36496
	v_mul_f32_e32 v32, 0x3e16c740, v46
	v_bfe_u32 v33, v32, 16, 1
	v_add3_u32 v32, v32, v33, s60
	ds_write_b16_d16_hi v51, v32 offset:37280
	v_mul_f32_e32 v32, 0x3e16c740, v47
	v_bfe_u32 v33, v32, 16, 1
	v_add3_u32 v32, v32, v33, s60
	v_mul_f32_e32 v16, 0x3e16c740, v16
	ds_write_b16_d16_hi v51, v32 offset:38064
	v_bfe_u32 v32, v16, 16, 1
	v_add3_u32 v16, v16, v32, s60
	ds_write_b16_d16_hi v51, v16 offset:16960
	v_mul_f32_e32 v16, 0x3e16c740, v17
	v_bfe_u32 v17, v16, 16, 1
	v_add3_u32 v16, v16, v17, s60
	ds_write_b16_d16_hi v51, v16 offset:17744
	v_mul_f32_e32 v16, 0x3e16c740, v18
	v_bfe_u32 v17, v16, 16, 1
	v_add3_u32 v16, v16, v17, s60
	ds_write_b16_d16_hi v51, v16 offset:18528
	v_mul_f32_e32 v16, 0x3e16c740, v19
	v_bfe_u32 v17, v16, 16, 1
	v_add3_u32 v16, v16, v17, s60
	ds_write_b16_d16_hi v51, v16 offset:19312
	v_mul_f32_e32 v16, 0x3e16c740, v20
	v_bfe_u32 v17, v16, 16, 1
	v_add3_u32 v16, v16, v17, s60
	ds_write_b16_d16_hi v51, v16 offset:23232
	v_mul_f32_e32 v16, 0x3e16c740, v21
	v_bfe_u32 v17, v16, 16, 1
	v_add3_u32 v16, v16, v17, s60
	ds_write_b16_d16_hi v51, v16 offset:24016
	v_mul_f32_e32 v16, 0x3e16c740, v22
	v_bfe_u32 v17, v16, 16, 1
	v_add3_u32 v16, v16, v17, s60
	ds_write_b16_d16_hi v51, v16 offset:24800
	v_mul_f32_e32 v16, 0x3e16c740, v23
	v_bfe_u32 v17, v16, 16, 1
	v_add3_u32 v16, v16, v17, s60
	ds_write_b16_d16_hi v51, v16 offset:25584
	v_mul_f32_e32 v16, 0x3e16c740, v24
	v_bfe_u32 v17, v16, 16, 1
	v_add3_u32 v16, v16, v17, s60
	ds_write_b16_d16_hi v51, v16 offset:29504
	v_mul_f32_e32 v16, 0x3e16c740, v25
	v_bfe_u32 v17, v16, 16, 1
	v_add3_u32 v16, v16, v17, s60
	ds_write_b16_d16_hi v51, v16 offset:30288
	v_mul_f32_e32 v16, 0x3e16c740, v26
	v_bfe_u32 v17, v16, 16, 1
	v_add3_u32 v16, v16, v17, s60
	ds_write_b16_d16_hi v51, v16 offset:31072
	v_mul_f32_e32 v16, 0x3e16c740, v27
	v_bfe_u32 v17, v16, 16, 1
	v_add3_u32 v16, v16, v17, s60
	ds_write_b16_d16_hi v51, v16 offset:31856
	v_mul_f32_e32 v16, 0x3e16c740, v28
	v_bfe_u32 v17, v16, 16, 1
	v_add3_u32 v16, v16, v17, s60
	ds_write_b16_d16_hi v51, v16 offset:35776
	v_mul_f32_e32 v16, 0x3e16c740, v29
	v_bfe_u32 v17, v16, 16, 1
	v_add3_u32 v16, v16, v17, s60
	ds_write_b16_d16_hi v51, v16 offset:36560
	v_mul_f32_e32 v16, 0x3e16c740, v30
	v_bfe_u32 v17, v16, 16, 1
	v_add3_u32 v16, v16, v17, s60
	ds_write_b16_d16_hi v51, v16 offset:37344
	v_mul_f32_e32 v16, 0x3e16c740, v31
	v_bfe_u32 v17, v16, 16, 1
	v_add3_u32 v16, v16, v17, s60
	ds_write_b16_d16_hi v51, v16 offset:38128
	v_and_b32_e32 v16, 7, v48
	v_cvt_f32_ubyte0_e32 v16, v16
	v_mul_f32_e32 v17, 0xbfd49a78, v16
	v_cmp_gt_f32_e32 vcc, s61, v17
	v_and_b32_e32 v18, 64, v131
	v_add_u32_e32 v18, 64, v18
	v_cndmask_b32_e32 v17, 0, v129, vcc
	v_fmac_f32_e32 v17, 0xbfd49a78, v16
	v_exp_f32_e32 v16, v17
	v_xor_b32_e32 v17, 8, v131
	v_cndmask_b32_e32 v19, 0, v130, vcc
	v_cmp_lt_i32_e32 vcc, v17, v18
	s_cmpk_gt_i32 s4, 0xff
	s_cselect_b64 s[10:11], -1, 0
	v_cndmask_b32_e32 v17, v131, v17, vcc
	v_lshlrev_b32_e32 v17, 2, v17
	ds_bpermute_b32 v18, v17, v0
	s_add_i32 s5, s4, 0xffffff00
	s_ashr_i32 s12, s5, 6
	s_and_b32 s13, s27, 32
	v_ldexp_f32 v16, v16, v19
	v_and_b32_e32 v19, 8, v48
	s_cmpk_lt_i32 s4, 0x100
	v_cmp_gt_u32_e64 s[6:7], 16, v57
	v_cmp_eq_u32_e64 s[4:5], 0, v19
	s_cbranch_scc1 .LBB0_1373
	v_or_b32_e32 v19, s13, v49
	v_mov_b32_e32 v20, s12
	v_cndmask_b32_e64 v19, v19, v20, s[6:7]
	v_cvt_f32_i32_e32 v19, v19
	v_mul_f32_e32 v19, v16, v19
	v_mul_f32_e32 v19, 0.15915494, v19
	v_sin_f32_e32 v20, v19
	v_cos_f32_e32 v19, v19
	s_waitcnt lgkmcnt(0)
	v_mul_f32_e32 v18, v20, v18
	v_cndmask_b32_e64 v18, v18, -v18, s[4:5]
	v_fmac_f32_e32 v18, v19, v0
	v_mov_b32_e32 v0, v18

.LBB0_1406:
	v_add_u32_e32 v4, s82, v135
	v_mul_hi_i32 v2, v4, s66
	v_lshrrev_b32_e32 v3, 31, v2
	v_ashrrev_i32_e32 v2, 3, v2
	v_add_u32_e32 v5, v2, v3
	v_mad_u64_u32 v[20:21], s[0:1], v5, s68, v[0:1]
	v_add_u32_e32 v6, s26, v5
	v_mov_b64_e32 v[2:3], s[54:55]
	v_add_u32_e32 v8, s81, v5
	v_mad_i64_i32 v[6:7], s[0:1], v6, s34, v[2:3]
	v_ashrrev_i32_e32 v21, 31, v20
	v_mad_u64_u32 v[18:19], s[0:1], v5, s67, v[4:5]
	v_lshl_add_u64 v[6:7], v[20:21], 1, v[6:7]
	v_cmp_lt_i32_e32 vcc, s27, v8
	v_lshl_add_u64 v[14:15], v[6:7], 0, s[22:23]
	v_add_co_u32_e64 v6, s[0:1], s69, v6
	v_cndmask_b32_e64 v11, 0, -1, vcc
	v_cndmask_b32_e32 v10, 0, v132, vcc
	v_cmp_gt_i32_e64 s[6:7], s80, v8
	v_addc_co_u32_e64 v7, s[0:1], 0, v7, s[0:1]
	v_lshl_add_u64 v[10:11], v[14:15], 0, v[10:11]
	global_load_dwordx4 v[6:9], v[6:7], off offset:1792
	v_cndmask_b32_e64 v64, 0, v133, s[6:7]
	global_load_dwordx4 v[10:13], v[10:11], off
	v_lshl_add_u64 v[14:15], v[14:15], 0, v[64:65]
	global_load_dwordx4 v[14:17], v[14:15], off
	v_cmp_gt_i32_e64 s[4:5], 32, v18
	v_cmp_gt_i32_e64 s[0:1], 16, v18
	v_lshl_add_u32 v5, v5, 4, v1
	v_add_u32_e32 v4, 0x100, v4
	s_addk_i32 s82, 0x200
	s_cmpk_eq_i32 s82, 0x600
	s_waitcnt vmcnt(0) lgkmcnt(0)
	v_lshlrev_b32_e32 v31, 16, v7
	v_and_b32_e32 v7, 0xffff0000, v7
	v_lshlrev_b32_e32 v26, 16, v12
	v_and_b32_e32 v27, 0xffff0000, v12
	v_lshlrev_b32_e32 v29, 16, v13
	v_and_b32_e32 v30, 0xffff0000, v13
	v_lshlrev_b64 v[12:13], 2, v[20:21]
	v_and_b32_e32 v19, 0xffff0000, v10
	v_lshlrev_b32_e32 v25, 16, v11
	v_and_b32_e32 v11, 0xffff0000, v11
	v_lshl_add_u64 v[20:21], s[12:13], 0, v[12:13]
	v_lshlrev_b32_e32 v10, 16, v10
	v_lshlrev_b32_e32 v32, 16, v14
	v_lshlrev_b32_e32 v33, 16, v15
	v_and_b32_e32 v36, 0xffff0000, v15
	v_and_b32_e32 v37, 0xffff0000, v14
	v_lshlrev_b32_e32 v38, 16, v16
	v_lshlrev_b32_e32 v39, 16, v17
	v_and_b32_e32 v40, 0xffff0000, v17
	v_and_b32_e32 v41, 0xffff0000, v16
	v_lshl_add_u64 v[22:23], s[24:25], 0, v[12:13]
	v_cndmask_b32_e32 v18, 0, v10, vcc
	v_cndmask_b32_e32 v24, 0, v19, vcc
	v_cndmask_b32_e32 v19, 0, v25, vcc
	v_cndmask_b32_e32 v25, 0, v11, vcc
	global_load_dwordx4 v[10:13], v[20:21], off
	global_load_dwordx4 v[14:17], v[22:23], off
	v_cndmask_b32_e32 v28, 0, v27, vcc
	v_cndmask_b32_e32 v27, 0, v29, vcc
	v_cndmask_b32_e32 v29, 0, v30, vcc
	v_lshlrev_b32_e32 v30, 16, v6
	v_cndmask_b32_e64 v33, 0, v33, s[6:7]
	v_cndmask_b32_e64 v32, 0, v32, s[6:7]
	v_pk_add_f32 v[18:19], v[18:19], v[30:31] neg_lo:[0,1] neg_hi:[0,1]
	v_and_b32_e32 v6, 0xffff0000, v6
	v_pk_add_f32 v[24:25], v[24:25], v[6:7] neg_lo:[0,1] neg_hi:[0,1]
	v_cndmask_b32_e32 v26, 0, v26, vcc
	s_waitcnt vmcnt(0) lgkmcnt(0)
	v_mov_b32_e32 v34, v10
	v_mov_b32_e32 v35, v12
	v_pk_fma_f32 v[18:19], v[34:35], v[18:19], v[30:31]
	v_pk_add_f32 v[30:31], v[32:33], v[30:31] neg_lo:[0,1] neg_hi:[0,1]
	v_mov_b32_e32 v32, v14
	v_mov_b32_e32 v33, v16
	v_pk_fma_f32 v[18:19], v[30:31], v[32:33], v[18:19]
	v_cndmask_b32_e64 v31, 0, v36, s[6:7]
	v_cndmask_b32_e64 v30, 0, v37, s[6:7]
	v_mov_b32_e32 v12, v11
	v_pk_fma_f32 v[12:13], v[12:13], v[24:25], v[6:7]
	v_pk_add_f32 v[6:7], v[30:31], v[6:7] neg_lo:[0,1] neg_hi:[0,1]
	v_mov_b32_e32 v16, v15
	v_pk_fma_f32 v[6:7], v[6:7], v[16:17], v[12:13]
	v_add_f32_e32 v10, v18, v18
	v_add_f32_e32 v11, v6, v6
	v_cndmask_b32_e64 v11, v11, v6, s[0:1]
	v_mul_f32_e32 v11, 0xbfb8aa3b, v11
	v_exp_f32_e32 v12, v11
	v_add_f32_e32 v11, v19, v19
	v_cndmask_b32_e64 v10, v10, v18, s[0:1]
	v_cndmask_b32_e64 v11, v11, v19, s[0:1]
	v_mul_f32_e32 v10, 0xbfb8aa3b, v10
	v_mul_f32_e32 v11, 0xbfb8aa3b, v11
	v_exp_f32_e32 v10, v10
	v_exp_f32_e32 v11, v11
	s_nop 0
	v_pk_add_f32 v[10:11], v[10:11], 1.0 op_sel_hi:[1,0]
	s_nop 0
	v_div_scale_f32 v13, s[84:85], v11, v11, 1.0
	v_rcp_f32_e32 v14, v13
	s_nop 0
	v_fma_f32 v15, -v13, v14, 1.0
	v_fmac_f32_e32 v14, v15, v14
	v_div_scale_f32 v15, vcc, 1.0, v11, 1.0
	v_mul_f32_e32 v16, v15, v14
	v_fma_f32 v17, -v13, v16, v15
	v_fmac_f32_e32 v16, v17, v14
	v_fma_f32 v13, -v13, v16, v15
	v_div_fmas_f32 v13, v13, v14, v16
	v_div_fixup_f32 v11, v13, v11, 1.0
	v_div_scale_f32 v13, s[84:85], v10, v10, 1.0
	v_rcp_f32_e32 v14, v13
	s_nop 0
	v_fma_f32 v15, -v13, v14, 1.0
	v_fmac_f32_e32 v14, v15, v14
	v_div_scale_f32 v15, vcc, 1.0, v10, 1.0
	v_mul_f32_e32 v16, v15, v14
	v_fma_f32 v17, -v13, v16, v15
	v_fmac_f32_e32 v16, v17, v14
	v_fma_f32 v13, -v13, v16, v15
	v_div_fmas_f32 v13, v13, v14, v16
	v_div_fixup_f32 v10, v13, v10, 1.0
	v_pk_fma_f32 v[14:15], v[10:11], 2.0, -1.0 op_sel_hi:[1,0,0]
	v_and_b32_e32 v17, 0xffff0000, v9
	v_cndmask_b32_e64 v13, v18, v14, s[4:5]
	v_cndmask_b32_e64 v25, v13, v10, s[0:1]
	v_add_f32_e32 v10, v7, v7
	v_cndmask_b32_e64 v10, v10, v7, s[0:1]
	v_mul_f32_e32 v10, 0xbfb8aa3b, v10
	v_exp_f32_e32 v13, v10
	v_cndmask_b32_e64 v14, v19, v15, s[4:5]
	v_cndmask_b32_e64 v24, v14, v11, s[0:1]
	v_cndmask_b32_e64 v19, 0, v39, s[6:7]
	v_pk_add_f32 v[10:11], v[12:13], 1.0 op_sel_hi:[1,0]
	v_cndmask_b32_e64 v18, 0, v38, s[6:7]
	v_div_scale_f32 v12, s[84:85], v11, v11, 1.0
	v_rcp_f32_e32 v13, v12
	s_nop 0
	v_fma_f32 v14, -v12, v13, 1.0
	v_fmac_f32_e32 v13, v14, v13
	v_div_scale_f32 v14, vcc, 1.0, v11, 1.0
	v_mul_f32_e32 v15, v14, v13
	v_fma_f32 v16, -v12, v15, v14
	v_fmac_f32_e32 v15, v16, v13
	v_fma_f32 v12, -v12, v15, v14
	v_div_fmas_f32 v12, v12, v13, v15
	v_div_fixup_f32 v11, v12, v11, 1.0
	v_div_scale_f32 v12, s[84:85], v10, v10, 1.0
	v_rcp_f32_e32 v13, v12
	s_nop 0
	v_fma_f32 v14, -v12, v13, 1.0
	v_fmac_f32_e32 v13, v14, v13
	v_div_scale_f32 v14, vcc, 1.0, v10, 1.0
	v_mul_f32_e32 v15, v14, v13
	v_fma_f32 v16, -v12, v15, v14
	v_fmac_f32_e32 v15, v16, v13
	v_fma_f32 v12, -v12, v15, v14
	v_div_fmas_f32 v12, v12, v13, v15
	v_div_fixup_f32 v10, v12, v10, 1.0
	v_pk_fma_f32 v[12:13], v[10:11], 2.0, -1.0 op_sel_hi:[1,0,0]
	v_lshlrev_b32_e32 v15, 16, v9
	v_cndmask_b32_e64 v7, v7, v13, s[4:5]
	v_cndmask_b32_e64 v6, v6, v12, s[4:5]
	v_cndmask_b32_e64 v30, v6, v10, s[0:1]
	v_cndmask_b32_e64 v31, v7, v11, s[0:1]
	v_lshlrev_b32_e32 v14, 16, v8
	v_and_b32_e32 v16, 0xffff0000, v8
	global_load_dwordx4 v[6:9], v[20:21], off offset:16
	global_load_dwordx4 v[10:13], v[22:23], off offset:16
	v_pk_add_f32 v[20:21], v[26:27], v[14:15] neg_lo:[0,1] neg_hi:[0,1]
	s_waitcnt vmcnt(0) lgkmcnt(0)
	v_mov_b32_e32 v22, v6
	v_mov_b32_e32 v23, v8
	v_pk_fma_f32 v[20:21], v[20:21], v[22:23], v[14:15]
	v_pk_add_f32 v[14:15], v[18:19], v[14:15] neg_lo:[0,1] neg_hi:[0,1]
	v_mov_b32_e32 v18, v10
	v_mov_b32_e32 v19, v12
	v_pk_fma_f32 v[14:15], v[14:15], v[18:19], v[20:21]
	v_cndmask_b32_e64 v19, 0, v40, s[6:7]
	v_cndmask_b32_e64 v18, 0, v41, s[6:7]
	v_pk_add_f32 v[20:21], v[28:29], v[16:17] neg_lo:[0,1] neg_hi:[0,1]
	v_mov_b32_e32 v8, v7
	v_pk_fma_f32 v[8:9], v[20:21], v[8:9], v[16:17]
	v_pk_add_f32 v[16:17], v[18:19], v[16:17] neg_lo:[0,1] neg_hi:[0,1]
	v_mov_b32_e32 v12, v11
	v_pk_fma_f32 v[8:9], v[16:17], v[12:13], v[8:9]
	v_add_f32_e32 v6, v14, v14
	v_add_f32_e32 v7, v8, v8
	v_cndmask_b32_e64 v7, v7, v8, s[0:1]
	v_mul_f32_e32 v7, 0xbfb8aa3b, v7
	v_exp_f32_e32 v10, v7
	v_add_f32_e32 v7, v15, v15
	v_cndmask_b32_e64 v6, v6, v14, s[0:1]
	v_cndmask_b32_e64 v7, v7, v15, s[0:1]
	v_mul_f32_e32 v6, 0xbfb8aa3b, v6
	v_mul_f32_e32 v7, 0xbfb8aa3b, v7
	v_exp_f32_e32 v6, v6
	v_exp_f32_e32 v7, v7
	s_nop 0
	v_pk_add_f32 v[6:7], v[6:7], 1.0 op_sel_hi:[1,0]
	s_nop 0
	v_div_scale_f32 v11, s[6:7], v7, v7, 1.0
	v_rcp_f32_e32 v12, v11
	s_nop 0
	v_fma_f32 v13, -v11, v12, 1.0
	v_fmac_f32_e32 v12, v13, v12
	v_div_scale_f32 v13, vcc, 1.0, v7, 1.0
	v_mul_f32_e32 v16, v13, v12
	v_fma_f32 v17, -v11, v16, v13
	v_fmac_f32_e32 v16, v17, v12
	v_fma_f32 v11, -v11, v16, v13
	v_div_fmas_f32 v11, v11, v12, v16
	v_div_fixup_f32 v7, v11, v7, 1.0
	v_div_scale_f32 v11, s[6:7], v6, v6, 1.0
	v_rcp_f32_e32 v12, v11
	s_nop 0
	v_fma_f32 v13, -v11, v12, 1.0
	v_fmac_f32_e32 v12, v13, v12
	v_div_scale_f32 v13, vcc, 1.0, v6, 1.0
	v_mul_f32_e32 v16, v13, v12
	v_fma_f32 v17, -v11, v16, v13
	v_fmac_f32_e32 v16, v17, v12
	v_fma_f32 v11, -v11, v16, v13
	v_div_fmas_f32 v11, v11, v12, v16
	v_div_fixup_f32 v6, v11, v6, 1.0
	v_pk_fma_f32 v[12:13], v[6:7], 2.0, -1.0 op_sel_hi:[1,0,0]
	s_nop 0
	v_cndmask_b32_e64 v11, v14, v12, s[4:5]
	v_cndmask_b32_e64 v12, v15, v13, s[4:5]
	v_cndmask_b32_e64 v13, v11, v6, s[0:1]
	v_add_f32_e32 v6, v9, v9
	v_cndmask_b32_e64 v6, v6, v9, s[0:1]
	v_mul_f32_e32 v6, 0xbfb8aa3b, v6
	v_exp_f32_e32 v11, v6
	v_cndmask_b32_e64 v12, v12, v7, s[0:1]
	v_pk_add_f32 v[6:7], v[10:11], 1.0 op_sel_hi:[1,0]
	s_nop 0
	v_div_scale_f32 v10, s[6:7], v7, v7, 1.0
	v_rcp_f32_e32 v11, v10
	s_nop 0
	v_fma_f32 v14, -v10, v11, 1.0
	v_fmac_f32_e32 v11, v14, v11
	v_div_scale_f32 v14, vcc, 1.0, v7, 1.0
	v_mul_f32_e32 v15, v14, v11
	v_fma_f32 v16, -v10, v15, v14
	v_fmac_f32_e32 v15, v16, v11
	v_fma_f32 v10, -v10, v15, v14
	v_div_fmas_f32 v10, v10, v11, v15
	v_div_fixup_f32 v7, v10, v7, 1.0
	v_div_scale_f32 v10, s[6:7], v6, v6, 1.0
	v_rcp_f32_e32 v11, v10
	s_nop 0
	v_fma_f32 v14, -v10, v11, 1.0
	v_fmac_f32_e32 v11, v14, v11
	v_div_scale_f32 v14, vcc, 1.0, v6, 1.0
	v_mul_f32_e32 v15, v14, v11
	v_fma_f32 v16, -v10, v15, v14
	v_fmac_f32_e32 v15, v16, v11
	v_fma_f32 v10, -v10, v15, v14
	v_div_fmas_f32 v10, v10, v11, v15
	v_div_fixup_f32 v6, v10, v6, 1.0
	v_pk_fma_f32 v[10:11], v[6:7], 2.0, -1.0 op_sel_hi:[1,0,0]
	v_bfe_u32 v14, v13, 16, 1
	v_cndmask_b32_e64 v9, v9, v11, s[4:5]
	v_cndmask_b32_e64 v8, v8, v10, s[4:5]
	v_cndmask_b32_e64 v6, v8, v6, s[0:1]
	v_cndmask_b32_e64 v7, v9, v7, s[0:1]
	v_bfe_u32 v8, v7, 16, 1
	v_bfe_u32 v9, v6, 16, 1
	v_add3_u32 v6, v6, v9, s60
	v_add3_u32 v7, v7, v8, s60
	v_bfe_u32 v8, v25, 16, 1
	v_bfe_u32 v9, v24, 16, 1
	v_bfe_u32 v15, v12, 16, 1
	v_bfe_u32 v10, v31, 16, 1
	v_bfe_u32 v11, v30, 16, 1
	v_add3_u32 v12, v12, v15, s60
	v_add3_u32 v13, v13, v14, s60
	v_add3_u32 v9, v24, v9, s60
	v_add3_u32 v8, v25, v8, s60
	v_add3_u32 v11, v30, v11, s60
	v_add3_u32 v10, v31, v10, s60
	v_lshrrev_b32_e32 v14, 16, v8
	v_lshrrev_b32_e32 v15, 16, v9
	v_lshrrev_b32_e32 v8, 16, v13
	v_lshrrev_b32_e32 v9, 16, v12
	v_and_or_b32 v9, v7, s56, v9
	v_and_or_b32 v8, v6, s56, v8
	v_and_or_b32 v7, v10, s56, v15
	v_and_or_b32 v6, v11, s56, v14
	ds_write_b128 v5, v[6:9]
	v_mul_hi_i32 v5, v4, s66
	v_lshrrev_b32_e32 v6, 31, v5
	v_ashrrev_i32_e32 v5, 3, v5
	v_add_u32_e32 v6, v5, v6
	v_mad_u64_u32 v[4:5], s[0:1], v6, s67, v[4:5]
	v_mul_lo_u32 v5, v6, s68
	s_movk_i32 s0, 0x800
	v_add3_u32 v20, v0, v5, s0
	v_add_u32_e32 v7, s26, v6
	v_mad_i64_i32 v[2:3], s[0:1], v7, s34, v[2:3]
	v_ashrrev_i32_e32 v21, 31, v20
	v_lshl_add_u64 v[2:3], v[20:21], 1, v[2:3]
	v_add_u32_e32 v5, s81, v6
	v_lshl_add_u64 v[16:17], v[2:3], 0, s[22:23]
	v_add_co_u32_e64 v2, s[0:1], s69, v2
	v_cmp_lt_i32_e32 vcc, s27, v5
	s_nop 0
	v_addc_co_u32_e64 v3, s[0:1], 0, v3, s[0:1]
	v_cmp_gt_i32_e64 s[6:7], s80, v5
	global_load_dwordx4 v[8:11], v[2:3], off offset:1792
	v_cndmask_b32_e64 v3, 0, -1, vcc
	v_cndmask_b32_e32 v2, 0, v132, vcc
	v_lshl_add_u64 v[2:3], v[16:17], 0, v[2:3]
	v_cndmask_b32_e64 v64, 0, v133, s[6:7]
	global_load_dwordx4 v[12:15], v[2:3], off
	v_lshl_add_u64 v[2:3], v[16:17], 0, v[64:65]
	global_load_dwordx4 v[16:19], v[2:3], off
	v_lshlrev_b64 v[2:3], 2, v[20:21]
	v_cmp_gt_i32_e64 s[4:5], 32, v4
	v_cmp_gt_i32_e64 s[0:1], 16, v4
	v_lshl_add_u32 v6, v6, 4, v1
	v_add_u32_e32 v1, 0x2000, v1
	v_add_u32_e32 v0, 0x1000, v0
	s_waitcnt vmcnt(0) lgkmcnt(0)
	v_lshlrev_b32_e32 v29, 16, v9
	v_lshlrev_b32_e32 v28, 16, v8
	v_and_b32_e32 v9, 0xffff0000, v9
	v_and_b32_e32 v8, 0xffff0000, v8
	v_and_b32_e32 v5, 0xffff0000, v12
	v_lshlrev_b32_e32 v7, 16, v13
	v_and_b32_e32 v13, 0xffff0000, v13
	v_lshlrev_b32_e32 v24, 16, v14
	v_and_b32_e32 v14, 0xffff0000, v14
	v_lshlrev_b32_e32 v25, 16, v15
	v_and_b32_e32 v15, 0xffff0000, v15
	v_lshlrev_b32_e32 v30, 16, v16
	v_lshlrev_b32_e32 v31, 16, v17
	v_and_b32_e32 v34, 0xffff0000, v17
	v_and_b32_e32 v35, 0xffff0000, v16
	v_lshlrev_b32_e32 v36, 16, v18
	v_lshlrev_b32_e32 v37, 16, v19
	v_and_b32_e32 v38, 0xffff0000, v19
	v_and_b32_e32 v39, 0xffff0000, v18
	v_lshl_add_u64 v[16:17], s[12:13], 0, v[2:3]
	v_lshl_add_u64 v[18:19], s[24:25], 0, v[2:3]
	v_lshlrev_b32_e32 v2, 16, v12
	v_cndmask_b32_e32 v20, 0, v2, vcc
	v_cndmask_b32_e32 v22, 0, v5, vcc
	v_cndmask_b32_e32 v23, 0, v13, vcc
	v_cndmask_b32_e32 v26, 0, v14, vcc
	v_cndmask_b32_e32 v27, 0, v15, vcc
	global_load_dwordx4 v[2:5], v[16:17], off
	global_load_dwordx4 v[12:15], v[18:19], off
	v_cndmask_b32_e32 v21, 0, v7, vcc
	v_cndmask_b32_e64 v31, 0, v31, s[6:7]
	v_cndmask_b32_e64 v30, 0, v30, s[6:7]
	v_pk_add_f32 v[20:21], v[20:21], v[28:29] neg_lo:[0,1] neg_hi:[0,1]
	v_pk_add_f32 v[22:23], v[22:23], v[8:9] neg_lo:[0,1] neg_hi:[0,1]
	v_cndmask_b32_e32 v24, 0, v24, vcc
	v_cndmask_b32_e32 v25, 0, v25, vcc
	s_waitcnt vmcnt(0) lgkmcnt(0)
	v_mov_b32_e32 v32, v2
	v_mov_b32_e32 v33, v4
	v_pk_fma_f32 v[20:21], v[32:33], v[20:21], v[28:29]
	v_pk_add_f32 v[28:29], v[30:31], v[28:29] neg_lo:[0,1] neg_hi:[0,1]
	v_mov_b32_e32 v30, v12
	v_mov_b32_e32 v31, v14
	v_pk_fma_f32 v[20:21], v[28:29], v[30:31], v[20:21]
	v_cndmask_b32_e64 v29, 0, v34, s[6:7]
	v_cndmask_b32_e64 v28, 0, v35, s[6:7]
	v_mov_b32_e32 v4, v3
	v_pk_fma_f32 v[4:5], v[4:5], v[22:23], v[8:9]
	v_pk_add_f32 v[8:9], v[28:29], v[8:9] neg_lo:[0,1] neg_hi:[0,1]
	v_mov_b32_e32 v14, v13
	v_pk_fma_f32 v[4:5], v[8:9], v[14:15], v[4:5]
	v_add_f32_e32 v2, v20, v20
	v_add_f32_e32 v3, v4, v4
	v_cndmask_b32_e64 v3, v3, v4, s[0:1]
	v_mul_f32_e32 v3, 0xbfb8aa3b, v3
	v_exp_f32_e32 v8, v3
	v_add_f32_e32 v3, v21, v21
	v_cndmask_b32_e64 v2, v2, v20, s[0:1]
	v_cndmask_b32_e64 v3, v3, v21, s[0:1]
	v_mul_f32_e32 v2, 0xbfb8aa3b, v2
	v_mul_f32_e32 v3, 0xbfb8aa3b, v3
	v_exp_f32_e32 v2, v2
	v_exp_f32_e32 v3, v3
	v_and_b32_e32 v15, 0xffff0000, v11
	v_pk_add_f32 v[2:3], v[2:3], 1.0 op_sel_hi:[1,0]
	s_nop 0
	v_div_scale_f32 v7, s[84:85], v3, v3, 1.0
	v_rcp_f32_e32 v9, v7
	s_nop 0
	v_fma_f32 v12, -v7, v9, 1.0
	v_fmac_f32_e32 v9, v12, v9
	v_div_scale_f32 v12, vcc, 1.0, v3, 1.0
	v_mul_f32_e32 v13, v12, v9
	v_fma_f32 v14, -v7, v13, v12
	v_fmac_f32_e32 v13, v14, v9
	v_fma_f32 v7, -v7, v13, v12
	v_div_fmas_f32 v7, v7, v9, v13
	v_div_fixup_f32 v3, v7, v3, 1.0
	v_div_scale_f32 v7, s[84:85], v2, v2, 1.0
	v_rcp_f32_e32 v9, v7
	s_nop 0
	v_fma_f32 v12, -v7, v9, 1.0
	v_fmac_f32_e32 v9, v12, v9
	v_div_scale_f32 v12, vcc, 1.0, v2, 1.0
	v_mul_f32_e32 v13, v12, v9
	v_fma_f32 v14, -v7, v13, v12
	v_fmac_f32_e32 v13, v14, v9
	v_fma_f32 v7, -v7, v13, v12
	v_div_fmas_f32 v7, v7, v9, v13
	v_div_fixup_f32 v2, v7, v2, 1.0
	v_pk_fma_f32 v[12:13], v[2:3], 2.0, -1.0 op_sel_hi:[1,0,0]
	s_nop 0
	v_cndmask_b32_e64 v7, v20, v12, s[4:5]
	v_cndmask_b32_e64 v7, v7, v2, s[0:1]
	v_add_f32_e32 v2, v5, v5
	v_cndmask_b32_e64 v2, v2, v5, s[0:1]
	v_cndmask_b32_e64 v9, v21, v13, s[4:5]
	v_mul_f32_e32 v2, 0xbfb8aa3b, v2
	v_cndmask_b32_e64 v22, v9, v3, s[0:1]
	v_exp_f32_e32 v9, v2
	s_nop 0
	v_pk_add_f32 v[2:3], v[8:9], 1.0 op_sel_hi:[1,0]
	s_nop 0
	v_div_scale_f32 v8, s[84:85], v3, v3, 1.0
	v_rcp_f32_e32 v9, v8
	s_nop 0
	v_fma_f32 v12, -v8, v9, 1.0
	v_fmac_f32_e32 v9, v12, v9
	v_div_scale_f32 v12, vcc, 1.0, v3, 1.0
	v_mul_f32_e32 v13, v12, v9
	v_fma_f32 v14, -v8, v13, v12
	v_fmac_f32_e32 v13, v14, v9
	v_fma_f32 v8, -v8, v13, v12
	v_div_fmas_f32 v8, v8, v9, v13
	v_div_fixup_f32 v3, v8, v3, 1.0
	v_div_scale_f32 v8, s[84:85], v2, v2, 1.0
	v_rcp_f32_e32 v9, v8
	s_nop 0
	v_fma_f32 v12, -v8, v9, 1.0
	v_fmac_f32_e32 v9, v12, v9
	v_div_scale_f32 v12, vcc, 1.0, v2, 1.0
	v_mul_f32_e32 v13, v12, v9
	v_fma_f32 v14, -v8, v13, v12
	v_fmac_f32_e32 v13, v14, v9
	v_fma_f32 v8, -v8, v13, v12
	v_div_fmas_f32 v8, v8, v9, v13
	v_div_fixup_f32 v2, v8, v2, 1.0
	v_pk_fma_f32 v[8:9], v[2:3], 2.0, -1.0 op_sel_hi:[1,0,0]
	v_lshlrev_b32_e32 v13, 16, v11
	v_cndmask_b32_e64 v5, v5, v9, s[4:5]
	v_cndmask_b32_e64 v4, v4, v8, s[4:5]
	v_cndmask_b32_e64 v23, v4, v2, s[0:1]
	v_cndmask_b32_e64 v28, v5, v3, s[0:1]
	v_lshlrev_b32_e32 v12, 16, v10
	v_and_b32_e32 v14, 0xffff0000, v10
	global_load_dwordx4 v[2:5], v[16:17], off offset:16
	global_load_dwordx4 v[8:11], v[18:19], off offset:16
	v_cndmask_b32_e64 v17, 0, v37, s[6:7]
	v_cndmask_b32_e64 v16, 0, v36, s[6:7]
	v_pk_add_f32 v[18:19], v[24:25], v[12:13] neg_lo:[0,1] neg_hi:[0,1]
	s_waitcnt vmcnt(0) lgkmcnt(0)
	v_mov_b32_e32 v20, v2
	v_mov_b32_e32 v21, v4
	v_pk_fma_f32 v[18:19], v[18:19], v[20:21], v[12:13]
	v_pk_add_f32 v[12:13], v[16:17], v[12:13] neg_lo:[0,1] neg_hi:[0,1]
	v_mov_b32_e32 v16, v8
	v_mov_b32_e32 v17, v10
	v_pk_fma_f32 v[12:13], v[12:13], v[16:17], v[18:19]
	v_cndmask_b32_e64 v17, 0, v38, s[6:7]
	v_cndmask_b32_e64 v16, 0, v39, s[6:7]
	v_pk_add_f32 v[18:19], v[26:27], v[14:15] neg_lo:[0,1] neg_hi:[0,1]
	v_mov_b32_e32 v4, v3
	v_pk_fma_f32 v[4:5], v[18:19], v[4:5], v[14:15]
	v_pk_add_f32 v[14:15], v[16:17], v[14:15] neg_lo:[0,1] neg_hi:[0,1]
	v_mov_b32_e32 v10, v9
	v_pk_fma_f32 v[4:5], v[14:15], v[10:11], v[4:5]
	v_add_f32_e32 v2, v12, v12
	v_add_f32_e32 v3, v4, v4
	v_cndmask_b32_e64 v3, v3, v4, s[0:1]
	v_mul_f32_e32 v3, 0xbfb8aa3b, v3
	v_exp_f32_e32 v8, v3
	v_add_f32_e32 v3, v13, v13
	v_cndmask_b32_e64 v2, v2, v12, s[0:1]
	v_cndmask_b32_e64 v3, v3, v13, s[0:1]
	v_mul_f32_e32 v2, 0xbfb8aa3b, v2
	v_mul_f32_e32 v3, 0xbfb8aa3b, v3
	v_exp_f32_e32 v2, v2
	v_exp_f32_e32 v3, v3
	s_nop 0
	v_pk_add_f32 v[2:3], v[2:3], 1.0 op_sel_hi:[1,0]
	s_nop 0
	v_div_scale_f32 v9, s[6:7], v3, v3, 1.0
	v_rcp_f32_e32 v10, v9
	s_nop 0
	v_fma_f32 v11, -v9, v10, 1.0
	v_fmac_f32_e32 v10, v11, v10
	v_div_scale_f32 v11, vcc, 1.0, v3, 1.0
	v_mul_f32_e32 v14, v11, v10
	v_fma_f32 v15, -v9, v14, v11
	v_fmac_f32_e32 v14, v15, v10
	v_fma_f32 v9, -v9, v14, v11
	v_div_fmas_f32 v9, v9, v10, v14
	v_div_fixup_f32 v3, v9, v3, 1.0
	v_div_scale_f32 v9, s[6:7], v2, v2, 1.0
	v_rcp_f32_e32 v10, v9
	s_nop 0
	v_fma_f32 v11, -v9, v10, 1.0
	v_fmac_f32_e32 v10, v11, v10
	v_div_scale_f32 v11, vcc, 1.0, v2, 1.0
	v_mul_f32_e32 v14, v11, v10
	v_fma_f32 v15, -v9, v14, v11
	v_fmac_f32_e32 v14, v15, v10
	v_fma_f32 v9, -v9, v14, v11
	v_div_fmas_f32 v9, v9, v10, v14
	v_div_fixup_f32 v2, v9, v2, 1.0
	v_pk_fma_f32 v[10:11], v[2:3], 2.0, -1.0 op_sel_hi:[1,0,0]
	s_nop 0
	v_cndmask_b32_e64 v9, v12, v10, s[4:5]
	v_cndmask_b32_e64 v10, v13, v11, s[4:5]
	v_cndmask_b32_e64 v11, v9, v2, s[0:1]
	v_add_f32_e32 v2, v5, v5
	v_cndmask_b32_e64 v2, v2, v5, s[0:1]
	v_mul_f32_e32 v2, 0xbfb8aa3b, v2
	v_exp_f32_e32 v9, v2
	v_cndmask_b32_e64 v10, v10, v3, s[0:1]
	v_pk_add_f32 v[2:3], v[8:9], 1.0 op_sel_hi:[1,0]
	s_nop 0
	v_div_scale_f32 v8, s[6:7], v3, v3, 1.0
	v_rcp_f32_e32 v9, v8
	s_nop 0
	v_fma_f32 v12, -v8, v9, 1.0
	v_fmac_f32_e32 v9, v12, v9
	v_div_scale_f32 v12, vcc, 1.0, v3, 1.0
	v_mul_f32_e32 v13, v12, v9
	v_fma_f32 v14, -v8, v13, v12
	v_fmac_f32_e32 v13, v14, v9
	v_fma_f32 v8, -v8, v13, v12
	v_div_fmas_f32 v8, v8, v9, v13
	v_div_fixup_f32 v3, v8, v3, 1.0
	v_div_scale_f32 v8, s[6:7], v2, v2, 1.0
	v_rcp_f32_e32 v9, v8
	s_nop 0
	v_fma_f32 v12, -v8, v9, 1.0
	v_fmac_f32_e32 v9, v12, v9
	v_div_scale_f32 v12, vcc, 1.0, v2, 1.0
	v_mul_f32_e32 v13, v12, v9
	v_fma_f32 v14, -v8, v13, v12
	v_fmac_f32_e32 v13, v14, v9
	v_fma_f32 v8, -v8, v13, v12
	v_div_fmas_f32 v8, v8, v9, v13
	v_div_fixup_f32 v2, v8, v2, 1.0
	v_pk_fma_f32 v[8:9], v[2:3], 2.0, -1.0 op_sel_hi:[1,0,0]
	v_bfe_u32 v12, v11, 16, 1
	v_cndmask_b32_e64 v5, v5, v9, s[4:5]
	v_cndmask_b32_e64 v4, v4, v8, s[4:5]
	v_cndmask_b32_e64 v2, v4, v2, s[0:1]
	v_cndmask_b32_e64 v3, v5, v3, s[0:1]
	v_bfe_u32 v4, v3, 16, 1
	v_bfe_u32 v5, v2, 16, 1
	v_add3_u32 v2, v2, v5, s60
	v_add3_u32 v3, v3, v4, s60
	v_bfe_u32 v4, v7, 16, 1
	v_bfe_u32 v5, v22, 16, 1
	v_bfe_u32 v13, v10, 16, 1
	v_bfe_u32 v8, v28, 16, 1
	v_bfe_u32 v9, v23, 16, 1
	v_add3_u32 v10, v10, v13, s60
	v_add3_u32 v11, v11, v12, s60
	v_add3_u32 v5, v22, v5, s60
	v_add3_u32 v4, v7, v4, s60
	v_add3_u32 v9, v23, v9, s60
	v_add3_u32 v8, v28, v8, s60
	v_lshrrev_b32_e32 v7, 16, v4
	v_lshrrev_b32_e32 v12, 16, v5
	v_lshrrev_b32_e32 v4, 16, v11
	v_lshrrev_b32_e32 v5, 16, v10
	v_and_or_b32 v5, v3, s56, v5
	v_and_or_b32 v4, v2, s56, v4
	v_and_or_b32 v3, v8, s56, v12
	v_and_or_b32 v2, v9, s56, v7
	ds_write_b128 v6, v[2:5] offset:4096
	s_cbranch_scc0 .LBB0_1406
	v_ashrrev_i32_e32 v137, 3, v135
	v_and_b32_e32 v138, -4, v137
	v_add_u32_e32 v18, s81, v138
	v_add_u32_e32 v0, -1, v18
	v_or_b32_e32 v44, 1, v18
	v_and_b32_e32 v126, 31, v135
	v_max_i32_e32 v0, s27, v0
	v_max_i32_e32 v2, s27, v18
	v_max_i32_e32 v10, s27, v44
	v_lshlrev_b32_e32 v34, 4, v126
	v_mov_b32_e32 v35, v65
	s_mulk_i32 s18, 0x900
	v_min_i32_e32 v0, s80, v0
	v_min_i32_e32 v2, s80, v2
	v_min_i32_e32 v10, s80, v10
	v_lshl_add_u64 v[88:89], s[54:55], 0, v[34:35]
	s_mov_b64 s[0:1], 0x7158100
	v_add_u32_e32 v0, s18, v0
	v_add_u32_e32 v2, s18, v2
	v_add_u32_e32 v10, s18, v10
	v_lshl_add_u64 v[8:9], v[88:89], 0, s[0:1]
	v_mul_hi_i32_i24_e32 v25, 0x1240, v0
	v_mul_i32_i24_e32 v24, 0x1240, v0
	v_mul_hi_i32_i24_e32 v27, 0x1240, v2
	v_mul_i32_i24_e32 v26, 0x1240, v2
	v_mul_hi_i32_i24_e32 v49, 0x1240, v10
	v_mul_i32_i24_e32 v48, 0x1240, v10
	v_lshl_add_u64 v[0:1], v[8:9], 0, v[24:25]
	v_lshl_add_u64 v[4:5], v[8:9], 0, v[26:27]
	v_lshl_add_u64 v[10:11], v[8:9], 0, v[48:49]
	v_or_b32_e32 v45, 2, v18
	global_load_dwordx4 v[0:3], v[0:1], off
	s_nop 0
	global_load_dwordx4 v[4:7], v[4:5], off
	v_or_b32_e32 v70, 3, v18
	global_load_dwordx4 v[36:39], v[10:11], off
	v_max_i32_e32 v10, s27, v45
	v_min_i32_e32 v10, s80, v10
	v_add_u32_e32 v10, s18, v10
	v_mul_hi_i32_i24_e32 v55, 0x1240, v10
	v_mul_i32_i24_e32 v54, 0x1240, v10
	v_lshl_add_u64 v[10:11], v[8:9], 0, v[54:55]
	global_load_dwordx4 v[40:43], v[10:11], off
	v_max_i32_e32 v10, s27, v70
	v_min_i32_e32 v10, s80, v10
	v_add_u32_e32 v10, s18, v10
	v_mul_hi_i32_i24_e32 v57, 0x1240, v10
	v_mul_i32_i24_e32 v56, 0x1240, v10
	v_lshl_add_u64 v[10:11], v[8:9], 0, v[56:57]
	v_add_u32_e32 v71, 4, v18
	global_load_dwordx4 v[60:63], v[10:11], off
	v_max_i32_e32 v10, s27, v71
	v_min_i32_e32 v10, s80, v10
	v_add_u32_e32 v10, s18, v10
	v_mul_hi_i32_i24_e32 v59, 0x1240, v10
	v_mul_i32_i24_e32 v58, 0x1240, v10
	v_lshl_add_u64 v[8:9], v[8:9], 0, v[58:59]
	global_load_dwordx4 v[66:69], v[8:9], off
	v_mov_b32_e32 v8, s54
	v_mov_b32_e32 v9, s55
	v_add_co_u32_e32 v32, vcc, s57, v8
	v_lshlrev_b32_e32 v64, 5, v126
	s_nop 0
	v_addc_co_u32_e32 v33, vcc, 0, v9, vcc
	v_lshl_add_u64 v[28:29], s[8:9], 0, v[64:65]
	v_add_co_u32_e32 v50, vcc, s35, v28
	v_lshl_add_u64 v[46:47], s[10:11], 0, v[64:65]
	s_nop 0
	v_addc_co_u32_e32 v51, vcc, 0, v29, vcc
	v_add_co_u32_e32 v52, vcc, s35, v46
	global_load_dwordx4 v[8:11], v[50:51], off offset:512
	s_nop 0
	v_addc_co_u32_e32 v53, vcc, 0, v47, vcc
	global_load_dwordx2 v[30:31], v[32:33], off offset:464
	global_load_dwordx4 v[12:15], v[52:53], off offset:512
	v_lshl_add_u64 v[16:17], v[28:29], 0, s[20:21]
	v_lshl_add_u64 v[20:21], v[46:47], 0, s[20:21]
	v_cmp_lt_i32_e32 vcc, s27, v18
	v_cmp_ge_i32_e64 s[0:1], s79, v18
	v_cmp_le_i32_e64 s[4:5], s27, v18
	v_cmp_gt_i32_e64 s[6:7], s79, v18
	global_load_dwordx4 v[16:19], v[16:17], off offset:16
	s_and_b64 vcc, vcc, s[0:1]
	global_load_dwordx4 v[20:23], v[20:21], off offset:16
	s_and_b64 s[4:5], s[4:5], s[6:7]
	v_cmp_le_i32_e64 s[0:1], s27, v44
	v_cmp_gt_i32_e64 s[6:7], s79, v44
	s_and_b64 s[6:7], s[0:1], s[6:7]
	v_cmp_le_i32_e64 s[0:1], s27, v45
	v_cmp_gt_i32_e64 s[8:9], s79, v45
	s_and_b64 s[8:9], s[0:1], s[8:9]
	v_cmp_le_i32_e64 s[0:1], s27, v70
	v_cmp_gt_i32_e64 s[10:11], s79, v70
	s_and_b64 s[10:11], s[0:1], s[10:11]
	v_cmp_le_i32_e64 s[0:1], s27, v71
	v_cmp_gt_i32_e64 s[12:13], s79, v71
	s_and_b64 s[12:13], s[0:1], s[12:13]
	v_add_u32_e32 v90, s26, v138
	v_ashrrev_i32_e32 v91, 31, v90
	s_mov_b32 s24, 0
	v_lshlrev_b32_e32 v126, 3, v126
	s_waitcnt vmcnt(0) lgkmcnt(0)
	v_cndmask_b32_e32 v72, 0, v1, vcc
	v_cndmask_b32_e32 v73, 0, v0, vcc
	v_cndmask_b32_e64 v77, 0, v5, s[4:5]
	v_cndmask_b32_e64 v79, 0, v4, s[4:5]
	v_cndmask_b32_e64 v80, 0, v39, s[6:7]
	v_cndmask_b32_e64 v82, 0, v38, s[6:7]
	v_cndmask_b32_e64 v38, 0, v37, s[6:7]
	v_cndmask_b32_e64 v39, 0, v36, s[6:7]
	v_and_b32_e32 v37, 0xffff0000, v72
	v_and_b32_e32 v36, 0xffff0000, v73
	v_cndmask_b32_e32 v74, 0, v3, vcc
	v_cndmask_b32_e32 v75, 0, v2, vcc
	v_cndmask_b32_e64 v76, 0, v7, s[4:5]
	v_cndmask_b32_e64 v78, 0, v6, s[4:5]
	v_lshlrev_b32_e32 v45, 16, v77
	v_lshlrev_b32_e32 v44, 16, v79
	v_and_b32_e32 v81, 0xffff0000, v80
	v_cndmask_b32_e64 v86, 0, v43, s[8:9]
	v_cndmask_b32_e64 v94, 0, v63, s[10:11]
	v_cndmask_b32_e64 v95, 0, v62, s[10:11]
	v_and_b32_e32 v63, 0xffff0000, v77
	v_and_b32_e32 v62, 0xffff0000, v79
	v_pk_add_f32 v[36:37], v[36:37], v[62:63] neg_lo:[0,1] neg_hi:[0,1]
	v_and_b32_e32 v77, 0xffff0000, v76
	v_lshlrev_b32_e32 v79, 16, v80
	v_cndmask_b32_e64 v122, 0, v69, s[12:13]
	v_cndmask_b32_e64 v123, 0, v68, s[12:13]
	v_and_b32_e32 v69, 0xffff0000, v38
	v_and_b32_e32 v68, 0xffff0000, v39
	v_cndmask_b32_e64 v118, 0, v67, s[12:13]
	v_cndmask_b32_e64 v119, 0, v66, s[12:13]
	v_lshlrev_b32_e32 v67, 16, v38
	v_lshlrev_b32_e32 v66, 16, v39
	v_pk_add_f32 v[38:39], v[66:67], v[44:45] neg_lo:[0,1] neg_hi:[0,1]
	v_and_b32_e32 v80, 0xffff0000, v82
	v_cndmask_b32_e64 v96, 0, v61, s[10:11]
	v_cndmask_b32_e64 v97, 0, v60, s[10:11]
	v_cndmask_b32_e64 v87, 0, v42, s[8:9]
	v_cndmask_b32_e64 v92, 0, v41, s[8:9]
	v_cndmask_b32_e64 v93, 0, v40, s[8:9]
	v_mov_b32_e32 v71, v10
	v_mov_b32_e32 v10, v9
	v_mov_b32_e32 v70, v8
	v_readfirstlane_b32 s1, v31
	v_readfirstlane_b32 s0, v30
	v_lshlrev_b32_e32 v31, 16, v72
	v_lshlrev_b32_e32 v30, 16, v73
	v_mov_b32_e32 v73, v14
	v_pk_fma_f32 v[8:9], v[10:11], v[36:37], v[62:63]
	v_pk_add_f32 v[36:37], v[68:69], v[62:63] neg_lo:[0,1] neg_hi:[0,1]
	v_mov_b32_e32 v14, v13
	v_pk_add_f32 v[30:31], v[30:31], v[44:45] neg_lo:[0,1] neg_hi:[0,1]
	v_mov_b32_e32 v72, v12
	v_pk_fma_f32 v[36:37], v[14:15], v[36:37], v[8:9]
	v_lshlrev_b32_e32 v9, 16, v74
	v_lshlrev_b32_e32 v8, 16, v75
	v_and_b32_e32 v13, 0xffff0000, v74
	v_and_b32_e32 v12, 0xffff0000, v75
	v_lshlrev_b32_e32 v75, 16, v76
	v_lshlrev_b32_e32 v74, 16, v78
	v_pk_fma_f32 v[30:31], v[70:71], v[30:31], v[44:45]
	v_and_b32_e32 v76, 0xffff0000, v78
	v_lshlrev_b32_e32 v78, 16, v82
	v_pk_add_f32 v[8:9], v[8:9], v[74:75] neg_lo:[0,1] neg_hi:[0,1]
	v_mov_b32_e32 v82, v16
	v_mov_b32_e32 v83, v18
	v_pk_fma_f32 v[30:31], v[72:73], v[38:39], v[30:31]
	v_pk_fma_f32 v[8:9], v[82:83], v[8:9], v[74:75]
	v_pk_add_f32 v[38:39], v[78:79], v[74:75] neg_lo:[0,1] neg_hi:[0,1]
	v_mov_b32_e32 v84, v20
	v_mov_b32_e32 v85, v22
	v_pk_fma_f32 v[98:99], v[84:85], v[38:39], v[8:9]
	v_pk_add_f32 v[8:9], v[12:13], v[76:77] neg_lo:[0,1] neg_hi:[0,1]
	v_mov_b32_e32 v18, v17
	v_pk_fma_f32 v[8:9], v[18:19], v[8:9], v[76:77]
	v_pk_add_f32 v[12:13], v[80:81], v[76:77] neg_lo:[0,1] neg_hi:[0,1]
	v_mov_b32_e32 v22, v21
	v_pk_fma_f32 v[100:101], v[22:23], v[12:13], v[8:9]
	v_bfe_u32 v8, v30, 16, 1
	v_bfe_u32 v9, v31, 16, 1
	v_bfe_u32 v12, v98, 16, 1
	v_bfe_u32 v13, v99, 16, 1
	v_lshl_add_u64 v[0:1], s[0:1], 0, v[64:65]
	s_mov_b64 s[0:1], 0x156d7900
	v_add3_u32 v13, v99, v13, s60
	v_add3_u32 v12, v98, v12, s60
	v_add3_u32 v9, v31, v9, s60
	v_add3_u32 v8, v30, v8, s60
	v_lshl_add_u64 v[60:61], v[88:89], 0, s[0:1]
	v_lshrrev_b32_e32 v8, 16, v8
	v_lshrrev_b32_e32 v9, 16, v9
	v_lshrrev_b32_e32 v12, 16, v12
	v_lshrrev_b32_e32 v13, 16, v13
	v_lshlrev_b64 v[38:39], 9, v[90:91]
	v_and_or_b32 v43, v101, s56, v13
	v_and_or_b32 v42, v100, s56, v12
	v_and_or_b32 v41, v37, s56, v9
	v_and_or_b32 v40, v36, s56, v8
	v_lshl_add_u64 v[8:9], v[60:61], 0, v[38:39]
	global_load_dwordx4 v[4:7], v[0:1], off offset:1024
	s_nop 0
	global_load_dwordx4 v[0:3], v[0:1], off offset:1040
	v_pk_add_f32 v[16:17], v[44:45], v[66:67] neg_lo:[0,1] neg_hi:[0,1]
	global_store_dwordx4 v[8:9], v[40:43], off
	v_lshlrev_b32_e32 v9, 16, v92
	v_lshlrev_b32_e32 v8, 16, v93
	v_pk_fma_f32 v[16:17], v[70:71], v[16:17], v[66:67]
	v_pk_add_f32 v[20:21], v[8:9], v[66:67] neg_lo:[0,1] neg_hi:[0,1]
	v_and_b32_e32 v13, 0xffff0000, v92
	v_and_b32_e32 v12, 0xffff0000, v93
	v_pk_fma_f32 v[102:103], v[72:73], v[20:21], v[16:17]
	v_pk_add_f32 v[16:17], v[62:63], v[68:69] neg_lo:[0,1] neg_hi:[0,1]
	v_pk_add_f32 v[20:21], v[12:13], v[68:69] neg_lo:[0,1] neg_hi:[0,1]
	v_pk_fma_f32 v[16:17], v[10:11], v[16:17], v[68:69]
	v_pk_add_f32 v[40:41], v[74:75], v[78:79] neg_lo:[0,1] neg_hi:[0,1]
	v_pk_fma_f32 v[104:105], v[14:15], v[20:21], v[16:17]
	v_lshlrev_b32_e32 v17, 16, v86
	v_lshlrev_b32_e32 v16, 16, v87
	v_pk_fma_f32 v[40:41], v[82:83], v[40:41], v[78:79]
	v_pk_add_f32 v[42:43], v[16:17], v[78:79] neg_lo:[0,1] neg_hi:[0,1]
	v_and_b32_e32 v21, 0xffff0000, v86
	v_and_b32_e32 v20, 0xffff0000, v87
	v_pk_fma_f32 v[106:107], v[84:85], v[42:43], v[40:41]
	v_pk_add_f32 v[40:41], v[76:77], v[80:81] neg_lo:[0,1] neg_hi:[0,1]
	v_pk_add_f32 v[42:43], v[20:21], v[80:81] neg_lo:[0,1] neg_hi:[0,1]
	v_pk_fma_f32 v[40:41], v[18:19], v[40:41], v[80:81]
	v_or_b32_e32 v92, 1, v90
	v_pk_fma_f32 v[108:109], v[22:23], v[42:43], v[40:41]
	v_bfe_u32 v40, v102, 16, 1
	v_bfe_u32 v41, v103, 16, 1
	v_bfe_u32 v42, v106, 16, 1
	v_bfe_u32 v43, v107, 16, 1
	v_add3_u32 v43, v107, v43, s60
	v_add3_u32 v42, v106, v42, s60
	v_add3_u32 v41, v103, v41, s60
	v_add3_u32 v40, v102, v40, s60
	v_lshrrev_b32_e32 v40, 16, v40
	v_lshrrev_b32_e32 v41, 16, v41
	v_lshrrev_b32_e32 v42, 16, v42
	v_lshrrev_b32_e32 v43, 16, v43
	v_ashrrev_i32_e32 v93, 31, v92
	v_and_or_b32 v45, v109, s56, v43
	v_and_or_b32 v44, v108, s56, v42
	v_and_or_b32 v43, v105, s56, v41
	v_and_or_b32 v42, v104, s56, v40
	v_lshlrev_b64 v[40:41], 9, v[92:93]
	v_lshl_add_u64 v[62:63], v[60:61], 0, v[40:41]
	global_store_dwordx4 v[62:63], v[42:45], off
	v_pk_add_f32 v[66:67], v[66:67], v[8:9] neg_lo:[0,1] neg_hi:[0,1]
	v_and_b32_e32 v63, 0xffff0000, v96
	v_lshlrev_b32_e32 v45, 16, v96
	v_lshlrev_b32_e32 v44, 16, v97
	v_pk_add_f32 v[42:43], v[44:45], v[8:9] neg_lo:[0,1] neg_hi:[0,1]
	v_pk_fma_f32 v[66:67], v[70:71], v[66:67], v[8:9]
	v_and_b32_e32 v62, 0xffff0000, v97
	v_pk_fma_f32 v[110:111], v[72:73], v[42:43], v[66:67]
	v_pk_add_f32 v[42:43], v[68:69], v[12:13] neg_lo:[0,1] neg_hi:[0,1]
	v_pk_add_f32 v[74:75], v[62:63], v[12:13] neg_lo:[0,1] neg_hi:[0,1]
	v_pk_fma_f32 v[42:43], v[10:11], v[42:43], v[12:13]
	v_pk_add_f32 v[68:69], v[78:79], v[16:17] neg_lo:[0,1] neg_hi:[0,1]
	v_pk_fma_f32 v[112:113], v[14:15], v[74:75], v[42:43]
	v_lshlrev_b32_e32 v75, 16, v94
	v_lshlrev_b32_e32 v74, 16, v95
	v_pk_add_f32 v[42:43], v[74:75], v[16:17] neg_lo:[0,1] neg_hi:[0,1]
	v_pk_fma_f32 v[68:69], v[82:83], v[68:69], v[16:17]
	v_and_b32_e32 v77, 0xffff0000, v94
	v_and_b32_e32 v76, 0xffff0000, v95
	v_pk_fma_f32 v[114:115], v[84:85], v[42:43], v[68:69]
	v_pk_add_f32 v[42:43], v[80:81], v[20:21] neg_lo:[0,1] neg_hi:[0,1]
	v_pk_add_f32 v[66:67], v[76:77], v[20:21] neg_lo:[0,1] neg_hi:[0,1]
	v_pk_fma_f32 v[42:43], v[18:19], v[42:43], v[20:21]
	v_or_b32_e32 v94, 2, v90
	v_pk_fma_f32 v[116:117], v[22:23], v[66:67], v[42:43]
	v_bfe_u32 v42, v110, 16, 1
	v_bfe_u32 v43, v111, 16, 1
	v_bfe_u32 v66, v114, 16, 1
	v_bfe_u32 v67, v115, 16, 1
	v_add3_u32 v67, v115, v67, s60
	v_add3_u32 v66, v114, v66, s60
	v_add3_u32 v43, v111, v43, s60
	v_add3_u32 v42, v110, v42, s60
	v_lshrrev_b32_e32 v42, 16, v42
	v_lshrrev_b32_e32 v43, 16, v43
	v_lshrrev_b32_e32 v66, 16, v66
	v_lshrrev_b32_e32 v67, 16, v67
	v_ashrrev_i32_e32 v95, 31, v94
	v_and_or_b32 v69, v117, s56, v67
	v_and_or_b32 v68, v116, s56, v66
	v_and_or_b32 v67, v113, s56, v43
	v_and_or_b32 v66, v112, s56, v42
	v_lshlrev_b64 v[42:43], 9, v[94:95]
	v_lshl_add_u64 v[78:79], v[60:61], 0, v[42:43]
	global_store_dwordx4 v[78:79], v[66:69], off
	v_pk_add_f32 v[8:9], v[8:9], v[44:45] neg_lo:[0,1] neg_hi:[0,1]
	v_pk_add_f32 v[12:13], v[12:13], v[62:63] neg_lo:[0,1] neg_hi:[0,1]
	v_lshlrev_b32_e32 v67, 16, v118
	v_lshlrev_b32_e32 v66, 16, v119
	v_and_b32_e32 v69, 0xffff0000, v118
	v_and_b32_e32 v68, 0xffff0000, v119
	v_pk_add_f32 v[66:67], v[66:67], v[44:45] neg_lo:[0,1] neg_hi:[0,1]
	v_pk_fma_f32 v[8:9], v[70:71], v[8:9], v[44:45]
	v_pk_add_f32 v[68:69], v[68:69], v[62:63] neg_lo:[0,1] neg_hi:[0,1]
	v_pk_fma_f32 v[118:119], v[72:73], v[66:67], v[8:9]
	v_pk_fma_f32 v[8:9], v[10:11], v[12:13], v[62:63]
	v_pk_add_f32 v[12:13], v[16:17], v[74:75] neg_lo:[0,1] neg_hi:[0,1]
	v_pk_fma_f32 v[120:121], v[14:15], v[68:69], v[8:9]
	v_lshlrev_b32_e32 v9, 16, v122
	v_lshlrev_b32_e32 v8, 16, v123
	v_and_b32_e32 v11, 0xffff0000, v122
	v_and_b32_e32 v10, 0xffff0000, v123
	v_pk_add_f32 v[8:9], v[8:9], v[74:75] neg_lo:[0,1] neg_hi:[0,1]
	v_pk_add_f32 v[14:15], v[20:21], v[76:77] neg_lo:[0,1] neg_hi:[0,1]
	v_pk_fma_f32 v[12:13], v[82:83], v[12:13], v[74:75]
	v_pk_add_f32 v[10:11], v[10:11], v[76:77] neg_lo:[0,1] neg_hi:[0,1]
	v_pk_fma_f32 v[122:123], v[84:85], v[8:9], v[12:13]
	v_pk_fma_f32 v[8:9], v[18:19], v[14:15], v[76:77]
	v_or_b32_e32 v96, 3, v90
	v_pk_fma_f32 v[124:125], v[22:23], v[10:11], v[8:9]
	v_bfe_u32 v8, v118, 16, 1
	v_bfe_u32 v9, v119, 16, 1
	v_bfe_u32 v10, v122, 16, 1
	v_bfe_u32 v11, v123, 16, 1
	v_add3_u32 v11, v123, v11, s60
	v_add3_u32 v10, v122, v10, s60
	v_add3_u32 v9, v119, v9, s60
	v_add3_u32 v8, v118, v8, s60
	v_ashrrev_i32_e32 v97, 31, v96
	v_lshrrev_b32_e32 v8, 16, v8
	v_lshrrev_b32_e32 v9, 16, v9
	v_lshrrev_b32_e32 v10, 16, v10
	v_lshrrev_b32_e32 v11, 16, v11
	v_lshlrev_b64 v[44:45], 9, v[96:97]
	v_and_or_b32 v11, v125, s56, v11
	v_and_or_b32 v10, v124, s56, v10
	v_and_or_b32 v9, v121, s56, v9
	v_and_or_b32 v8, v120, s56, v8
	v_lshl_add_u64 v[12:13], v[60:61], 0, v[44:45]
	global_store_dwordx4 v[12:13], v[8:11], off
	v_lshl_add_u64 v[16:17], v[28:29], 0, s[36:37]
	v_lshl_add_u64 v[20:21], v[46:47], 0, s[36:37]
	v_lshl_add_u64 v[8:9], v[88:89], 0, s[38:39]
	v_lshl_add_u64 v[10:11], v[8:9], 0, v[24:25]
	global_load_dwordx4 v[60:63], v[10:11], off
	v_lshl_add_u64 v[10:11], v[8:9], 0, v[26:27]
	global_load_dwordx4 v[66:69], v[10:11], off
	v_lshl_add_u64 v[10:11], v[8:9], 0, v[48:49]
	global_load_dwordx4 v[70:73], v[10:11], off
	v_lshl_add_u64 v[10:11], v[8:9], 0, v[54:55]
	global_load_dwordx4 v[74:77], v[10:11], off
	v_lshl_add_u64 v[10:11], v[8:9], 0, v[56:57]
	global_load_dwordx4 v[78:81], v[10:11], off
	v_lshl_add_u64 v[8:9], v[8:9], 0, v[58:59]
	global_load_dwordx4 v[82:85], v[8:9], off
	s_nop 0
	global_load_dwordx4 v[8:11], v[50:51], off offset:2560
	global_load_dwordx4 v[12:15], v[52:53], off offset:2560
	s_waitcnt vmcnt(0) lgkmcnt(0)
	v_mul_f32_e32 v159, v98, v0
	global_load_dwordx4 v[16:19], v[16:17], off offset:16
	v_mul_f32_e32 v160, v100, v1
	global_load_dwordx4 v[20:23], v[20:21], off offset:16
	v_mul_f32_e32 v161, v99, v2
	v_mul_f32_e32 v162, v101, v3
	v_mul_f32_e32 v163, v4, v102
	v_mul_f32_e32 v168, v5, v104
	v_mul_f32_e32 v169, v103, v6
	v_mul_f32_e32 v170, v105, v7
	v_mul_f32_e32 v171, v106, v0
	v_mul_f32_e32 v114, v114, v0
	v_mul_f32_e32 v187, v122, v0
	v_mul_f32_e32 v172, v108, v1
	v_mul_f32_e32 v116, v116, v1
	v_mul_f32_e32 v188, v124, v1
	v_bitop3_b32 v1, v135, 31, v130 bitop3:0xe0
	v_mul_f32_e32 v173, v107, v2
	v_mul_f32_e32 v174, v109, v3
	v_mul_f32_e32 v175, v4, v110
	v_mul_f32_e32 v176, v5, v112
	v_mul_f32_e32 v177, v6, v111
	v_mul_f32_e32 v178, v113, v7
	v_mul_f32_e32 v115, v115, v2
	v_mul_f32_e32 v117, v117, v3
	v_mul_f32_e32 v179, v4, v118
	v_mul_f32_e32 v184, v5, v120
	v_mul_f32_e32 v185, v6, v119
	v_mul_f32_e32 v186, v7, v121
	v_mul_f32_e32 v189, v123, v2
	v_mul_f32_e32 v190, v125, v3
	v_or_b32_e32 v110, 3, v137
	v_mul_lo_u32 v110, v110, s70
	v_add_u32_e32 v119, v64, v110
	v_lshlrev_b64 v[110:111], 11, v[96:97]
	v_lshl_add_u64 v[110:111], s[54:55], 0, v[110:111]
	v_cndmask_b32_e32 v136, 0, v61, vcc
	v_cndmask_b32_e32 v139, 0, v60, vcc
	v_cndmask_b32_e64 v140, 0, v69, s[4:5]
	v_cndmask_b32_e64 v141, 0, v68, s[4:5]
	v_cndmask_b32_e64 v68, 0, v67, s[4:5]
	v_cndmask_b32_e64 v69, 0, v66, s[4:5]
	v_cndmask_b32_e64 v142, 0, v73, s[6:7]
	v_cndmask_b32_e64 v143, 0, v72, s[6:7]
	v_cndmask_b32_e64 v144, 0, v71, s[6:7]
	v_cndmask_b32_e64 v145, 0, v70, s[6:7]
	v_and_b32_e32 v67, 0xffff0000, v136
	v_and_b32_e32 v66, 0xffff0000, v139
	v_and_b32_e32 v73, 0xffff0000, v68
	v_and_b32_e32 v72, 0xffff0000, v69
	v_cndmask_b32_e64 v146, 0, v77, s[8:9]
	v_cndmask_b32_e64 v147, 0, v76, s[8:9]
	v_cndmask_b32_e64 v152, 0, v79, s[10:11]
	v_and_b32_e32 v77, 0xffff0000, v144
	v_and_b32_e32 v76, 0xffff0000, v145
	v_mov_b32_e32 v79, v10
	v_pk_add_f32 v[66:67], v[66:67], v[72:73] neg_lo:[0,1] neg_hi:[0,1]
	v_mov_b32_e32 v10, v9
	v_cndmask_b32_e32 v86, 0, v63, vcc
	v_cndmask_b32_e32 v87, 0, v62, vcc
	v_cndmask_b32_e64 v150, 0, v81, s[10:11]
	v_cndmask_b32_e64 v153, 0, v78, s[10:11]
	v_mov_b32_e32 v78, v8
	v_mov_b32_e32 v81, v14
	v_pk_fma_f32 v[8:9], v[10:11], v[66:67], v[72:73]
	v_pk_add_f32 v[66:67], v[76:77], v[72:73] neg_lo:[0,1] neg_hi:[0,1]
	v_mov_b32_e32 v14, v13
	v_cndmask_b32_e64 v154, 0, v85, s[12:13]
	v_cndmask_b32_e64 v155, 0, v84, s[12:13]
	v_lshlrev_b32_e32 v63, 16, v136
	v_lshlrev_b32_e32 v62, 16, v139
	v_lshlrev_b32_e32 v71, 16, v68
	v_lshlrev_b32_e32 v70, 16, v69
	v_pk_fma_f32 v[8:9], v[14:15], v[66:67], v[8:9]
	v_and_b32_e32 v67, 0xffff0000, v86
	v_and_b32_e32 v66, 0xffff0000, v87
	v_and_b32_e32 v85, 0xffff0000, v140
	v_and_b32_e32 v84, 0xffff0000, v141
	v_cndmask_b32_e64 v148, 0, v75, s[8:9]
	v_cndmask_b32_e64 v149, 0, v74, s[8:9]
	v_cndmask_b32_e64 v151, 0, v80, s[10:11]
	v_cndmask_b32_e64 v156, 0, v83, s[12:13]
	v_cndmask_b32_e64 v157, 0, v82, s[12:13]
	v_lshlrev_b32_e32 v75, 16, v144
	v_lshlrev_b32_e32 v74, 16, v145
	v_pk_add_f32 v[62:63], v[62:63], v[70:71] neg_lo:[0,1] neg_hi:[0,1]
	v_mov_b32_e32 v80, v12
	v_lshlrev_b32_e32 v13, 16, v86
	v_lshlrev_b32_e32 v12, 16, v87
	v_lshlrev_b32_e32 v83, 16, v140
	v_lshlrev_b32_e32 v82, 16, v141
	v_lshlrev_b32_e32 v86, 16, v143
	v_and_b32_e32 v141, 0xffff0000, v142
	v_and_b32_e32 v140, 0xffff0000, v143
	s_waitcnt vmcnt(0) lgkmcnt(0)
	v_mov_b32_e32 v143, v18
	v_pk_add_f32 v[66:67], v[66:67], v[84:85] neg_lo:[0,1] neg_hi:[0,1]
	v_mov_b32_e32 v18, v17
	v_pk_fma_f32 v[62:63], v[78:79], v[62:63], v[70:71]
	v_pk_add_f32 v[68:69], v[74:75], v[70:71] neg_lo:[0,1] neg_hi:[0,1]
	v_lshlrev_b32_e32 v87, 16, v142
	v_pk_add_f32 v[12:13], v[12:13], v[82:83] neg_lo:[0,1] neg_hi:[0,1]
	v_mov_b32_e32 v142, v16
	v_mov_b32_e32 v145, v22
	v_pk_fma_f32 v[16:17], v[18:19], v[66:67], v[84:85]
	v_pk_add_f32 v[66:67], v[140:141], v[84:85] neg_lo:[0,1] neg_hi:[0,1]
	v_mov_b32_e32 v22, v21
	v_pk_fma_f32 v[62:63], v[80:81], v[68:69], v[62:63]
	v_pk_fma_f32 v[12:13], v[142:143], v[12:13], v[82:83]
	v_pk_add_f32 v[68:69], v[86:87], v[82:83] neg_lo:[0,1] neg_hi:[0,1]
	v_mov_b32_e32 v144, v20
	v_pk_fma_f32 v[16:17], v[22:23], v[66:67], v[16:17]
	v_pk_fma_f32 v[12:13], v[144:145], v[68:69], v[12:13]
	v_bfe_u32 v20, v17, 16, 1
	v_bfe_u32 v21, v16, 16, 1
	v_bfe_u32 v66, v9, 16, 1
	v_bfe_u32 v67, v8, 16, 1
	v_add3_u32 v8, v8, v67, s60
	v_add3_u32 v9, v9, v66, s60
	v_add3_u32 v16, v16, v21, s60
	v_add3_u32 v17, v17, v20, s60
	v_bfe_u32 v20, v62, 16, 1
	v_bfe_u32 v21, v63, 16, 1
	v_bfe_u32 v66, v12, 16, 1
	v_bfe_u32 v67, v13, 16, 1
	v_add3_u32 v13, v13, v67, s60
	v_add3_u32 v12, v12, v66, s60
	v_add3_u32 v21, v63, v21, s60
	v_add3_u32 v20, v62, v20, s60
	v_lshl_add_u64 v[60:61], v[88:89], 0, s[40:41]
	v_lshrrev_b32_e32 v20, 16, v20
	v_lshrrev_b32_e32 v21, 16, v21
	v_lshrrev_b32_e32 v12, 16, v12
	v_lshrrev_b32_e32 v13, 16, v13
	v_and_or_b32 v69, v17, s56, v13
	v_and_or_b32 v68, v16, s56, v12
	v_and_or_b32 v67, v9, s56, v21
	v_and_or_b32 v66, v8, s56, v20
	v_lshl_add_u64 v[8:9], v[60:61], 0, v[38:39]
	global_store_dwordx4 v[8:9], v[66:69], off
	v_lshlrev_b32_e32 v9, 16, v148
	v_lshlrev_b32_e32 v8, 16, v149
	v_pk_add_f32 v[16:17], v[70:71], v[74:75] neg_lo:[0,1] neg_hi:[0,1]
	v_pk_add_f32 v[20:21], v[8:9], v[74:75] neg_lo:[0,1] neg_hi:[0,1]
	v_pk_fma_f32 v[16:17], v[78:79], v[16:17], v[74:75]
	v_and_b32_e32 v13, 0xffff0000, v148
	v_and_b32_e32 v12, 0xffff0000, v149
	v_pk_fma_f32 v[16:17], v[80:81], v[20:21], v[16:17]
	v_pk_add_f32 v[20:21], v[72:73], v[76:77] neg_lo:[0,1] neg_hi:[0,1]
	v_pk_add_f32 v[62:63], v[12:13], v[76:77] neg_lo:[0,1] neg_hi:[0,1]
	v_pk_fma_f32 v[20:21], v[10:11], v[20:21], v[76:77]
	v_pk_add_f32 v[66:67], v[82:83], v[86:87] neg_lo:[0,1] neg_hi:[0,1]
	v_pk_fma_f32 v[20:21], v[14:15], v[62:63], v[20:21]
	v_lshlrev_b32_e32 v63, 16, v146
	v_lshlrev_b32_e32 v62, 16, v147
	v_pk_fma_f32 v[66:67], v[142:143], v[66:67], v[86:87]
	v_pk_add_f32 v[68:69], v[62:63], v[86:87] neg_lo:[0,1] neg_hi:[0,1]
	v_and_b32_e32 v71, 0xffff0000, v146
	v_and_b32_e32 v70, 0xffff0000, v147
	v_pk_fma_f32 v[66:67], v[144:145], v[68:69], v[66:67]
	v_pk_add_f32 v[68:69], v[84:85], v[140:141] neg_lo:[0,1] neg_hi:[0,1]
	v_pk_add_f32 v[72:73], v[70:71], v[140:141] neg_lo:[0,1] neg_hi:[0,1]
	v_pk_fma_f32 v[68:69], v[18:19], v[68:69], v[140:141]
	v_bfe_u32 v82, v21, 16, 1
	v_pk_fma_f32 v[68:69], v[22:23], v[72:73], v[68:69]
	v_bfe_u32 v83, v20, 16, 1
	v_bfe_u32 v72, v69, 16, 1
	v_bfe_u32 v73, v68, 16, 1
	v_add3_u32 v20, v20, v83, s60
	v_add3_u32 v21, v21, v82, s60
	v_add3_u32 v68, v68, v73, s60
	v_add3_u32 v69, v69, v72, s60
	v_bfe_u32 v72, v16, 16, 1
	v_bfe_u32 v73, v17, 16, 1
	v_bfe_u32 v82, v66, 16, 1
	v_bfe_u32 v83, v67, 16, 1
	v_add3_u32 v67, v67, v83, s60
	v_add3_u32 v66, v66, v82, s60
	v_add3_u32 v17, v17, v73, s60
	v_add3_u32 v16, v16, v72, s60
	v_lshrrev_b32_e32 v16, 16, v16
	v_lshrrev_b32_e32 v17, 16, v17
	v_lshrrev_b32_e32 v66, 16, v66
	v_lshrrev_b32_e32 v67, 16, v67
	v_and_or_b32 v69, v69, s56, v67
	v_and_or_b32 v68, v68, s56, v66
	v_and_or_b32 v67, v21, s56, v17
	v_and_or_b32 v66, v20, s56, v16
	v_lshl_add_u64 v[16:17], v[60:61], 0, v[40:41]
	global_store_dwordx4 v[16:17], v[66:69], off
	v_lshlrev_b32_e32 v17, 16, v152
	v_lshlrev_b32_e32 v16, 16, v153
	v_pk_add_f32 v[72:73], v[74:75], v[8:9] neg_lo:[0,1] neg_hi:[0,1]
	v_pk_add_f32 v[66:67], v[16:17], v[8:9] neg_lo:[0,1] neg_hi:[0,1]
	v_pk_fma_f32 v[72:73], v[78:79], v[72:73], v[8:9]
	v_and_b32_e32 v21, 0xffff0000, v152
	v_and_b32_e32 v20, 0xffff0000, v153
	v_pk_fma_f32 v[66:67], v[80:81], v[66:67], v[72:73]
	v_pk_add_f32 v[72:73], v[76:77], v[12:13] neg_lo:[0,1] neg_hi:[0,1]
	v_pk_add_f32 v[68:69], v[20:21], v[12:13] neg_lo:[0,1] neg_hi:[0,1]
	v_pk_fma_f32 v[72:73], v[10:11], v[72:73], v[12:13]
	v_pk_add_f32 v[84:85], v[86:87], v[62:63] neg_lo:[0,1] neg_hi:[0,1]
	v_pk_fma_f32 v[68:69], v[14:15], v[68:69], v[72:73]
	v_lshlrev_b32_e32 v73, 16, v150
	v_lshlrev_b32_e32 v72, 16, v151
	v_pk_add_f32 v[76:77], v[72:73], v[62:63] neg_lo:[0,1] neg_hi:[0,1]
	v_pk_fma_f32 v[84:85], v[142:143], v[84:85], v[62:63]
	v_and_b32_e32 v75, 0xffff0000, v150
	v_and_b32_e32 v74, 0xffff0000, v151
	v_pk_fma_f32 v[76:77], v[144:145], v[76:77], v[84:85]
	v_pk_add_f32 v[84:85], v[140:141], v[70:71] neg_lo:[0,1] neg_hi:[0,1]
	v_pk_add_f32 v[82:83], v[74:75], v[70:71] neg_lo:[0,1] neg_hi:[0,1]
	v_pk_fma_f32 v[84:85], v[18:19], v[84:85], v[70:71]
	v_bfe_u32 v86, v69, 16, 1
	v_pk_fma_f32 v[82:83], v[22:23], v[82:83], v[84:85]
	v_bfe_u32 v87, v68, 16, 1
	v_bfe_u32 v84, v83, 16, 1
	v_bfe_u32 v85, v82, 16, 1
	v_add3_u32 v87, v68, v87, s60
	v_add3_u32 v86, v69, v86, s60
	v_add3_u32 v68, v82, v85, s60
	v_add3_u32 v69, v83, v84, s60
	v_bfe_u32 v82, v66, 16, 1
	v_bfe_u32 v83, v67, 16, 1
	v_bfe_u32 v84, v76, 16, 1
	v_bfe_u32 v85, v77, 16, 1
	v_add3_u32 v77, v77, v85, s60
	v_add3_u32 v76, v76, v84, s60
	v_add3_u32 v67, v67, v83, s60
	v_add3_u32 v66, v66, v82, s60
	v_lshrrev_b32_e32 v66, 16, v66
	v_lshrrev_b32_e32 v67, 16, v67
	v_lshrrev_b32_e32 v76, 16, v76
	v_lshrrev_b32_e32 v77, 16, v77
	v_and_or_b32 v69, v69, s56, v77
	v_and_or_b32 v68, v68, s56, v76
	v_and_or_b32 v67, v86, s56, v67
	v_and_or_b32 v66, v87, s56, v66
	v_lshl_add_u64 v[76:77], v[60:61], 0, v[42:43]
	global_store_dwordx4 v[76:77], v[66:69], off
	v_pk_add_f32 v[8:9], v[8:9], v[16:17] neg_lo:[0,1] neg_hi:[0,1]
	v_pk_add_f32 v[12:13], v[12:13], v[20:21] neg_lo:[0,1] neg_hi:[0,1]
	v_lshlrev_b32_e32 v67, 16, v156
	v_lshlrev_b32_e32 v66, 16, v157
	v_and_b32_e32 v69, 0xffff0000, v156
	v_and_b32_e32 v68, 0xffff0000, v157
	v_pk_add_f32 v[66:67], v[66:67], v[16:17] neg_lo:[0,1] neg_hi:[0,1]
	v_pk_add_f32 v[68:69], v[68:69], v[20:21] neg_lo:[0,1] neg_hi:[0,1]
	v_pk_fma_f32 v[8:9], v[78:79], v[8:9], v[16:17]
	v_pk_fma_f32 v[10:11], v[10:11], v[12:13], v[20:21]
	v_lshlrev_b32_e32 v13, 16, v154
	v_lshlrev_b32_e32 v12, 16, v155
	v_pk_add_f32 v[16:17], v[62:63], v[72:73] neg_lo:[0,1] neg_hi:[0,1]
	v_pk_fma_f32 v[10:11], v[14:15], v[68:69], v[10:11]
	v_and_b32_e32 v15, 0xffff0000, v154
	v_and_b32_e32 v14, 0xffff0000, v155
	v_pk_add_f32 v[12:13], v[12:13], v[72:73] neg_lo:[0,1] neg_hi:[0,1]
	v_pk_add_f32 v[20:21], v[70:71], v[74:75] neg_lo:[0,1] neg_hi:[0,1]
	v_pk_fma_f32 v[16:17], v[142:143], v[16:17], v[72:73]
	v_pk_add_f32 v[14:15], v[14:15], v[74:75] neg_lo:[0,1] neg_hi:[0,1]
	v_pk_fma_f32 v[12:13], v[144:145], v[12:13], v[16:17]
	v_pk_fma_f32 v[16:17], v[18:19], v[20:21], v[74:75]
	v_pk_fma_f32 v[8:9], v[80:81], v[66:67], v[8:9]
	v_pk_fma_f32 v[14:15], v[22:23], v[14:15], v[16:17]
	v_bfe_u32 v18, v11, 16, 1
	v_bfe_u32 v16, v15, 16, 1
	v_bfe_u32 v17, v14, 16, 1
	v_bfe_u32 v19, v10, 16, 1
	v_add3_u32 v19, v10, v19, s60
	v_add3_u32 v18, v11, v18, s60
	v_add3_u32 v10, v14, v17, s60
	v_add3_u32 v11, v15, v16, s60
	v_bfe_u32 v14, v8, 16, 1
	v_bfe_u32 v15, v9, 16, 1
	v_bfe_u32 v16, v12, 16, 1
	v_bfe_u32 v17, v13, 16, 1
	v_add3_u32 v13, v13, v17, s60
	v_add3_u32 v12, v12, v16, s60
	v_add3_u32 v9, v9, v15, s60
	v_add3_u32 v8, v8, v14, s60
	v_lshrrev_b32_e32 v8, 16, v8
	v_lshrrev_b32_e32 v9, 16, v9
	v_lshrrev_b32_e32 v12, 16, v12
	v_lshrrev_b32_e32 v13, 16, v13
	v_and_or_b32 v11, v11, s56, v13
	v_and_or_b32 v10, v10, s56, v12
	v_and_or_b32 v9, v18, s56, v9
	v_and_or_b32 v8, v19, s56, v8
	v_lshl_add_u64 v[12:13], v[60:61], 0, v[44:45]
	global_store_dwordx4 v[12:13], v[8:11], off
	v_lshl_add_u64 v[12:13], v[88:89], 0, s[44:45]
	v_lshl_add_u64 v[14:15], v[12:13], 0, v[26:27]
	v_lshl_add_u64 v[8:9], v[12:13], 0, v[24:25]
	global_load_dwordx4 v[8:11], v[8:9], off
	v_lshl_add_u64 v[26:27], v[28:29], 0, s[42:43]
	global_load_dwordx4 v[22:25], v[14:15], off
	v_lshl_add_u64 v[14:15], v[12:13], 0, v[48:49]
	global_load_dwordx4 v[60:63], v[14:15], off
	v_lshl_add_u64 v[14:15], v[12:13], 0, v[54:55]
	global_load_dwordx4 v[66:69], v[14:15], off
	v_lshl_add_u64 v[14:15], v[12:13], 0, v[56:57]
	global_load_dwordx4 v[54:57], v[14:15], off
	v_lshl_add_u64 v[12:13], v[12:13], 0, v[58:59]
	global_load_dwordx4 v[70:73], v[12:13], off
	s_nop 0
	global_load_dwordx2 v[12:13], v[32:33], off offset:448
	global_load_dwordx4 v[18:21], v[50:51], off offset:1536
	global_load_dwordx4 v[14:17], v[52:53], off offset:1536
	v_lshl_add_u64 v[28:29], v[46:47], 0, s[42:43]
	v_lshl_add_u64 v[52:53], v[88:89], 0, s[46:47]
	v_lshl_add_u64 v[46:47], v[52:53], 0, v[38:39]
	v_lshl_add_u64 v[48:49], v[52:53], 0, v[40:41]
	v_lshl_add_u64 v[50:51], v[52:53], 0, v[42:43]
	v_lshl_add_u64 v[52:53], v[52:53], 0, v[44:45]
	v_and_b32_e32 v136, 0xffffffc0, v135
	s_waitcnt vmcnt(0) lgkmcnt(0)
	v_cndmask_b32_e32 v82, 0, v9, vcc
	v_cndmask_b32_e32 v83, 0, v8, vcc
	v_cndmask_b32_e64 v147, 0, v25, s[4:5]
	v_cndmask_b32_e64 v148, 0, v24, s[4:5]
	v_cndmask_b32_e64 v58, 0, v23, s[4:5]
	v_cndmask_b32_e64 v59, 0, v22, s[4:5]
	global_load_dwordx4 v[22:25], v[26:27], off offset:16
	v_cndmask_b32_e32 v139, 0, v11, vcc
	global_load_dwordx4 v[26:29], v[28:29], off offset:16
	v_cndmask_b32_e64 v55, 0, v55, s[10:11]
	v_cndmask_b32_e64 v54, 0, v54, s[10:11]
	v_cndmask_b32_e32 v146, 0, v10, vcc
	v_cndmask_b32_e64 v61, 0, v61, s[6:7]
	v_cndmask_b32_e64 v60, 0, v60, s[6:7]
	v_cndmask_b32_e64 v153, 0, v57, s[10:11]
	v_cndmask_b32_e64 v154, 0, v56, s[10:11]
	v_cndmask_b32_e64 v157, 0, v71, s[12:13]
	v_cndmask_b32_e64 v158, 0, v70, s[12:13]
	v_lshlrev_b32_e32 v8, 16, v83
	v_lshlrev_b32_e32 v9, 16, v82
	v_lshlrev_b32_e32 v10, 16, v59
	v_lshlrev_b32_e32 v11, 16, v58
	v_lshlrev_b32_e32 v70, 16, v54
	v_lshlrev_b32_e32 v71, 16, v55
	v_readfirstlane_b32 s1, v13
	v_readfirstlane_b32 s0, v12
	v_and_b32_e32 v79, 0xffff0000, v55
	v_and_b32_e32 v78, 0xffff0000, v54
	v_and_b32_e32 v55, 0xffff0000, v58
	v_and_b32_e32 v54, 0xffff0000, v59
	v_and_b32_e32 v57, 0xffff0000, v82
	v_and_b32_e32 v56, 0xffff0000, v83
	v_cndmask_b32_e64 v149, 0, v63, s[6:7]
	v_cndmask_b32_e64 v150, 0, v62, s[6:7]
	v_lshlrev_b32_e32 v62, 16, v60
	v_lshlrev_b32_e32 v63, 16, v61
	v_lshl_add_u64 v[12:13], s[0:1], 0, v[64:65]
	v_pk_add_f32 v[8:9], v[8:9], v[10:11] neg_lo:[0,1] neg_hi:[0,1]
	v_pk_add_f32 v[56:57], v[56:57], v[54:55] neg_lo:[0,1] neg_hi:[0,1]
	v_mov_b32_e32 v82, v18
	v_mov_b32_e32 v83, v20
	v_mov_b32_e32 v20, v19
	v_pk_add_f32 v[58:59], v[10:11], v[62:63] neg_lo:[0,1] neg_hi:[0,1]
	v_pk_fma_f32 v[140:141], v[82:83], v[8:9], v[10:11]
	v_pk_fma_f32 v[18:19], v[20:21], v[56:57], v[54:55]
	v_pk_add_f32 v[56:57], v[62:63], v[10:11] neg_lo:[0,1] neg_hi:[0,1]
	global_load_dwordx4 v[8:11], v[12:13], off offset:1024
	v_mov_b32_e32 v144, v14
	v_mov_b32_e32 v145, v16
	v_mov_b32_e32 v16, v15
	global_load_dwordx4 v[12:15], v[12:13], off offset:1040
	v_cndmask_b32_e64 v67, 0, v67, s[8:9]
	v_cndmask_b32_e64 v66, 0, v66, s[8:9]
	v_cndmask_b32_e64 v151, 0, v69, s[8:9]
	v_cndmask_b32_e64 v152, 0, v68, s[8:9]
	v_lshlrev_b32_e32 v68, 16, v66
	v_lshlrev_b32_e32 v69, 16, v67
	v_and_b32_e32 v77, 0xffff0000, v67
	v_and_b32_e32 v76, 0xffff0000, v66
	v_and_b32_e32 v67, 0xffff0000, v61
	v_and_b32_e32 v66, 0xffff0000, v60
	v_pk_add_f32 v[142:143], v[66:67], v[54:55] neg_lo:[0,1] neg_hi:[0,1]
	v_pk_add_f32 v[60:61], v[54:55], v[66:67] neg_lo:[0,1] neg_hi:[0,1]
	v_pk_fma_f32 v[54:55], v[144:145], v[56:57], v[140:141]
	v_pk_fma_f32 v[56:57], v[16:17], v[142:143], v[18:19]
	v_pk_fma_f32 v[18:19], v[82:83], v[58:59], v[62:63]
	v_pk_add_f32 v[58:59], v[68:69], v[62:63] neg_lo:[0,1] neg_hi:[0,1]
	v_and_b32_e32 v141, 0xffff0000, v157
	v_pk_fma_f32 v[58:59], v[144:145], v[58:59], v[18:19]
	v_pk_fma_f32 v[18:19], v[20:21], v[60:61], v[66:67]
	v_pk_add_f32 v[60:61], v[76:77], v[66:67] neg_lo:[0,1] neg_hi:[0,1]
	v_and_b32_e32 v140, 0xffff0000, v158
	v_pk_fma_f32 v[60:61], v[16:17], v[60:61], v[18:19]
	v_pk_add_f32 v[18:19], v[62:63], v[68:69] neg_lo:[0,1] neg_hi:[0,1]
	v_pk_add_f32 v[62:63], v[70:71], v[68:69] neg_lo:[0,1] neg_hi:[0,1]
	v_pk_fma_f32 v[18:19], v[82:83], v[18:19], v[68:69]
	v_pk_add_f32 v[68:69], v[68:69], v[70:71] neg_lo:[0,1] neg_hi:[0,1]
	v_pk_fma_f32 v[62:63], v[144:145], v[62:63], v[18:19]
	v_pk_add_f32 v[18:19], v[66:67], v[76:77] neg_lo:[0,1] neg_hi:[0,1]
	v_pk_add_f32 v[66:67], v[78:79], v[76:77] neg_lo:[0,1] neg_hi:[0,1]
	v_pk_fma_f32 v[18:19], v[20:21], v[18:19], v[76:77]
	v_pk_fma_f32 v[68:69], v[82:83], v[68:69], v[70:71]
	v_pk_fma_f32 v[66:67], v[16:17], v[66:67], v[18:19]
	v_lshlrev_b32_e32 v19, 16, v157
	v_lshlrev_b32_e32 v18, 16, v158
	v_pk_add_f32 v[18:19], v[18:19], v[70:71] neg_lo:[0,1] neg_hi:[0,1]
	v_cndmask_b32_e64 v155, 0, v73, s[12:13]
	v_pk_fma_f32 v[68:69], v[144:145], v[18:19], v[68:69]
	v_pk_add_f32 v[18:19], v[76:77], v[78:79] neg_lo:[0,1] neg_hi:[0,1]
	v_cndmask_b32_e64 v156, 0, v72, s[12:13]
	v_lshlrev_b32_e32 v74, 16, v146
	v_lshlrev_b32_e32 v75, 16, v139
	v_lshlrev_b32_e32 v72, 16, v148
	v_lshlrev_b32_e32 v73, 16, v147
	v_pk_fma_f32 v[18:19], v[20:21], v[18:19], v[78:79]
	v_pk_add_f32 v[20:21], v[140:141], v[78:79] neg_lo:[0,1] neg_hi:[0,1]
	v_and_b32_e32 v77, 0xffff0000, v147
	v_and_b32_e32 v76, 0xffff0000, v148
	v_and_b32_e32 v141, 0xffff0000, v139
	v_and_b32_e32 v140, 0xffff0000, v146
	v_lshlrev_b32_e32 v80, 16, v150
	v_lshlrev_b32_e32 v81, 16, v149
	v_pk_fma_f32 v[70:71], v[16:17], v[20:21], v[18:19]
	v_and_b32_e32 v17, 0xffff0000, v149
	v_and_b32_e32 v16, 0xffff0000, v150
	v_pk_add_f32 v[74:75], v[74:75], v[72:73] neg_lo:[0,1] neg_hi:[0,1]
	v_pk_add_f32 v[140:141], v[140:141], v[76:77] neg_lo:[0,1] neg_hi:[0,1]
	s_waitcnt vmcnt(0) lgkmcnt(0)
	v_mov_b32_e32 v142, v22
	v_mov_b32_e32 v143, v24
	v_mov_b32_e32 v24, v23
	v_lshlrev_b32_e32 v86, 16, v152
	v_lshlrev_b32_e32 v87, 16, v151
	v_pk_add_f32 v[78:79], v[72:73], v[80:81] neg_lo:[0,1] neg_hi:[0,1]
	v_pk_add_f32 v[82:83], v[76:77], v[16:17] neg_lo:[0,1] neg_hi:[0,1]
	v_pk_fma_f32 v[74:75], v[142:143], v[74:75], v[72:73]
	v_pk_fma_f32 v[22:23], v[24:25], v[140:141], v[76:77]
	v_pk_add_f32 v[72:73], v[80:81], v[72:73] neg_lo:[0,1] neg_hi:[0,1]
	v_pk_add_f32 v[76:77], v[16:17], v[76:77] neg_lo:[0,1] neg_hi:[0,1]
	v_mov_b32_e32 v140, v26
	v_mov_b32_e32 v141, v28
	v_mov_b32_e32 v28, v27
	v_and_b32_e32 v19, 0xffff0000, v151
	v_and_b32_e32 v18, 0xffff0000, v152
	v_pk_fma_f32 v[72:73], v[140:141], v[72:73], v[74:75]
	v_pk_fma_f32 v[74:75], v[28:29], v[76:77], v[22:23]
	v_pk_fma_f32 v[22:23], v[142:143], v[78:79], v[80:81]
	v_pk_add_f32 v[26:27], v[86:87], v[80:81] neg_lo:[0,1] neg_hi:[0,1]
	v_lshlrev_b32_e32 v84, 16, v154
	v_pk_fma_f32 v[76:77], v[140:141], v[26:27], v[22:23]
	v_pk_fma_f32 v[22:23], v[24:25], v[82:83], v[16:17]
	v_pk_add_f32 v[26:27], v[18:19], v[16:17] neg_lo:[0,1] neg_hi:[0,1]
	v_lshlrev_b32_e32 v85, 16, v153
	v_pk_fma_f32 v[78:79], v[28:29], v[26:27], v[22:23]
	v_pk_add_f32 v[22:23], v[80:81], v[86:87] neg_lo:[0,1] neg_hi:[0,1]
	v_and_b32_e32 v21, 0xffff0000, v153
	v_and_b32_e32 v20, 0xffff0000, v154
	v_pk_fma_f32 v[22:23], v[142:143], v[22:23], v[86:87]
	v_pk_add_f32 v[26:27], v[84:85], v[86:87] neg_lo:[0,1] neg_hi:[0,1]
	v_pk_add_f32 v[16:17], v[16:17], v[18:19] neg_lo:[0,1] neg_hi:[0,1]
	v_pk_fma_f32 v[80:81], v[140:141], v[26:27], v[22:23]
	v_pk_fma_f32 v[16:17], v[24:25], v[16:17], v[18:19]
	v_pk_add_f32 v[22:23], v[20:21], v[18:19] neg_lo:[0,1] neg_hi:[0,1]
	v_and_b32_e32 v27, 0xffff0000, v155
	v_pk_fma_f32 v[82:83], v[28:29], v[22:23], v[16:17]
	v_pk_add_f32 v[16:17], v[86:87], v[84:85] neg_lo:[0,1] neg_hi:[0,1]
	v_lshlrev_b32_e32 v23, 16, v155
	v_pk_fma_f32 v[86:87], v[142:143], v[16:17], v[84:85]
	v_mov_b32_e32 v16, v8
	v_mov_b32_e32 v17, v10
	v_mov_b32_e32 v10, v9
	v_pk_mul_f32 v[142:143], v[16:17], v[54:55]
	v_pk_mul_f32 v[144:145], v[56:57], v[10:11]
	v_mov_b32_e32 v8, v143
	v_mov_b32_e32 v9, v145
	v_pk_mul_f32 v[146:147], v[8:9], v[8:9]
	v_mov_b32_e32 v8, v12
	v_mov_b32_e32 v9, v14
	v_mov_b32_e32 v14, v13
	v_mul_f32_e32 v139, v142, v142
	v_pk_mul_f32 v[148:149], v[72:73], v[8:9]
	v_pk_mul_f32 v[12:13], v[74:75], v[14:15]
	v_fmac_f32_e32 v139, v144, v144
	v_mov_b32_e32 v150, v148
	v_mov_b32_e32 v151, v12
	v_add_f32_e32 v139, v139, v146
	v_pk_mul_f32 v[150:151], v[150:151], v[150:151]
	v_add_f32_e32 v139, v139, v147
	v_mov_b32_e32 v152, v149
	v_mov_b32_e32 v153, v13
	v_add_f32_e32 v139, v139, v150
	v_pk_mul_f32 v[152:153], v[152:153], v[152:153]
	v_add_f32_e32 v139, v139, v151
	v_add_f32_e32 v139, v139, v152
	v_add_f32_e32 v139, v139, v153
	v_lshlrev_b32_e32 v22, 16, v156
	v_pk_add_f32 v[22:23], v[22:23], v[84:85] neg_lo:[0,1] neg_hi:[0,1]
	v_add_f32_dpp v139, v139, v139 quad_perm:[1,0,3,2] row_mask:0xf bank_mask:0xf bound_ctrl:1
	v_pk_fma_f32 v[84:85], v[140:141], v[22:23], v[86:87]
	v_and_b32_e32 v26, 0xffff0000, v156
	v_add_f32_dpp v139, v139, v139 quad_perm:[2,3,0,1] row_mask:0xf bank_mask:0xf bound_ctrl:1
	v_pk_add_f32 v[18:19], v[18:19], v[20:21] neg_lo:[0,1] neg_hi:[0,1]
	v_pk_mul_f32 v[140:141], v[78:79], v[14:15]
	v_add_f32_dpp v139, v139, v139 row_half_mirror row_mask:0xf bank_mask:0xf bound_ctrl:1
	v_mul_f32_e32 v146, 0x4f800000, v139
	v_cmp_gt_f32_e32 vcc, s71, v139
	v_pk_fma_f32 v[18:19], v[24:25], v[18:19], v[20:21]
	v_pk_add_f32 v[20:21], v[26:27], v[20:21] neg_lo:[0,1] neg_hi:[0,1]
	v_cndmask_b32_e32 v139, v139, v146, vcc
	v_sqrt_f32_e32 v146, v139
	v_mul_f32_e32 v156, v36, v5
	v_mul_f32_e32 v157, v31, v6
	v_mul_f32_e32 v158, v37, v7
	v_add_u32_e32 v22, -1, v146
	v_fma_f32 v23, -v22, v146, v139
	v_cmp_ge_f32_e64 s[0:1], 0, v23
	v_add_u32_e32 v23, 1, v146
	v_fma_f32 v86, -v23, v146, v139
	v_cndmask_b32_e64 v22, v146, v22, s[0:1]
	v_cmp_lt_f32_e64 s[0:1], 0, v86
	v_pk_fma_f32 v[86:87], v[28:29], v[20:21], v[18:19]
	v_pk_mul_f32 v[28:29], v[76:77], v[8:9]
	v_cndmask_b32_e64 v22, v22, v23, s[0:1]
	v_mul_f32_e32 v23, 0x37800000, v22
	v_cndmask_b32_e32 v22, v22, v23, vcc
	v_cmp_class_f32_e32 vcc, v139, v128
	v_lshlrev_b64 v[36:37], 11, v[94:95]
	v_lshl_add_u64 v[36:37], s[54:55], 0, v[36:37]
	v_cndmask_b32_e32 v22, v22, v139, vcc
	v_max_f32_e32 v22, 0x2b8cbccc, v22
	v_div_scale_f32 v23, s[0:1], v22, v22, 1.0
	v_rcp_f32_e32 v139, v23
	v_lshl_add_u64 v[36:37], v[36:37], 0, v[34:35]
	v_mul_f32_e32 v121, v156, v56
	v_mul_f32_e32 v122, v157, v55
	v_fma_f32 v18, -v23, v139, 1.0
	v_fmac_f32_e32 v139, v18, v139
	v_div_scale_f32 v18, vcc, 1.0, v22, 1.0
	v_mul_f32_e32 v19, v18, v139
	v_fma_f32 v20, -v23, v19, v18
	v_fmac_f32_e32 v19, v20, v139
	v_fma_f32 v18, -v23, v19, v18
	v_div_fmas_f32 v18, v18, v139, v19
	v_div_fixup_f32 v18, v18, v22, 1.0
	v_pk_mul_f32 v[20:21], v[142:143], v[18:19] op_sel_hi:[1,0]
	v_pk_mul_f32 v[22:23], v[148:149], v[18:19] op_sel_hi:[1,0]
	v_bfe_u32 v19, v20, 16, 1
	v_bfe_u32 v24, v21, 16, 1
	v_bfe_u32 v25, v22, 16, 1
	v_bfe_u32 v26, v23, 16, 1
	v_add3_u32 v23, v23, v26, s60
	v_add3_u32 v22, v22, v25, s60
	v_add3_u32 v21, v21, v24, s60
	v_add3_u32 v19, v20, v19, s60
	v_pk_mul_f32 v[24:25], v[58:59], v[16:17]
	v_pk_mul_f32 v[26:27], v[60:61], v[10:11]
	v_lshrrev_b32_e32 v139, 16, v19
	v_lshrrev_b32_e32 v19, 16, v21
	v_mov_b32_e32 v20, v27
	v_mov_b32_e32 v21, v25
	v_mul_f32_e32 v148, v24, v24
	v_pk_mul_f32 v[20:21], v[20:21], v[20:21]
	v_fmac_f32_e32 v148, v26, v26
	v_mov_b32_e32 v142, v140
	v_mov_b32_e32 v143, v28
	v_add_f32_e32 v21, v21, v148
	v_pk_mul_f32 v[142:143], v[142:143], v[142:143]
	v_add_f32_e32 v20, v20, v21
	v_lshrrev_b32_e32 v146, 16, v22
	v_lshrrev_b32_e32 v147, 16, v23
	v_pk_mul_f32 v[22:23], v[144:145], v[18:19] op_sel_hi:[1,0]
	v_mov_b32_e32 v144, v141
	v_mov_b32_e32 v145, v29
	v_add_f32_e32 v20, v143, v20
	v_pk_mul_f32 v[144:145], v[144:145], v[144:145]
	v_add_f32_e32 v20, v142, v20
	v_add_f32_e32 v20, v145, v20
	v_add_f32_e32 v20, v144, v20
	v_pk_mul_f32 v[12:13], v[12:13], v[18:19] op_sel_hi:[1,0]
	v_and_or_b32 v19, v23, s56, v19
	v_add_f32_dpp v20, v20, v20 quad_perm:[1,0,3,2] row_mask:0xf bank_mask:0xf bound_ctrl:1
	v_mul_f32_e32 v123, v158, v57
	v_mul_f32_e32 v124, v163, v58
	v_add_f32_dpp v20, v20, v20 quad_perm:[2,3,0,1] row_mask:0xf bank_mask:0xf bound_ctrl:1
	v_mul_f32_e32 v125, v168, v60
	v_mul_f32_e32 v137, v169, v59
	v_add_f32_dpp v20, v20, v20 row_half_mirror row_mask:0xf bank_mask:0xf bound_ctrl:1
	v_mul_f32_e32 v21, 0x4f800000, v20
	v_cmp_gt_f32_e32 vcc, s71, v20
	v_mul_f32_e32 v156, v116, v82
	v_mul_f32_e32 v157, v115, v81
	v_cndmask_b32_e32 v142, v20, v21, vcc
	v_sqrt_f32_e32 v143, v142
	v_and_or_b32 v20, v12, s56, v146
	v_and_or_b32 v21, v13, s56, v147
	v_mul_f32_e32 v158, v117, v83
	v_add_u32_e32 v12, -1, v143
	v_fma_f32 v13, -v12, v143, v142
	v_cmp_ge_f32_e64 s[0:1], 0, v13
	v_add_u32_e32 v13, 1, v143
	v_fma_f32 v18, -v13, v143, v142
	v_cndmask_b32_e64 v12, v143, v12, s[0:1]
	v_cmp_lt_f32_e64 s[0:1], 0, v18
	v_and_or_b32 v18, v22, s56, v139
	global_store_dwordx4 v[46:47], v[18:21], off
	v_cndmask_b32_e64 v12, v12, v13, s[0:1]
	v_mul_f32_e32 v13, 0x37800000, v12
	v_cndmask_b32_e32 v12, v12, v13, vcc
	v_cmp_class_f32_e32 vcc, v142, v128
	s_nop 1
	v_cndmask_b32_e32 v12, v12, v142, vcc
	v_max_f32_e32 v12, 0x2b8cbccc, v12
	v_div_scale_f32 v13, s[0:1], v12, v12, 1.0
	v_rcp_f32_e32 v142, v13
	s_nop 0
	v_fma_f32 v18, -v13, v142, 1.0
	v_fmac_f32_e32 v142, v18, v142
	v_div_scale_f32 v18, vcc, 1.0, v12, 1.0
	v_mul_f32_e32 v19, v18, v142
	v_fma_f32 v20, -v13, v19, v18
	v_fmac_f32_e32 v19, v20, v142
	v_fma_f32 v13, -v13, v19, v18
	v_div_fmas_f32 v13, v13, v142, v19
	v_div_fixup_f32 v12, v13, v12, 1.0
	v_pk_mul_f32 v[18:19], v[24:25], v[12:13] op_sel_hi:[1,0]
	v_pk_mul_f32 v[20:21], v[28:29], v[12:13] op_sel_hi:[1,0]
	v_bfe_u32 v13, v18, 16, 1
	v_bfe_u32 v22, v19, 16, 1
	v_bfe_u32 v23, v20, 16, 1
	v_bfe_u32 v24, v21, 16, 1
	v_add3_u32 v21, v21, v24, s60
	v_add3_u32 v20, v20, v23, s60
	v_add3_u32 v19, v19, v22, s60
	v_add3_u32 v13, v18, v13, s60
	v_pk_mul_f32 v[22:23], v[16:17], v[62:63]
	v_pk_mul_f32 v[24:25], v[66:67], v[10:11]
	v_lshrrev_b32_e32 v139, 16, v13
	v_lshrrev_b32_e32 v146, 16, v19
	v_lshrrev_b32_e32 v147, 16, v20
	v_lshrrev_b32_e32 v148, 16, v21
	v_pk_mul_f32 v[18:19], v[26:27], v[12:13] op_sel_hi:[1,0]
	v_mov_b32_e32 v20, v25
	v_mov_b32_e32 v21, v23
	v_mul_f32_e32 v13, v22, v22
	v_pk_mul_f32 v[20:21], v[20:21], v[20:21]
	v_pk_mul_f32 v[26:27], v[80:81], v[8:9]
	v_pk_mul_f32 v[28:29], v[82:83], v[14:15]
	v_fmac_f32_e32 v13, v24, v24
	v_mov_b32_e32 v142, v28
	v_mov_b32_e32 v143, v26
	v_add_f32_e32 v13, v21, v13
	v_pk_mul_f32 v[142:143], v[142:143], v[142:143]
	v_add_f32_e32 v13, v20, v13
	v_mov_b32_e32 v144, v29
	v_mov_b32_e32 v145, v27
	v_add_f32_e32 v13, v143, v13
	v_pk_mul_f32 v[144:145], v[144:145], v[144:145]
	v_add_f32_e32 v13, v142, v13
	v_add_f32_e32 v13, v145, v13
	v_add_f32_e32 v13, v144, v13
	v_and_or_b32 v19, v19, s56, v146
	v_and_or_b32 v18, v18, s56, v139
	v_add_f32_dpp v13, v13, v13 quad_perm:[1,0,3,2] row_mask:0xf bank_mask:0xf bound_ctrl:1
	v_pk_mul_f32 v[16:17], v[16:17], v[68:69]
	v_pk_mul_f32 v[14:15], v[86:87], v[14:15]
	v_add_f32_dpp v13, v13, v13 quad_perm:[2,3,0,1] row_mask:0xf bank_mask:0xf bound_ctrl:1
	s_nop 1
	v_add_f32_dpp v13, v13, v13 row_half_mirror row_mask:0xf bank_mask:0xf bound_ctrl:1
	v_mul_f32_e32 v20, 0x4f800000, v13
	v_cmp_gt_f32_e32 vcc, s71, v13
	s_nop 1
	v_cndmask_b32_e32 v142, v13, v20, vcc
	v_sqrt_f32_e32 v143, v142
	v_pk_mul_f32 v[12:13], v[140:141], v[12:13] op_sel_hi:[1,0]
	s_nop 0
	v_and_or_b32 v20, v12, s56, v147
	v_add_u32_e32 v12, -1, v143
	v_and_or_b32 v21, v13, s56, v148
	v_fma_f32 v13, -v12, v143, v142
	v_cmp_ge_f32_e64 s[0:1], 0, v13
	v_add_u32_e32 v13, 1, v143
	v_fma_f32 v140, -v13, v143, v142
	v_cndmask_b32_e64 v12, v143, v12, s[0:1]
	v_cmp_lt_f32_e64 s[0:1], 0, v140
	global_store_dwordx4 v[48:49], v[18:21], off
	s_nop 0
	v_cndmask_b32_e64 v12, v12, v13, s[0:1]
	v_mul_f32_e32 v13, 0x37800000, v12
	v_cndmask_b32_e32 v12, v12, v13, vcc
	v_cmp_class_f32_e32 vcc, v142, v128
	s_nop 1
	v_cndmask_b32_e32 v12, v12, v142, vcc
	v_max_f32_e32 v12, 0x2b8cbccc, v12
	v_div_scale_f32 v13, s[0:1], v12, v12, 1.0
	v_rcp_f32_e32 v140, v13
	s_nop 0
	v_fma_f32 v18, -v13, v140, 1.0
	v_fmac_f32_e32 v140, v18, v140
	v_div_scale_f32 v18, vcc, 1.0, v12, 1.0
	v_mul_f32_e32 v19, v18, v140
	v_fma_f32 v20, -v13, v19, v18
	v_fmac_f32_e32 v19, v20, v140
	v_fma_f32 v13, -v13, v19, v18
	v_div_fmas_f32 v13, v13, v140, v19
	v_div_fixup_f32 v12, v13, v12, 1.0
	v_pk_mul_f32 v[20:21], v[26:27], v[12:13] op_sel_hi:[1,0]
	v_pk_mul_f32 v[18:19], v[22:23], v[12:13] op_sel_hi:[1,0]
	v_bfe_u32 v23, v20, 16, 1
	v_bfe_u32 v26, v21, 16, 1
	v_add3_u32 v21, v21, v26, s60
	v_add3_u32 v20, v20, v23, s60
	v_lshrrev_b32_e32 v27, 16, v20
	v_lshrrev_b32_e32 v139, 16, v21
	v_pk_mul_f32 v[20:21], v[10:11], v[70:71]
	v_bfe_u32 v22, v19, 16, 1
	v_mov_b32_e32 v10, v21
	v_mov_b32_e32 v11, v17
	v_mul_f32_e32 v140, v16, v16
	v_bfe_u32 v13, v18, 16, 1
	v_add3_u32 v19, v19, v22, s60
	v_pk_mul_f32 v[10:11], v[10:11], v[10:11]
	v_pk_mul_f32 v[22:23], v[84:85], v[8:9]
	v_fmac_f32_e32 v140, v20, v20
	v_add3_u32 v13, v18, v13, s60
	v_mov_b32_e32 v8, v14
	v_mov_b32_e32 v9, v22
	v_add_f32_e32 v11, v11, v140
	v_lshrrev_b32_e32 v13, 16, v13
	v_pk_mul_f32 v[8:9], v[8:9], v[8:9]
	v_add_f32_e32 v10, v10, v11
	v_lshrrev_b32_e32 v26, 16, v19
	v_pk_mul_f32 v[18:19], v[24:25], v[12:13] op_sel_hi:[1,0]
	v_mov_b32_e32 v24, v15
	v_mov_b32_e32 v25, v23
	v_add_f32_e32 v9, v9, v10
	v_pk_mul_f32 v[24:25], v[24:25], v[24:25]
	v_add_f32_e32 v8, v8, v9
	v_add_f32_e32 v8, v25, v8
	v_add_f32_e32 v8, v24, v8
	s_nop 1
	v_add_f32_dpp v8, v8, v8 quad_perm:[1,0,3,2] row_mask:0xf bank_mask:0xf bound_ctrl:1
	s_nop 1
	v_add_f32_dpp v8, v8, v8 quad_perm:[2,3,0,1] row_mask:0xf bank_mask:0xf bound_ctrl:1
	s_nop 1
	v_add_f32_dpp v8, v8, v8 row_half_mirror row_mask:0xf bank_mask:0xf bound_ctrl:1
	v_mul_f32_e32 v9, 0x4f800000, v8
	v_cmp_gt_f32_e32 vcc, s71, v8
	s_nop 1
	v_cndmask_b32_e32 v24, v8, v9, vcc
	v_sqrt_f32_e32 v25, v24
	v_pk_mul_f32 v[8:9], v[28:29], v[12:13] op_sel_hi:[1,0]
	s_nop 0
	v_and_or_b32 v10, v8, s56, v27
	v_add_u32_e32 v8, -1, v25
	v_and_or_b32 v11, v9, s56, v139
	v_fma_f32 v9, -v8, v25, v24
	v_cmp_ge_f32_e64 s[0:1], 0, v9
	v_add_u32_e32 v9, 1, v25
	v_fma_f32 v12, -v9, v25, v24
	v_cndmask_b32_e64 v8, v25, v8, s[0:1]
	v_cmp_lt_f32_e64 s[0:1], 0, v12
	v_mul_f32_e32 v139, v4, v30
	v_mul_f32_e32 v120, v139, v54
	v_cndmask_b32_e64 v8, v8, v9, s[0:1]
	v_mul_f32_e32 v9, 0x37800000, v8
	v_cndmask_b32_e32 v8, v8, v9, vcc
	v_cmp_class_f32_e32 vcc, v24, v128
	v_and_or_b32 v9, v19, s56, v26
	v_mul_f32_e32 v139, v175, v62
	v_cndmask_b32_e32 v8, v8, v24, vcc
	v_max_f32_e32 v12, 0x2b8cbccc, v8
	v_div_scale_f32 v24, s[0:1], v12, v12, 1.0
	v_rcp_f32_e32 v25, v24
	v_and_or_b32 v8, v18, s56, v13
	global_store_dwordx4 v[50:51], v[8:11], off
	s_nop 1
	v_fma_f32 v8, -v24, v25, 1.0
	v_fmac_f32_e32 v25, v8, v25
	v_div_scale_f32 v8, vcc, 1.0, v12, 1.0
	v_mul_f32_e32 v9, v8, v25
	v_fma_f32 v10, -v24, v9, v8
	v_fmac_f32_e32 v9, v10, v25
	v_fma_f32 v8, -v24, v9, v8
	v_div_fmas_f32 v8, v8, v25, v9
	v_div_fixup_f32 v8, v8, v12, 1.0
	v_pk_mul_f32 v[10:11], v[16:17], v[8:9] op_sel_hi:[1,0]
	v_pk_mul_f32 v[12:13], v[22:23], v[8:9] op_sel_hi:[1,0]
	v_bfe_u32 v9, v10, 16, 1
	v_bfe_u32 v16, v11, 16, 1
	v_bfe_u32 v17, v12, 16, 1
	v_bfe_u32 v18, v13, 16, 1
	v_add3_u32 v13, v13, v18, s60
	v_add3_u32 v12, v12, v17, s60
	v_add3_u32 v11, v11, v16, s60
	v_add3_u32 v9, v10, v9, s60
	v_lshrrev_b32_e32 v16, 16, v9
	v_lshrrev_b32_e32 v17, 16, v11
	v_lshrrev_b32_e32 v10, 16, v12
	v_lshrrev_b32_e32 v11, 16, v13
	v_pk_mul_f32 v[12:13], v[20:21], v[8:9] op_sel_hi:[1,0]
	v_pk_mul_f32 v[8:9], v[14:15], v[8:9] op_sel_hi:[1,0]
	v_lshlrev_b64 v[24:25], 11, v[90:91]
	v_and_or_b32 v11, v9, s56, v11
	v_and_or_b32 v10, v8, s56, v10
	v_and_or_b32 v9, v13, s56, v17
	v_and_or_b32 v8, v12, s56, v16
	global_store_dwordx4 v[52:53], v[8:11], off
	s_waitcnt lgkmcnt(0)
	s_barrier
	v_mov_b32_e32 v8, v65
	v_lshl_add_u64 v[24:25], s[54:55], 0, v[24:25]
	v_mbcnt_lo_u32_b32 v8, -1, v8
	v_mbcnt_hi_u32_b32 v10, -1, v8
	v_and_b32_e32 v20, 31, v10
	v_or_b32_e32 v8, v20, v136
	v_ashrrev_i32_e32 v9, 31, v8
	v_ashrrev_i32_e32 v10, 2, v10
	v_lshlrev_b64 v[8:9], 8, v[8:9]
	v_and_b32_e32 v12, -8, v10
	v_lshl_add_u64 v[8:9], s[54:55], 0, v[8:9]
	v_ashrrev_i32_e32 v13, 31, v12
	v_lshl_add_u64 v[14:15], v[12:13], 1, v[8:9]
	v_add_co_u32_e32 v8, vcc, s72, v14
	v_lshl_add_u64 v[166:167], v[14:15], 0, s[48:49]
	s_nop 0
	v_addc_co_u32_e32 v9, vcc, 0, v15, vcc
	v_add_co_u32_e32 v164, vcc, s73, v14
	global_load_dwordx4 v[208:211], v[8:9], off
	s_nop 0
	v_addc_co_u32_e32 v165, vcc, 0, v15, vcc
	global_load_dwordx4 v[212:215], v[164:165], off
	global_load_dwordx4 v[216:219], v[166:167], off offset:32
	global_load_dwordx4 v[220:223], v[164:165], off offset:32
	global_load_dwordx4 v[224:227], v[166:167], off offset:64
	global_load_dwordx4 v[228:231], v[166:167], off offset:96
	global_load_dwordx4 v[232:235], v[164:165], off offset:64
	global_load_dwordx4 v[236:239], v[164:165], off offset:96
	global_load_dwordx4 v[240:243], v[166:167], off offset:128
	global_load_dwordx4 v[244:247], v[164:165], off offset:128
	global_load_dwordx4 v[248:251], v[166:167], off offset:160
	v_lshlrev_b32_e32 v0, 1, v12
	v_mad_u32_u24 v191, v20, s65, v0
	ds_read_b128 v[20:23], v191
	ds_read_b128 v[106:109], v191 offset:32
	v_lshrrev_b32_e32 v0, 3, v135
	v_and_b32_e32 v0, 4, v0
	v_mul_u32_u24_e32 v0, 0x410, v0
	v_lshl_add_u64 v[180:181], v[24:25], 0, v[34:35]
	v_lshlrev_b64 v[24:25], 11, v[92:93]
	v_lshl_add_u32 v192, v1, 2, v0
	v_mul_lo_u32 v0, v138, s70
	v_lshl_add_u64 v[24:25], s[54:55], 0, v[24:25]
	v_add_u32_e32 v118, v64, v0
	s_waitcnt lgkmcnt(0)
	s_waitcnt vmcnt(10)
	v_mfma_f32_32x32x16_bf16 v[0:15], v[20:23], v[208:211], 0
	global_load_dwordx4 v[208:211], v[164:165], off offset:160
	v_lshl_add_u64 v[182:183], v[24:25], 0, v[34:35]
	v_lshl_add_u64 v[34:35], v[110:111], 0, v[34:35]
	ds_read_b128 v[110:113], v191 offset:64
	v_mul_f32_e32 v138, v170, v61
	s_waitcnt vmcnt(10)
	v_mfma_f32_32x32x16_bf16 v[16:31], v[20:23], v[212:215], 0
	global_load_dwordx4 v[212:215], v[166:167], off offset:192
	s_waitcnt vmcnt(10)
	v_mfma_f32_32x32x16_bf16 v[0:15], v[106:109], v[216:219], v[0:15]
	global_load_dwordx4 v[216:219], v[164:165], off offset:192
	v_mul_f32_e32 v140, v176, v66
	v_mul_f32_e32 v141, v177, v63
	v_mul_f32_e32 v142, v178, v67
	v_mul_f32_e32 v143, v179, v68
	s_waitcnt vmcnt(10)
	v_mfma_f32_32x32x16_bf16 v[16:31], v[106:109], v[220:223], v[16:31]
	global_load_dwordx4 v[220:223], v[166:167], off offset:224
	ds_read_b128 v[106:109], v191 offset:96
	v_mul_f32_e32 v144, v184, v70
	v_mul_f32_e32 v145, v185, v69
	v_mul_f32_e32 v146, v186, v71
	v_mul_f32_e32 v147, v159, v72
	v_mul_f32_e32 v159, v187, v84
	s_waitcnt lgkmcnt(1)
	s_waitcnt vmcnt(10)
	v_mfma_f32_32x32x16_bf16 v[0:15], v[110:113], v[224:227], v[0:15]
	global_load_dwordx4 v[224:227], v[164:165], off offset:224
	v_mul_f32_e32 v148, v160, v74
	v_mul_f32_e32 v149, v161, v73
	v_mul_f32_e32 v150, v162, v75
	v_mul_f32_e32 v151, v171, v76
	v_mul_f32_e32 v160, v188, v86
	v_mul_f32_e32 v161, v189, v85
	v_mul_f32_e32 v162, v190, v87
	s_waitcnt vmcnt(9)
	v_mfma_f32_32x32x16_bf16 v[16:31], v[110:113], v[232:235], v[16:31]
	v_mul_f32_e32 v152, v172, v78
	v_mul_f32_e32 v153, v173, v77
	v_mul_f32_e32 v154, v174, v79
	v_mul_f32_e32 v155, v114, v80
	s_waitcnt lgkmcnt(0)
	v_mfma_f32_32x32x16_bf16 v[0:15], v[106:109], v[228:231], v[0:15]
	s_waitcnt vmcnt(8)
	v_mfma_f32_32x32x16_bf16 v[16:31], v[106:109], v[236:239], v[16:31]
	ds_read_b128 v[106:109], v191 offset:128
	ds_read_b128 v[114:117], v191 offset:160
	s_waitcnt lgkmcnt(0)
	s_waitcnt vmcnt(7)
	v_mfma_f32_32x32x16_bf16 v[0:15], v[106:109], v[240:243], v[0:15]
	s_waitcnt vmcnt(6)
	v_mfma_f32_32x32x16_bf16 v[16:31], v[106:109], v[244:247], v[16:31]
	s_waitcnt vmcnt(5)
	v_mfma_f32_32x32x16_bf16 v[0:15], v[114:117], v[248:251], v[0:15]
	ds_read_b128 v[110:113], v191 offset:192
	s_waitcnt lgkmcnt(0)
	s_waitcnt vmcnt(4)
	v_mfma_f32_32x32x16_bf16 v[16:31], v[114:117], v[208:211], v[16:31]
	ds_read_b128 v[114:117], v191 offset:224
	s_waitcnt vmcnt(3)
	v_mfma_f32_32x32x16_bf16 v[0:15], v[110:113], v[212:215], v[0:15]
	s_waitcnt vmcnt(2)
	v_mfma_f32_32x32x16_bf16 v[16:31], v[110:113], v[216:219], v[16:31]
	s_waitcnt lgkmcnt(0)
	s_waitcnt vmcnt(1)
	v_mfma_f32_32x32x16_bf16 v[0:15], v[114:117], v[220:223], v[0:15]
	s_waitcnt vmcnt(0)
	v_mfma_f32_32x32x16_bf16 v[16:31], v[114:117], v[224:227], v[16:31]
	v_add_u32_e32 v163, 0x6000, v192
	v_add_u32_e32 v164, 0x6400, v192
	v_add_u32_e32 v165, 0x6800, v192
	v_add_u32_e32 v166, 0x6c00, v192
	v_add_u32_e32 v167, 0x8000, v192
	v_add_u32_e32 v168, 0x8400, v192
	v_add_u32_e32 v169, 0x8800, v192
	v_add_u32_e32 v170, 0x8c00, v192
	v_add_u32_e32 v171, 0xa000, v192
	v_add_u32_e32 v172, 0xa400, v192
	v_add_u32_e32 v173, 0xa800, v192
	v_add_u32_e32 v174, 0xac00, v192
	v_add_u32_e32 v175, 0xc200, v192
	v_add_u32_e32 v176, 0xc600, v192
	v_add_u32_e32 v177, 0xca00, v192
	v_add_u32_e32 v178, 0xce00, v192
	ds_write2_b32 v163, v0, v16 offset0:128 offset1:160
	ds_write2_b32 v164, v1, v17 offset0:132 offset1:164
	ds_write2_b32 v165, v2, v18 offset0:136 offset1:168
	ds_write2_b32 v166, v3, v19 offset0:140 offset1:172
	ds_write2_b32 v167, v4, v20 offset0:160 offset1:192
	ds_write2_b32 v168, v5, v21 offset0:164 offset1:196
	ds_write2_b32 v169, v6, v22 offset0:168 offset1:200
	ds_write2_b32 v170, v7, v23 offset0:172 offset1:204
	ds_write2_b32 v171, v8, v24 offset0:192 offset1:224
	ds_write2_b32 v172, v9, v25 offset0:196 offset1:228
	ds_write2_b32 v173, v10, v26 offset0:200 offset1:232
	ds_write2_b32 v174, v11, v27 offset0:204 offset1:236
	ds_write2_b32 v175, v12, v28 offset0:96 offset1:128
	ds_write2_b32 v176, v13, v29 offset0:100 offset1:132
	ds_write2_b32 v177, v14, v30 offset0:104 offset1:136
	ds_write2_b32 v178, v15, v31 offset0:108 offset1:140
	s_waitcnt lgkmcnt(0)
	s_barrier
	ds_read_b128 v[0:3], v118 offset:25088
	ds_read_b128 v[4:7], v118 offset:25104
	s_add_u32 s79, s54, 0x1b0d7900
	s_addc_u32 s80, s55, 0
	s_add_u32 s81, s54, 0x1d4d7900
	s_waitcnt lgkmcnt(1)
	v_and_b32_sdwa v8, v2, v134 dst_sel:DWORD dst_unused:UNUSED_PAD src0_sel:WORD_1 src1_sel:DWORD
	v_and_b32_sdwa v9, v0, v134 dst_sel:DWORD dst_unused:UNUSED_PAD src0_sel:WORD_1 src1_sel:DWORD
	v_add3_u32 v2, v2, v8, s60
	v_and_b32_sdwa v8, v3, v134 dst_sel:DWORD dst_unused:UNUSED_PAD src0_sel:WORD_1 src1_sel:DWORD
	v_add3_u32 v0, v0, v9, s60
	v_and_b32_sdwa v9, v1, v134 dst_sel:DWORD dst_unused:UNUSED_PAD src0_sel:WORD_1 src1_sel:DWORD
	v_add3_u32 v3, v3, v8, s60
	v_add3_u32 v1, v1, v9, s60
	v_and_b32_e32 v3, 0xffff0000, v3
	v_and_b32_e32 v8, 0xffff0000, v1
	v_or_b32_sdwa v1, v3, v2 dst_sel:DWORD dst_unused:UNUSED_PAD src0_sel:DWORD src1_sel:WORD_1
	s_waitcnt lgkmcnt(0)
	v_and_b32_sdwa v2, v6, v134 dst_sel:DWORD dst_unused:UNUSED_PAD src0_sel:WORD_1 src1_sel:DWORD
	v_and_b32_sdwa v3, v4, v134 dst_sel:DWORD dst_unused:UNUSED_PAD src0_sel:WORD_1 src1_sel:DWORD
	v_add3_u32 v4, v4, v3, s60
	v_add3_u32 v2, v6, v2, s60
	v_and_b32_sdwa v3, v7, v134 dst_sel:DWORD dst_unused:UNUSED_PAD src0_sel:WORD_1 src1_sel:DWORD
	v_and_b32_sdwa v6, v5, v134 dst_sel:DWORD dst_unused:UNUSED_PAD src0_sel:WORD_1 src1_sel:DWORD
	v_add3_u32 v3, v7, v3, s60
	v_add3_u32 v5, v5, v6, s60
	v_and_b32_e32 v3, 0xffff0000, v3
	v_and_b32_e32 v5, 0xffff0000, v5
	v_or_b32_sdwa v3, v3, v2 dst_sel:DWORD dst_unused:UNUSED_PAD src0_sel:DWORD src1_sel:WORD_1
	v_or_b32_sdwa v2, v5, v4 dst_sel:DWORD dst_unused:UNUSED_PAD src0_sel:DWORD src1_sel:WORD_1
	v_add_co_u32_e32 v4, vcc, s75, v180
	v_or_b32_sdwa v0, v8, v0 dst_sel:DWORD dst_unused:UNUSED_PAD src0_sel:DWORD src1_sel:WORD_1
	s_nop 0
	v_addc_co_u32_e32 v5, vcc, 0, v181, vcc
	global_store_dwordx4 v[4:5], v[0:3], off offset:2816
	ds_read_b128 v[0:3], v118 offset:26128
	ds_read_b128 v[4:7], v118 offset:26144
	s_addc_u32 s82, s55, 0
	s_add_u32 s83, s54, 0x1738000
	s_addc_u32 s84, s55, 0
	s_waitcnt lgkmcnt(0)
	v_and_b32_sdwa v8, v2, v134 dst_sel:DWORD dst_unused:UNUSED_PAD src0_sel:WORD_1 src1_sel:DWORD
	v_and_b32_sdwa v9, v0, v134 dst_sel:DWORD dst_unused:UNUSED_PAD src0_sel:WORD_1 src1_sel:DWORD
	v_add3_u32 v2, v2, v8, s60
	v_and_b32_sdwa v8, v3, v134 dst_sel:DWORD dst_unused:UNUSED_PAD src0_sel:WORD_1 src1_sel:DWORD
	v_add3_u32 v0, v0, v9, s60
	v_and_b32_sdwa v9, v1, v134 dst_sel:DWORD dst_unused:UNUSED_PAD src0_sel:WORD_1 src1_sel:DWORD
	v_add3_u32 v3, v3, v8, s60
	v_add3_u32 v1, v1, v9, s60
	v_and_b32_e32 v3, 0xffff0000, v3
	v_and_b32_e32 v8, 0xffff0000, v1
	v_or_b32_sdwa v1, v3, v2 dst_sel:DWORD dst_unused:UNUSED_PAD src0_sel:DWORD src1_sel:WORD_1
	v_and_b32_sdwa v2, v6, v134 dst_sel:DWORD dst_unused:UNUSED_PAD src0_sel:WORD_1 src1_sel:DWORD
	v_and_b32_sdwa v3, v4, v134 dst_sel:DWORD dst_unused:UNUSED_PAD src0_sel:WORD_1 src1_sel:DWORD
	v_add3_u32 v4, v4, v3, s60
	v_add3_u32 v2, v6, v2, s60
	v_and_b32_sdwa v3, v7, v134 dst_sel:DWORD dst_unused:UNUSED_PAD src0_sel:WORD_1 src1_sel:DWORD
	v_and_b32_sdwa v6, v5, v134 dst_sel:DWORD dst_unused:UNUSED_PAD src0_sel:WORD_1 src1_sel:DWORD
	v_add3_u32 v3, v7, v3, s60
	v_add3_u32 v5, v5, v6, s60
	v_and_b32_e32 v3, 0xffff0000, v3
	v_and_b32_e32 v5, 0xffff0000, v5
	v_or_b32_sdwa v3, v3, v2 dst_sel:DWORD dst_unused:UNUSED_PAD src0_sel:DWORD src1_sel:WORD_1
	v_or_b32_sdwa v2, v5, v4 dst_sel:DWORD dst_unused:UNUSED_PAD src0_sel:DWORD src1_sel:WORD_1
	v_add_co_u32_e32 v4, vcc, s75, v182
	v_or_b32_sdwa v0, v8, v0 dst_sel:DWORD dst_unused:UNUSED_PAD src0_sel:DWORD src1_sel:WORD_1
	s_nop 0
	v_addc_co_u32_e32 v5, vcc, 0, v183, vcc
	global_store_dwordx4 v[4:5], v[0:3], off offset:2816
	ds_read_b128 v[0:3], v118 offset:27168
	ds_read_b128 v[4:7], v118 offset:27184
	v_lshl_add_u64 v[88:89], v[88:89], 0, s[50:51]
	s_mov_b64 s[8:9], -1
	s_waitcnt lgkmcnt(0)
	v_and_b32_sdwa v8, v2, v134 dst_sel:DWORD dst_unused:UNUSED_PAD src0_sel:WORD_1 src1_sel:DWORD
	v_and_b32_sdwa v9, v0, v134 dst_sel:DWORD dst_unused:UNUSED_PAD src0_sel:WORD_1 src1_sel:DWORD
	v_add3_u32 v2, v2, v8, s60
	v_and_b32_sdwa v8, v3, v134 dst_sel:DWORD dst_unused:UNUSED_PAD src0_sel:WORD_1 src1_sel:DWORD
	v_add3_u32 v0, v0, v9, s60
	v_and_b32_sdwa v9, v1, v134 dst_sel:DWORD dst_unused:UNUSED_PAD src0_sel:WORD_1 src1_sel:DWORD
	v_add3_u32 v3, v3, v8, s60
	v_add3_u32 v1, v1, v9, s60
	v_and_b32_e32 v3, 0xffff0000, v3
	v_and_b32_e32 v8, 0xffff0000, v1
	v_or_b32_sdwa v1, v3, v2 dst_sel:DWORD dst_unused:UNUSED_PAD src0_sel:DWORD src1_sel:WORD_1
	v_and_b32_sdwa v2, v6, v134 dst_sel:DWORD dst_unused:UNUSED_PAD src0_sel:WORD_1 src1_sel:DWORD
	v_and_b32_sdwa v3, v4, v134 dst_sel:DWORD dst_unused:UNUSED_PAD src0_sel:WORD_1 src1_sel:DWORD
	v_add3_u32 v4, v4, v3, s60
	v_add3_u32 v2, v6, v2, s60
	v_and_b32_sdwa v3, v7, v134 dst_sel:DWORD dst_unused:UNUSED_PAD src0_sel:WORD_1 src1_sel:DWORD
	v_and_b32_sdwa v6, v5, v134 dst_sel:DWORD dst_unused:UNUSED_PAD src0_sel:WORD_1 src1_sel:DWORD
	v_add3_u32 v3, v7, v3, s60
	v_add3_u32 v5, v5, v6, s60
	v_and_b32_e32 v3, 0xffff0000, v3
	v_and_b32_e32 v5, 0xffff0000, v5
	v_or_b32_sdwa v3, v3, v2 dst_sel:DWORD dst_unused:UNUSED_PAD src0_sel:DWORD src1_sel:WORD_1
	v_or_b32_sdwa v2, v5, v4 dst_sel:DWORD dst_unused:UNUSED_PAD src0_sel:DWORD src1_sel:WORD_1
	v_add_co_u32_e32 v4, vcc, s75, v36
	v_or_b32_sdwa v0, v8, v0 dst_sel:DWORD dst_unused:UNUSED_PAD src0_sel:DWORD src1_sel:WORD_1
	s_nop 0
	v_addc_co_u32_e32 v5, vcc, 0, v37, vcc
	global_store_dwordx4 v[4:5], v[0:3], off offset:2816
	ds_read_b128 v[0:3], v119 offset:25088
	ds_read_b128 v[4:7], v119 offset:25104
	s_waitcnt lgkmcnt(0)
	v_and_b32_sdwa v8, v2, v134 dst_sel:DWORD dst_unused:UNUSED_PAD src0_sel:WORD_1 src1_sel:DWORD
	v_and_b32_sdwa v9, v0, v134 dst_sel:DWORD dst_unused:UNUSED_PAD src0_sel:WORD_1 src1_sel:DWORD
	v_add3_u32 v2, v2, v8, s60
	v_and_b32_sdwa v8, v3, v134 dst_sel:DWORD dst_unused:UNUSED_PAD src0_sel:WORD_1 src1_sel:DWORD
	v_add3_u32 v0, v0, v9, s60
	v_and_b32_sdwa v9, v1, v134 dst_sel:DWORD dst_unused:UNUSED_PAD src0_sel:WORD_1 src1_sel:DWORD
	v_add3_u32 v3, v3, v8, s60
	v_add3_u32 v1, v1, v9, s60
	v_and_b32_e32 v3, 0xffff0000, v3
	v_and_b32_e32 v8, 0xffff0000, v1
	v_or_b32_sdwa v1, v3, v2 dst_sel:DWORD dst_unused:UNUSED_PAD src0_sel:DWORD src1_sel:WORD_1
	v_and_b32_sdwa v2, v6, v134 dst_sel:DWORD dst_unused:UNUSED_PAD src0_sel:WORD_1 src1_sel:DWORD
	v_and_b32_sdwa v3, v4, v134 dst_sel:DWORD dst_unused:UNUSED_PAD src0_sel:WORD_1 src1_sel:DWORD
	v_add3_u32 v4, v4, v3, s60
	v_add3_u32 v2, v6, v2, s60
	v_and_b32_sdwa v3, v7, v134 dst_sel:DWORD dst_unused:UNUSED_PAD src0_sel:WORD_1 src1_sel:DWORD
	v_and_b32_sdwa v6, v5, v134 dst_sel:DWORD dst_unused:UNUSED_PAD src0_sel:WORD_1 src1_sel:DWORD
	v_add3_u32 v3, v7, v3, s60
	v_add3_u32 v5, v5, v6, s60
	v_and_b32_e32 v3, 0xffff0000, v3
	v_and_b32_e32 v5, 0xffff0000, v5
	v_or_b32_sdwa v3, v3, v2 dst_sel:DWORD dst_unused:UNUSED_PAD src0_sel:DWORD src1_sel:WORD_1
	v_or_b32_sdwa v2, v5, v4 dst_sel:DWORD dst_unused:UNUSED_PAD src0_sel:DWORD src1_sel:WORD_1
	v_add_co_u32_e32 v4, vcc, s75, v34
	v_or_b32_sdwa v0, v8, v0 dst_sel:DWORD dst_unused:UNUSED_PAD src0_sel:DWORD src1_sel:WORD_1
	s_nop 0
	v_addc_co_u32_e32 v5, vcc, 0, v35, vcc
	global_store_dwordx4 v[4:5], v[0:3], off offset:2816
	s_waitcnt lgkmcnt(0)
	s_barrier
	global_load_dwordx2 v[0:1], v[32:33], off offset:456
	v_and_b32_e32 v8, 7, v135
	v_lshlrev_b64 v[2:3], 8, v[92:93]
	v_lshlrev_b64 v[4:5], 8, v[94:95]
	v_lshlrev_b64 v[6:7], 8, v[96:97]
	v_cmp_eq_u32_e64 s[4:5], 0, v8
	v_or_b32_e32 v2, v2, v126
	v_or_b32_e32 v4, v4, v126
	v_or_b32_e32 v6, v6, v126
	v_lshlrev_b64 v[92:93], 4, v[92:93]
	v_lshlrev_b64 v[94:95], 4, v[94:95]
	v_lshlrev_b64 v[96:97], 4, v[96:97]
	v_lshlrev_b64 v[104:105], 1, v[2:3]
	v_lshlrev_b64 v[106:107], 1, v[4:5]
	v_lshlrev_b64 v[108:109], 1, v[6:7]
	s_waitcnt vmcnt(0) lgkmcnt(0)
	v_readfirstlane_b32 s1, v1
	v_readfirstlane_b32 s0, v0
	s_nop 1
	v_lshl_add_u64 v[0:1], s[0:1], 0, v[64:65]
	global_load_dwordx4 v[30:33], v[0:1], off offset:1024
	global_load_dwordx4 v[34:37], v[0:1], off offset:1040
	s_add_u32 s0, s54, 0x2954198
	s_addc_u32 s1, s55, 0
	s_add_u32 s85, s54, 0x1748000
	v_lshlrev_b64 v[0:1], 8, v[90:91]
	s_addc_u32 s86, s55, 0
	v_bfe_u32 v64, v135, 1, 4
	v_or_b32_e32 v0, v0, v126
	s_add_u32 s6, s54, 0x29541a8
	v_lshl_add_u64 v[8:9], s[54:55], 0, v[64:65]
	v_lshlrev_b64 v[90:91], 4, v[90:91]
	s_addc_u32 s7, s55, 0
	v_lshl_add_u64 v[98:99], v[8:9], 0, s[52:53]
	v_lshlrev_b32_e32 v64, 2, v126
	s_waitcnt vmcnt(0) lgkmcnt(0)
	v_mov_b32_e32 v100, v30
	v_mov_b32_e32 v101, v32
	v_mov_b32_e32 v32, v31
	v_mov_b32_e32 v102, v34
	v_mov_b32_e32 v103, v36
	v_mov_b32_e32 v36, v35
	v_lshlrev_b64 v[34:35], 1, v[0:1]
	s_branch .LBB0_1409

.LBB0_1409:
	v_mov_b32_e32 v0, v65
	s_mul_i32 s18, s24, 0x9000
	v_mbcnt_lo_u32_b32 v0, -1, v0
	s_lshl_b64 s[26:27], s[18:19], 9
	v_mbcnt_hi_u32_b32 v2, -1, v0
	s_add_u32 s10, s81, s26
	v_and_b32_e32 v6, 31, v2
	s_addc_u32 s11, s82, s27
	s_lshl_b32 s54, s24, 7
	s_lshl_b32 s55, s24, 15
	v_or_b32_e32 v0, v6, v136
	s_add_u32 s12, s83, s55
	v_ashrrev_i32_e32 v1, 31, v0
	v_ashrrev_i32_e32 v2, 2, v2
	s_addc_u32 s13, s84, 0
	v_lshlrev_b64 v[0:1], 7, v[0:1]
	v_and_b32_e32 v4, -8, v2
	v_lshl_add_u64 v[0:1], s[12:13], 0, v[0:1]
	v_ashrrev_i32_e32 v5, 31, v4
	v_lshl_add_u64 v[188:189], v[4:5], 1, v[0:1]
	global_load_dwordx4 v[0:3], v[188:189], off
	global_load_dwordx4 v[110:113], v[188:189], off offset:32
	v_mul_u32_u24_e32 v5, 0x310, v6
	v_lshlrev_b32_e32 v4, 1, v4
	v_add3_u32 v126, s54, v5, v4
	ds_read_b128 v[16:19], v126 offset:256
	ds_read_b128 v[114:117], v126 offset:288
	v_add_co_u32_e32 v190, vcc, s35, v188
	ds_read_b128 v[184:187], v126 offset:320
	s_nop 0
	v_addc_co_u32_e32 v191, vcc, 0, v189, vcc
	global_load_dwordx4 v[20:23], v[190:191], off
	global_load_dwordx4 v[180:183], v[190:191], off offset:32
	s_waitcnt vmcnt(0) lgkmcnt(0)
	global_load_dwordx4 v[208:211], v[188:189], off offset:64
	global_load_dwordx4 v[212:215], v[188:189], off offset:96
	global_load_dwordx4 v[216:219], v[190:191], off offset:64
	global_load_dwordx4 v[220:223], v[190:191], off offset:96
	v_mfma_f32_32x32x16_bf16 v[0:15], v[16:19], v[0:3], 0
	v_mfma_f32_32x32x16_bf16 v[0:15], v[114:117], v[110:113], v[0:15]
	v_mfma_f32_32x32x16_bf16 v[16:31], v[16:19], v[20:23], 0
	s_waitcnt lgkmcnt(0)
	s_waitcnt vmcnt(3)
	v_mfma_f32_32x32x16_bf16 v[0:15], v[184:187], v[208:211], v[0:15]
	v_mfma_f32_32x32x16_bf16 v[16:31], v[114:117], v[180:183], v[16:31]
	s_waitcnt lgkmcnt(0)
	s_waitcnt vmcnt(1)
	v_mfma_f32_32x32x16_bf16 v[16:31], v[184:187], v[216:219], v[16:31]
	ds_read_b128 v[114:117], v126 offset:352
	s_waitcnt lgkmcnt(0)
	v_mfma_f32_32x32x16_bf16 v[0:15], v[114:117], v[212:215], v[0:15]
	s_waitcnt lgkmcnt(0)
	s_waitcnt vmcnt(0)
	v_mfma_f32_32x32x16_bf16 v[16:31], v[114:117], v[220:223], v[16:31]
	s_nop 11
	ds_write2_b32 v163, v0, v16 offset0:128 offset1:160
	ds_write2_b32 v164, v1, v17 offset0:132 offset1:164
	ds_write2_b32 v165, v2, v18 offset0:136 offset1:168
	ds_write2_b32 v166, v3, v19 offset0:140 offset1:172
	ds_write2_b32 v167, v4, v20 offset0:160 offset1:192
	ds_write2_b32 v168, v5, v21 offset0:164 offset1:196
	ds_write2_b32 v169, v6, v22 offset0:168 offset1:200
	ds_write2_b32 v170, v7, v23 offset0:172 offset1:204
	ds_write2_b32 v171, v8, v24 offset0:192 offset1:224
	ds_write2_b32 v172, v9, v25 offset0:196 offset1:228
	ds_write2_b32 v173, v10, v26 offset0:200 offset1:232
	ds_write2_b32 v174, v11, v27 offset0:204 offset1:236
	ds_write2_b32 v175, v12, v28 offset0:96 offset1:128
	ds_write2_b32 v176, v13, v29 offset0:100 offset1:132
	ds_write2_b32 v177, v14, v30 offset0:104 offset1:136
	ds_write2_b32 v178, v15, v31 offset0:108 offset1:140
	v_mov_b64_e32 v[0:1], s[0:1]
	s_waitcnt lgkmcnt(0)
	s_barrier
	global_load_dwordx2 v[0:1], v[0:1], off
	s_add_u32 s12, s79, s26
	s_addc_u32 s13, s80, s27
	s_lshl_b32 s24, s24, 8
	s_mov_b32 s25, s19
	s_lshl_b64 s[24:25], s[24:25], 2
	v_lshl_add_u64 v[16:17], v[88:89], 0, s[26:27]
	s_waitcnt vmcnt(0) lgkmcnt(0)
	v_readfirstlane_b32 s88, v0
	v_readfirstlane_b32 s87, v1
	s_add_u32 s88, s88, s24
	s_addc_u32 s89, s87, s25
	v_lshl_add_u64 v[0:1], s[88:89], 0, v[64:65]
	global_load_dwordx4 v[4:7], v[0:1], off offset:2048
	s_nop 0
	global_load_dwordx4 v[0:3], v[0:1], off offset:2064
	ds_read_b128 v[12:15], v118 offset:25088
	ds_read_b128 v[8:11], v118 offset:25104
	s_waitcnt vmcnt(0) lgkmcnt(0)
	v_add_f32_e32 v12, v4, v12
	v_mul_f32_e32 v12, 0xbfb8aa3b, v12
	v_exp_f32_e32 v12, v12
	v_add_f32_e32 v13, v5, v13
	v_mul_f32_e32 v13, 0xbfb8aa3b, v13
	v_exp_f32_e32 v13, v13
	v_add_f32_e32 v12, 1.0, v12
	v_div_scale_f32 v18, s[26:27], v12, v12, 1.0
	v_rcp_f32_e32 v19, v18
	v_add_f32_e32 v13, 1.0, v13
	v_add_f32_e32 v8, v0, v8
	v_mul_f32_e32 v8, 0xbfb8aa3b, v8
	v_fma_f32 v20, -v18, v19, 1.0
	v_fmac_f32_e32 v19, v20, v19
	v_div_scale_f32 v20, vcc, 1.0, v12, 1.0
	v_mul_f32_e32 v21, v20, v19
	v_fma_f32 v22, -v18, v21, v20
	v_fmac_f32_e32 v21, v22, v19
	v_fma_f32 v18, -v18, v21, v20
	v_div_fmas_f32 v18, v18, v19, v21
	v_div_fixup_f32 v12, v18, v12, 1.0
	v_div_scale_f32 v18, s[26:27], v13, v13, 1.0
	v_rcp_f32_e32 v19, v18
	v_exp_f32_e32 v8, v8
	v_add_f32_e32 v9, v1, v9
	v_mul_f32_e32 v9, 0xbfb8aa3b, v9
	v_fma_f32 v20, -v18, v19, 1.0
	v_fmac_f32_e32 v19, v20, v19
	v_div_scale_f32 v20, vcc, 1.0, v13, 1.0
	v_mul_f32_e32 v21, v20, v19
	v_fma_f32 v22, -v18, v21, v20
	v_fmac_f32_e32 v21, v22, v19
	v_fma_f32 v18, -v18, v21, v20
	v_div_fmas_f32 v18, v18, v19, v21
	v_div_fixup_f32 v13, v18, v13, 1.0
	v_mul_f32_e32 v13, 0xbf1b4598, v13
	v_mul_f32_e32 v13, 0x3fb8aa3b, v13
	v_exp_f32_e32 v18, v13
	v_add_f32_e32 v13, v6, v14
	v_mul_f32_e32 v13, 0xbfb8aa3b, v13
	v_exp_f32_e32 v13, v13
	v_add_f32_e32 v8, 1.0, v8
	v_exp_f32_e32 v9, v9
	v_mul_f32_e32 v12, 0xbf1b4598, v12
	v_add_f32_e32 v13, 1.0, v13
	v_div_scale_f32 v14, s[26:27], v13, v13, 1.0
	v_rcp_f32_e32 v19, v14
	v_add_f32_e32 v9, 1.0, v9
	v_mul_f32_e32 v12, 0x3fb8aa3b, v12
	v_exp_f32_e32 v12, v12
	v_fma_f32 v20, -v14, v19, 1.0
	v_fmac_f32_e32 v19, v20, v19
	v_div_scale_f32 v20, vcc, 1.0, v13, 1.0
	v_mul_f32_e32 v21, v20, v19
	v_fma_f32 v22, -v14, v21, v20
	v_fmac_f32_e32 v21, v22, v19
	v_fma_f32 v14, -v14, v21, v20
	v_div_fmas_f32 v14, v14, v19, v21
	v_div_fixup_f32 v13, v14, v13, 1.0
	v_add_f32_e32 v14, v7, v15
	v_mul_f32_e32 v14, 0xbfb8aa3b, v14
	v_exp_f32_e32 v14, v14
	v_mul_f32_e32 v13, 0xbf1b4598, v13
	v_mul_f32_e32 v13, 0x3fb8aa3b, v13
	v_exp_f32_e32 v13, v13
	v_add_f32_e32 v14, 1.0, v14
	v_div_scale_f32 v15, s[26:27], v14, v14, 1.0
	v_rcp_f32_e32 v19, v15
	v_sub_f32_e32 v18, 1.0, v18
	v_fma_f32 v20, -v15, v19, 1.0
	v_fmac_f32_e32 v19, v20, v19
	v_div_scale_f32 v20, vcc, 1.0, v14, 1.0
	v_mul_f32_e32 v21, v20, v19
	v_fma_f32 v22, -v15, v21, v20
	v_fmac_f32_e32 v21, v22, v19
	v_fma_f32 v15, -v15, v21, v20
	v_div_fmas_f32 v15, v15, v19, v21
	v_div_fixup_f32 v14, v15, v14, 1.0
	v_div_scale_f32 v15, s[26:27], v8, v8, 1.0
	v_rcp_f32_e32 v19, v15
	v_mul_f32_e32 v14, 0xbf1b4598, v14
	v_mul_f32_e32 v14, 0x3fb8aa3b, v14
	v_exp_f32_e32 v14, v14
	v_fma_f32 v20, -v15, v19, 1.0
	v_fmac_f32_e32 v19, v20, v19
	v_div_scale_f32 v20, vcc, 1.0, v8, 1.0
	v_mul_f32_e32 v21, v20, v19
	v_fma_f32 v22, -v15, v21, v20
	v_fmac_f32_e32 v21, v22, v19
	v_fma_f32 v15, -v15, v21, v20
	v_div_fmas_f32 v15, v15, v19, v21
	v_div_fixup_f32 v8, v15, v8, 1.0
	v_div_scale_f32 v15, s[26:27], v9, v9, 1.0
	v_rcp_f32_e32 v19, v15
	v_mul_f32_e32 v8, 0xbf1b4598, v8
	v_mul_f32_e32 v8, 0x3fb8aa3b, v8
	v_exp_f32_e32 v8, v8
	v_fma_f32 v20, -v15, v19, 1.0
	v_fmac_f32_e32 v19, v20, v19
	v_div_scale_f32 v20, vcc, 1.0, v9, 1.0
	v_mul_f32_e32 v21, v20, v19
	v_fma_f32 v22, -v15, v21, v20
	v_fmac_f32_e32 v21, v22, v19
	v_fma_f32 v15, -v15, v21, v20
	v_div_fmas_f32 v15, v15, v19, v21
	v_div_fixup_f32 v9, v15, v9, 1.0
	v_mul_f32_e32 v9, 0xbf1b4598, v9
	v_mul_f32_e32 v9, 0x3fb8aa3b, v9
	v_exp_f32_e32 v15, v9
	v_add_f32_e32 v9, v2, v10
	v_mul_f32_e32 v9, 0xbfb8aa3b, v9
	v_exp_f32_e32 v9, v9
	v_sub_f32_e32 v14, 1.0, v14
	v_add_f32_e32 v9, 1.0, v9
	v_div_scale_f32 v10, s[26:27], v9, v9, 1.0
	v_rcp_f32_e32 v19, v10
	s_nop 0
	v_fma_f32 v20, -v10, v19, 1.0
	v_fmac_f32_e32 v19, v20, v19
	v_div_scale_f32 v20, vcc, 1.0, v9, 1.0
	v_mul_f32_e32 v21, v20, v19
	v_fma_f32 v22, -v10, v21, v20
	v_fmac_f32_e32 v21, v22, v19
	v_fma_f32 v10, -v10, v21, v20
	v_div_fmas_f32 v10, v10, v19, v21
	v_div_fixup_f32 v9, v10, v9, 1.0
	v_add_f32_e32 v10, v3, v11
	v_mul_f32_e32 v10, 0xbfb8aa3b, v10
	v_exp_f32_e32 v10, v10
	v_mul_f32_e32 v9, 0xbf1b4598, v9
	v_mul_f32_e32 v9, 0x3fb8aa3b, v9
	v_exp_f32_e32 v9, v9
	v_add_f32_e32 v10, 1.0, v10
	v_div_scale_f32 v11, s[26:27], v10, v10, 1.0
	v_rcp_f32_e32 v19, v11
	v_pk_add_f32 v[8:9], v[8:9], 1.0 op_sel_hi:[1,0] neg_lo:[1,0] neg_hi:[1,0]
	v_fma_f32 v20, -v11, v19, 1.0
	v_fmac_f32_e32 v19, v20, v19
	v_div_scale_f32 v20, vcc, 1.0, v10, 1.0
	v_mul_f32_e32 v21, v20, v19
	v_fma_f32 v22, -v11, v21, v20
	v_fmac_f32_e32 v21, v22, v19
	v_fma_f32 v11, -v11, v21, v20
	v_div_fmas_f32 v11, v11, v19, v21
	v_div_fixup_f32 v10, v11, v10, 1.0
	v_mul_f32_e32 v10, 0xbf1b4598, v10
	v_mul_f32_e32 v10, 0x3fb8aa3b, v10
	v_exp_f32_e32 v19, v10
	v_pk_add_f32 v[10:11], v[12:13], 1.0 op_sel_hi:[1,0] neg_lo:[1,0] neg_hi:[1,0]
	v_bfe_u32 v20, v8, 16, 1
	v_bfe_u32 v12, v10, 16, 1
	v_bfe_u32 v13, v11, 16, 1
	v_bfe_u32 v21, v9, 16, 1
	v_add3_u32 v9, v9, v21, s60
	v_add3_u32 v8, v8, v20, s60
	v_add3_u32 v11, v11, v13, s60
	v_add3_u32 v10, v10, v12, s60
	v_lshrrev_b32_e32 v12, 16, v10
	v_lshrrev_b32_e32 v13, 16, v11
	v_lshrrev_b32_e32 v8, 16, v8
	v_lshrrev_b32_e32 v9, 16, v9
	v_sub_f32_e32 v10, 1.0, v15
	v_sub_f32_e32 v11, 1.0, v19
	v_and_or_b32 v11, v11, s56, v9
	v_and_or_b32 v10, v10, s56, v8
	v_and_or_b32 v9, v14, s56, v13
	v_and_or_b32 v8, v18, s56, v12
	v_lshl_add_u64 v[12:13], v[16:17], 0, v[38:39]
	global_store_dwordx4 v[12:13], v[8:11], off
	ds_read_b128 v[12:15], v118 offset:26128
	ds_read_b128 v[8:11], v118 offset:26144
	s_waitcnt lgkmcnt(0)
	v_add_f32_e32 v12, v4, v12
	v_mul_f32_e32 v12, 0xbfb8aa3b, v12
	v_exp_f32_e32 v12, v12
	v_add_f32_e32 v13, v5, v13
	v_mul_f32_e32 v13, 0xbfb8aa3b, v13
	v_exp_f32_e32 v13, v13
	v_add_f32_e32 v12, 1.0, v12
	v_div_scale_f32 v18, s[26:27], v12, v12, 1.0
	v_rcp_f32_e32 v19, v18
	v_add_f32_e32 v13, 1.0, v13
	v_add_f32_e32 v8, v0, v8
	v_mul_f32_e32 v8, 0xbfb8aa3b, v8
	v_fma_f32 v20, -v18, v19, 1.0
	v_fmac_f32_e32 v19, v20, v19
	v_div_scale_f32 v20, vcc, 1.0, v12, 1.0
	v_mul_f32_e32 v21, v20, v19
	v_fma_f32 v22, -v18, v21, v20
	v_fmac_f32_e32 v21, v22, v19
	v_fma_f32 v18, -v18, v21, v20
	v_div_fmas_f32 v18, v18, v19, v21
	v_div_fixup_f32 v12, v18, v12, 1.0
	v_div_scale_f32 v18, s[26:27], v13, v13, 1.0
	v_rcp_f32_e32 v19, v18
	v_exp_f32_e32 v8, v8
	v_add_f32_e32 v9, v1, v9
	v_mul_f32_e32 v9, 0xbfb8aa3b, v9
	v_fma_f32 v20, -v18, v19, 1.0
	v_fmac_f32_e32 v19, v20, v19
	v_div_scale_f32 v20, vcc, 1.0, v13, 1.0
	v_mul_f32_e32 v21, v20, v19
	v_fma_f32 v22, -v18, v21, v20
	v_fmac_f32_e32 v21, v22, v19
	v_fma_f32 v18, -v18, v21, v20
	v_div_fmas_f32 v18, v18, v19, v21
	v_div_fixup_f32 v13, v18, v13, 1.0
	v_mul_f32_e32 v13, 0xbf1b4598, v13
	v_mul_f32_e32 v13, 0x3fb8aa3b, v13
	v_exp_f32_e32 v18, v13
	v_add_f32_e32 v13, v6, v14
	v_mul_f32_e32 v13, 0xbfb8aa3b, v13
	v_exp_f32_e32 v13, v13
	v_add_f32_e32 v8, 1.0, v8
	v_exp_f32_e32 v9, v9
	v_mul_f32_e32 v12, 0xbf1b4598, v12
	v_add_f32_e32 v13, 1.0, v13
	v_div_scale_f32 v14, s[26:27], v13, v13, 1.0
	v_rcp_f32_e32 v19, v14
	v_add_f32_e32 v9, 1.0, v9
	v_mul_f32_e32 v12, 0x3fb8aa3b, v12
	v_exp_f32_e32 v12, v12
	v_fma_f32 v20, -v14, v19, 1.0
	v_fmac_f32_e32 v19, v20, v19
	v_div_scale_f32 v20, vcc, 1.0, v13, 1.0
	v_mul_f32_e32 v21, v20, v19
	v_fma_f32 v22, -v14, v21, v20
	v_fmac_f32_e32 v21, v22, v19
	v_fma_f32 v14, -v14, v21, v20
	v_div_fmas_f32 v14, v14, v19, v21
	v_div_fixup_f32 v13, v14, v13, 1.0
	v_add_f32_e32 v14, v7, v15
	v_mul_f32_e32 v14, 0xbfb8aa3b, v14
	v_exp_f32_e32 v14, v14
	v_mul_f32_e32 v13, 0xbf1b4598, v13
	v_mul_f32_e32 v13, 0x3fb8aa3b, v13
	v_exp_f32_e32 v13, v13
	v_add_f32_e32 v14, 1.0, v14
	v_div_scale_f32 v15, s[26:27], v14, v14, 1.0
	v_rcp_f32_e32 v19, v15
	v_sub_f32_e32 v18, 1.0, v18
	v_fma_f32 v20, -v15, v19, 1.0
	v_fmac_f32_e32 v19, v20, v19
	v_div_scale_f32 v20, vcc, 1.0, v14, 1.0
	v_mul_f32_e32 v21, v20, v19
	v_fma_f32 v22, -v15, v21, v20
	v_fmac_f32_e32 v21, v22, v19
	v_fma_f32 v15, -v15, v21, v20
	v_div_fmas_f32 v15, v15, v19, v21
	v_div_fixup_f32 v14, v15, v14, 1.0
	v_div_scale_f32 v15, s[26:27], v8, v8, 1.0
	v_rcp_f32_e32 v19, v15
	v_mul_f32_e32 v14, 0xbf1b4598, v14
	v_mul_f32_e32 v14, 0x3fb8aa3b, v14
	v_exp_f32_e32 v14, v14
	v_fma_f32 v20, -v15, v19, 1.0
	v_fmac_f32_e32 v19, v20, v19
	v_div_scale_f32 v20, vcc, 1.0, v8, 1.0
	v_mul_f32_e32 v21, v20, v19
	v_fma_f32 v22, -v15, v21, v20
	v_fmac_f32_e32 v21, v22, v19
	v_fma_f32 v15, -v15, v21, v20
	v_div_fmas_f32 v15, v15, v19, v21
	v_div_fixup_f32 v8, v15, v8, 1.0
	v_div_scale_f32 v15, s[26:27], v9, v9, 1.0
	v_rcp_f32_e32 v19, v15
	v_mul_f32_e32 v8, 0xbf1b4598, v8
	v_mul_f32_e32 v8, 0x3fb8aa3b, v8
	v_exp_f32_e32 v8, v8
	v_fma_f32 v20, -v15, v19, 1.0
	v_fmac_f32_e32 v19, v20, v19
	v_div_scale_f32 v20, vcc, 1.0, v9, 1.0
	v_mul_f32_e32 v21, v20, v19
	v_fma_f32 v22, -v15, v21, v20
	v_fmac_f32_e32 v21, v22, v19
	v_fma_f32 v15, -v15, v21, v20
	v_div_fmas_f32 v15, v15, v19, v21
	v_div_fixup_f32 v9, v15, v9, 1.0
	v_mul_f32_e32 v9, 0xbf1b4598, v9
	v_mul_f32_e32 v9, 0x3fb8aa3b, v9
	v_exp_f32_e32 v15, v9
	v_add_f32_e32 v9, v2, v10
	v_mul_f32_e32 v9, 0xbfb8aa3b, v9
	v_exp_f32_e32 v9, v9
	v_sub_f32_e32 v14, 1.0, v14
	v_add_f32_e32 v9, 1.0, v9
	v_div_scale_f32 v10, s[26:27], v9, v9, 1.0
	v_rcp_f32_e32 v19, v10
	s_nop 0
	v_fma_f32 v20, -v10, v19, 1.0
	v_fmac_f32_e32 v19, v20, v19
	v_div_scale_f32 v20, vcc, 1.0, v9, 1.0
	v_mul_f32_e32 v21, v20, v19
	v_fma_f32 v22, -v10, v21, v20
	v_fmac_f32_e32 v21, v22, v19
	v_fma_f32 v10, -v10, v21, v20
	v_div_fmas_f32 v10, v10, v19, v21
	v_div_fixup_f32 v9, v10, v9, 1.0
	v_add_f32_e32 v10, v3, v11
	v_mul_f32_e32 v10, 0xbfb8aa3b, v10
	v_exp_f32_e32 v10, v10
	v_mul_f32_e32 v9, 0xbf1b4598, v9
	v_mul_f32_e32 v9, 0x3fb8aa3b, v9
	v_exp_f32_e32 v9, v9
	v_add_f32_e32 v10, 1.0, v10
	v_div_scale_f32 v11, s[26:27], v10, v10, 1.0
	v_rcp_f32_e32 v19, v11
	v_pk_add_f32 v[8:9], v[8:9], 1.0 op_sel_hi:[1,0] neg_lo:[1,0] neg_hi:[1,0]
	v_fma_f32 v20, -v11, v19, 1.0
	v_fmac_f32_e32 v19, v20, v19
	v_div_scale_f32 v20, vcc, 1.0, v10, 1.0
	v_mul_f32_e32 v21, v20, v19
	v_fma_f32 v22, -v11, v21, v20
	v_fmac_f32_e32 v21, v22, v19
	v_fma_f32 v11, -v11, v21, v20
	v_div_fmas_f32 v11, v11, v19, v21
	v_div_fixup_f32 v10, v11, v10, 1.0
	v_mul_f32_e32 v10, 0xbf1b4598, v10
	v_mul_f32_e32 v10, 0x3fb8aa3b, v10
	v_exp_f32_e32 v19, v10
	v_pk_add_f32 v[10:11], v[12:13], 1.0 op_sel_hi:[1,0] neg_lo:[1,0] neg_hi:[1,0]
	v_bfe_u32 v20, v8, 16, 1
	v_bfe_u32 v12, v10, 16, 1
	v_bfe_u32 v13, v11, 16, 1
	v_bfe_u32 v21, v9, 16, 1
	v_add3_u32 v9, v9, v21, s60
	v_add3_u32 v8, v8, v20, s60
	v_add3_u32 v11, v11, v13, s60
	v_add3_u32 v10, v10, v12, s60
	v_lshrrev_b32_e32 v12, 16, v10
	v_lshrrev_b32_e32 v13, 16, v11
	v_lshrrev_b32_e32 v8, 16, v8
	v_lshrrev_b32_e32 v9, 16, v9
	v_sub_f32_e32 v10, 1.0, v15
	v_sub_f32_e32 v11, 1.0, v19
	v_and_or_b32 v11, v11, s56, v9
	v_and_or_b32 v10, v10, s56, v8
	v_and_or_b32 v9, v14, s56, v13
	v_and_or_b32 v8, v18, s56, v12
	v_lshl_add_u64 v[12:13], v[16:17], 0, v[40:41]
	global_store_dwordx4 v[12:13], v[8:11], off
	ds_read_b128 v[12:15], v118 offset:27168
	ds_read_b128 v[8:11], v118 offset:27184
	s_waitcnt lgkmcnt(0)
	v_add_f32_e32 v12, v4, v12
	v_mul_f32_e32 v12, 0xbfb8aa3b, v12
	v_exp_f32_e32 v12, v12
	v_add_f32_e32 v13, v5, v13
	v_mul_f32_e32 v13, 0xbfb8aa3b, v13
	v_exp_f32_e32 v13, v13
	v_add_f32_e32 v12, 1.0, v12
	v_div_scale_f32 v18, s[26:27], v12, v12, 1.0
	v_rcp_f32_e32 v19, v18
	v_add_f32_e32 v13, 1.0, v13
	v_add_f32_e32 v8, v0, v8
	v_mul_f32_e32 v8, 0xbfb8aa3b, v8
	v_fma_f32 v20, -v18, v19, 1.0
	v_fmac_f32_e32 v19, v20, v19
	v_div_scale_f32 v20, vcc, 1.0, v12, 1.0
	v_mul_f32_e32 v21, v20, v19
	v_fma_f32 v22, -v18, v21, v20
	v_fmac_f32_e32 v21, v22, v19
	v_fma_f32 v18, -v18, v21, v20
	v_div_fmas_f32 v18, v18, v19, v21
	v_div_fixup_f32 v12, v18, v12, 1.0
	v_div_scale_f32 v18, s[26:27], v13, v13, 1.0
	v_rcp_f32_e32 v19, v18
	v_exp_f32_e32 v8, v8
	v_add_f32_e32 v9, v1, v9
	v_mul_f32_e32 v9, 0xbfb8aa3b, v9
	v_fma_f32 v20, -v18, v19, 1.0
	v_fmac_f32_e32 v19, v20, v19
	v_div_scale_f32 v20, vcc, 1.0, v13, 1.0
	v_mul_f32_e32 v21, v20, v19
	v_fma_f32 v22, -v18, v21, v20
	v_fmac_f32_e32 v21, v22, v19
	v_fma_f32 v18, -v18, v21, v20
	v_div_fmas_f32 v18, v18, v19, v21
	v_div_fixup_f32 v13, v18, v13, 1.0
	v_mul_f32_e32 v13, 0xbf1b4598, v13
	v_mul_f32_e32 v13, 0x3fb8aa3b, v13
	v_exp_f32_e32 v18, v13
	v_add_f32_e32 v13, v6, v14
	v_mul_f32_e32 v13, 0xbfb8aa3b, v13
	v_exp_f32_e32 v13, v13
	v_add_f32_e32 v8, 1.0, v8
	v_exp_f32_e32 v9, v9
	v_mul_f32_e32 v12, 0xbf1b4598, v12
	v_add_f32_e32 v13, 1.0, v13
	v_div_scale_f32 v14, s[26:27], v13, v13, 1.0
	v_rcp_f32_e32 v19, v14
	v_add_f32_e32 v9, 1.0, v9
	v_mul_f32_e32 v12, 0x3fb8aa3b, v12
	v_exp_f32_e32 v12, v12
	v_fma_f32 v20, -v14, v19, 1.0
	v_fmac_f32_e32 v19, v20, v19
	v_div_scale_f32 v20, vcc, 1.0, v13, 1.0
	v_mul_f32_e32 v21, v20, v19
	v_fma_f32 v22, -v14, v21, v20
	v_fmac_f32_e32 v21, v22, v19
	v_fma_f32 v14, -v14, v21, v20
	v_div_fmas_f32 v14, v14, v19, v21
	v_div_fixup_f32 v13, v14, v13, 1.0
	v_add_f32_e32 v14, v7, v15
	v_mul_f32_e32 v14, 0xbfb8aa3b, v14
	v_exp_f32_e32 v14, v14
	v_mul_f32_e32 v13, 0xbf1b4598, v13
	v_mul_f32_e32 v13, 0x3fb8aa3b, v13
	v_exp_f32_e32 v13, v13
	v_add_f32_e32 v14, 1.0, v14
	v_div_scale_f32 v15, s[26:27], v14, v14, 1.0
	v_rcp_f32_e32 v19, v15
	v_sub_f32_e32 v18, 1.0, v18
	v_fma_f32 v20, -v15, v19, 1.0
	v_fmac_f32_e32 v19, v20, v19
	v_div_scale_f32 v20, vcc, 1.0, v14, 1.0
	v_mul_f32_e32 v21, v20, v19
	v_fma_f32 v22, -v15, v21, v20
	v_fmac_f32_e32 v21, v22, v19
	v_fma_f32 v15, -v15, v21, v20
	v_div_fmas_f32 v15, v15, v19, v21
	v_div_fixup_f32 v14, v15, v14, 1.0
	v_div_scale_f32 v15, s[26:27], v8, v8, 1.0
	v_rcp_f32_e32 v19, v15
	v_mul_f32_e32 v14, 0xbf1b4598, v14
	v_mul_f32_e32 v14, 0x3fb8aa3b, v14
	v_exp_f32_e32 v14, v14
	v_fma_f32 v20, -v15, v19, 1.0
	v_fmac_f32_e32 v19, v20, v19
	v_div_scale_f32 v20, vcc, 1.0, v8, 1.0
	v_mul_f32_e32 v21, v20, v19
	v_fma_f32 v22, -v15, v21, v20
	v_fmac_f32_e32 v21, v22, v19
	v_fma_f32 v15, -v15, v21, v20
	v_div_fmas_f32 v15, v15, v19, v21
	v_div_fixup_f32 v8, v15, v8, 1.0
	v_div_scale_f32 v15, s[26:27], v9, v9, 1.0
	v_rcp_f32_e32 v19, v15
	v_mul_f32_e32 v8, 0xbf1b4598, v8
	v_mul_f32_e32 v8, 0x3fb8aa3b, v8
	v_exp_f32_e32 v8, v8
	v_fma_f32 v20, -v15, v19, 1.0
	v_fmac_f32_e32 v19, v20, v19
	v_div_scale_f32 v20, vcc, 1.0, v9, 1.0
	v_mul_f32_e32 v21, v20, v19
	v_fma_f32 v22, -v15, v21, v20
	v_fmac_f32_e32 v21, v22, v19
	v_fma_f32 v15, -v15, v21, v20
	v_div_fmas_f32 v15, v15, v19, v21
	v_div_fixup_f32 v9, v15, v9, 1.0
	v_mul_f32_e32 v9, 0xbf1b4598, v9
	v_mul_f32_e32 v9, 0x3fb8aa3b, v9
	v_exp_f32_e32 v15, v9
	v_add_f32_e32 v9, v2, v10
	v_mul_f32_e32 v9, 0xbfb8aa3b, v9
	v_exp_f32_e32 v9, v9
	v_sub_f32_e32 v14, 1.0, v14
	v_add_f32_e32 v9, 1.0, v9
	v_div_scale_f32 v10, s[26:27], v9, v9, 1.0
	v_rcp_f32_e32 v19, v10
	s_nop 0
	v_fma_f32 v20, -v10, v19, 1.0
	v_fmac_f32_e32 v19, v20, v19
	v_div_scale_f32 v20, vcc, 1.0, v9, 1.0
	v_mul_f32_e32 v21, v20, v19
	v_fma_f32 v22, -v10, v21, v20
	v_fmac_f32_e32 v21, v22, v19
	v_fma_f32 v10, -v10, v21, v20
	v_div_fmas_f32 v10, v10, v19, v21
	v_div_fixup_f32 v9, v10, v9, 1.0
	v_add_f32_e32 v10, v3, v11
	v_mul_f32_e32 v10, 0xbfb8aa3b, v10
	v_exp_f32_e32 v10, v10
	v_mul_f32_e32 v9, 0xbf1b4598, v9
	v_mul_f32_e32 v9, 0x3fb8aa3b, v9
	v_exp_f32_e32 v9, v9
	v_add_f32_e32 v10, 1.0, v10
	v_div_scale_f32 v11, s[26:27], v10, v10, 1.0
	v_rcp_f32_e32 v19, v11
	v_pk_add_f32 v[8:9], v[8:9], 1.0 op_sel_hi:[1,0] neg_lo:[1,0] neg_hi:[1,0]
	v_fma_f32 v20, -v11, v19, 1.0
	v_fmac_f32_e32 v19, v20, v19
	v_div_scale_f32 v20, vcc, 1.0, v10, 1.0
	v_mul_f32_e32 v21, v20, v19
	v_fma_f32 v22, -v11, v21, v20
	v_fmac_f32_e32 v21, v22, v19
	v_fma_f32 v11, -v11, v21, v20
	v_div_fmas_f32 v11, v11, v19, v21
	v_div_fixup_f32 v10, v11, v10, 1.0
	v_mul_f32_e32 v10, 0xbf1b4598, v10
	v_mul_f32_e32 v10, 0x3fb8aa3b, v10
	v_exp_f32_e32 v19, v10
	v_pk_add_f32 v[10:11], v[12:13], 1.0 op_sel_hi:[1,0] neg_lo:[1,0] neg_hi:[1,0]
	v_bfe_u32 v20, v8, 16, 1
	v_bfe_u32 v12, v10, 16, 1
	v_bfe_u32 v13, v11, 16, 1
	v_bfe_u32 v21, v9, 16, 1
	v_add3_u32 v9, v9, v21, s60
	v_add3_u32 v8, v8, v20, s60
	v_add3_u32 v11, v11, v13, s60
	v_add3_u32 v10, v10, v12, s60
	v_lshrrev_b32_e32 v12, 16, v10
	v_lshrrev_b32_e32 v13, 16, v11
	v_lshrrev_b32_e32 v8, 16, v8
	v_lshrrev_b32_e32 v9, 16, v9
	v_sub_f32_e32 v10, 1.0, v15
	v_sub_f32_e32 v11, 1.0, v19
	v_and_or_b32 v11, v11, s56, v9
	v_and_or_b32 v10, v10, s56, v8
	v_and_or_b32 v9, v14, s56, v13
	v_and_or_b32 v8, v18, s56, v12
	v_lshl_add_u64 v[12:13], v[16:17], 0, v[42:43]
	global_store_dwordx4 v[12:13], v[8:11], off
	ds_read_b128 v[12:15], v119 offset:25088
	ds_read_b128 v[8:11], v119 offset:25104
	s_waitcnt lgkmcnt(0)
	v_add_f32_e32 v4, v4, v12
	v_mul_f32_e32 v4, 0xbfb8aa3b, v4
	v_exp_f32_e32 v4, v4
	v_add_f32_e32 v5, v5, v13
	v_mul_f32_e32 v5, 0xbfb8aa3b, v5
	v_exp_f32_e32 v5, v5
	v_add_f32_e32 v4, 1.0, v4
	v_div_scale_f32 v12, s[26:27], v4, v4, 1.0
	v_rcp_f32_e32 v18, v12
	v_add_f32_e32 v5, 1.0, v5
	v_add_f32_e32 v0, v0, v8
	v_mul_f32_e32 v0, 0xbfb8aa3b, v0
	v_fma_f32 v19, -v12, v18, 1.0
	v_fmac_f32_e32 v18, v19, v18
	v_div_scale_f32 v19, vcc, 1.0, v4, 1.0
	v_mul_f32_e32 v20, v19, v18
	v_fma_f32 v21, -v12, v20, v19
	v_fmac_f32_e32 v20, v21, v18
	v_fma_f32 v12, -v12, v20, v19
	v_div_fmas_f32 v12, v12, v18, v20
	v_div_fixup_f32 v4, v12, v4, 1.0
	v_div_scale_f32 v12, s[26:27], v5, v5, 1.0
	v_rcp_f32_e32 v13, v12
	v_exp_f32_e32 v0, v0
	v_add_f32_e32 v1, v1, v9
	v_mul_f32_e32 v1, 0xbfb8aa3b, v1
	v_fma_f32 v18, -v12, v13, 1.0
	v_fmac_f32_e32 v13, v18, v13
	v_div_scale_f32 v18, vcc, 1.0, v5, 1.0
	v_mul_f32_e32 v19, v18, v13
	v_fma_f32 v20, -v12, v19, v18
	v_fmac_f32_e32 v19, v20, v13
	v_fma_f32 v12, -v12, v19, v18
	v_div_fmas_f32 v12, v12, v13, v19
	v_div_fixup_f32 v5, v12, v5, 1.0
	v_mul_f32_e32 v5, 0xbf1b4598, v5
	v_mul_f32_e32 v5, 0x3fb8aa3b, v5
	v_exp_f32_e32 v12, v5
	v_add_f32_e32 v5, v6, v14
	v_mul_f32_e32 v5, 0xbfb8aa3b, v5
	v_exp_f32_e32 v5, v5
	v_add_f32_e32 v0, 1.0, v0
	v_exp_f32_e32 v1, v1
	v_mul_f32_e32 v4, 0xbf1b4598, v4
	v_add_f32_e32 v5, 1.0, v5
	v_div_scale_f32 v6, s[26:27], v5, v5, 1.0
	v_rcp_f32_e32 v13, v6
	v_add_f32_e32 v1, 1.0, v1
	v_mul_f32_e32 v4, 0x3fb8aa3b, v4
	v_exp_f32_e32 v4, v4
	v_fma_f32 v14, -v6, v13, 1.0
	v_fmac_f32_e32 v13, v14, v13
	v_div_scale_f32 v14, vcc, 1.0, v5, 1.0
	v_mul_f32_e32 v18, v14, v13
	v_fma_f32 v19, -v6, v18, v14
	v_fmac_f32_e32 v18, v19, v13
	v_fma_f32 v6, -v6, v18, v14
	v_div_fmas_f32 v6, v6, v13, v18
	v_div_fixup_f32 v5, v6, v5, 1.0
	v_add_f32_e32 v6, v7, v15
	v_mul_f32_e32 v6, 0xbfb8aa3b, v6
	v_exp_f32_e32 v6, v6
	v_mul_f32_e32 v5, 0xbf1b4598, v5
	v_mul_f32_e32 v5, 0x3fb8aa3b, v5
	v_exp_f32_e32 v5, v5
	v_add_f32_e32 v6, 1.0, v6
	v_div_scale_f32 v7, s[26:27], v6, v6, 1.0
	v_rcp_f32_e32 v13, v7
	s_nop 0
	v_fma_f32 v14, -v7, v13, 1.0
	v_fmac_f32_e32 v13, v14, v13
	v_div_scale_f32 v14, vcc, 1.0, v6, 1.0
	v_mul_f32_e32 v15, v14, v13
	v_fma_f32 v18, -v7, v15, v14
	v_fmac_f32_e32 v15, v18, v13
	v_fma_f32 v7, -v7, v15, v14
	v_div_fmas_f32 v7, v7, v13, v15
	v_div_fixup_f32 v6, v7, v6, 1.0
	v_div_scale_f32 v7, s[26:27], v0, v0, 1.0
	v_rcp_f32_e32 v8, v7
	v_mul_f32_e32 v6, 0xbf1b4598, v6
	v_mul_f32_e32 v6, 0x3fb8aa3b, v6
	v_exp_f32_e32 v6, v6
	v_fma_f32 v13, -v7, v8, 1.0
	v_fmac_f32_e32 v8, v13, v8
	v_div_scale_f32 v13, vcc, 1.0, v0, 1.0
	v_mul_f32_e32 v14, v13, v8
	v_fma_f32 v15, -v7, v14, v13
	v_fmac_f32_e32 v14, v15, v8
	v_fma_f32 v7, -v7, v14, v13
	v_div_fmas_f32 v7, v7, v8, v14
	v_div_fixup_f32 v0, v7, v0, 1.0
	v_div_scale_f32 v7, s[26:27], v1, v1, 1.0
	v_rcp_f32_e32 v8, v7
	v_mul_f32_e32 v0, 0xbf1b4598, v0
	v_mul_f32_e32 v0, 0x3fb8aa3b, v0
	v_exp_f32_e32 v0, v0
	v_fma_f32 v9, -v7, v8, 1.0
	v_fmac_f32_e32 v8, v9, v8
	v_div_scale_f32 v9, vcc, 1.0, v1, 1.0
	v_mul_f32_e32 v13, v9, v8
	v_fma_f32 v14, -v7, v13, v9
	v_fmac_f32_e32 v13, v14, v8
	v_fma_f32 v7, -v7, v13, v9
	v_div_fmas_f32 v7, v7, v8, v13
	v_div_fixup_f32 v1, v7, v1, 1.0
	v_mul_f32_e32 v1, 0xbf1b4598, v1
	v_mul_f32_e32 v1, 0x3fb8aa3b, v1
	v_exp_f32_e32 v7, v1
	v_add_f32_e32 v1, v2, v10
	v_mul_f32_e32 v1, 0xbfb8aa3b, v1
	v_exp_f32_e32 v1, v1
	v_sub_f32_e32 v6, 1.0, v6
	v_add_f32_e32 v1, 1.0, v1
	v_div_scale_f32 v2, s[26:27], v1, v1, 1.0
	v_rcp_f32_e32 v8, v2
	s_nop 0
	v_fma_f32 v9, -v2, v8, 1.0
	v_fmac_f32_e32 v8, v9, v8
	v_div_scale_f32 v9, vcc, 1.0, v1, 1.0
	v_mul_f32_e32 v10, v9, v8
	v_fma_f32 v13, -v2, v10, v9
	v_fmac_f32_e32 v10, v13, v8
	v_fma_f32 v2, -v2, v10, v9
	v_div_fmas_f32 v2, v2, v8, v10
	v_div_fixup_f32 v1, v2, v1, 1.0
	v_add_f32_e32 v2, v3, v11
	v_mul_f32_e32 v2, 0xbfb8aa3b, v2
	v_exp_f32_e32 v2, v2
	v_mul_f32_e32 v1, 0xbf1b4598, v1
	v_mul_f32_e32 v1, 0x3fb8aa3b, v1
	v_exp_f32_e32 v1, v1
	v_add_f32_e32 v2, 1.0, v2
	v_div_scale_f32 v3, s[26:27], v2, v2, 1.0
	v_rcp_f32_e32 v8, v3
	v_pk_add_f32 v[0:1], v[0:1], 1.0 op_sel_hi:[1,0] neg_lo:[1,0] neg_hi:[1,0]
	s_add_u32 s26, s85, s55
	s_addc_u32 s27, s86, 0
	v_fma_f32 v9, -v3, v8, 1.0
	v_fmac_f32_e32 v8, v9, v8
	v_div_scale_f32 v9, vcc, 1.0, v2, 1.0
	v_mul_f32_e32 v10, v9, v8
	v_fma_f32 v11, -v3, v10, v9
	v_fmac_f32_e32 v10, v11, v8
	v_fma_f32 v3, -v3, v10, v9
	v_div_fmas_f32 v3, v3, v8, v10
	v_div_fixup_f32 v2, v3, v2, 1.0
	v_mul_f32_e32 v2, 0xbf1b4598, v2
	v_mul_f32_e32 v2, 0x3fb8aa3b, v2
	v_exp_f32_e32 v8, v2
	v_pk_add_f32 v[2:3], v[4:5], 1.0 op_sel_hi:[1,0] neg_lo:[1,0] neg_hi:[1,0]
	v_bfe_u32 v9, v0, 16, 1
	v_bfe_u32 v4, v2, 16, 1
	v_bfe_u32 v5, v3, 16, 1
	v_bfe_u32 v10, v1, 16, 1
	v_add3_u32 v1, v1, v10, s60
	v_add3_u32 v0, v0, v9, s60
	v_add3_u32 v3, v3, v5, s60
	v_add3_u32 v2, v2, v4, s60
	v_lshrrev_b32_e32 v4, 16, v2
	v_lshrrev_b32_e32 v5, 16, v3
	v_lshrrev_b32_e32 v0, 16, v0
	v_lshrrev_b32_e32 v1, 16, v1
	v_sub_f32_e32 v9, 1.0, v12
	v_sub_f32_e32 v2, 1.0, v7
	v_sub_f32_e32 v3, 1.0, v8
	v_and_or_b32 v3, v3, s56, v1
	v_and_or_b32 v2, v2, s56, v0
	v_and_or_b32 v1, v6, s56, v5
	v_and_or_b32 v0, v9, s56, v4
	v_lshl_add_u64 v[4:5], v[16:17], 0, v[44:45]
	global_store_dwordx4 v[4:5], v[0:3], off
	s_waitcnt lgkmcnt(0)
	s_barrier
	v_mov_b32_e32 v0, v65
	s_nop 0
	v_mbcnt_lo_u32_b32 v0, -1, v0
	v_mbcnt_hi_u32_b32 v2, -1, v0
	v_and_b32_e32 v6, 31, v2
	v_or_b32_e32 v0, v6, v136
	v_ashrrev_i32_e32 v1, 31, v0
	v_ashrrev_i32_e32 v2, 2, v2
	v_lshlrev_b64 v[0:1], 7, v[0:1]
	v_and_b32_e32 v2, -8, v2
	v_lshl_add_u64 v[0:1], s[26:27], 0, v[0:1]
	v_ashrrev_i32_e32 v3, 31, v2
	v_lshl_add_u64 v[4:5], v[2:3], 1, v[0:1]
	v_mul_u32_u24_e32 v0, 0x310, v6
	v_add_co_u32_e32 v6, vcc, s35, v4
	v_lshlrev_b32_e32 v1, 1, v2
	s_nop 0
	v_addc_co_u32_e32 v7, vcc, 0, v5, vcc
	v_add3_u32 v8, s54, v0, v1
	global_load_dwordx4 v[0:3], v[4:5], off
	global_load_dwordx4 v[16:19], v[6:7], off
	ds_read_b128 v[20:23], v8 offset:512
	ds_read_b128 v[110:113], v8 offset:544
	global_load_dwordx4 v[114:117], v[4:5], off offset:32
	global_load_dwordx4 v[180:183], v[6:7], off offset:32
	ds_read_b128 v[184:187], v8 offset:576
	global_load_dwordx4 v[188:191], v[4:5], off offset:64
	global_load_dwordx4 v[192:195], v[6:7], off offset:64
	ds_read_b128 v[196:199], v8 offset:608
	global_load_dwordx4 v[200:203], v[4:5], off offset:96
	global_load_dwordx4 v[204:207], v[6:7], off offset:96
	s_waitcnt vmcnt(0) lgkmcnt(0)
	v_mfma_f32_32x32x16_bf16 v[0:15], v[20:23], v[0:3], 0
	v_mfma_f32_32x32x16_bf16 v[16:31], v[20:23], v[16:19], 0
	v_mfma_f32_32x32x16_bf16 v[0:15], v[110:113], v[114:117], v[0:15]
	v_mfma_f32_32x32x16_bf16 v[16:31], v[110:113], v[180:183], v[16:31]
	v_mfma_f32_32x32x16_bf16 v[0:15], v[184:187], v[188:191], v[0:15]
	v_mfma_f32_32x32x16_bf16 v[16:31], v[184:187], v[192:195], v[16:31]
	v_mfma_f32_32x32x16_bf16 v[0:15], v[196:199], v[200:203], v[0:15]
	v_mfma_f32_32x32x16_bf16 v[16:31], v[196:199], v[204:207], v[16:31]
	s_nop 11
	ds_write2_b32 v163, v0, v16 offset0:128 offset1:160
	ds_write2_b32 v164, v1, v17 offset0:132 offset1:164
	ds_write2_b32 v165, v2, v18 offset0:136 offset1:168
	ds_write2_b32 v166, v3, v19 offset0:140 offset1:172
	ds_write2_b32 v167, v4, v20 offset0:160 offset1:192
	ds_write2_b32 v168, v5, v21 offset0:164 offset1:196
	ds_write2_b32 v169, v6, v22 offset0:168 offset1:200
	ds_write2_b32 v170, v7, v23 offset0:172 offset1:204
	ds_write2_b32 v171, v8, v24 offset0:192 offset1:224
	ds_write2_b32 v172, v9, v25 offset0:196 offset1:228
	ds_write2_b32 v173, v10, v26 offset0:200 offset1:232
	ds_write2_b32 v174, v11, v27 offset0:204 offset1:236
	ds_write2_b32 v175, v12, v28 offset0:96 offset1:128
	ds_write2_b32 v176, v13, v29 offset0:100 offset1:132
	ds_write2_b32 v177, v14, v30 offset0:104 offset1:136
	ds_write2_b32 v178, v15, v31 offset0:108 offset1:140
	v_mov_b64_e32 v[0:1], s[6:7]
	s_waitcnt lgkmcnt(0)
	s_barrier
	global_load_dwordx2 v[0:1], v[0:1], off
	v_lshl_add_u64 v[24:25], s[18:19], 4, v[98:99]
	s_waitcnt vmcnt(0) lgkmcnt(0)
	v_readfirstlane_b32 s27, v0
	v_readfirstlane_b32 s26, v1
	s_add_u32 s24, s27, s24
	s_addc_u32 s25, s26, s25
	v_lshl_add_u64 v[0:1], s[24:25], 0, v[64:65]
	global_load_dwordx4 v[8:11], v[0:1], off offset:2048
	global_load_dwordx4 v[4:7], v[0:1], off offset:2064
	global_load_dwordx4 v[20:23], v[46:47], off
	global_load_dwordx4 v[16:19], v[48:49], off
	global_load_dwordx4 v[12:15], v[50:51], off
	s_nop 0
	global_load_dwordx4 v[0:3], v[52:53], off
	ds_read_b128 v[28:31], v118 offset:25088
	ds_read_b128 v[114:117], v118 offset:25104
	s_waitcnt vmcnt(0) lgkmcnt(0)
	v_add_f32_e32 v27, v9, v29
	v_mul_f32_e32 v27, 0xbfb8aa3b, v27
	v_add_f32_e32 v26, v8, v28
	v_exp_f32_e32 v28, v27
	v_add_f32_e32 v27, v10, v30
	v_add_f32_e32 v30, v4, v114
	v_mul_f32_e32 v30, 0xbfb8aa3b, v30
	v_mul_f32_e32 v26, 0xbfb8aa3b, v26
	v_mul_f32_e32 v27, 0xbfb8aa3b, v27
	v_exp_f32_e32 v112, v30
	v_add_f32_e32 v30, v5, v115
	v_exp_f32_e32 v26, v26
	v_exp_f32_e32 v27, v27
	v_mul_f32_e32 v30, 0xbfb8aa3b, v30
	v_exp_f32_e32 v114, v30
	v_add_f32_e32 v30, v6, v116
	v_mul_f32_e32 v30, 0xbfb8aa3b, v30
	v_exp_f32_e32 v113, v30
	v_add_f32_e32 v30, v7, v117
	v_mul_f32_e32 v30, 0xbfb8aa3b, v30
	v_pk_add_f32 v[26:27], v[26:27], 1.0 op_sel_hi:[1,0]
	v_exp_f32_e32 v115, v30
	v_div_scale_f32 v30, s[24:25], v27, v27, 1.0
	v_add_f32_e32 v29, v11, v31
	v_rcp_f32_e32 v31, v30
	v_mul_f32_e32 v29, 0xbfb8aa3b, v29
	v_exp_f32_e32 v29, v29
	v_pk_add_f32 v[112:113], v[112:113], 1.0 op_sel_hi:[1,0]
	v_fma_f32 v110, -v30, v31, 1.0
	v_fmac_f32_e32 v31, v110, v31
	v_div_scale_f32 v110, vcc, 1.0, v27, 1.0
	v_mul_f32_e32 v111, v110, v31
	v_fma_f32 v116, -v30, v111, v110
	v_fmac_f32_e32 v111, v116, v31
	v_fma_f32 v30, -v30, v111, v110
	v_div_fmas_f32 v30, v30, v31, v111
	v_div_fixup_f32 v27, v30, v27, 1.0
	v_div_scale_f32 v30, s[24:25], v26, v26, 1.0
	v_rcp_f32_e32 v31, v30
	v_pk_add_f32 v[28:29], v[28:29], 1.0 op_sel_hi:[1,0]
	v_pk_add_f32 v[114:115], v[114:115], 1.0 op_sel_hi:[1,0]
	v_fma_f32 v110, -v30, v31, 1.0
	v_fmac_f32_e32 v31, v110, v31
	v_div_scale_f32 v110, vcc, 1.0, v26, 1.0
	v_mul_f32_e32 v111, v110, v31
	v_fma_f32 v116, -v30, v111, v110
	v_fmac_f32_e32 v111, v116, v31
	v_fma_f32 v30, -v30, v111, v110
	v_div_fmas_f32 v30, v30, v31, v111
	v_div_fixup_f32 v26, v30, v26, 1.0
	v_pk_add_f32 v[30:31], v[26:27], -1.0 op_sel_hi:[1,0]
	s_nop 0
	v_pk_fma_f32 v[116:117], v[100:101], v[30:31], 1.0 op_sel_hi:[1,1,0]
	v_div_scale_f32 v30, s[24:25], v29, v29, 1.0
	v_rcp_f32_e32 v31, v30
	v_fma_f32 v126, v120, v116, 0
	v_fma_f32 v110, -v30, v31, 1.0
	v_fmac_f32_e32 v31, v110, v31
	v_div_scale_f32 v110, vcc, 1.0, v29, 1.0
	v_mul_f32_e32 v111, v110, v31
	v_fma_f32 v135, -v30, v111, v110
	v_fmac_f32_e32 v111, v135, v31
	v_fma_f32 v30, -v30, v111, v110
	v_div_fmas_f32 v30, v30, v31, v111
	v_div_fixup_f32 v29, v30, v29, 1.0
	v_div_scale_f32 v30, s[24:25], v28, v28, 1.0
	v_rcp_f32_e32 v31, v30
	s_nop 0
	v_fma_f32 v110, -v30, v31, 1.0
	v_fmac_f32_e32 v31, v110, v31
	v_div_scale_f32 v110, vcc, 1.0, v28, 1.0
	v_mul_f32_e32 v111, v110, v31
	v_fma_f32 v135, -v30, v111, v110
	v_fmac_f32_e32 v111, v135, v31
	v_fma_f32 v30, -v30, v111, v110
	v_div_fmas_f32 v30, v30, v31, v111
	v_div_fixup_f32 v28, v30, v28, 1.0
	v_pk_add_f32 v[30:31], v[28:29], -1.0 op_sel_hi:[1,0]
	v_pk_mul_f32 v[110:111], v[54:55], v[116:117]
	v_pk_fma_f32 v[30:31], v[32:33], v[30:31], 1.0 op_sel_hi:[1,1,0]
	v_div_scale_f32 v116, s[24:25], v113, v113, 1.0
	v_fmac_f32_e32 v126, v121, v30
	v_fmac_f32_e32 v126, v122, v117
	v_rcp_f32_e32 v117, v116
	v_fmac_f32_e32 v126, v123, v31
	v_pk_mul_f32 v[30:31], v[56:57], v[30:31]
	v_fma_f32 v135, -v116, v117, 1.0
	v_fmac_f32_e32 v117, v135, v117
	v_div_scale_f32 v135, vcc, 1.0, v113, 1.0
	v_mul_f32_e32 v179, v135, v117
	v_fma_f32 v180, -v116, v179, v135
	v_fmac_f32_e32 v179, v180, v117
	v_fma_f32 v116, -v116, v179, v135
	v_div_fmas_f32 v116, v116, v117, v179
	v_div_fixup_f32 v113, v116, v113, 1.0
	v_div_scale_f32 v116, s[24:25], v112, v112, 1.0
	v_rcp_f32_e32 v117, v116
	s_nop 0
	v_fma_f32 v135, -v116, v117, 1.0
	v_fmac_f32_e32 v117, v135, v117
	v_div_scale_f32 v135, vcc, 1.0, v112, 1.0
	v_mul_f32_e32 v179, v135, v117
	v_fma_f32 v180, -v116, v179, v135
	v_fmac_f32_e32 v179, v180, v117
	v_fma_f32 v116, -v116, v179, v135
	v_div_scale_f32 v135, s[24:25], v115, v115, 1.0
	v_div_fmas_f32 v116, v116, v117, v179
	v_rcp_f32_e32 v179, v135
	v_div_fixup_f32 v112, v116, v112, 1.0
	v_pk_add_f32 v[116:117], v[112:113], -1.0 op_sel_hi:[1,0]
	v_fma_f32 v180, -v135, v179, 1.0
	v_fmac_f32_e32 v179, v180, v179
	v_div_scale_f32 v180, vcc, 1.0, v115, 1.0
	v_mul_f32_e32 v181, v180, v179
	v_fma_f32 v182, -v135, v181, v180
	v_fmac_f32_e32 v181, v182, v179
	v_fma_f32 v135, -v135, v181, v180
	v_div_fmas_f32 v135, v135, v179, v181
	v_div_fixup_f32 v115, v135, v115, 1.0
	v_div_scale_f32 v135, s[24:25], v114, v114, 1.0
	v_rcp_f32_e32 v179, v135
	v_pk_fma_f32 v[116:117], v[102:103], v[116:117], 1.0 op_sel_hi:[1,1,0]
	v_fma_f32 v180, -v135, v179, 1.0
	v_fmac_f32_e32 v179, v180, v179
	v_div_scale_f32 v180, vcc, 1.0, v114, 1.0
	v_mul_f32_e32 v181, v180, v179
	v_fma_f32 v182, -v135, v181, v180
	v_fmac_f32_e32 v181, v182, v179
	v_fma_f32 v135, -v135, v181, v180
	v_div_fmas_f32 v135, v135, v179, v181
	v_div_fixup_f32 v114, v135, v114, 1.0
	v_pk_add_f32 v[180:181], v[114:115], -1.0 op_sel_hi:[1,0]
	v_fmac_f32_e32 v126, v147, v116
	v_pk_fma_f32 v[180:181], v[36:37], v[180:181], 1.0 op_sel_hi:[1,1,0]
	v_pk_mul_f32 v[182:183], v[72:73], v[116:117]
	v_fmac_f32_e32 v126, v148, v180
	v_fmac_f32_e32 v126, v149, v117
	v_bfe_u32 v116, v110, 16, 1
	v_bfe_u32 v117, v111, 16, 1
	v_bfe_u32 v135, v182, 16, 1
	v_bfe_u32 v179, v183, 16, 1
	v_add3_u32 v179, v183, v179, s60
	v_add3_u32 v135, v182, v135, s60
	v_add3_u32 v111, v111, v117, s60
	v_add3_u32 v110, v110, v116, s60
	v_lshrrev_b32_e32 v116, 16, v110
	v_lshrrev_b32_e32 v117, 16, v111
	v_lshrrev_b32_e32 v135, 16, v135
	v_lshrrev_b32_e32 v179, 16, v179
	v_pk_mul_f32 v[110:111], v[74:75], v[180:181]
	v_fmac_f32_e32 v126, v150, v181
	v_and_or_b32 v183, v111, s56, v179
	v_and_or_b32 v182, v110, s56, v135
	v_and_or_b32 v181, v31, s56, v117
	v_and_or_b32 v180, v30, s56, v116
	v_lshl_add_u64 v[30:31], s[12:13], 0, v[34:35]
	global_store_dwordx4 v[30:31], v[180:183], off
	v_lshlrev_b32_e32 v31, 16, v21
	v_lshlrev_b32_e32 v30, 16, v20
	v_pk_mul_f32 v[26:27], v[26:27], v[30:31]
	v_lshlrev_b32_e32 v31, 16, v23
	v_lshlrev_b32_e32 v30, 16, v22
	v_pk_mul_f32 v[30:31], v[112:113], v[30:31]
	v_bfe_u32 v110, v26, 16, 1
	v_bfe_u32 v111, v27, 16, 1
	v_bfe_u32 v112, v30, 16, 1
	v_bfe_u32 v113, v31, 16, 1
	v_add3_u32 v31, v31, v113, s60
	v_add3_u32 v30, v30, v112, s60
	v_add3_u32 v27, v27, v111, s60
	v_add3_u32 v26, v26, v110, s60
	v_and_b32_e32 v23, 0xffff0000, v23
	v_and_b32_e32 v22, 0xffff0000, v22
	v_and_b32_e32 v21, 0xffff0000, v21
	v_and_b32_e32 v20, 0xffff0000, v20
	v_lshrrev_b32_e32 v26, 16, v26
	v_lshrrev_b32_e32 v27, 16, v27
	v_lshrrev_b32_e32 v30, 16, v30
	v_lshrrev_b32_e32 v31, 16, v31
	v_pk_mul_f32 v[20:21], v[28:29], v[20:21]
	v_pk_mul_f32 v[22:23], v[114:115], v[22:23]
	v_and_or_b32 v21, v21, s56, v27
	v_and_or_b32 v23, v23, s56, v31
	v_and_or_b32 v22, v22, s56, v30
	v_and_or_b32 v20, v20, s56, v26
	v_lshl_add_u64 v[26:27], s[10:11], 0, v[34:35]
	global_store_dwordx4 v[26:27], v[20:23], off
	s_nop 1
	v_add_f32_dpp v20, v126, v126 quad_perm:[1,0,3,2] row_mask:0xf bank_mask:0xf bound_ctrl:1
	s_nop 1
	v_add_f32_dpp v20, v20, v20 quad_perm:[2,3,0,1] row_mask:0xf bank_mask:0xf bound_ctrl:1
	s_nop 1
	v_mov_b32_dpp v21, v20 row_half_mirror row_mask:0xf bank_mask:0xf bound_ctrl:1
	s_and_saveexec_b64 s[24:25], s[4:5]
	s_cbranch_execz .LBB0_1411
	v_add_f32_e32 v22, v20, v21
	v_lshl_add_u64 v[20:21], v[24:25], 0, v[90:91]
	global_store_dword v[20:21], v22, off

.LBB0_1667:
	v_add_u32_e32 v35, s0, v24
	v_add_u32_e32 v37, s0, v25
	ds_read_b128 v[50:53], v35
	ds_read_b128 v[54:57], v37
	s_addk_i32 s0, 0x200
	s_cmpk_lg_i32 s0, 0x3e00
	s_waitcnt lgkmcnt(1)
	v_lshlrev_b32_e32 v75, 16, v51
	v_lshlrev_b32_e32 v74, 16, v50
	s_waitcnt lgkmcnt(0)
	v_lshlrev_b32_e32 v77, 16, v55
	v_lshlrev_b32_e32 v76, 16, v54
	v_and_b32_e32 v51, 0xffff0000, v51
	v_and_b32_e32 v50, 0xffff0000, v50
	v_and_b32_e32 v55, 0xffff0000, v55
	v_and_b32_e32 v54, 0xffff0000, v54
	v_lshlrev_b32_e32 v79, 16, v53
	v_lshlrev_b32_e32 v78, 16, v52
	v_lshlrev_b32_e32 v81, 16, v57
	v_lshlrev_b32_e32 v80, 16, v56
	v_and_b32_e32 v53, 0xffff0000, v53
	v_and_b32_e32 v52, 0xffff0000, v52
	v_and_b32_e32 v57, 0xffff0000, v57
	v_and_b32_e32 v56, 0xffff0000, v56
	v_pk_fma_f32 v[68:69], v[8:9], v[76:77], v[68:69]
	v_pk_fma_f32 v[64:65], v[12:13], v[54:55], v[64:65]
	v_pk_fma_f32 v[60:61], v[16:17], v[80:81], v[60:61]
	v_pk_fma_f32 v[58:59], v[22:23], v[56:57], v[58:59]
	v_pk_fma_f32 v[72:73], v[0:1], v[76:77], v[72:73]
	v_pk_fma_f32 v[70:71], v[4:5], v[54:55], v[70:71]
	v_pk_fma_f32 v[66:67], v[10:11], v[80:81], v[66:67]
	v_pk_fma_f32 v[62:63], v[18:19], v[56:57], v[62:63]
	v_pk_fma_f32 v[48:49], v[2:3], v[76:77], v[48:49]
	v_pk_fma_f32 v[46:47], v[6:7], v[54:55], v[46:47]
	v_pk_fma_f32 v[44:45], v[14:15], v[80:81], v[44:45]
	v_pk_fma_f32 v[42:43], v[20:21], v[56:57], v[42:43]
	v_pk_fma_f32 v[40:41], v[74:75], v[76:77], v[40:41]
	v_pk_fma_f32 v[30:31], v[50:51], v[54:55], v[30:31]
	v_pk_fma_f32 v[28:29], v[78:79], v[80:81], v[28:29]
	v_pk_fma_f32 v[26:27], v[52:53], v[56:57], v[26:27]
	v_mov_b64_e32 v[22:23], v[18:19]
	v_mov_b64_e32 v[18:19], v[20:21]
	v_mov_b64_e32 v[20:21], v[52:53]
	v_mov_b64_e32 v[16:17], v[10:11]
	v_mov_b64_e32 v[10:11], v[14:15]
	v_mov_b64_e32 v[14:15], v[78:79]
	v_mov_b64_e32 v[12:13], v[4:5]
	v_mov_b64_e32 v[4:5], v[6:7]
	v_mov_b64_e32 v[6:7], v[50:51]
	v_mov_b64_e32 v[8:9], v[0:1]
	v_mov_b64_e32 v[0:1], v[2:3]
	v_mov_b64_e32 v[2:3], v[74:75]
	s_cbranch_scc1 .LBB0_1667
	v_mov_b32_e32 v0, s8
	v_add_co_u32_e32 v4, vcc, 0x2954000, v0
	v_mov_b32_e32 v0, s9
	s_nop 0
	v_addc_co_u32_e32 v5, vcc, 0, v0, vcc
	global_load_dwordx4 v[0:3], v[4:5], off offset:344
	s_nop 0
	global_load_dwordx2 v[4:5], v[4:5], off offset:360
	v_lshlrev_b32_e32 v116, 2, v38
	v_mov_b64_e32 v[52:53], s[22:23]
	s_waitcnt vmcnt(0) lgkmcnt(0)
	v_readfirstlane_b32 s1, v1
	v_readfirstlane_b32 s0, v0
	v_readfirstlane_b32 s5, v3
	v_readfirstlane_b32 s4, v2
	v_lshl_add_u64 v[0:1], s[0:1], 0, v[116:117]
	global_load_dwordx4 v[16:19], v[0:1], off offset:1024
	v_readfirstlane_b32 s7, v5
	v_readfirstlane_b32 s6, v4
	v_lshl_add_u64 v[2:3], s[4:5], 0, v[116:117]
	global_load_dwordx4 v[8:11], v[2:3], off offset:1024
	v_lshl_add_u64 v[4:5], s[6:7], 0, v[116:117]
	global_load_dwordx4 v[12:15], v[4:5], off offset:1024
	global_load_dwordx4 v[20:23], v[0:1], off offset:1040
	s_nop 0
	global_load_dwordx4 v[0:3], v[2:3], off offset:1040
	s_nop 0
	global_load_dwordx4 v[4:7], v[4:5], off offset:1040
	v_mad_u64_u32 v[24:25], s[0:1], v33, s66, v[36:37]
	s_waitcnt lgkmcnt(0)
	s_barrier
	s_waitcnt vmcnt(0)
	v_mov_b32_e32 v54, v16
	v_mov_b32_e32 v55, v18
	v_mov_b32_e32 v18, v17
	v_pk_add_f32 v[74:75], v[72:73], v[54:55]
	v_mov_b32_e32 v56, v20
	v_mov_b32_e32 v57, v22
	v_mov_b32_e32 v22, v21
	v_pk_add_f32 v[20:21], v[68:69], v[54:55]
	v_mov_b32_e32 v16, v8
	v_mov_b32_e32 v17, v10
	v_mov_b32_e32 v10, v9
	v_mov_b32_e32 v8, v0
	v_mov_b32_e32 v9, v2
	v_pk_add_f32 v[64:65], v[64:65], v[18:19]
	v_pk_add_f32 v[76:77], v[70:71], v[18:19]
	v_add_f32_e32 v0, 0, v20
	v_add_f32_e32 v2, 0, v74
	v_add_f32_e32 v0, v0, v64
	v_add_f32_e32 v2, v2, v76
	v_add_f32_e32 v0, v0, v21
	v_add_f32_e32 v2, v2, v75
	v_pk_add_f32 v[60:61], v[60:61], v[56:57]
	v_pk_add_f32 v[78:79], v[66:67], v[56:57]
	v_add_f32_e32 v0, v0, v65
	v_add_f32_e32 v2, v2, v77
	v_pk_add_f32 v[58:59], v[58:59], v[22:23]
	v_pk_add_f32 v[80:81], v[62:63], v[22:23]
	v_add_f32_e32 v0, v0, v60
	v_add_f32_e32 v2, v2, v78
	v_add_f32_e32 v0, v0, v58
	v_add_f32_e32 v2, v2, v80
	v_add_f32_e32 v0, v0, v61
	v_add_f32_e32 v2, v2, v79
	v_add_f32_e32 v0, v0, v59
	v_add_f32_e32 v2, v2, v81
	v_mov_b32_e32 v50, v12
	v_add_f32_dpp v0, v0, v0 quad_perm:[1,0,3,2] row_mask:0xf bank_mask:0xf bound_ctrl:1
	v_add_f32_dpp v2, v2, v2 quad_perm:[1,0,3,2] row_mask:0xf bank_mask:0xf bound_ctrl:1
	v_mov_b32_e32 v12, v4
	v_add_f32_dpp v0, v0, v0 quad_perm:[2,3,0,1] row_mask:0xf bank_mask:0xf bound_ctrl:1
	v_add_f32_dpp v2, v2, v2 quad_perm:[2,3,0,1] row_mask:0xf bank_mask:0xf bound_ctrl:1
	v_mov_b32_e32 v51, v14
	v_add_f32_dpp v0, v0, v0 row_half_mirror row_mask:0xf bank_mask:0xf bound_ctrl:1
	v_add_f32_dpp v2, v2, v2 row_half_mirror row_mask:0xf bank_mask:0xf bound_ctrl:1
	v_mul_f32_e32 v0, 0x3c800000, v0
	v_mul_f32_e32 v2, 0x3c800000, v2
	v_pk_add_f32 v[72:73], v[20:21], v[0:1] op_sel_hi:[1,0] neg_lo:[0,1] neg_hi:[0,1]
	v_pk_add_f32 v[70:71], v[64:65], v[0:1] op_sel_hi:[1,0] neg_lo:[0,1] neg_hi:[0,1]
	v_pk_add_f32 v[68:69], v[60:61], v[0:1] op_sel_hi:[1,0] neg_lo:[0,1] neg_hi:[0,1]
	v_pk_add_f32 v[62:63], v[74:75], v[2:3] op_sel_hi:[1,0] neg_lo:[0,1] neg_hi:[0,1]
	v_pk_add_f32 v[60:61], v[76:77], v[2:3] op_sel_hi:[1,0] neg_lo:[0,1] neg_hi:[0,1]
	v_pk_add_f32 v[20:21], v[80:81], v[2:3] op_sel_hi:[1,0] neg_lo:[0,1] neg_hi:[0,1]
	v_mov_b32_e32 v64, v72
	v_mov_b32_e32 v65, v70
	v_mov_b32_e32 v80, v62
	v_mov_b32_e32 v81, v60
	v_mov_b32_e32 v74, v71
	v_mov_b32_e32 v75, v73
	v_mov_b32_e32 v82, v61
	v_mov_b32_e32 v83, v63
	v_pk_mul_f32 v[64:65], v[64:65], v[64:65]
	v_pk_mul_f32 v[80:81], v[80:81], v[80:81]
	v_pk_add_f32 v[66:67], v[58:59], v[0:1] op_sel_hi:[1,0] neg_lo:[0,1] neg_hi:[0,1]
	v_pk_add_f32 v[58:59], v[78:79], v[2:3] op_sel_hi:[1,0] neg_lo:[0,1] neg_hi:[0,1]
	v_pk_mul_f32 v[74:75], v[74:75], v[74:75]
	v_pk_mul_f32 v[82:83], v[82:83], v[82:83]
	v_mov_b32_e32 v88, v80
	v_mov_b32_e32 v89, v64
	v_mov_b32_e32 v64, v81
	v_mov_b32_e32 v76, v66
	v_mov_b32_e32 v77, v68
	v_mov_b32_e32 v84, v20
	v_mov_b32_e32 v85, v58
	v_mov_b32_e32 v80, v83
	v_mov_b32_e32 v81, v75
	v_pk_add_f32 v[64:65], v[88:89], v[64:65]
	v_pk_mul_f32 v[76:77], v[76:77], v[76:77]
	v_pk_mul_f32 v[84:85], v[84:85], v[84:85]
	v_mov_b32_e32 v83, v74
	v_pk_add_f32 v[64:65], v[80:81], v[64:65]
	v_mov_b32_e32 v78, v67
	v_mov_b32_e32 v79, v69
	v_mov_b32_e32 v86, v21
	v_mov_b32_e32 v87, v59
	v_mov_b32_e32 v74, v85
	v_mov_b32_e32 v75, v77
	v_pk_add_f32 v[64:65], v[82:83], v[64:65]
	v_pk_mul_f32 v[78:79], v[78:79], v[78:79]
	v_pk_mul_f32 v[86:87], v[86:87], v[86:87]
	v_mov_b32_e32 v85, v76
	v_pk_add_f32 v[64:65], v[74:75], v[64:65]
	v_mov_b32_e32 v76, v87
	v_mov_b32_e32 v77, v79
	v_pk_add_f32 v[64:65], v[84:85], v[64:65]
	v_mov_b32_e32 v87, v78
	v_pk_add_f32 v[64:65], v[76:77], v[64:65]
	v_mov_b32_e32 v2, v1
	v_pk_add_f32 v[64:65], v[86:87], v[64:65]
	v_mov_b32_e32 v14, v13
	v_mov_b32_e32 v13, v6
	v_mov_b32_dpp v75, v65 quad_perm:[1,0,3,2] row_mask:0xf bank_mask:0xf bound_ctrl:1
	v_mov_b32_dpp v74, v64 quad_perm:[1,0,3,2] row_mask:0xf bank_mask:0xf bound_ctrl:1
	v_pk_add_f32 v[64:65], v[64:65], v[74:75]
	v_mov_b32_e32 v6, v5
	v_pk_add_f32 v[42:43], v[42:43], v[22:23]
	v_mov_b32_dpp v75, v65 quad_perm:[2,3,0,1] row_mask:0xf bank_mask:0xf bound_ctrl:1
	v_mov_b32_dpp v74, v64 quad_perm:[2,3,0,1] row_mask:0xf bank_mask:0xf bound_ctrl:1
	v_pk_add_f32 v[64:65], v[64:65], v[74:75]
	v_pk_add_f32 v[28:29], v[28:29], v[56:57]
	v_pk_add_f32 v[22:23], v[26:27], v[22:23]
	v_mov_b32_dpp v75, v65 row_half_mirror row_mask:0xf bank_mask:0xf bound_ctrl:1
	v_mov_b32_dpp v74, v64 row_half_mirror row_mask:0xf bank_mask:0xf bound_ctrl:1
	v_pk_add_f32 v[64:65], v[64:65], v[74:75]
	s_nop 0
	v_pk_fma_f32 v[64:65], v[64:65], s[20:21], v[52:53] op_sel_hi:[1,0,0]
	s_nop 0
	v_mul_f32_e32 v0, 0x4b800000, v65
	v_cmp_gt_f32_e32 vcc, s67, v65
	s_nop 1
	v_cndmask_b32_e32 v0, v65, v0, vcc
	v_rsq_f32_e32 v0, v0
	s_nop 0
	v_mul_f32_e32 v1, 0x45800000, v0
	v_cndmask_b32_e32 v4, v0, v1, vcc
	v_pk_mul_f32 v[0:1], v[72:73], v[4:5] op_sel_hi:[1,0]
	v_pk_mul_f32 v[70:71], v[70:71], v[4:5] op_sel_hi:[1,0]
	v_pk_fma_f32 v[72:73], v[16:17], v[0:1], v[50:51]
	v_pk_mul_f32 v[68:69], v[68:69], v[4:5] op_sel_hi:[1,0]
	v_mul_f32_e32 v5, 0xbfb8aa3b, v72
	v_mul_f32_e32 v35, 0xbfb8aa3b, v73
	v_pk_fma_f32 v[70:71], v[10:11], v[70:71], v[14:15]
	v_pk_fma_f32 v[0:1], v[8:9], v[68:69], v[12:13]
	v_exp_f32_e32 v68, v5
	v_exp_f32_e32 v69, v35
	v_mul_f32_e32 v25, 0xbfb8aa3b, v70
	v_mul_f32_e32 v37, 0xbfb8aa3b, v71
	v_exp_f32_e32 v74, v25
	v_exp_f32_e32 v75, v37
	v_pk_mul_f32 v[78:79], v[66:67], v[4:5] op_sel_hi:[1,0]
	v_pk_add_f32 v[4:5], v[68:69], 1.0 op_sel_hi:[1,0]
	v_mul_f32_e32 v65, 0xbfb8aa3b, v1
	v_div_scale_f32 v25, s[0:1], v5, v5, 1.0
	v_pk_add_f32 v[68:69], v[74:75], 1.0 op_sel_hi:[1,0]
	v_div_scale_f32 v37, s[0:1], v4, v4, 1.0
	v_rcp_f32_e32 v80, v25
	v_exp_f32_e32 v77, v65
	v_div_scale_f32 v65, s[4:5], v69, v69, 1.0
	v_rcp_f32_e32 v81, v37
	v_div_scale_f32 v75, s[6:7], v68, v68, 1.0
	v_rcp_f32_e32 v82, v65
	v_mul_f32_e32 v39, 0xbfb8aa3b, v0
	v_rcp_f32_e32 v83, v75
	v_exp_f32_e32 v76, v39
	v_fma_f32 v84, -v25, v80, 1.0
	v_div_scale_f32 v35, vcc, 1.0, v5, 1.0
	v_fma_f32 v85, -v37, v81, 1.0
	v_fmac_f32_e32 v80, v84, v80
	v_div_scale_f32 v39, s[0:1], 1.0, v4, 1.0
	v_fma_f32 v86, -v65, v82, 1.0
	v_fmac_f32_e32 v81, v85, v81
	v_mul_f32_e32 v84, v35, v80
	v_div_scale_f32 v74, s[4:5], 1.0, v69, 1.0
	v_fma_f32 v87, -v75, v83, 1.0
	v_fmac_f32_e32 v82, v86, v82
	v_mul_f32_e32 v85, v39, v81
	v_fma_f32 v88, -v25, v84, v35
	v_pk_add_f32 v[66:67], v[76:77], 1.0 op_sel_hi:[1,0]
	v_div_scale_f32 v76, s[6:7], 1.0, v68, 1.0
	v_fmac_f32_e32 v83, v87, v83
	v_mul_f32_e32 v86, v74, v82
	v_fma_f32 v89, -v37, v85, v39
	v_fmac_f32_e32 v84, v88, v80
	v_mul_f32_e32 v87, v76, v83
	v_fma_f32 v90, -v65, v86, v74
	v_fmac_f32_e32 v85, v89, v81
	v_fma_f32 v25, -v25, v84, v35
	v_fma_f32 v91, -v75, v87, v76
	v_fmac_f32_e32 v86, v90, v82
	v_fma_f32 v35, -v37, v85, v39
	v_div_fmas_f32 v25, v25, v80, v84
	s_mov_b64 vcc, s[0:1]
	v_fmac_f32_e32 v87, v91, v83
	v_fma_f32 v37, -v65, v86, v74
	v_div_fixup_f32 v5, v25, v5, 1.0
	v_div_fmas_f32 v25, v35, v81, v85
	s_mov_b64 vcc, s[4:5]
	v_fma_f32 v39, -v75, v87, v76
	v_div_fixup_f32 v4, v25, v4, 1.0
	v_div_fmas_f32 v25, v37, v82, v86
	s_mov_b64 vcc, s[6:7]
	v_div_scale_f32 v77, s[24:25], v67, v67, 1.0
	v_div_fixup_f32 v69, v25, v69, 1.0
	v_div_fmas_f32 v25, v39, v83, v87
	v_div_fixup_f32 v68, v25, v68, 1.0
	v_rcp_f32_e32 v25, v77
	v_pk_mul_f32 v[68:69], v[70:71], v[68:69]
	v_pk_fma_f32 v[70:71], v[2:3], v[78:79], v[6:7]
	v_pk_mul_f32 v[4:5], v[72:73], v[4:5]
	v_mul_f32_e32 v35, 0xbfb8aa3b, v70
	v_exp_f32_e32 v72, v35
	v_fma_f32 v35, -v77, v25, 1.0
	v_fmac_f32_e32 v25, v35, v25
	v_div_scale_f32 v35, vcc, 1.0, v67, 1.0
	v_mul_f32_e32 v37, v35, v25
	v_fma_f32 v39, -v77, v37, v35
	v_fmac_f32_e32 v37, v39, v25
	v_div_scale_f32 v39, s[0:1], v66, v66, 1.0
	v_rcp_f32_e32 v65, v39
	v_fma_f32 v35, -v77, v37, v35
	v_div_fmas_f32 v25, v35, v25, v37
	v_mul_f32_e32 v37, 0xbfb8aa3b, v71
	v_exp_f32_e32 v73, v37
	v_div_fixup_f32 v67, v25, v67, 1.0
	v_fma_f32 v25, -v39, v65, 1.0
	v_fmac_f32_e32 v65, v25, v65
	v_div_scale_f32 v25, vcc, 1.0, v66, 1.0
	v_mul_f32_e32 v35, v25, v65
	v_fma_f32 v37, -v39, v35, v25
	v_pk_add_f32 v[72:73], v[72:73], 1.0 op_sel_hi:[1,0]
	v_fmac_f32_e32 v35, v37, v65
	v_div_scale_f32 v37, s[0:1], v73, v73, 1.0
	v_fma_f32 v25, -v39, v35, v25
	v_rcp_f32_e32 v39, v37
	v_div_fmas_f32 v25, v25, v65, v35
	v_div_fixup_f32 v66, v25, v66, 1.0
	v_pk_mul_f32 v[0:1], v[0:1], v[66:67]
	v_fma_f32 v25, -v37, v39, 1.0
	v_fmac_f32_e32 v39, v25, v39
	v_div_scale_f32 v25, vcc, 1.0, v73, 1.0
	v_mul_f32_e32 v35, v25, v39
	v_fma_f32 v65, -v37, v35, v25
	v_fmac_f32_e32 v35, v65, v39
	v_fma_f32 v25, -v37, v35, v25
	v_div_scale_f32 v37, s[0:1], v72, v72, 1.0
	v_rcp_f32_e32 v65, v37
	v_div_fmas_f32 v25, v25, v39, v35
	v_div_fixup_f32 v67, v25, v73, 1.0
	v_fma_f32 v25, -v37, v65, 1.0
	v_fmac_f32_e32 v65, v25, v65
	v_div_scale_f32 v25, vcc, 1.0, v72, 1.0
	v_mul_f32_e32 v35, v25, v65
	v_fma_f32 v39, -v37, v35, v25
	v_fmac_f32_e32 v35, v39, v65
	v_fma_f32 v25, -v37, v35, v25
	v_div_fmas_f32 v25, v25, v65, v35
	v_div_fixup_f32 v66, v25, v72, 1.0
	v_pk_mul_f32 v[66:67], v[70:71], v[66:67]
	v_bfe_u32 v39, v68, 16, 1
	v_bfe_u32 v35, v66, 16, 1
	v_add3_u32 v35, v66, v35, s61
	v_bfe_u32 v65, v4, 16, 1
	v_bfe_u32 v66, v5, 16, 1
	v_add3_u32 v39, v68, v39, s61
	v_bfe_u32 v68, v1, 16, 1
	v_add3_u32 v5, v5, v66, s61
	v_add3_u32 v4, v4, v65, s61
	v_add3_u32 v1, v1, v68, s61
	v_lshrrev_b32_e32 v68, 16, v4
	v_lshrrev_b32_e32 v4, 16, v5
	v_mul_f32_e32 v5, 0x4b800000, v64
	v_cmp_gt_f32_e32 vcc, s67, v64
	v_bfe_u32 v25, v67, 16, 1
	v_add3_u32 v25, v67, v25, s61
	v_cndmask_b32_e32 v5, v64, v5, vcc
	v_rsq_f32_e32 v5, v5
	v_bfe_u32 v67, v0, 16, 1
	v_add3_u32 v0, v0, v67, s61
	v_bfe_u32 v37, v69, 16, 1
	v_lshrrev_b32_e32 v0, 16, v0
	v_add3_u32 v37, v69, v37, s61
	v_and_or_b32 v66, v35, s65, v0
	v_mul_f32_e32 v0, 0x45800000, v5
	v_lshrrev_b32_e32 v1, 16, v1
	v_and_or_b32 v65, v37, s65, v4
	v_cndmask_b32_e32 v4, v5, v0, vcc
	v_and_or_b32 v67, v25, s65, v1
	v_pk_mul_f32 v[0:1], v[62:63], v[4:5] op_sel_hi:[1,0]
	v_and_or_b32 v64, v39, s65, v68
	v_pk_fma_f32 v[0:1], v[16:17], v[0:1], v[50:51]
	ds_write_b128 v24, v[64:67]
	v_mul_f32_e32 v5, 0xbfb8aa3b, v0
	v_exp_f32_e32 v62, v5
	v_mul_f32_e32 v5, 0xbfb8aa3b, v1
	v_exp_f32_e32 v63, v5
	v_pk_mul_f32 v[60:61], v[60:61], v[4:5] op_sel_hi:[1,0]
	v_pk_add_f32 v[62:63], v[62:63], 1.0 op_sel_hi:[1,0]
	s_nop 0
	v_div_scale_f32 v5, s[0:1], v63, v63, 1.0
	v_rcp_f32_e32 v25, v5
	v_pk_fma_f32 v[60:61], v[10:11], v[60:61], v[14:15]
	s_nop 0
	v_mul_f32_e32 v35, 0xbfb8aa3b, v60
	v_exp_f32_e32 v64, v35
	v_fma_f32 v35, -v5, v25, 1.0
	v_fmac_f32_e32 v25, v35, v25
	v_div_scale_f32 v35, vcc, 1.0, v63, 1.0
	v_mul_f32_e32 v37, v35, v25
	v_fma_f32 v39, -v5, v37, v35
	v_fmac_f32_e32 v37, v39, v25
	v_fma_f32 v5, -v5, v37, v35
	v_div_scale_f32 v35, s[0:1], v62, v62, 1.0
	v_rcp_f32_e32 v39, v35
	v_div_fmas_f32 v5, v5, v25, v37
	v_mul_f32_e32 v37, 0xbfb8aa3b, v61
	v_div_fixup_f32 v63, v5, v63, 1.0
	v_fma_f32 v5, -v35, v39, 1.0
	v_exp_f32_e32 v65, v37
	v_fmac_f32_e32 v39, v5, v39
	v_div_scale_f32 v5, vcc, 1.0, v62, 1.0
	v_mul_f32_e32 v25, v5, v39
	v_fma_f32 v37, -v35, v25, v5
	v_fmac_f32_e32 v25, v37, v39
	v_pk_add_f32 v[64:65], v[64:65], 1.0 op_sel_hi:[1,0]
	v_fma_f32 v5, -v35, v25, v5
	v_div_scale_f32 v35, s[0:1], v65, v65, 1.0
	v_rcp_f32_e32 v37, v35
	v_div_fmas_f32 v5, v5, v39, v25
	v_div_fixup_f32 v62, v5, v62, 1.0
	v_pk_mul_f32 v[0:1], v[0:1], v[62:63]
	v_fma_f32 v5, -v35, v37, 1.0
	v_fmac_f32_e32 v37, v5, v37
	v_div_scale_f32 v5, vcc, 1.0, v65, 1.0
	v_mul_f32_e32 v25, v5, v37
	v_fma_f32 v39, -v35, v25, v5
	v_fmac_f32_e32 v25, v39, v37
	v_fma_f32 v5, -v35, v25, v5
	v_div_scale_f32 v35, s[0:1], v64, v64, 1.0
	v_rcp_f32_e32 v39, v35
	v_div_fmas_f32 v5, v5, v37, v25
	v_div_fixup_f32 v63, v5, v65, 1.0
	v_fma_f32 v5, -v35, v39, 1.0
	v_fmac_f32_e32 v39, v5, v39
	v_div_scale_f32 v5, vcc, 1.0, v64, 1.0
	v_mul_f32_e32 v25, v5, v39
	v_fma_f32 v37, -v35, v25, v5
	v_fmac_f32_e32 v25, v37, v39
	v_fma_f32 v5, -v35, v25, v5
	v_div_fmas_f32 v5, v5, v39, v25
	v_pk_mul_f32 v[58:59], v[58:59], v[4:5] op_sel_hi:[1,0]
	v_div_fixup_f32 v62, v5, v64, 1.0
	v_pk_fma_f32 v[58:59], v[8:9], v[58:59], v[12:13]
	v_pk_mul_f32 v[4:5], v[20:21], v[4:5] op_sel_hi:[1,0]
	v_mul_f32_e32 v25, 0xbfb8aa3b, v58
	v_exp_f32_e32 v66, v25
	v_mul_f32_e32 v25, 0xbfb8aa3b, v59
	v_exp_f32_e32 v67, v25
	v_pk_fma_f32 v[4:5], v[2:3], v[4:5], v[6:7]
	v_pk_mul_f32 v[60:61], v[60:61], v[62:63]
	v_mul_f32_e32 v37, 0xbfb8aa3b, v4
	v_pk_add_f32 v[20:21], v[66:67], 1.0 op_sel_hi:[1,0]
	v_exp_f32_e32 v62, v37
	v_div_scale_f32 v25, s[0:1], v21, v21, 1.0
	v_rcp_f32_e32 v35, v25
	s_nop 0
	v_fma_f32 v37, -v25, v35, 1.0
	v_fmac_f32_e32 v35, v37, v35
	v_div_scale_f32 v37, vcc, 1.0, v21, 1.0
	v_mul_f32_e32 v39, v37, v35
	v_fma_f32 v63, -v25, v39, v37
	v_fmac_f32_e32 v39, v63, v35
	v_fma_f32 v25, -v25, v39, v37
	v_div_scale_f32 v37, s[0:1], v20, v20, 1.0
	v_rcp_f32_e32 v64, v37
	v_div_fmas_f32 v25, v25, v35, v39
	v_mul_f32_e32 v39, 0xbfb8aa3b, v5
	v_div_fixup_f32 v21, v25, v21, 1.0
	v_fma_f32 v25, -v37, v64, 1.0
	v_exp_f32_e32 v63, v39
	v_fmac_f32_e32 v64, v25, v64
	v_div_scale_f32 v25, vcc, 1.0, v20, 1.0
	v_mul_f32_e32 v35, v25, v64
	v_fma_f32 v39, -v37, v35, v25
	v_fmac_f32_e32 v35, v39, v64
	v_pk_add_f32 v[62:63], v[62:63], 1.0 op_sel_hi:[1,0]
	v_fma_f32 v25, -v37, v35, v25
	v_div_scale_f32 v37, s[0:1], v63, v63, 1.0
	v_rcp_f32_e32 v39, v37
	v_div_fmas_f32 v25, v25, v64, v35
	v_div_fixup_f32 v20, v25, v20, 1.0
	v_pk_mul_f32 v[20:21], v[58:59], v[20:21]
	v_fma_f32 v25, -v37, v39, 1.0
	v_fmac_f32_e32 v39, v25, v39
	v_div_scale_f32 v25, vcc, 1.0, v63, 1.0
	v_mul_f32_e32 v35, v25, v39
	v_fma_f32 v58, -v37, v35, v25
	v_fmac_f32_e32 v35, v58, v39
	v_fma_f32 v25, -v37, v35, v25
	v_div_scale_f32 v37, s[0:1], v62, v62, 1.0
	v_rcp_f32_e32 v58, v37
	v_div_fmas_f32 v25, v25, v39, v35
	v_div_fixup_f32 v59, v25, v63, 1.0
	v_fma_f32 v25, -v37, v58, 1.0
	v_fmac_f32_e32 v58, v25, v58
	v_div_scale_f32 v25, vcc, 1.0, v62, 1.0
	v_mul_f32_e32 v35, v25, v58
	v_fma_f32 v39, -v37, v35, v25
	v_fmac_f32_e32 v35, v39, v58
	v_fma_f32 v25, -v37, v35, v25
	v_div_fmas_f32 v25, v25, v58, v35
	v_div_fixup_f32 v58, v25, v62, 1.0
	v_pk_mul_f32 v[4:5], v[4:5], v[58:59]
	v_bfe_u32 v58, v20, 16, 1
	v_bfe_u32 v25, v5, 16, 1
	v_bfe_u32 v35, v4, 16, 1
	v_add3_u32 v35, v4, v35, s61
	v_add3_u32 v25, v5, v25, s61
	v_bfe_u32 v4, v0, 16, 1
	v_bfe_u32 v5, v1, 16, 1
	v_add3_u32 v1, v1, v5, s61
	v_add3_u32 v0, v0, v4, s61
	v_add3_u32 v20, v20, v58, s61
	v_lshrrev_b32_e32 v64, 16, v0
	v_lshrrev_b32_e32 v65, 16, v1
	v_pk_add_f32 v[0:1], v[48:49], v[54:55]
	v_lshrrev_b32_e32 v66, 16, v20
	v_add_f32_e32 v20, 0, v0
	v_pk_add_f32 v[4:5], v[46:47], v[18:19]
	v_bfe_u32 v59, v21, 16, 1
	v_add_f32_e32 v20, v20, v4
	v_add3_u32 v21, v21, v59, s61
	v_add_f32_e32 v20, v20, v1
	v_lshrrev_b32_e32 v67, 16, v21
	v_add_f32_e32 v46, v20, v5
	v_pk_add_f32 v[20:21], v[44:45], v[56:57]
	v_bfe_u32 v37, v61, 16, 1
	v_add_f32_e32 v44, v46, v20
	v_add_f32_e32 v44, v44, v42
	v_add_f32_e32 v44, v44, v21
	v_add_f32_e32 v44, v44, v43
	v_bfe_u32 v39, v60, 16, 1
	v_add3_u32 v39, v60, v39, s61
	v_add_f32_dpp v44, v44, v44 quad_perm:[1,0,3,2] row_mask:0xf bank_mask:0xf bound_ctrl:1
	v_add3_u32 v37, v61, v37, s61
	v_pk_add_f32 v[18:19], v[30:31], v[18:19]
	v_add_f32_dpp v44, v44, v44 quad_perm:[2,3,0,1] row_mask:0xf bank_mask:0xf bound_ctrl:1
	s_nop 1
	v_add_f32_dpp v44, v44, v44 row_half_mirror row_mask:0xf bank_mask:0xf bound_ctrl:1
	v_mul_f32_e32 v46, 0x3c800000, v44
	v_pk_add_f32 v[48:49], v[0:1], v[46:47] op_sel_hi:[1,0] neg_lo:[0,1] neg_hi:[0,1]
	v_pk_add_f32 v[58:59], v[4:5], v[46:47] op_sel_hi:[1,0] neg_lo:[0,1] neg_hi:[0,1]
	v_mov_b32_e32 v5, v49
	v_mov_b32_e32 v4, v59
	v_pk_add_f32 v[44:45], v[20:21], v[46:47] op_sel_hi:[1,0] neg_lo:[0,1] neg_hi:[0,1]
	v_pk_add_f32 v[42:43], v[42:43], v[46:47] op_sel_hi:[1,0] neg_lo:[0,1] neg_hi:[0,1]
	v_pk_mul_f32 v[60:61], v[4:5], v[4:5]
	v_mov_b32_e32 v4, v42
	v_mov_b32_e32 v5, v44
	v_pk_mul_f32 v[46:47], v[4:5], v[4:5]
	v_mov_b32_e32 v4, v43
	v_mov_b32_e32 v5, v45
	v_pk_mul_f32 v[62:63], v[4:5], v[4:5]
	v_pk_add_f32 v[4:5], v[40:41], v[54:55]
	v_mov_b32_e32 v0, v48
	v_add_f32_e32 v20, 0, v4
	v_add_f32_e32 v20, v20, v18
	v_add_f32_e32 v20, v20, v5
	v_add_f32_e32 v20, v20, v19
	v_add_f32_e32 v20, v20, v28
	v_add_f32_e32 v20, v20, v22
	v_add_f32_e32 v20, v20, v29
	v_add_f32_e32 v20, v20, v23
	v_mov_b32_e32 v1, v58
	v_pk_mul_f32 v[0:1], v[0:1], v[0:1]
	v_add_f32_dpp v20, v20, v20 quad_perm:[1,0,3,2] row_mask:0xf bank_mask:0xf bound_ctrl:1
	v_mov_b32_e32 v31, v0
	s_nop 0
	v_add_f32_dpp v20, v20, v20 quad_perm:[2,3,0,1] row_mask:0xf bank_mask:0xf bound_ctrl:1
	s_nop 1
	v_add_f32_dpp v20, v20, v20 row_half_mirror row_mask:0xf bank_mask:0xf bound_ctrl:1
	v_mul_f32_e32 v26, 0x3c800000, v20
	v_pk_add_f32 v[20:21], v[4:5], v[26:27] op_sel_hi:[1,0] neg_lo:[0,1] neg_hi:[0,1]
	v_pk_add_f32 v[18:19], v[18:19], v[26:27] op_sel_hi:[1,0] neg_lo:[0,1] neg_hi:[0,1]
	v_mov_b32_e32 v4, v20
	v_mov_b32_e32 v5, v18
	v_pk_mul_f32 v[4:5], v[4:5], v[4:5]
	s_nop 0
	v_mov_b32_e32 v30, v4
	v_mov_b32_e32 v0, v5
	v_pk_add_f32 v[30:31], v[30:31], v[0:1]
	v_mov_b32_e32 v0, v19
	v_mov_b32_e32 v1, v21
	v_pk_mul_f32 v[40:41], v[0:1], v[0:1]
	v_pk_add_f32 v[4:5], v[28:29], v[26:27] op_sel_hi:[1,0] neg_lo:[0,1] neg_hi:[0,1]
	v_pk_add_f32 v[0:1], v[22:23], v[26:27] op_sel_hi:[1,0] neg_lo:[0,1] neg_hi:[0,1]
	v_mov_b32_e32 v23, v4
	v_mov_b32_e32 v22, v0
	v_mov_b32_e32 v28, v41
	v_mov_b32_e32 v29, v61
	v_pk_mul_f32 v[22:23], v[22:23], v[22:23]
	v_pk_add_f32 v[28:29], v[28:29], v[30:31]
	v_mov_b32_e32 v41, v60
	v_mov_b32_e32 v26, v1
	v_mov_b32_e32 v27, v5
	v_pk_add_f32 v[28:29], v[40:41], v[28:29]
	v_mov_b32_e32 v30, v23
	v_mov_b32_e32 v31, v47
	v_pk_mul_f32 v[26:27], v[26:27], v[26:27]
	v_pk_add_f32 v[28:29], v[30:31], v[28:29]
	v_mov_b32_e32 v23, v46
	v_pk_add_f32 v[22:23], v[22:23], v[28:29]
	v_mov_b32_e32 v28, v27
	v_mov_b32_e32 v29, v63
	v_pk_add_f32 v[22:23], v[28:29], v[22:23]
	v_mov_b32_e32 v27, v62
	v_pk_add_f32 v[22:23], v[26:27], v[22:23]
	v_and_or_b32 v29, v25, s65, v67
	v_and_or_b32 v28, v35, s65, v66
	v_mov_b32_dpp v27, v23 quad_perm:[1,0,3,2] row_mask:0xf bank_mask:0xf bound_ctrl:1
	v_mov_b32_dpp v26, v22 quad_perm:[1,0,3,2] row_mask:0xf bank_mask:0xf bound_ctrl:1
	v_pk_add_f32 v[22:23], v[22:23], v[26:27]
	s_nop 1
	v_mov_b32_dpp v27, v23 quad_perm:[2,3,0,1] row_mask:0xf bank_mask:0xf bound_ctrl:1
	v_mov_b32_dpp v26, v22 quad_perm:[2,3,0,1] row_mask:0xf bank_mask:0xf bound_ctrl:1
	v_pk_add_f32 v[22:23], v[22:23], v[26:27]
	s_nop 1
	v_mov_b32_dpp v27, v23 row_half_mirror row_mask:0xf bank_mask:0xf bound_ctrl:1
	v_mov_b32_dpp v26, v22 row_half_mirror row_mask:0xf bank_mask:0xf bound_ctrl:1
	v_pk_add_f32 v[22:23], v[22:23], v[26:27]
	v_and_or_b32 v27, v37, s65, v65
	v_pk_fma_f32 v[22:23], v[22:23], s[20:21], v[52:53] op_sel_hi:[1,0,0]
	s_nop 0
	v_mul_f32_e32 v26, 0x4b800000, v23
	v_cmp_gt_f32_e32 vcc, s67, v23
	s_nop 1
	v_cndmask_b32_e32 v23, v23, v26, vcc
	v_rsq_f32_e32 v23, v23
	v_and_or_b32 v26, v39, s65, v64
	ds_write_b128 v24, v[26:29] offset:528
	v_mul_f32_e32 v25, 0x45800000, v23
	v_cndmask_b32_e32 v30, v23, v25, vcc
	v_pk_mul_f32 v[40:41], v[48:49], v[30:31] op_sel_hi:[1,0]
	v_pk_mul_f32 v[26:27], v[58:59], v[30:31] op_sel_hi:[1,0]
	v_pk_fma_f32 v[40:41], v[16:17], v[40:41], v[50:51]
	s_nop 0
	v_mul_f32_e32 v23, 0xbfb8aa3b, v40
	v_exp_f32_e32 v46, v23
	v_mul_f32_e32 v23, 0xbfb8aa3b, v41
	v_exp_f32_e32 v47, v23
	s_nop 0
	v_pk_add_f32 v[28:29], v[46:47], 1.0 op_sel_hi:[1,0]
	s_nop 0
	v_div_scale_f32 v23, s[0:1], v29, v29, 1.0
	v_rcp_f32_e32 v25, v23
	v_pk_fma_f32 v[46:47], v[10:11], v[26:27], v[14:15]
	v_fma_f32 v27, -v23, v25, 1.0
	v_fmac_f32_e32 v25, v27, v25
	v_div_scale_f32 v27, vcc, 1.0, v29, 1.0
	v_mul_f32_e32 v31, v27, v25
	v_fma_f32 v35, -v23, v31, v27
	v_fmac_f32_e32 v31, v35, v25
	v_div_scale_f32 v35, s[0:1], v28, v28, 1.0
	v_rcp_f32_e32 v37, v35
	v_mul_f32_e32 v26, 0xbfb8aa3b, v46
	v_fma_f32 v23, -v23, v31, v27
	v_mul_f32_e32 v27, 0xbfb8aa3b, v47
	v_exp_f32_e32 v26, v26
	v_div_fmas_f32 v23, v23, v25, v31
	v_exp_f32_e32 v27, v27
	v_div_fixup_f32 v29, v23, v29, 1.0
	v_fma_f32 v23, -v35, v37, 1.0
	v_fmac_f32_e32 v37, v23, v37
	v_div_scale_f32 v23, vcc, 1.0, v28, 1.0
	v_mul_f32_e32 v25, v23, v37
	v_fma_f32 v31, -v35, v25, v23
	v_pk_add_f32 v[48:49], v[26:27], 1.0 op_sel_hi:[1,0]
	v_fmac_f32_e32 v25, v31, v37
	v_div_scale_f32 v31, s[0:1], v49, v49, 1.0
	v_fma_f32 v23, -v35, v25, v23
	v_rcp_f32_e32 v35, v31
	v_div_fmas_f32 v23, v23, v37, v25
	v_div_fixup_f32 v28, v23, v28, 1.0
	v_pk_mul_f32 v[26:27], v[40:41], v[28:29]
	v_fma_f32 v23, -v31, v35, 1.0
	v_fmac_f32_e32 v35, v23, v35
	v_div_scale_f32 v23, vcc, 1.0, v49, 1.0
	v_mul_f32_e32 v25, v23, v35
	v_fma_f32 v28, -v31, v25, v23
	v_fmac_f32_e32 v25, v28, v35
	v_div_scale_f32 v28, s[0:1], v48, v48, 1.0
	v_fma_f32 v23, -v31, v25, v23
	v_rcp_f32_e32 v31, v28
	v_div_fmas_f32 v23, v23, v35, v25
	v_div_fixup_f32 v29, v23, v49, 1.0
	v_fma_f32 v23, -v28, v31, 1.0
	v_fmac_f32_e32 v31, v23, v31
	v_div_scale_f32 v23, vcc, 1.0, v48, 1.0
	v_mul_f32_e32 v25, v23, v31
	v_fma_f32 v35, -v28, v25, v23
	v_fmac_f32_e32 v25, v35, v31
	v_pk_mul_f32 v[40:41], v[44:45], v[30:31] op_sel_hi:[1,0]
	v_fma_f32 v23, -v28, v25, v23
	v_pk_fma_f32 v[40:41], v[8:9], v[40:41], v[12:13]
	v_div_fmas_f32 v23, v23, v31, v25
	v_mul_f32_e32 v25, 0xbfb8aa3b, v40
	v_exp_f32_e32 v44, v25
	v_mul_f32_e32 v25, 0xbfb8aa3b, v41
	v_exp_f32_e32 v45, v25
	v_pk_mul_f32 v[30:31], v[42:43], v[30:31] op_sel_hi:[1,0]
	v_div_fixup_f32 v28, v23, v48, 1.0
	v_pk_fma_f32 v[30:31], v[2:3], v[30:31], v[6:7]
	v_pk_add_f32 v[42:43], v[44:45], 1.0 op_sel_hi:[1,0]
	v_mul_f32_e32 v35, 0xbfb8aa3b, v30
	v_div_scale_f32 v23, s[0:1], v43, v43, 1.0
	v_rcp_f32_e32 v25, v23
	v_exp_f32_e32 v44, v35
	v_pk_mul_f32 v[28:29], v[46:47], v[28:29]
	v_fma_f32 v35, -v23, v25, 1.0
	v_fmac_f32_e32 v25, v35, v25
	v_div_scale_f32 v35, vcc, 1.0, v43, 1.0
	v_mul_f32_e32 v37, v35, v25
	v_fma_f32 v39, -v23, v37, v35
	v_fmac_f32_e32 v37, v39, v25
	v_fma_f32 v23, -v23, v37, v35
	v_div_scale_f32 v35, s[0:1], v42, v42, 1.0
	v_rcp_f32_e32 v39, v35
	v_div_fmas_f32 v23, v23, v25, v37
	v_mul_f32_e32 v37, 0xbfb8aa3b, v31
	v_div_fixup_f32 v43, v23, v43, 1.0
	v_fma_f32 v23, -v35, v39, 1.0
	v_exp_f32_e32 v45, v37
	v_fmac_f32_e32 v39, v23, v39
	v_div_scale_f32 v23, vcc, 1.0, v42, 1.0
	v_mul_f32_e32 v25, v23, v39
	v_fma_f32 v37, -v35, v25, v23
	v_fmac_f32_e32 v25, v37, v39
	v_pk_add_f32 v[44:45], v[44:45], 1.0 op_sel_hi:[1,0]
	v_fma_f32 v23, -v35, v25, v23
	v_div_scale_f32 v35, s[0:1], v45, v45, 1.0
	v_rcp_f32_e32 v37, v35
	v_div_fmas_f32 v23, v23, v39, v25
	v_div_fixup_f32 v42, v23, v42, 1.0
	v_pk_mul_f32 v[40:41], v[40:41], v[42:43]
	v_fma_f32 v23, -v35, v37, 1.0
	v_fmac_f32_e32 v37, v23, v37
	v_div_scale_f32 v23, vcc, 1.0, v45, 1.0
	v_mul_f32_e32 v25, v23, v37
	v_fma_f32 v39, -v35, v25, v23
	v_fmac_f32_e32 v25, v39, v37
	v_fma_f32 v23, -v35, v25, v23
	v_div_scale_f32 v35, s[0:1], v44, v44, 1.0
	v_rcp_f32_e32 v39, v35
	v_div_fmas_f32 v23, v23, v37, v25
	v_div_fixup_f32 v43, v23, v45, 1.0
	v_fma_f32 v23, -v35, v39, 1.0
	v_fmac_f32_e32 v39, v23, v39
	v_div_scale_f32 v23, vcc, 1.0, v44, 1.0
	v_mul_f32_e32 v25, v23, v39
	v_fma_f32 v37, -v35, v25, v23
	v_fmac_f32_e32 v25, v37, v39
	v_fma_f32 v23, -v35, v25, v23
	v_div_fmas_f32 v23, v23, v39, v25
	v_div_fixup_f32 v42, v23, v44, 1.0
	v_pk_mul_f32 v[30:31], v[30:31], v[42:43]
	v_bfe_u32 v37, v28, 16, 1
	v_bfe_u32 v25, v30, 16, 1
	v_add3_u32 v25, v30, v25, s61
	v_bfe_u32 v30, v40, 16, 1
	v_add3_u32 v37, v28, v37, s61
	v_bfe_u32 v28, v26, 16, 1
	v_add3_u32 v30, v40, v30, s61
	v_add3_u32 v26, v26, v28, s61
	v_lshrrev_b32_e32 v28, 16, v30
	v_mul_f32_e32 v30, 0x4b800000, v22
	v_cmp_gt_f32_e32 vcc, s67, v22
	v_bfe_u32 v23, v31, 16, 1
	v_bfe_u32 v35, v29, 16, 1
	v_cndmask_b32_e32 v22, v22, v30, vcc
	v_rsq_f32_e32 v22, v22
	v_add3_u32 v23, v31, v23, s61
	v_bfe_u32 v31, v41, 16, 1
	v_add3_u32 v35, v29, v35, s61
	v_bfe_u32 v29, v27, 16, 1
	v_add3_u32 v31, v41, v31, s61
	v_add3_u32 v27, v27, v29, s61
	v_lshrrev_b32_e32 v29, 16, v31
	v_and_or_b32 v29, v23, s65, v29
	v_mul_f32_e32 v23, 0x45800000, v22
	v_cndmask_b32_e32 v22, v22, v23, vcc
	v_pk_mul_f32 v[20:21], v[20:21], v[22:23] op_sel_hi:[1,0]
	v_pk_mul_f32 v[18:19], v[18:19], v[22:23] op_sel_hi:[1,0]
	v_pk_fma_f32 v[16:17], v[16:17], v[20:21], v[50:51]
	v_and_or_b32 v28, v25, s65, v28
	v_mul_f32_e32 v20, 0xbfb8aa3b, v16
	v_mul_f32_e32 v21, 0xbfb8aa3b, v17
	v_exp_f32_e32 v20, v20
	v_exp_f32_e32 v21, v21
	v_pk_fma_f32 v[14:15], v[10:11], v[18:19], v[14:15]
	v_lshrrev_b32_e32 v26, 16, v26
	v_lshrrev_b32_e32 v27, 16, v27
	v_pk_add_f32 v[20:21], v[20:21], 1.0 op_sel_hi:[1,0]
	v_and_or_b32 v27, v35, s65, v27
	v_div_scale_f32 v23, s[0:1], v21, v21, 1.0
	v_rcp_f32_e32 v25, v23
	v_and_or_b32 v26, v37, s65, v26
	ds_write_b128 v24, v[26:29] offset:1056
	v_mul_f32_e32 v10, 0xbfb8aa3b, v14
	v_fma_f32 v11, -v23, v25, 1.0
	v_fmac_f32_e32 v25, v11, v25
	v_div_scale_f32 v11, vcc, 1.0, v21, 1.0
	v_mul_f32_e32 v18, v11, v25
	v_fma_f32 v19, -v23, v18, v11
	v_fmac_f32_e32 v18, v19, v25
	v_fma_f32 v11, -v23, v18, v11
	v_div_scale_f32 v23, s[0:1], v20, v20, 1.0
	v_rcp_f32_e32 v28, v23
	v_div_fmas_f32 v11, v11, v25, v18
	v_div_fixup_f32 v19, v11, v21, 1.0
	v_exp_f32_e32 v10, v10
	v_fma_f32 v11, -v23, v28, 1.0
	v_fmac_f32_e32 v28, v11, v28
	v_mul_f32_e32 v11, 0xbfb8aa3b, v15
	v_exp_f32_e32 v11, v11
	v_div_scale_f32 v18, vcc, 1.0, v20, 1.0
	v_mul_f32_e32 v21, v18, v28
	v_fma_f32 v25, -v23, v21, v18
	v_fmac_f32_e32 v21, v25, v28
	v_pk_add_f32 v[26:27], v[10:11], 1.0 op_sel_hi:[1,0]
	v_fma_f32 v18, -v23, v21, v18
	v_div_scale_f32 v23, s[0:1], v27, v27, 1.0
	v_rcp_f32_e32 v25, v23
	v_div_fmas_f32 v10, v18, v28, v21
	v_div_fixup_f32 v18, v10, v20, 1.0
	v_pk_mul_f32 v[10:11], v[16:17], v[18:19]
	v_fma_f32 v16, -v23, v25, 1.0
	v_fmac_f32_e32 v25, v16, v25
	v_div_scale_f32 v16, vcc, 1.0, v27, 1.0
	v_mul_f32_e32 v17, v16, v25
	v_fma_f32 v18, -v23, v17, v16
	v_fmac_f32_e32 v17, v18, v25
	v_div_scale_f32 v18, s[0:1], v26, v26, 1.0
	v_rcp_f32_e32 v19, v18
	v_fma_f32 v16, -v23, v17, v16
	v_div_fmas_f32 v16, v16, v25, v17
	v_div_fixup_f32 v17, v16, v27, 1.0
	v_fma_f32 v16, -v18, v19, 1.0
	v_pk_mul_f32 v[4:5], v[4:5], v[22:23] op_sel_hi:[1,0]
	v_fmac_f32_e32 v19, v16, v19
	v_div_scale_f32 v16, vcc, 1.0, v26, 1.0
	v_pk_fma_f32 v[4:5], v[8:9], v[4:5], v[12:13]
	v_mul_f32_e32 v20, v16, v19
	v_mul_f32_e32 v8, 0xbfb8aa3b, v4
	v_mul_f32_e32 v9, 0xbfb8aa3b, v5
	v_fma_f32 v21, -v18, v20, v16
	v_exp_f32_e32 v8, v8
	v_exp_f32_e32 v9, v9
	v_fmac_f32_e32 v20, v21, v19
	v_fma_f32 v16, -v18, v20, v16
	v_div_fmas_f32 v16, v16, v19, v20
	v_div_fixup_f32 v16, v16, v26, 1.0
	v_pk_add_f32 v[8:9], v[8:9], 1.0 op_sel_hi:[1,0]
	v_pk_mul_f32 v[12:13], v[14:15], v[16:17]
	v_div_scale_f32 v14, s[0:1], v9, v9, 1.0
	v_rcp_f32_e32 v15, v14
	v_pk_mul_f32 v[0:1], v[0:1], v[22:23] op_sel_hi:[1,0]
	s_nop 0
	v_pk_fma_f32 v[0:1], v[2:3], v[0:1], v[6:7]
	v_fma_f32 v3, -v14, v15, 1.0
	v_fmac_f32_e32 v15, v3, v15
	v_div_scale_f32 v3, vcc, 1.0, v9, 1.0
	v_mul_f32_e32 v6, v3, v15
	v_fma_f32 v7, -v14, v6, v3
	v_fmac_f32_e32 v6, v7, v15
	v_fma_f32 v3, -v14, v6, v3
	v_div_scale_f32 v14, s[0:1], v8, v8, 1.0
	v_rcp_f32_e32 v16, v14
	v_div_fmas_f32 v3, v3, v15, v6
	v_div_fixup_f32 v7, v3, v9, 1.0
	v_mul_f32_e32 v2, 0xbfb8aa3b, v0
	v_fma_f32 v3, -v14, v16, 1.0
	v_fmac_f32_e32 v16, v3, v16
	v_mul_f32_e32 v3, 0xbfb8aa3b, v1
	v_exp_f32_e32 v2, v2
	v_exp_f32_e32 v3, v3
	v_div_scale_f32 v6, vcc, 1.0, v8, 1.0
	v_mul_f32_e32 v9, v6, v16
	v_fma_f32 v15, -v14, v9, v6
	v_fmac_f32_e32 v9, v15, v16
	v_pk_add_f32 v[2:3], v[2:3], 1.0 op_sel_hi:[1,0]
	v_fma_f32 v6, -v14, v9, v6
	v_div_scale_f32 v14, s[0:1], v3, v3, 1.0
	v_rcp_f32_e32 v15, v14
	v_div_fmas_f32 v6, v6, v16, v9
	v_div_fixup_f32 v6, v6, v8, 1.0
	v_pk_mul_f32 v[4:5], v[4:5], v[6:7]
	v_fma_f32 v6, -v14, v15, 1.0
	v_fmac_f32_e32 v15, v6, v15
	v_div_scale_f32 v6, vcc, 1.0, v3, 1.0
	v_mul_f32_e32 v7, v6, v15
	v_fma_f32 v8, -v14, v7, v6
	v_fmac_f32_e32 v7, v8, v15
	v_div_scale_f32 v8, s[0:1], v2, v2, 1.0
	v_rcp_f32_e32 v9, v8
	v_fma_f32 v6, -v14, v7, v6
	v_div_fmas_f32 v6, v6, v15, v7
	v_div_fixup_f32 v3, v6, v3, 1.0
	v_fma_f32 v6, -v8, v9, 1.0
	v_fmac_f32_e32 v9, v6, v9
	v_div_scale_f32 v6, vcc, 1.0, v2, 1.0
	v_mul_f32_e32 v7, v6, v9
	v_fma_f32 v14, -v8, v7, v6
	v_fmac_f32_e32 v7, v14, v9
	v_fma_f32 v6, -v8, v7, v6
	v_div_fmas_f32 v6, v6, v9, v7
	v_div_fixup_f32 v2, v6, v2, 1.0
	v_pk_mul_f32 v[0:1], v[0:1], v[2:3]
	v_bfe_u32 v8, v4, 16, 1
	v_bfe_u32 v2, v1, 16, 1
	v_bfe_u32 v3, v0, 16, 1
	v_add3_u32 v0, v0, v3, s61
	v_add3_u32 v1, v1, v2, s61
	v_bfe_u32 v2, v10, 16, 1
	v_bfe_u32 v3, v11, 16, 1
	v_bfe_u32 v9, v5, 16, 1
	v_bfe_u32 v6, v13, 16, 1
	v_bfe_u32 v7, v12, 16, 1
	v_add3_u32 v5, v5, v9, s61
	v_add3_u32 v4, v4, v8, s61
	v_add3_u32 v3, v11, v3, s61
	v_add3_u32 v2, v10, v2, s61
	v_add3_u32 v7, v12, v7, s61
	v_add3_u32 v6, v13, v6, s61
	v_lshrrev_b32_e32 v8, 16, v2
	v_lshrrev_b32_e32 v9, 16, v3
	v_lshrrev_b32_e32 v2, 16, v4
	v_lshrrev_b32_e32 v3, 16, v5
	v_and_or_b32 v3, v1, s65, v3
	v_and_or_b32 v2, v0, s65, v2
	v_and_or_b32 v1, v6, s65, v9
	v_and_or_b32 v0, v7, s65, v8
	ds_write_b128 v24, v[0:3] offset:1584
	v_mov_b32_e32 v0, v117
	s_waitcnt lgkmcnt(0)
	s_barrier
	s_nop 0
	v_mbcnt_lo_u32_b32 v0, -1, v0
	v_mbcnt_hi_u32_b32 v2, -1, v0
	v_and_b32_e32 v12, 31, v2
	v_and_or_b32 v0, v32, s68, v12
	v_ashrrev_i32_e32 v1, 31, v0
	v_ashrrev_i32_e32 v2, 2, v2
	v_lshlrev_b64 v[0:1], 9, v[0:1]
	v_and_b32_e32 v8, -8, v2
	v_lshl_add_u64 v[0:1], s[8:9], 0, v[0:1]
	v_ashrrev_i32_e32 v9, 31, v8
	v_lshl_add_u64 v[10:11], v[8:9], 1, v[0:1]
	v_add_co_u32_e32 v0, vcc, s69, v10
	v_lshl_add_u64 v[62:63], v[10:11], 0, s[36:37]
	s_nop 0
	v_addc_co_u32_e32 v1, vcc, 0, v11, vcc
	global_load_dwordx4 v[198:201], v[0:1], off
	global_load_dwordx4 v[202:205], v[62:63], off offset:32
	v_add_co_u32_e32 v60, vcc, s70, v10
	s_nop 0
	s_nop 0
	v_addc_co_u32_e32 v61, vcc, 0, v11, vcc
	global_load_dwordx4 v[206:209], v[60:61], off
	global_load_dwordx4 v[210:213], v[60:61], off offset:32
	global_load_dwordx4 v[214:217], v[62:63], off offset:64
	global_load_dwordx4 v[218:221], v[60:61], off offset:64
	global_load_dwordx4 v[224:227], v[62:63], off offset:96
	global_load_dwordx4 v[228:231], v[60:61], off offset:96
	global_load_dwordx4 v[232:235], v[62:63], off offset:128
	global_load_dwordx4 v[236:239], v[60:61], off offset:128
	global_load_dwordx4 v[240:243], v[62:63], off offset:160
	global_load_dwordx4 v[248:251], v[60:61], off offset:160
	v_lshlrev_b32_e32 v8, 1, v8
	v_mad_u32_u24 v35, v12, s62, v8
	ds_read_b128 v[8:11], v35
	ds_read_b128 v[44:47], v35 offset:32
	s_waitcnt lgkmcnt(0)
	s_waitcnt vmcnt(11)
	v_mfma_f32_32x32x16_bf16 v[16:31], v[8:11], v[198:201], 0
	global_load_dwordx4 v[198:201], v[62:63], off offset:192
	s_waitcnt vmcnt(11)
	v_mfma_f32_32x32x16_bf16 v[16:31], v[44:47], v[202:205], v[16:31]
	global_load_dwordx4 v[202:205], v[60:61], off offset:192
	s_waitcnt vmcnt(11)
	v_mfma_f32_32x32x16_bf16 v[0:15], v[8:11], v[206:209], 0
	global_load_dwordx4 v[206:209], v[62:63], off offset:224
	s_waitcnt lgkmcnt(0)
	s_waitcnt vmcnt(11)
	v_mfma_f32_32x32x16_bf16 v[0:15], v[44:47], v[210:213], v[0:15]
	global_load_dwordx4 v[210:213], v[60:61], off offset:224
	ds_read_b128 v[44:47], v35 offset:64
	ds_read_b128 v[48:51], v35 offset:96
	s_waitcnt lgkmcnt(1)
	s_waitcnt vmcnt(10)
	v_mfma_f32_32x32x16_bf16 v[0:15], v[44:47], v[218:221], v[0:15]
	v_mfma_f32_32x32x16_bf16 v[16:31], v[44:47], v[214:217], v[16:31]
	global_load_dwordx4 v[214:217], v[62:63], off offset:256
	global_load_dwordx4 v[218:221], v[60:61], off offset:256
	s_waitcnt lgkmcnt(0)
	s_waitcnt vmcnt(11)
	v_mfma_f32_32x32x16_bf16 v[16:31], v[48:51], v[224:227], v[16:31]
	global_load_dwordx4 v[224:227], v[62:63], off offset:288
	s_waitcnt lgkmcnt(0)
	s_waitcnt vmcnt(11)
	v_mfma_f32_32x32x16_bf16 v[0:15], v[48:51], v[228:231], v[0:15]
	global_load_dwordx4 v[228:231], v[60:61], off offset:288
	ds_read_b128 v[48:51], v35 offset:128
	ds_read_b128 v[56:59], v35 offset:160
	s_waitcnt lgkmcnt(0)
	s_waitcnt vmcnt(11)
	v_mfma_f32_32x32x16_bf16 v[16:31], v[48:51], v[232:235], v[16:31]
	global_load_dwordx4 v[232:235], v[62:63], off offset:320
	s_waitcnt vmcnt(11)
	v_mfma_f32_32x32x16_bf16 v[0:15], v[48:51], v[236:239], v[0:15]
	global_load_dwordx4 v[236:239], v[60:61], off offset:320
	s_waitcnt vmcnt(11)
	v_mfma_f32_32x32x16_bf16 v[16:31], v[56:59], v[240:243], v[16:31]
	global_load_dwordx4 v[240:243], v[62:63], off offset:352
	ds_read_b128 v[52:55], v35 offset:192
	s_waitcnt lgkmcnt(0)
	s_waitcnt vmcnt(11)
	v_mfma_f32_32x32x16_bf16 v[0:15], v[56:59], v[248:251], v[0:15]
	global_load_dwordx4 v[248:251], v[60:61], off offset:352
	ds_read_b128 v[56:59], v35 offset:224
	s_waitcnt vmcnt(11)
	v_mfma_f32_32x32x16_bf16 v[16:31], v[52:55], v[198:201], v[16:31]
	global_load_dwordx4 v[198:201], v[62:63], off offset:384
	s_waitcnt vmcnt(11)
	v_mfma_f32_32x32x16_bf16 v[0:15], v[52:55], v[202:205], v[0:15]
	global_load_dwordx4 v[202:205], v[60:61], off offset:384
	s_waitcnt lgkmcnt(0)
	s_waitcnt vmcnt(11)
	v_mfma_f32_32x32x16_bf16 v[16:31], v[56:59], v[206:209], v[16:31]
	global_load_dwordx4 v[206:209], v[62:63], off offset:416
	s_waitcnt vmcnt(11)
	v_mfma_f32_32x32x16_bf16 v[0:15], v[56:59], v[210:213], v[0:15]
	global_load_dwordx4 v[210:213], v[60:61], off offset:416
	ds_read_b128 v[48:51], v35 offset:256
	ds_read_b128 v[56:59], v35 offset:288
	s_waitcnt lgkmcnt(0)
	s_waitcnt vmcnt(11)
	v_mfma_f32_32x32x16_bf16 v[16:31], v[48:51], v[214:217], v[16:31]
	global_load_dwordx4 v[214:217], v[62:63], off offset:448
	s_waitcnt vmcnt(11)
	v_mfma_f32_32x32x16_bf16 v[0:15], v[48:51], v[218:221], v[0:15]
	global_load_dwordx4 v[218:221], v[60:61], off offset:448
	s_waitcnt vmcnt(11)
	v_mfma_f32_32x32x16_bf16 v[16:31], v[56:59], v[224:227], v[16:31]
	global_load_dwordx4 v[224:227], v[62:63], off offset:480
	ds_read_b128 v[52:55], v35 offset:320
	s_waitcnt lgkmcnt(0)
	s_waitcnt vmcnt(11)
	v_mfma_f32_32x32x16_bf16 v[0:15], v[56:59], v[228:231], v[0:15]
	global_load_dwordx4 v[228:231], v[60:61], off offset:480
	ds_read_b128 v[56:59], v35 offset:352
	s_waitcnt vmcnt(11)
	v_mfma_f32_32x32x16_bf16 v[16:31], v[52:55], v[232:235], v[16:31]
	s_waitcnt vmcnt(10)
	v_mfma_f32_32x32x16_bf16 v[0:15], v[52:55], v[236:239], v[0:15]
	s_waitcnt lgkmcnt(0)
	s_waitcnt vmcnt(9)
	v_mfma_f32_32x32x16_bf16 v[16:31], v[56:59], v[240:243], v[16:31]
	s_waitcnt vmcnt(8)
	v_mfma_f32_32x32x16_bf16 v[0:15], v[56:59], v[248:251], v[0:15]
	ds_read_b128 v[48:51], v35 offset:384
	ds_read_b128 v[56:59], v35 offset:416
	s_waitcnt lgkmcnt(0)
	s_waitcnt vmcnt(7)
	v_mfma_f32_32x32x16_bf16 v[16:31], v[48:51], v[198:201], v[16:31]
	s_waitcnt vmcnt(6)
	v_mfma_f32_32x32x16_bf16 v[0:15], v[48:51], v[202:205], v[0:15]
	s_waitcnt vmcnt(5)
	v_mfma_f32_32x32x16_bf16 v[16:31], v[56:59], v[206:209], v[16:31]
	ds_read_b128 v[52:55], v35 offset:448
	s_waitcnt lgkmcnt(0)
	s_waitcnt vmcnt(4)
	v_mfma_f32_32x32x16_bf16 v[0:15], v[56:59], v[210:213], v[0:15]
	ds_read_b128 v[56:59], v35 offset:480
	s_waitcnt vmcnt(3)
	v_mfma_f32_32x32x16_bf16 v[16:31], v[52:55], v[214:217], v[16:31]
	s_waitcnt vmcnt(2)
	v_mfma_f32_32x32x16_bf16 v[0:15], v[52:55], v[218:221], v[0:15]
	s_waitcnt lgkmcnt(0)
	s_waitcnt vmcnt(1)
	v_mfma_f32_32x32x16_bf16 v[16:31], v[56:59], v[224:227], v[16:31]
	s_waitcnt vmcnt(0)
	v_mfma_f32_32x32x16_bf16 v[0:15], v[56:59], v[228:231], v[0:15]
	v_lshrrev_b32_e32 v35, 3, v32
	v_and_b32_e32 v35, 4, v35
	v_mul_u32_u24_e32 v35, 0x108, v35
	v_and_b32_e32 v37, 0x7fffffdf, v32
	s_nop 6
	v_bfe_u32 v39, v16, 16, 1
	v_lshlrev_b32_e32 v35, 1, v35
	v_add3_u32 v16, v16, v39, s61
	v_lshl_add_u32 v35, v37, 1, v35
	ds_write_b16_d16_hi v35, v16 offset:16896
	v_bfe_u32 v16, v17, 16, 1
	v_add3_u32 v16, v17, v16, s61
	ds_write_b16_d16_hi v35, v16 offset:17424
	v_bfe_u32 v16, v18, 16, 1
	v_add3_u32 v16, v18, v16, s61
	ds_write_b16_d16_hi v35, v16 offset:17952
	v_bfe_u32 v16, v19, 16, 1
	v_add3_u32 v16, v19, v16, s61
	ds_write_b16_d16_hi v35, v16 offset:18480
	v_bfe_u32 v16, v20, 16, 1
	v_add3_u32 v16, v20, v16, s61
	ds_write_b16_d16_hi v35, v16 offset:21120
	v_bfe_u32 v16, v21, 16, 1
	v_add3_u32 v16, v21, v16, s61
	ds_write_b16_d16_hi v35, v16 offset:21648
	v_bfe_u32 v16, v22, 16, 1
	v_add3_u32 v16, v22, v16, s61
	ds_write_b16_d16_hi v35, v16 offset:22176
	v_bfe_u32 v16, v23, 16, 1
	v_add3_u32 v16, v23, v16, s61
	ds_write_b16_d16_hi v35, v16 offset:22704
	v_bfe_u32 v16, v24, 16, 1
	v_add3_u32 v16, v24, v16, s61
	ds_write_b16_d16_hi v35, v16 offset:25344
	v_bfe_u32 v16, v25, 16, 1
	v_add3_u32 v16, v25, v16, s61
	ds_write_b16_d16_hi v35, v16 offset:25872
	v_bfe_u32 v16, v26, 16, 1
	v_add3_u32 v16, v26, v16, s61
	ds_write_b16_d16_hi v35, v16 offset:26400
	v_bfe_u32 v16, v27, 16, 1
	v_add3_u32 v16, v27, v16, s61
	ds_write_b16_d16_hi v35, v16 offset:26928
	v_bfe_u32 v16, v28, 16, 1
	v_add3_u32 v16, v28, v16, s61
	ds_write_b16_d16_hi v35, v16 offset:29568
	v_bfe_u32 v16, v29, 16, 1
	v_add3_u32 v16, v29, v16, s61
	ds_write_b16_d16_hi v35, v16 offset:30096
	v_bfe_u32 v16, v30, 16, 1
	v_add3_u32 v16, v30, v16, s61
	ds_write_b16_d16_hi v35, v16 offset:30624
	v_bfe_u32 v16, v31, 16, 1
	v_add3_u32 v16, v31, v16, s61
	ds_write_b16_d16_hi v35, v16 offset:31152
	v_bfe_u32 v16, v0, 16, 1
	v_add3_u32 v0, v0, v16, s61
	ds_write_b16_d16_hi v35, v0 offset:16960
	v_bfe_u32 v0, v1, 16, 1
	v_add3_u32 v0, v1, v0, s61
	ds_write_b16_d16_hi v35, v0 offset:17488
	v_bfe_u32 v0, v2, 16, 1
	v_add3_u32 v0, v2, v0, s61
	ds_write_b16_d16_hi v35, v0 offset:18016
	v_bfe_u32 v0, v3, 16, 1
	v_add3_u32 v0, v3, v0, s61
	ds_write_b16_d16_hi v35, v0 offset:18544
	v_bfe_u32 v0, v4, 16, 1
	v_add3_u32 v0, v4, v0, s61
	ds_write_b16_d16_hi v35, v0 offset:21184
	v_bfe_u32 v0, v5, 16, 1
	v_add3_u32 v0, v5, v0, s61
	ds_write_b16_d16_hi v35, v0 offset:21712
	v_bfe_u32 v0, v6, 16, 1
	v_add3_u32 v0, v6, v0, s61
	ds_write_b16_d16_hi v35, v0 offset:22240
	v_bfe_u32 v0, v7, 16, 1
	v_add3_u32 v0, v7, v0, s61
	ds_write_b16_d16_hi v35, v0 offset:22768
	v_bfe_u32 v0, v8, 16, 1
	v_add3_u32 v0, v8, v0, s61
	ds_write_b16_d16_hi v35, v0 offset:25408
	v_bfe_u32 v0, v9, 16, 1
	v_add3_u32 v0, v9, v0, s61
	ds_write_b16_d16_hi v35, v0 offset:25936
	v_bfe_u32 v0, v10, 16, 1
	v_add3_u32 v0, v10, v0, s61
	ds_write_b16_d16_hi v35, v0 offset:26464
	v_bfe_u32 v0, v11, 16, 1
	v_add3_u32 v0, v11, v0, s61
	ds_write_b16_d16_hi v35, v0 offset:26992
	v_bfe_u32 v0, v12, 16, 1
	v_add3_u32 v0, v12, v0, s61
	ds_write_b16_d16_hi v35, v0 offset:29632
	v_bfe_u32 v0, v13, 16, 1
	v_add3_u32 v0, v13, v0, s61
	ds_write_b16_d16_hi v35, v0 offset:30160
	v_bfe_u32 v0, v14, 16, 1
	v_add3_u32 v0, v14, v0, s61
	ds_write_b16_d16_hi v35, v0 offset:30688
	v_bfe_u32 v0, v15, 16, 1
	v_add3_u32 v0, v15, v0, s61
	v_lshlrev_b32_e32 v116, 1, v38
	ds_write_b16_d16_hi v35, v0 offset:31216
	v_lshl_add_u64 v[0:1], s[8:9], 0, v[116:117]
	v_lshl_add_u64 v[4:5], v[0:1], 0, s[38:39]
	v_mad_u64_u32 v[0:1], s[0:1], v33, s62, v[36:37]
	s_waitcnt lgkmcnt(0)
	s_barrier
	ds_read_b128 v[0:3], v0 offset:16896
	v_add_u32_e32 v6, s55, v33
	v_ashrrev_i32_e32 v7, 31, v6
	v_lshlrev_b64 v[6:7], 11, v[6:7]
	v_lshl_add_u64 v[6:7], v[4:5], 0, v[6:7]
	s_waitcnt lgkmcnt(0)
	global_store_dwordx4 v[6:7], v[0:3], off
	s_nop 1
	v_add_u32_e32 v0, 0x100, v32
	v_ashrrev_i32_e32 v6, 5, v0
	v_mad_u64_u32 v[0:1], s[0:1], v6, s62, v[36:37]
	ds_read_b128 v[0:3], v0 offset:16896
	v_add_u32_e32 v6, s55, v6
	v_ashrrev_i32_e32 v7, 31, v6
	v_lshlrev_b64 v[6:7], 11, v[6:7]
	v_lshl_add_u64 v[6:7], v[4:5], 0, v[6:7]
	s_waitcnt lgkmcnt(0)
	global_store_dwordx4 v[6:7], v[0:3], off
	v_ashrrev_i32_e32 v6, 5, v34
	s_nop 0
	v_mad_u64_u32 v[0:1], s[0:1], v6, s62, v[36:37]
	ds_read_b128 v[0:3], v0 offset:16896
	v_add_u32_e32 v6, s55, v6
	v_ashrrev_i32_e32 v7, 31, v6
	v_lshlrev_b64 v[6:7], 11, v[6:7]
	v_lshl_add_u64 v[6:7], v[4:5], 0, v[6:7]
	s_waitcnt lgkmcnt(0)
	global_store_dwordx4 v[6:7], v[0:3], off
	s_nop 1
	v_add_u32_e32 v0, 0x300, v32
	v_ashrrev_i32_e32 v6, 5, v0
	v_mad_u64_u32 v[0:1], s[0:1], v6, s62, v[36:37]
	ds_read_b128 v[0:3], v0 offset:16896
	v_add_u32_e32 v6, s55, v6
	v_ashrrev_i32_e32 v7, 31, v6
	v_lshlrev_b64 v[6:7], 11, v[6:7]
	v_lshl_add_u64 v[4:5], v[4:5], 0, v[6:7]
	s_waitcnt lgkmcnt(0)
	global_store_dwordx4 v[4:5], v[0:3], off
